# v12 + sc0 cache policy on all K-loop LDS-DMA tile loads (TCP no-reuse hint); nt on B loads was +12% slower
# speedup vs baseline: 1.0012x; 1.0012x over previous
; #define PG8_STAGE(bufoff, gbase, voff) do { _Pragma("unroll") for (int _i = 0; _i < 2; ++_i) \
;         __builtin_amdgcn_global_load_lds((const unsigned*)((const char*)(gbase) + (voff)[_i]), (PG8_LAS unsigned*)(lds + (bufoff) + ldsw + _i * 8192), 16, 0, 0); } while (0)
; #define PG8_LDA(dst, b, h) do { _Pragma("unroll") for (int m = 0; m < 4; ++m) _Pragma("unroll") for (int k = 0; k < 2; ++k) dst[m][k] = *(const PG8_LAS bf16x8*)(lds + PG8_SA(b, h) + aoff + m * 2048 + k * 1024); } while (0)
; #define PG8_LDB(dst, b, h) do { _Pragma("unroll") for (int n = 0; n < 2; ++n) _Pragma("unroll") for (int k = 0; k < 2; ++k) dst[n][k] = *(const PG8_LAS bf16x8*)(lds + PG8_SB(b, h) + boff + n * 2048 + k * 1024); } while (0)
; #define PG8_MMA(ai, bj, At, Bt) do { __builtin_amdgcn_s_setprio(1); _Pragma("unroll") for (int m = 0; m < 4; ++m) _Pragma("unroll") for (int n = 0; n < 2; ++n) _Pragma("unroll") for (int k = 0; k < 2; ++k) \
;         acc[ai][bj][m][n] = __builtin_amdgcn_mfma_f32_16x16x32_bf16(Bt[n][k], At[m][k], acc[ai][bj][m][n], 0, 0, 0); __builtin_amdgcn_s_setprio(0); } while (0)
; #define PG8_WAIT_V(n) asm volatile("s_waitcnt vmcnt(" #n ")" ::: "memory")
; #define PG8_WAIT_L(n) asm volatile("s_waitcnt lgkmcnt(" #n ")" ::: "memory")
; #define PG8_BAR __builtin_amdgcn_s_barrier()
; #define PG8_SCHED __builtin_amdgcn_sched_barrier(0)
; template <class Epi>
; __device__ __forceinline__ void gemm_phase(PG8_LAS unsigned char* lds, PG8_LAS unsigned char* xl, const Gemm g, const Sched& S, const Epi& E, const int wid) {
;     ...
;             PG8_LDB(B0, 0, 0); PG8_LDB(B1, 0, 1); PG8_SCHED; PG8_LDA(At, 0, 0); PG8_STAGE(PG8_SA(1, 1), a1 + hstepA, voffA);
;             PG8_WAIT_V(8); PG8_WAIT_L(0); PG8_BAR; if (do0) { PG8_MMA(0, 0, At, B0); PG8_MMA(0, 1, At, B1); } PG8_BAR; PG8_SCHED;
;             PG8_LDA(At, 0, 1); PG8_STAGE(PG8_SB(0, 0), b2, voffB); PG8_STAGE(PG8_SB(0, 1), b2 + hstepB, voffB); PG8_STAGE(PG8_SA(0, 0), a2, voffA);
;             PG8_WAIT_V(8); PG8_WAIT_L(0); PG8_BAR; if (do1) { PG8_MMA(1, 0, At, B0); PG8_MMA(1, 1, At, B1); } PG8_BAR; PG8_SCHED;
.Ldefbar_skip_0:
	v_add_u32_e32 v141, s22, v128
	v_add_u32_e32 v226, s22, v130
	v_add_u32_e32 v227, s22, v132
	v_add_u32_e32 v228, s22, v134
	v_add_u32_e32 v229, 0x10000, v142
	s_add_u32 s52, s50, 0x100
	s_addc_u32 s53, s51, 0
	s_add_i32 s54, 0, 0x10000
	s_cmp_eq_u32 s43, 28
	s_cselect_b32 s59, s8, s53
	s_cselect_b32 s58, s9, s52
	s_cselect_b32 s57, s10, s21
	s_cselect_b32 s56, s11, s13
	s_add_i32 s55, 0, 0x14000
	ds_read_b128 v[144:147], v229 offset:0
	ds_read_b128 v[148:151], v229 offset:1024
	ds_read_b128 v[152:155], v229 offset:2048
	ds_read_b128 v[156:159], v229 offset:3072
	ds_read_b128 v[160:163], v229 offset:16384
	ds_read_b128 v[164:167], v229 offset:17408
	ds_read_b128 v[168:171], v229 offset:18432
	ds_read_b128 v[172:175], v229 offset:19456
	s_add_i32 m0, s37, 0xc000
	ds_read_b128 v[176:179], v143
	ds_read_b128 v[180:183], v143 offset:1024
	ds_read_b128 v[184:187], v143 offset:2048
	ds_read_b128 v[188:191], v143 offset:3072
	ds_read_b128 v[210:213], v143 offset:4096
	ds_read_b128 v[214:217], v143 offset:5120
	ds_read_b128 v[218:221], v143 offset:6144
	ds_read_b128 v[222:225], v143 offset:7168
	global_load_lds_dwordx4 v136, s[50:51] sc0
	s_add_i32 m0, s37, 0xe000
	s_nop 0
	global_load_lds_dwordx4 v138, s[50:51] sc0
	s_waitcnt vmcnt(8)
	s_waitcnt lgkmcnt(0)
	s_setprio 1
	s_barrier
	v_mfma_f32_16x16x32_bf16 v[124:127], v[144:147], v[176:179], 0
	v_mfma_f32_16x16x32_bf16 v[120:123], v[152:155], v[176:179], 0
	v_mfma_f32_16x16x32_bf16 v[116:119], v[144:147], v[184:187], 0
	v_mfma_f32_16x16x32_bf16 v[108:111], v[152:155], v[184:187], 0
	v_mfma_f32_16x16x32_bf16 v[100:103], v[144:147], v[210:213], 0
	v_mfma_f32_16x16x32_bf16 v[92:95], v[152:155], v[210:213], 0
	v_mfma_f32_16x16x32_bf16 v[84:87], v[144:147], v[218:221], 0
	v_mfma_f32_16x16x32_bf16 v[76:79], v[152:155], v[218:221], 0
	v_mfma_f32_16x16x32_bf16 v[124:127], v[148:151], v[180:183], v[124:127]
	v_mfma_f32_16x16x32_bf16 v[120:123], v[156:159], v[180:183], v[120:123]
	v_mfma_f32_16x16x32_bf16 v[116:119], v[148:151], v[188:191], v[116:119]
	v_mfma_f32_16x16x32_bf16 v[108:111], v[156:159], v[188:191], v[108:111]
	v_mfma_f32_16x16x32_bf16 v[100:103], v[148:151], v[214:217], v[100:103]
	v_mfma_f32_16x16x32_bf16 v[92:95], v[156:159], v[214:217], v[92:95]
	v_mfma_f32_16x16x32_bf16 v[84:87], v[148:151], v[222:225], v[84:87]
	v_mfma_f32_16x16x32_bf16 v[76:79], v[156:159], v[222:225], v[76:79]
	s_setprio 0
	s_setprio 1
	v_mfma_f32_16x16x32_bf16 v[112:115], v[160:163], v[176:179], 0
	v_mfma_f32_16x16x32_bf16 v[104:107], v[168:171], v[176:179], 0
	v_mfma_f32_16x16x32_bf16 v[96:99], v[160:163], v[184:187], 0
	v_mfma_f32_16x16x32_bf16 v[88:91], v[168:171], v[184:187], 0
	v_mfma_f32_16x16x32_bf16 v[80:83], v[160:163], v[210:213], 0
	v_mfma_f32_16x16x32_bf16 v[72:75], v[168:171], v[210:213], 0
	v_mfma_f32_16x16x32_bf16 v[68:71], v[160:163], v[218:221], 0
	v_mfma_f32_16x16x32_bf16 v[64:67], v[168:171], v[218:221], 0
	v_mfma_f32_16x16x32_bf16 v[112:115], v[164:167], v[180:183], v[112:115]
	v_mfma_f32_16x16x32_bf16 v[104:107], v[172:175], v[180:183], v[104:107]
	v_mfma_f32_16x16x32_bf16 v[96:99], v[164:167], v[188:191], v[96:99]
	v_mfma_f32_16x16x32_bf16 v[88:91], v[172:175], v[188:191], v[88:91]
	v_mfma_f32_16x16x32_bf16 v[80:83], v[164:167], v[214:217], v[80:83]
	v_mfma_f32_16x16x32_bf16 v[72:75], v[172:175], v[214:217], v[72:75]
	v_mfma_f32_16x16x32_bf16 v[68:71], v[164:167], v[222:225], v[68:71]
	v_mfma_f32_16x16x32_bf16 v[64:67], v[172:175], v[222:225], v[64:67]
	s_barrier
	s_setprio 0
	s_add_i32 s50, s54, s29
	s_mov_b32 m0, s50
	ds_read_b128 v[176:179], v143 offset:16384
	ds_read_b128 v[180:183], v143 offset:17408
	ds_read_b128 v[184:187], v143 offset:18432
	ds_read_b128 v[188:191], v143 offset:19456
	ds_read_b128 v[210:213], v143 offset:20480
	ds_read_b128 v[214:217], v143 offset:21504
	ds_read_b128 v[218:221], v143 offset:22528
	ds_read_b128 v[222:225], v143 offset:23552
	global_load_lds_dwordx4 v132, s[56:57] sc0
	s_add_i32 m0, s50, 0x2000
	s_add_u32 s50, s56, 0x80000
	s_addc_u32 s51, s57, 0
	s_add_i32 s54, s55, s29
	global_load_lds_dwordx4 v128, s[56:57] sc0
	s_mov_b32 m0, s54
	s_nop 0
	global_load_lds_dwordx4 v132, s[50:51] sc0
	s_add_i32 m0, s54, 0x2000
	s_nop 0
	global_load_lds_dwordx4 v128, s[50:51] sc0
	s_mov_b32 m0, s37
	s_nop 0
	global_load_lds_dwordx4 v134, s[58:59] sc0
	s_mov_b32 m0, s68
	s_nop 0
	global_load_lds_dwordx4 v130, s[58:59] sc0
	s_waitcnt vmcnt(8)
	s_waitcnt lgkmcnt(0)
	s_setprio 1
	s_barrier
	v_mfma_f32_16x16x32_bf16 v[60:63], v[144:147], v[176:179], 0
	v_mfma_f32_16x16x32_bf16 v[56:59], v[152:155], v[176:179], 0
	v_mfma_f32_16x16x32_bf16 v[52:55], v[144:147], v[184:187], 0
	v_mfma_f32_16x16x32_bf16 v[44:47], v[152:155], v[184:187], 0
	v_mfma_f32_16x16x32_bf16 v[36:39], v[144:147], v[210:213], 0
	v_mfma_f32_16x16x32_bf16 v[28:31], v[152:155], v[210:213], 0
	v_mfma_f32_16x16x32_bf16 v[20:23], v[144:147], v[218:221], 0
	v_mfma_f32_16x16x32_bf16 v[12:15], v[152:155], v[218:221], 0
	v_mfma_f32_16x16x32_bf16 v[60:63], v[148:151], v[180:183], v[60:63]
	v_mfma_f32_16x16x32_bf16 v[56:59], v[156:159], v[180:183], v[56:59]
	v_mfma_f32_16x16x32_bf16 v[52:55], v[148:151], v[188:191], v[52:55]
	v_mfma_f32_16x16x32_bf16 v[44:47], v[156:159], v[188:191], v[44:47]
	v_mfma_f32_16x16x32_bf16 v[36:39], v[148:151], v[214:217], v[36:39]
	v_mfma_f32_16x16x32_bf16 v[28:31], v[156:159], v[214:217], v[28:31]
	v_mfma_f32_16x16x32_bf16 v[20:23], v[148:151], v[222:225], v[20:23]
	v_mfma_f32_16x16x32_bf16 v[12:15], v[156:159], v[222:225], v[12:15]
	s_setprio 0
	s_setprio 1
	v_mfma_f32_16x16x32_bf16 v[48:51], v[160:163], v[176:179], 0
	v_mfma_f32_16x16x32_bf16 v[40:43], v[168:171], v[176:179], 0
	v_mfma_f32_16x16x32_bf16 v[32:35], v[160:163], v[184:187], 0
	v_mfma_f32_16x16x32_bf16 v[24:27], v[168:171], v[184:187], 0
	v_mfma_f32_16x16x32_bf16 v[16:19], v[160:163], v[210:213], 0
	v_mfma_f32_16x16x32_bf16 v[8:11], v[168:171], v[210:213], 0
	v_mfma_f32_16x16x32_bf16 v[4:7], v[160:163], v[218:221], 0
	v_mfma_f32_16x16x32_bf16 v[0:3], v[168:171], v[218:221], 0
	v_mfma_f32_16x16x32_bf16 v[48:51], v[164:167], v[180:183], v[48:51]
	v_mfma_f32_16x16x32_bf16 v[40:43], v[172:175], v[180:183], v[40:43]
	v_mfma_f32_16x16x32_bf16 v[32:35], v[164:167], v[188:191], v[32:35]
	v_mfma_f32_16x16x32_bf16 v[24:27], v[172:175], v[188:191], v[24:27]
	v_mfma_f32_16x16x32_bf16 v[16:19], v[164:167], v[214:217], v[16:19]
	v_mfma_f32_16x16x32_bf16 v[8:11], v[172:175], v[214:217], v[8:11]
	v_mfma_f32_16x16x32_bf16 v[4:7], v[164:167], v[222:225], v[4:7]
	v_mfma_f32_16x16x32_bf16 v[0:3], v[172:175], v[222:225], v[0:3]
	s_barrier
; #define PG8_STAGE(bufoff, gbase, voff) do { _Pragma("unroll") for (int _i = 0; _i < 2; ++_i) \
;         __builtin_amdgcn_global_load_lds((const unsigned*)((const char*)(gbase) + (voff)[_i]), (PG8_LAS unsigned*)(lds + (bufoff) + ldsw + _i * 8192), 16, 0, 0); } while (0)
; #define PG8_LDA(dst, b, h) do { _Pragma("unroll") for (int m = 0; m < 4; ++m) _Pragma("unroll") for (int k = 0; k < 2; ++k) dst[m][k] = *(const PG8_LAS bf16x8*)(lds + PG8_SA(b, h) + aoff + m * 2048 + k * 1024); } while (0)
; #define PG8_LDB(dst, b, h) do { _Pragma("unroll") for (int n = 0; n < 2; ++n) _Pragma("unroll") for (int k = 0; k < 2; ++k) dst[n][k] = *(const PG8_LAS bf16x8*)(lds + PG8_SB(b, h) + boff + n * 2048 + k * 1024); } while (0)
; #define PG8_MMA(ai, bj, At, Bt) do { __builtin_amdgcn_s_setprio(1); _Pragma("unroll") for (int m = 0; m < 4; ++m) _Pragma("unroll") for (int n = 0; n < 2; ++n) _Pragma("unroll") for (int k = 0; k < 2; ++k) \
;         acc[ai][bj][m][n] = __builtin_amdgcn_mfma_f32_16x16x32_bf16(Bt[n][k], At[m][k], acc[ai][bj][m][n], 0, 0, 0); __builtin_amdgcn_s_setprio(0); } while (0)
; #define PG8_WAIT_V(n) asm volatile("s_waitcnt vmcnt(" #n ")" ::: "memory")
; #define PG8_WAIT_L(n) asm volatile("s_waitcnt lgkmcnt(" #n ")" ::: "memory")
; #define PG8_BAR __builtin_amdgcn_s_barrier()
; #define PG8_SCHED __builtin_amdgcn_sched_barrier(0)
; template <class Epi>
; __device__ __forceinline__ void gemm_phase(PG8_LAS unsigned char* lds, PG8_LAS unsigned char* xl, const Gemm g, const Sched& S, const Epi& E, const int wid) {
;     ...
;             PG8_LDB(B0, 1, 0); PG8_LDB(B1, 1, 1); PG8_SCHED; PG8_LDA(At, 1, 0); PG8_STAGE(PG8_SA(0, 1), a2 + hstepA, voffA);
;             PG8_WAIT_V(8); PG8_WAIT_L(0); PG8_BAR; if (do0) { PG8_MMA(0, 0, At, B0); PG8_MMA(0, 1, At, B1); } PG8_BAR; PG8_SCHED;
;             PG8_LDA(At, 1, 1); PG8_STAGE(PG8_SB(1, 0), b3, voffB); PG8_STAGE(PG8_SB(1, 1), b3 + hstepB, voffB); PG8_STAGE(PG8_SA(1, 0), a3, voffA);
;             PG8_WAIT_V(8); PG8_WAIT_L(0); PG8_BAR; if (do1) { PG8_MMA(1, 0, At, B0); PG8_MMA(1, 1, At, B1); } PG8_BAR; PG8_SCHED;
;         }
	s_setprio 0
	s_add_i32 s54, 0, 0x18000
	s_add_i32 s55, 0, 0x1c000
	ds_read_b128 v[144:147], v229 offset:32768
	ds_read_b128 v[148:151], v229 offset:33792
	ds_read_b128 v[152:155], v229 offset:34816
	ds_read_b128 v[156:159], v229 offset:35840
	ds_read_b128 v[160:163], v229 offset:49152
	ds_read_b128 v[164:167], v229 offset:50176
	ds_read_b128 v[168:171], v229 offset:51200
	ds_read_b128 v[172:175], v229 offset:52224
	s_add_u32 s50, s58, 0x80000
	s_addc_u32 s51, s59, 0
	s_mov_b32 m0, s69
	ds_read_b128 v[176:179], v143 offset:32768
	ds_read_b128 v[180:183], v143 offset:33792
	ds_read_b128 v[184:187], v143 offset:34816
	ds_read_b128 v[188:191], v143 offset:35840
	ds_read_b128 v[210:213], v143 offset:36864
	ds_read_b128 v[214:217], v143 offset:37888
	ds_read_b128 v[218:221], v143 offset:38912
	ds_read_b128 v[222:225], v143 offset:39936
	global_load_lds_dwordx4 v134, s[50:51] sc0
	s_mov_b32 m0, s70
	s_nop 0
	global_load_lds_dwordx4 v130, s[50:51] sc0
	s_waitcnt vmcnt(8)
	s_waitcnt lgkmcnt(0)
	s_setprio 1
	s_barrier
	v_mfma_f32_16x16x32_bf16 v[124:127], v[144:147], v[176:179], v[124:127]
	v_mfma_f32_16x16x32_bf16 v[120:123], v[152:155], v[176:179], v[120:123]
	v_mfma_f32_16x16x32_bf16 v[116:119], v[144:147], v[184:187], v[116:119]
	v_mfma_f32_16x16x32_bf16 v[108:111], v[152:155], v[184:187], v[108:111]
	v_mfma_f32_16x16x32_bf16 v[100:103], v[144:147], v[210:213], v[100:103]
	v_mfma_f32_16x16x32_bf16 v[92:95], v[152:155], v[210:213], v[92:95]
	v_mfma_f32_16x16x32_bf16 v[84:87], v[144:147], v[218:221], v[84:87]
	v_mfma_f32_16x16x32_bf16 v[76:79], v[152:155], v[218:221], v[76:79]
	v_mfma_f32_16x16x32_bf16 v[124:127], v[148:151], v[180:183], v[124:127]
	v_mfma_f32_16x16x32_bf16 v[120:123], v[156:159], v[180:183], v[120:123]
	v_mfma_f32_16x16x32_bf16 v[116:119], v[148:151], v[188:191], v[116:119]
	v_mfma_f32_16x16x32_bf16 v[108:111], v[156:159], v[188:191], v[108:111]
	v_mfma_f32_16x16x32_bf16 v[100:103], v[148:151], v[214:217], v[100:103]
	v_mfma_f32_16x16x32_bf16 v[92:95], v[156:159], v[214:217], v[92:95]
	v_mfma_f32_16x16x32_bf16 v[84:87], v[148:151], v[222:225], v[84:87]
	v_mfma_f32_16x16x32_bf16 v[76:79], v[156:159], v[222:225], v[76:79]
	s_setprio 0
	s_setprio 1
	v_mfma_f32_16x16x32_bf16 v[112:115], v[160:163], v[176:179], v[112:115]
	v_mfma_f32_16x16x32_bf16 v[104:107], v[168:171], v[176:179], v[104:107]
	v_mfma_f32_16x16x32_bf16 v[96:99], v[160:163], v[184:187], v[96:99]
	v_mfma_f32_16x16x32_bf16 v[88:91], v[168:171], v[184:187], v[88:91]
	v_mfma_f32_16x16x32_bf16 v[80:83], v[160:163], v[210:213], v[80:83]
	v_mfma_f32_16x16x32_bf16 v[72:75], v[168:171], v[210:213], v[72:75]
	v_mfma_f32_16x16x32_bf16 v[68:71], v[160:163], v[218:221], v[68:71]
	v_mfma_f32_16x16x32_bf16 v[64:67], v[168:171], v[218:221], v[64:67]
	v_mfma_f32_16x16x32_bf16 v[112:115], v[164:167], v[180:183], v[112:115]
	v_mfma_f32_16x16x32_bf16 v[104:107], v[172:175], v[180:183], v[104:107]
	v_mfma_f32_16x16x32_bf16 v[96:99], v[164:167], v[188:191], v[96:99]
	v_mfma_f32_16x16x32_bf16 v[88:91], v[172:175], v[188:191], v[88:91]
	v_mfma_f32_16x16x32_bf16 v[80:83], v[164:167], v[214:217], v[80:83]
	v_mfma_f32_16x16x32_bf16 v[72:75], v[172:175], v[214:217], v[72:75]
	v_mfma_f32_16x16x32_bf16 v[68:71], v[164:167], v[222:225], v[68:71]
	v_mfma_f32_16x16x32_bf16 v[64:67], v[172:175], v[222:225], v[64:67]
	s_barrier
	s_setprio 0
	s_add_i32 s50, s54, s29
	s_mov_b32 m0, s50
	ds_read_b128 v[176:179], v143 offset:49152
	ds_read_b128 v[180:183], v143 offset:50176
	ds_read_b128 v[184:187], v143 offset:51200
	ds_read_b128 v[188:191], v143 offset:52224
	ds_read_b128 v[210:213], v143 offset:53248
	ds_read_b128 v[214:217], v143 offset:54272
	ds_read_b128 v[218:221], v143 offset:55296
	ds_read_b128 v[222:225], v143 offset:56320
	global_load_lds_dwordx4 v227, s[56:57] sc0
	s_add_i32 m0, s50, 0x2000
	s_add_u32 s50, s56, 0x80080
	global_load_lds_dwordx4 v141, s[56:57] sc0
	s_addc_u32 s51, s57, 0
	s_add_i32 s54, s55, s29
	s_mov_b32 m0, s54
	s_nop 0
	global_load_lds_dwordx4 v132, s[50:51] sc0
	s_add_i32 m0, s54, 0x2000
	s_nop 0
	global_load_lds_dwordx4 v128, s[50:51] sc0
	s_mov_b32 m0, s77
	s_nop 0
	global_load_lds_dwordx4 v228, s[58:59] sc0
	s_mov_b32 m0, s87
	s_nop 0
	global_load_lds_dwordx4 v226, s[58:59] sc0
	s_waitcnt vmcnt(8)
	s_waitcnt lgkmcnt(0)
	s_setprio 1
	s_barrier
	v_mfma_f32_16x16x32_bf16 v[60:63], v[144:147], v[176:179], v[60:63]
	v_mfma_f32_16x16x32_bf16 v[56:59], v[152:155], v[176:179], v[56:59]
	v_mfma_f32_16x16x32_bf16 v[52:55], v[144:147], v[184:187], v[52:55]
	v_mfma_f32_16x16x32_bf16 v[44:47], v[152:155], v[184:187], v[44:47]
	v_mfma_f32_16x16x32_bf16 v[36:39], v[144:147], v[210:213], v[36:39]
	v_mfma_f32_16x16x32_bf16 v[28:31], v[152:155], v[210:213], v[28:31]
	v_mfma_f32_16x16x32_bf16 v[20:23], v[144:147], v[218:221], v[20:23]
	v_mfma_f32_16x16x32_bf16 v[12:15], v[152:155], v[218:221], v[12:15]
	v_mfma_f32_16x16x32_bf16 v[60:63], v[148:151], v[180:183], v[60:63]
	v_mfma_f32_16x16x32_bf16 v[56:59], v[156:159], v[180:183], v[56:59]
	v_mfma_f32_16x16x32_bf16 v[52:55], v[148:151], v[188:191], v[52:55]
	v_mfma_f32_16x16x32_bf16 v[44:47], v[156:159], v[188:191], v[44:47]
	v_mfma_f32_16x16x32_bf16 v[36:39], v[148:151], v[214:217], v[36:39]
	v_mfma_f32_16x16x32_bf16 v[28:31], v[156:159], v[214:217], v[28:31]
	v_mfma_f32_16x16x32_bf16 v[20:23], v[148:151], v[222:225], v[20:23]
	v_mfma_f32_16x16x32_bf16 v[12:15], v[156:159], v[222:225], v[12:15]
	s_setprio 0
	s_setprio 1
	v_mfma_f32_16x16x32_bf16 v[48:51], v[160:163], v[176:179], v[48:51]
	v_mfma_f32_16x16x32_bf16 v[40:43], v[168:171], v[176:179], v[40:43]
	v_mfma_f32_16x16x32_bf16 v[32:35], v[160:163], v[184:187], v[32:35]
	v_mfma_f32_16x16x32_bf16 v[24:27], v[168:171], v[184:187], v[24:27]
	v_mfma_f32_16x16x32_bf16 v[16:19], v[160:163], v[210:213], v[16:19]
	v_mfma_f32_16x16x32_bf16 v[8:11], v[168:171], v[210:213], v[8:11]
	v_mfma_f32_16x16x32_bf16 v[4:7], v[160:163], v[218:221], v[4:7]
	v_mfma_f32_16x16x32_bf16 v[0:3], v[168:171], v[218:221], v[0:3]
	v_mfma_f32_16x16x32_bf16 v[48:51], v[164:167], v[180:183], v[48:51]
	v_mfma_f32_16x16x32_bf16 v[40:43], v[172:175], v[180:183], v[40:43]
	v_mfma_f32_16x16x32_bf16 v[32:35], v[164:167], v[188:191], v[32:35]
	v_mfma_f32_16x16x32_bf16 v[24:27], v[172:175], v[188:191], v[24:27]
	v_mfma_f32_16x16x32_bf16 v[16:19], v[164:167], v[214:217], v[16:19]
	v_mfma_f32_16x16x32_bf16 v[8:11], v[172:175], v[214:217], v[8:11]
	v_mfma_f32_16x16x32_bf16 v[4:7], v[164:167], v[222:225], v[4:7]
	v_mfma_f32_16x16x32_bf16 v[0:3], v[172:175], v[222:225], v[0:3]
	s_barrier
	s_setprio 0
	s_add_i32 s43, s43, 2
	s_add_u32 s13, s13, 0x100
	s_addc_u32 s21, s21, 0
	s_cmp_gt_u32 s43, 29
	s_mov_b64 s[50:51], s[52:53]
; #define PG8_STAGE(bufoff, gbase, voff) do { _Pragma("unroll") for (int _i = 0; _i < 2; ++_i) \
;         __builtin_amdgcn_global_load_lds((const unsigned*)((const char*)(gbase) + (voff)[_i]), (PG8_LAS unsigned*)(lds + (bufoff) + ldsw + _i * 8192), 16, 0, 0); } while (0)
; #define PG8_LDA(dst, b, h) do { _Pragma("unroll") for (int m = 0; m < 4; ++m) _Pragma("unroll") for (int k = 0; k < 2; ++k) dst[m][k] = *(const PG8_LAS bf16x8*)(lds + PG8_SA(b, h) + aoff + m * 2048 + k * 1024); } while (0)
; #define PG8_LDB(dst, b, h) do { _Pragma("unroll") for (int n = 0; n < 2; ++n) _Pragma("unroll") for (int k = 0; k < 2; ++k) dst[n][k] = *(const PG8_LAS bf16x8*)(lds + PG8_SB(b, h) + boff + n * 2048 + k * 1024); } while (0)
; #define PG8_MMA(ai, bj, At, Bt) do { __builtin_amdgcn_s_setprio(1); _Pragma("unroll") for (int m = 0; m < 4; ++m) _Pragma("unroll") for (int n = 0; n < 2; ++n) _Pragma("unroll") for (int k = 0; k < 2; ++k) \
;         acc[ai][bj][m][n] = __builtin_amdgcn_mfma_f32_16x16x32_bf16(Bt[n][k], At[m][k], acc[ai][bj][m][n], 0, 0, 0); __builtin_amdgcn_s_setprio(0); } while (0)
; #define PG8_WAIT_V(n) asm volatile("s_waitcnt vmcnt(" #n ")" ::: "memory")
; #define PG8_WAIT_L(n) asm volatile("s_waitcnt lgkmcnt(" #n ")" ::: "memory")
; #define PG8_BAR __builtin_amdgcn_s_barrier()
; #define PG8_SCHED __builtin_amdgcn_sched_barrier(0)
; template <class Epi>
; __device__ __forceinline__ void gemm_phase(PG8_LAS unsigned char* lds, PG8_LAS unsigned char* xl, const Gemm g, const Sched& S, const Epi& E, const int wid) {
;     ...
;             PG8_LDB(B0, 0, 0); PG8_LDB(B1, 0, 1); PG8_SCHED; PG8_LDA(At, 0, 0); PG8_STAGE(PG8_SA(1, 1), a1 + hstepA, voffA);
;             PG8_WAIT_V(8); PG8_WAIT_L(0); PG8_BAR; if (do0) { PG8_MMA(0, 0, At, B0); PG8_MMA(0, 1, At, B1); } PG8_BAR; PG8_SCHED;
;             PG8_LDA(At, 0, 1); PG8_STAGE(PG8_SB(0, 0), b2, voffB); PG8_STAGE(PG8_SB(0, 1), b2 + hstepB, voffB); PG8_STAGE(PG8_SA(0, 0), a2, voffA);
;             PG8_WAIT_V(8); PG8_WAIT_L(0); PG8_BAR; if (do1) { PG8_MMA(1, 0, At, B0); PG8_MMA(1, 1, At, B1); } PG8_BAR; PG8_SCHED;
.LBB0_220:
	s_add_u32 s52, s50, 0x100
	s_addc_u32 s53, s51, 0
	s_add_i32 s54, 0, 0x10000
	s_cmp_eq_u32 s43, 28
	s_cselect_b32 s59, s8, s53
	s_cselect_b32 s58, s9, s52
	s_cselect_b32 s57, s10, s21
	s_cselect_b32 s56, s11, s13
	s_add_i32 s55, 0, 0x14000
	ds_read_b128 v[144:147], v229 offset:0
	ds_read_b128 v[148:151], v229 offset:1024
	ds_read_b128 v[152:155], v229 offset:2048
	ds_read_b128 v[156:159], v229 offset:3072
	ds_read_b128 v[160:163], v229 offset:16384
	ds_read_b128 v[164:167], v229 offset:17408
	ds_read_b128 v[168:171], v229 offset:18432
	ds_read_b128 v[172:175], v229 offset:19456
	s_add_i32 m0, s37, 0xc000
	ds_read_b128 v[176:179], v143
	ds_read_b128 v[180:183], v143 offset:1024
	ds_read_b128 v[184:187], v143 offset:2048
	ds_read_b128 v[188:191], v143 offset:3072
	ds_read_b128 v[210:213], v143 offset:4096
	ds_read_b128 v[214:217], v143 offset:5120
	ds_read_b128 v[218:221], v143 offset:6144
	ds_read_b128 v[222:225], v143 offset:7168
	global_load_lds_dwordx4 v136, s[50:51] sc0
	s_add_i32 m0, s37, 0xe000
	s_nop 0
	global_load_lds_dwordx4 v138, s[50:51] sc0
	s_waitcnt vmcnt(8)
	s_waitcnt lgkmcnt(0)
	s_setprio 1
	s_barrier
	v_mfma_f32_16x16x32_bf16 v[124:127], v[144:147], v[176:179], v[124:127]
	v_mfma_f32_16x16x32_bf16 v[120:123], v[152:155], v[176:179], v[120:123]
	v_mfma_f32_16x16x32_bf16 v[116:119], v[144:147], v[184:187], v[116:119]
	v_mfma_f32_16x16x32_bf16 v[108:111], v[152:155], v[184:187], v[108:111]
	v_mfma_f32_16x16x32_bf16 v[100:103], v[144:147], v[210:213], v[100:103]
	v_mfma_f32_16x16x32_bf16 v[92:95], v[152:155], v[210:213], v[92:95]
	v_mfma_f32_16x16x32_bf16 v[84:87], v[144:147], v[218:221], v[84:87]
	v_mfma_f32_16x16x32_bf16 v[76:79], v[152:155], v[218:221], v[76:79]
	v_mfma_f32_16x16x32_bf16 v[124:127], v[148:151], v[180:183], v[124:127]
	v_mfma_f32_16x16x32_bf16 v[120:123], v[156:159], v[180:183], v[120:123]
	v_mfma_f32_16x16x32_bf16 v[116:119], v[148:151], v[188:191], v[116:119]
	v_mfma_f32_16x16x32_bf16 v[108:111], v[156:159], v[188:191], v[108:111]
	v_mfma_f32_16x16x32_bf16 v[100:103], v[148:151], v[214:217], v[100:103]
	v_mfma_f32_16x16x32_bf16 v[92:95], v[156:159], v[214:217], v[92:95]
	v_mfma_f32_16x16x32_bf16 v[84:87], v[148:151], v[222:225], v[84:87]
	v_mfma_f32_16x16x32_bf16 v[76:79], v[156:159], v[222:225], v[76:79]
	s_setprio 0
	s_setprio 1
	v_mfma_f32_16x16x32_bf16 v[112:115], v[160:163], v[176:179], v[112:115]
	v_mfma_f32_16x16x32_bf16 v[104:107], v[168:171], v[176:179], v[104:107]
	v_mfma_f32_16x16x32_bf16 v[96:99], v[160:163], v[184:187], v[96:99]
	v_mfma_f32_16x16x32_bf16 v[88:91], v[168:171], v[184:187], v[88:91]
	v_mfma_f32_16x16x32_bf16 v[80:83], v[160:163], v[210:213], v[80:83]
	v_mfma_f32_16x16x32_bf16 v[72:75], v[168:171], v[210:213], v[72:75]
	v_mfma_f32_16x16x32_bf16 v[68:71], v[160:163], v[218:221], v[68:71]
	v_mfma_f32_16x16x32_bf16 v[64:67], v[168:171], v[218:221], v[64:67]
	v_mfma_f32_16x16x32_bf16 v[112:115], v[164:167], v[180:183], v[112:115]
	v_mfma_f32_16x16x32_bf16 v[104:107], v[172:175], v[180:183], v[104:107]
	v_mfma_f32_16x16x32_bf16 v[96:99], v[164:167], v[188:191], v[96:99]
	v_mfma_f32_16x16x32_bf16 v[88:91], v[172:175], v[188:191], v[88:91]
	v_mfma_f32_16x16x32_bf16 v[80:83], v[164:167], v[214:217], v[80:83]
	v_mfma_f32_16x16x32_bf16 v[72:75], v[172:175], v[214:217], v[72:75]
	v_mfma_f32_16x16x32_bf16 v[68:71], v[164:167], v[222:225], v[68:71]
	v_mfma_f32_16x16x32_bf16 v[64:67], v[172:175], v[222:225], v[64:67]
	s_barrier
	s_setprio 0
	s_add_i32 s50, s54, s29
	s_mov_b32 m0, s50
	ds_read_b128 v[176:179], v143 offset:16384
	ds_read_b128 v[180:183], v143 offset:17408
	ds_read_b128 v[184:187], v143 offset:18432
	ds_read_b128 v[188:191], v143 offset:19456
	ds_read_b128 v[210:213], v143 offset:20480
	ds_read_b128 v[214:217], v143 offset:21504
	ds_read_b128 v[218:221], v143 offset:22528
	ds_read_b128 v[222:225], v143 offset:23552
	global_load_lds_dwordx4 v132, s[56:57] sc0
	s_add_i32 m0, s50, 0x2000
	s_add_u32 s50, s56, 0x80000
	s_addc_u32 s51, s57, 0
	s_add_i32 s54, s55, s29
	global_load_lds_dwordx4 v128, s[56:57] sc0
	s_mov_b32 m0, s54
	s_nop 0
	global_load_lds_dwordx4 v132, s[50:51] sc0
	s_add_i32 m0, s54, 0x2000
	s_nop 0
	global_load_lds_dwordx4 v128, s[50:51] sc0
	s_mov_b32 m0, s37
	s_nop 0
	global_load_lds_dwordx4 v134, s[58:59] sc0
	s_mov_b32 m0, s68
	s_nop 0
	global_load_lds_dwordx4 v130, s[58:59] sc0
	s_waitcnt vmcnt(8)
	s_waitcnt lgkmcnt(0)
	s_setprio 1
	s_barrier
	v_mfma_f32_16x16x32_bf16 v[60:63], v[144:147], v[176:179], v[60:63]
	v_mfma_f32_16x16x32_bf16 v[56:59], v[152:155], v[176:179], v[56:59]
	v_mfma_f32_16x16x32_bf16 v[52:55], v[144:147], v[184:187], v[52:55]
	v_mfma_f32_16x16x32_bf16 v[44:47], v[152:155], v[184:187], v[44:47]
	v_mfma_f32_16x16x32_bf16 v[36:39], v[144:147], v[210:213], v[36:39]
	v_mfma_f32_16x16x32_bf16 v[28:31], v[152:155], v[210:213], v[28:31]
	v_mfma_f32_16x16x32_bf16 v[20:23], v[144:147], v[218:221], v[20:23]
	v_mfma_f32_16x16x32_bf16 v[12:15], v[152:155], v[218:221], v[12:15]
	v_mfma_f32_16x16x32_bf16 v[60:63], v[148:151], v[180:183], v[60:63]
	v_mfma_f32_16x16x32_bf16 v[56:59], v[156:159], v[180:183], v[56:59]
	v_mfma_f32_16x16x32_bf16 v[52:55], v[148:151], v[188:191], v[52:55]
	v_mfma_f32_16x16x32_bf16 v[44:47], v[156:159], v[188:191], v[44:47]
	v_mfma_f32_16x16x32_bf16 v[36:39], v[148:151], v[214:217], v[36:39]
	v_mfma_f32_16x16x32_bf16 v[28:31], v[156:159], v[214:217], v[28:31]
	v_mfma_f32_16x16x32_bf16 v[20:23], v[148:151], v[222:225], v[20:23]
	v_mfma_f32_16x16x32_bf16 v[12:15], v[156:159], v[222:225], v[12:15]
	s_setprio 0
	s_setprio 1
	v_mfma_f32_16x16x32_bf16 v[48:51], v[160:163], v[176:179], v[48:51]
	v_mfma_f32_16x16x32_bf16 v[40:43], v[168:171], v[176:179], v[40:43]
	v_mfma_f32_16x16x32_bf16 v[32:35], v[160:163], v[184:187], v[32:35]
	v_mfma_f32_16x16x32_bf16 v[24:27], v[168:171], v[184:187], v[24:27]
	v_mfma_f32_16x16x32_bf16 v[16:19], v[160:163], v[210:213], v[16:19]
	v_mfma_f32_16x16x32_bf16 v[8:11], v[168:171], v[210:213], v[8:11]
	v_mfma_f32_16x16x32_bf16 v[4:7], v[160:163], v[218:221], v[4:7]
	v_mfma_f32_16x16x32_bf16 v[0:3], v[168:171], v[218:221], v[0:3]
	v_mfma_f32_16x16x32_bf16 v[48:51], v[164:167], v[180:183], v[48:51]
	v_mfma_f32_16x16x32_bf16 v[40:43], v[172:175], v[180:183], v[40:43]
	v_mfma_f32_16x16x32_bf16 v[32:35], v[164:167], v[188:191], v[32:35]
	v_mfma_f32_16x16x32_bf16 v[24:27], v[172:175], v[188:191], v[24:27]
	v_mfma_f32_16x16x32_bf16 v[16:19], v[164:167], v[214:217], v[16:19]
	v_mfma_f32_16x16x32_bf16 v[8:11], v[172:175], v[214:217], v[8:11]
	v_mfma_f32_16x16x32_bf16 v[4:7], v[164:167], v[222:225], v[4:7]
	v_mfma_f32_16x16x32_bf16 v[0:3], v[172:175], v[222:225], v[0:3]
	s_barrier
; #define PG8_STAGE(bufoff, gbase, voff) do { _Pragma("unroll") for (int _i = 0; _i < 2; ++_i) \
;         __builtin_amdgcn_global_load_lds((const unsigned*)((const char*)(gbase) + (voff)[_i]), (PG8_LAS unsigned*)(lds + (bufoff) + ldsw + _i * 8192), 16, 0, 0); } while (0)
; #define PG8_LDA(dst, b, h) do { _Pragma("unroll") for (int m = 0; m < 4; ++m) _Pragma("unroll") for (int k = 0; k < 2; ++k) dst[m][k] = *(const PG8_LAS bf16x8*)(lds + PG8_SA(b, h) + aoff + m * 2048 + k * 1024); } while (0)
; #define PG8_LDB(dst, b, h) do { _Pragma("unroll") for (int n = 0; n < 2; ++n) _Pragma("unroll") for (int k = 0; k < 2; ++k) dst[n][k] = *(const PG8_LAS bf16x8*)(lds + PG8_SB(b, h) + boff + n * 2048 + k * 1024); } while (0)
; #define PG8_MMA(ai, bj, At, Bt) do { __builtin_amdgcn_s_setprio(1); _Pragma("unroll") for (int m = 0; m < 4; ++m) _Pragma("unroll") for (int n = 0; n < 2; ++n) _Pragma("unroll") for (int k = 0; k < 2; ++k) \
;         acc[ai][bj][m][n] = __builtin_amdgcn_mfma_f32_16x16x32_bf16(Bt[n][k], At[m][k], acc[ai][bj][m][n], 0, 0, 0); __builtin_amdgcn_s_setprio(0); } while (0)
; #define PG8_WAIT_V(n) asm volatile("s_waitcnt vmcnt(" #n ")" ::: "memory")
; #define PG8_WAIT_L(n) asm volatile("s_waitcnt lgkmcnt(" #n ")" ::: "memory")
; #define PG8_BAR __builtin_amdgcn_s_barrier()
; #define PG8_SCHED __builtin_amdgcn_sched_barrier(0)
; template <class Epi>
; __device__ __forceinline__ void gemm_phase(PG8_LAS unsigned char* lds, PG8_LAS unsigned char* xl, const Gemm g, const Sched& S, const Epi& E, const int wid) {
;     ...
;             PG8_LDB(B0, 1, 0); PG8_LDB(B1, 1, 1); PG8_SCHED; PG8_LDA(At, 1, 0); PG8_STAGE(PG8_SA(0, 1), a2 + hstepA, voffA);
;             PG8_WAIT_V(8); PG8_WAIT_L(0); PG8_BAR; if (do0) { PG8_MMA(0, 0, At, B0); PG8_MMA(0, 1, At, B1); } PG8_BAR; PG8_SCHED;
;             PG8_LDA(At, 1, 1); PG8_STAGE(PG8_SB(1, 0), b3, voffB); PG8_STAGE(PG8_SB(1, 1), b3 + hstepB, voffB); PG8_STAGE(PG8_SA(1, 0), a3, voffA);
;             PG8_WAIT_V(8); PG8_WAIT_L(0); PG8_BAR; if (do1) { PG8_MMA(1, 0, At, B0); PG8_MMA(1, 1, At, B1); } PG8_BAR; PG8_SCHED;
;         }
;         if (wr == 0) PG8_BAR;
	s_setprio 0
	s_add_i32 s54, 0, 0x18000
	s_add_i32 s55, 0, 0x1c000
	ds_read_b128 v[144:147], v229 offset:32768
	ds_read_b128 v[148:151], v229 offset:33792
	ds_read_b128 v[152:155], v229 offset:34816
	ds_read_b128 v[156:159], v229 offset:35840
	ds_read_b128 v[160:163], v229 offset:49152
	ds_read_b128 v[164:167], v229 offset:50176
	ds_read_b128 v[168:171], v229 offset:51200
	ds_read_b128 v[172:175], v229 offset:52224
	s_add_u32 s50, s58, 0x80000
	s_addc_u32 s51, s59, 0
	s_mov_b32 m0, s69
	ds_read_b128 v[176:179], v143 offset:32768
	ds_read_b128 v[180:183], v143 offset:33792
	ds_read_b128 v[184:187], v143 offset:34816
	ds_read_b128 v[188:191], v143 offset:35840
	ds_read_b128 v[210:213], v143 offset:36864
	ds_read_b128 v[214:217], v143 offset:37888
	ds_read_b128 v[218:221], v143 offset:38912
	ds_read_b128 v[222:225], v143 offset:39936
	global_load_lds_dwordx4 v134, s[50:51] sc0
	s_mov_b32 m0, s70
	s_nop 0
	global_load_lds_dwordx4 v130, s[50:51] sc0
	s_waitcnt vmcnt(8)
	s_waitcnt lgkmcnt(0)
	s_setprio 1
	s_barrier
	v_mfma_f32_16x16x32_bf16 v[124:127], v[144:147], v[176:179], v[124:127]
	v_mfma_f32_16x16x32_bf16 v[120:123], v[152:155], v[176:179], v[120:123]
	v_mfma_f32_16x16x32_bf16 v[116:119], v[144:147], v[184:187], v[116:119]
	v_mfma_f32_16x16x32_bf16 v[108:111], v[152:155], v[184:187], v[108:111]
	v_mfma_f32_16x16x32_bf16 v[100:103], v[144:147], v[210:213], v[100:103]
	v_mfma_f32_16x16x32_bf16 v[92:95], v[152:155], v[210:213], v[92:95]
	v_mfma_f32_16x16x32_bf16 v[84:87], v[144:147], v[218:221], v[84:87]
	v_mfma_f32_16x16x32_bf16 v[76:79], v[152:155], v[218:221], v[76:79]
	v_mfma_f32_16x16x32_bf16 v[124:127], v[148:151], v[180:183], v[124:127]
	v_mfma_f32_16x16x32_bf16 v[120:123], v[156:159], v[180:183], v[120:123]
	v_mfma_f32_16x16x32_bf16 v[116:119], v[148:151], v[188:191], v[116:119]
	v_mfma_f32_16x16x32_bf16 v[108:111], v[156:159], v[188:191], v[108:111]
	v_mfma_f32_16x16x32_bf16 v[100:103], v[148:151], v[214:217], v[100:103]
	v_mfma_f32_16x16x32_bf16 v[92:95], v[156:159], v[214:217], v[92:95]
	v_mfma_f32_16x16x32_bf16 v[84:87], v[148:151], v[222:225], v[84:87]
	v_mfma_f32_16x16x32_bf16 v[76:79], v[156:159], v[222:225], v[76:79]
	s_setprio 0
	s_setprio 1
	v_mfma_f32_16x16x32_bf16 v[112:115], v[160:163], v[176:179], v[112:115]
	v_mfma_f32_16x16x32_bf16 v[104:107], v[168:171], v[176:179], v[104:107]
	v_mfma_f32_16x16x32_bf16 v[96:99], v[160:163], v[184:187], v[96:99]
	v_mfma_f32_16x16x32_bf16 v[88:91], v[168:171], v[184:187], v[88:91]
	v_mfma_f32_16x16x32_bf16 v[80:83], v[160:163], v[210:213], v[80:83]
	v_mfma_f32_16x16x32_bf16 v[72:75], v[168:171], v[210:213], v[72:75]
	v_mfma_f32_16x16x32_bf16 v[68:71], v[160:163], v[218:221], v[68:71]
	v_mfma_f32_16x16x32_bf16 v[64:67], v[168:171], v[218:221], v[64:67]
	v_mfma_f32_16x16x32_bf16 v[112:115], v[164:167], v[180:183], v[112:115]
	v_mfma_f32_16x16x32_bf16 v[104:107], v[172:175], v[180:183], v[104:107]
	v_mfma_f32_16x16x32_bf16 v[96:99], v[164:167], v[188:191], v[96:99]
	v_mfma_f32_16x16x32_bf16 v[88:91], v[172:175], v[188:191], v[88:91]
	v_mfma_f32_16x16x32_bf16 v[80:83], v[164:167], v[214:217], v[80:83]
	v_mfma_f32_16x16x32_bf16 v[72:75], v[172:175], v[214:217], v[72:75]
	v_mfma_f32_16x16x32_bf16 v[68:71], v[164:167], v[222:225], v[68:71]
	v_mfma_f32_16x16x32_bf16 v[64:67], v[172:175], v[222:225], v[64:67]
	s_barrier
	s_setprio 0
	s_add_i32 s50, s54, s29
	s_mov_b32 m0, s50
	ds_read_b128 v[176:179], v143 offset:49152
	ds_read_b128 v[180:183], v143 offset:50176
	ds_read_b128 v[184:187], v143 offset:51200
	ds_read_b128 v[188:191], v143 offset:52224
	ds_read_b128 v[210:213], v143 offset:53248
	ds_read_b128 v[214:217], v143 offset:54272
	ds_read_b128 v[218:221], v143 offset:55296
	ds_read_b128 v[222:225], v143 offset:56320
	global_load_lds_dwordx4 v227, s[56:57] sc0
	s_add_i32 m0, s50, 0x2000
	s_add_u32 s50, s56, 0x80080
	global_load_lds_dwordx4 v141, s[56:57] sc0
	s_addc_u32 s51, s57, 0
	s_add_i32 s54, s55, s29
	s_mov_b32 m0, s54
	s_nop 0
	global_load_lds_dwordx4 v132, s[50:51] sc0
	s_add_i32 m0, s54, 0x2000
	s_nop 0
	global_load_lds_dwordx4 v128, s[50:51] sc0
	s_mov_b32 m0, s77
	s_nop 0
	global_load_lds_dwordx4 v228, s[58:59] sc0
	s_mov_b32 m0, s87
	s_nop 0
	global_load_lds_dwordx4 v226, s[58:59] sc0
	s_waitcnt vmcnt(8)
	s_waitcnt lgkmcnt(0)
	s_setprio 1
	s_barrier
	v_mfma_f32_16x16x32_bf16 v[60:63], v[144:147], v[176:179], v[60:63]
	v_mfma_f32_16x16x32_bf16 v[56:59], v[152:155], v[176:179], v[56:59]
	v_mfma_f32_16x16x32_bf16 v[52:55], v[144:147], v[184:187], v[52:55]
	v_mfma_f32_16x16x32_bf16 v[44:47], v[152:155], v[184:187], v[44:47]
	v_mfma_f32_16x16x32_bf16 v[36:39], v[144:147], v[210:213], v[36:39]
	v_mfma_f32_16x16x32_bf16 v[28:31], v[152:155], v[210:213], v[28:31]
	v_mfma_f32_16x16x32_bf16 v[20:23], v[144:147], v[218:221], v[20:23]
	v_mfma_f32_16x16x32_bf16 v[12:15], v[152:155], v[218:221], v[12:15]
	v_mfma_f32_16x16x32_bf16 v[60:63], v[148:151], v[180:183], v[60:63]
	v_mfma_f32_16x16x32_bf16 v[56:59], v[156:159], v[180:183], v[56:59]
	v_mfma_f32_16x16x32_bf16 v[52:55], v[148:151], v[188:191], v[52:55]
	v_mfma_f32_16x16x32_bf16 v[44:47], v[156:159], v[188:191], v[44:47]
	v_mfma_f32_16x16x32_bf16 v[36:39], v[148:151], v[214:217], v[36:39]
	v_mfma_f32_16x16x32_bf16 v[28:31], v[156:159], v[214:217], v[28:31]
	v_mfma_f32_16x16x32_bf16 v[20:23], v[148:151], v[222:225], v[20:23]
	v_mfma_f32_16x16x32_bf16 v[12:15], v[156:159], v[222:225], v[12:15]
	s_setprio 0
	s_setprio 1
	v_mfma_f32_16x16x32_bf16 v[48:51], v[160:163], v[176:179], v[48:51]
	v_mfma_f32_16x16x32_bf16 v[40:43], v[168:171], v[176:179], v[40:43]
	v_mfma_f32_16x16x32_bf16 v[32:35], v[160:163], v[184:187], v[32:35]
	v_mfma_f32_16x16x32_bf16 v[24:27], v[168:171], v[184:187], v[24:27]
	v_mfma_f32_16x16x32_bf16 v[16:19], v[160:163], v[210:213], v[16:19]
	v_mfma_f32_16x16x32_bf16 v[8:11], v[168:171], v[210:213], v[8:11]
	v_mfma_f32_16x16x32_bf16 v[4:7], v[160:163], v[218:221], v[4:7]
	v_mfma_f32_16x16x32_bf16 v[0:3], v[168:171], v[218:221], v[0:3]
	v_mfma_f32_16x16x32_bf16 v[48:51], v[164:167], v[180:183], v[48:51]
	v_mfma_f32_16x16x32_bf16 v[40:43], v[172:175], v[180:183], v[40:43]
	v_mfma_f32_16x16x32_bf16 v[32:35], v[164:167], v[188:191], v[32:35]
	v_mfma_f32_16x16x32_bf16 v[24:27], v[172:175], v[188:191], v[24:27]
	v_mfma_f32_16x16x32_bf16 v[16:19], v[164:167], v[214:217], v[16:19]
	v_mfma_f32_16x16x32_bf16 v[8:11], v[172:175], v[214:217], v[8:11]
	v_mfma_f32_16x16x32_bf16 v[4:7], v[164:167], v[222:225], v[4:7]
	v_mfma_f32_16x16x32_bf16 v[0:3], v[172:175], v[222:225], v[0:3]
	s_barrier
	s_setprio 0
	s_add_i32 s43, s43, 2
	s_add_u32 s13, s13, 0x100
	s_addc_u32 s21, s21, 0
	s_cmp_gt_u32 s43, 29
	s_mov_b64 s[50:51], s[52:53]
	s_cbranch_scc0 .LBB0_220
	s_and_b64 vcc, exec, s[14:15]
	s_cbranch_vccz .LBB0_223
	s_barrier

; #define PG8_STAGE(bufoff, gbase, voff) do { _Pragma("unroll") for (int _i = 0; _i < 2; ++_i) \
;         __builtin_amdgcn_global_load_lds((const unsigned*)((const char*)(gbase) + (voff)[_i]), (PG8_LAS unsigned*)(lds + (bufoff) + ldsw + _i * 8192), 16, 0, 0); } while (0)
; #define PG8_LDA(dst, b, h) do { _Pragma("unroll") for (int m = 0; m < 4; ++m) _Pragma("unroll") for (int k = 0; k < 2; ++k) dst[m][k] = *(const PG8_LAS bf16x8*)(lds + PG8_SA(b, h) + aoff + m * 2048 + k * 1024); } while (0)
; #define PG8_LDB(dst, b, h) do { _Pragma("unroll") for (int n = 0; n < 2; ++n) _Pragma("unroll") for (int k = 0; k < 2; ++k) dst[n][k] = *(const PG8_LAS bf16x8*)(lds + PG8_SB(b, h) + boff + n * 2048 + k * 1024); } while (0)
; #define PG8_MMA(ai, bj, At, Bt) do { __builtin_amdgcn_s_setprio(1); _Pragma("unroll") for (int m = 0; m < 4; ++m) _Pragma("unroll") for (int n = 0; n < 2; ++n) _Pragma("unroll") for (int k = 0; k < 2; ++k) \
;         acc[ai][bj][m][n] = __builtin_amdgcn_mfma_f32_16x16x32_bf16(Bt[n][k], At[m][k], acc[ai][bj][m][n], 0, 0, 0); __builtin_amdgcn_s_setprio(0); } while (0)
; #define PG8_WAIT_V(n) asm volatile("s_waitcnt vmcnt(" #n ")" ::: "memory")
; #define PG8_WAIT_L(n) asm volatile("s_waitcnt lgkmcnt(" #n ")" ::: "memory")
; #define PG8_BAR __builtin_amdgcn_s_barrier()
; #define PG8_SCHED __builtin_amdgcn_sched_barrier(0)
; template <class Epi>
; __device__ __forceinline__ void gemm_phase(PG8_LAS unsigned char* lds, PG8_LAS unsigned char* xl, const Gemm g, const Sched& S, const Epi& E, const int wid) {
;     ...
;             PG8_LDB(B0, 0, 0); PG8_LDB(B1, 0, 1); PG8_SCHED; PG8_LDA(At, 0, 0); PG8_STAGE(PG8_SA(1, 1), a1 + hstepA, voffA);
;             PG8_WAIT_V(8); PG8_WAIT_L(0); PG8_BAR; if (do0) { PG8_MMA(0, 0, At, B0); PG8_MMA(0, 1, At, B1); } PG8_BAR; PG8_SCHED;
;             PG8_LDA(At, 0, 1); PG8_STAGE(PG8_SB(0, 0), b2, voffB); PG8_STAGE(PG8_SB(0, 1), b2 + hstepB, voffB); PG8_STAGE(PG8_SA(0, 0), a2, voffA);
;             PG8_WAIT_V(8); PG8_WAIT_L(0); PG8_BAR; if (do1) { PG8_MMA(1, 0, At, B0); PG8_MMA(1, 1, At, B1); } PG8_BAR; PG8_SCHED;
.Ldefbar_skip_1:
	v_add_u32_e32 v157, s22, v140
	v_add_u32_e32 v234, s22, v142
	v_add_u32_e32 v235, s22, v144
	v_add_u32_e32 v236, s22, v146
	v_add_u32_e32 v237, 0x10000, v158
	s_add_u32 s30, s20, 0x100
	s_addc_u32 s31, s21, 0
	s_add_i32 s54, 0, 0x10000
	s_cmp_eq_u32 s62, 28
	s_cselect_b32 s47, s8, s31
	s_cselect_b32 s46, s9, s30
	s_cselect_b32 s45, s10, s57
	s_cselect_b32 s44, s11, s13
	s_add_i32 s55, 0, 0x14000
	ds_read_b128 v[18:21], v237 offset:0
	ds_read_b128 v[22:25], v237 offset:1024
	ds_read_b128 v[160:163], v237 offset:2048
	ds_read_b128 v[164:167], v237 offset:3072
	ds_read_b128 v[168:171], v237 offset:16384
	ds_read_b128 v[172:175], v237 offset:17408
	ds_read_b128 v[176:179], v237 offset:18432
	ds_read_b128 v[180:183], v237 offset:19456
	s_add_i32 m0, s77, 0xc000
	ds_read_b128 v[184:187], v159
	ds_read_b128 v[188:191], v159 offset:1024
	ds_read_b128 v[210:213], v159 offset:2048
	ds_read_b128 v[214:217], v159 offset:3072
	ds_read_b128 v[218:221], v159 offset:4096
	ds_read_b128 v[222:225], v159 offset:5120
	ds_read_b128 v[226:229], v159 offset:6144
	ds_read_b128 v[230:233], v159 offset:7168
	global_load_lds_dwordx4 v148, s[20:21] sc0
	s_add_i32 m0, s77, 0xe000
	s_nop 0
	global_load_lds_dwordx4 v150, s[20:21] sc0
	s_waitcnt vmcnt(8)
	s_waitcnt lgkmcnt(0)
	s_setprio 1
	s_barrier
	v_mfma_f32_16x16x32_bf16 v[136:139], v[18:21], v[184:187], 0
	v_mfma_f32_16x16x32_bf16 v[132:135], v[160:163], v[184:187], 0
	v_mfma_f32_16x16x32_bf16 v[120:123], v[18:21], v[210:213], 0
	v_mfma_f32_16x16x32_bf16 v[116:119], v[160:163], v[210:213], 0
	v_mfma_f32_16x16x32_bf16 v[104:107], v[18:21], v[218:221], 0
	v_mfma_f32_16x16x32_bf16 v[100:103], v[160:163], v[218:221], 0
	v_mfma_f32_16x16x32_bf16 v[86:89], v[18:21], v[226:229], 0
	v_mfma_f32_16x16x32_bf16 v[82:85], v[160:163], v[226:229], 0
	v_mfma_f32_16x16x32_bf16 v[136:139], v[22:25], v[188:191], v[136:139]
	v_mfma_f32_16x16x32_bf16 v[132:135], v[164:167], v[188:191], v[132:135]
	v_mfma_f32_16x16x32_bf16 v[120:123], v[22:25], v[214:217], v[120:123]
	v_mfma_f32_16x16x32_bf16 v[116:119], v[164:167], v[214:217], v[116:119]
	v_mfma_f32_16x16x32_bf16 v[104:107], v[22:25], v[222:225], v[104:107]
	v_mfma_f32_16x16x32_bf16 v[100:103], v[164:167], v[222:225], v[100:103]
	v_mfma_f32_16x16x32_bf16 v[86:89], v[22:25], v[230:233], v[86:89]
	v_mfma_f32_16x16x32_bf16 v[82:85], v[164:167], v[230:233], v[82:85]
	s_setprio 0
	s_setprio 1
	v_mfma_f32_16x16x32_bf16 v[128:131], v[168:171], v[184:187], 0
	v_mfma_f32_16x16x32_bf16 v[124:127], v[176:179], v[184:187], 0
	v_mfma_f32_16x16x32_bf16 v[112:115], v[168:171], v[210:213], 0
	v_mfma_f32_16x16x32_bf16 v[108:111], v[176:179], v[210:213], 0
	v_mfma_f32_16x16x32_bf16 v[96:99], v[168:171], v[218:221], 0
	v_mfma_f32_16x16x32_bf16 v[92:95], v[176:179], v[218:221], 0
	v_mfma_f32_16x16x32_bf16 v[78:81], v[168:171], v[226:229], 0
	v_mfma_f32_16x16x32_bf16 v[74:77], v[176:179], v[226:229], 0
	v_mfma_f32_16x16x32_bf16 v[128:131], v[172:175], v[188:191], v[128:131]
	v_mfma_f32_16x16x32_bf16 v[124:127], v[180:183], v[188:191], v[124:127]
	v_mfma_f32_16x16x32_bf16 v[112:115], v[172:175], v[214:217], v[112:115]
	v_mfma_f32_16x16x32_bf16 v[108:111], v[180:183], v[214:217], v[108:111]
	v_mfma_f32_16x16x32_bf16 v[96:99], v[172:175], v[222:225], v[96:99]
	v_mfma_f32_16x16x32_bf16 v[92:95], v[180:183], v[222:225], v[92:95]
	v_mfma_f32_16x16x32_bf16 v[78:81], v[172:175], v[230:233], v[78:81]
	v_mfma_f32_16x16x32_bf16 v[74:77], v[180:183], v[230:233], v[74:77]
	s_barrier
	s_setprio 0
	s_add_i32 s20, s54, s29
	s_mov_b32 m0, s20
	ds_read_b128 v[184:187], v159 offset:16384
	ds_read_b128 v[188:191], v159 offset:17408
	ds_read_b128 v[210:213], v159 offset:18432
	ds_read_b128 v[214:217], v159 offset:19456
	ds_read_b128 v[218:221], v159 offset:20480
	ds_read_b128 v[222:225], v159 offset:21504
	ds_read_b128 v[226:229], v159 offset:22528
	ds_read_b128 v[230:233], v159 offset:23552
	global_load_lds_dwordx4 v142, s[44:45] sc0
	s_add_i32 m0, s20, 0x2000
	s_add_u32 s20, s44, 0x80000
	s_addc_u32 s21, s45, 0
	s_add_i32 s54, s55, s29
	global_load_lds_dwordx4 v146, s[44:45] sc0
	s_mov_b32 m0, s54
	s_nop 0
	global_load_lds_dwordx4 v142, s[20:21] sc0
	s_add_i32 m0, s54, 0x2000
	s_nop 0
	global_load_lds_dwordx4 v146, s[20:21] sc0
	s_mov_b32 m0, s77
	s_nop 0
	global_load_lds_dwordx4 v140, s[46:47] sc0
	s_mov_b32 m0, s49
	s_nop 0
	global_load_lds_dwordx4 v144, s[46:47] sc0
	s_waitcnt vmcnt(8)
	s_waitcnt lgkmcnt(0)
	s_setprio 1
	s_barrier
	v_mfma_f32_16x16x32_bf16 v[70:73], v[18:21], v[184:187], 0
	v_mfma_f32_16x16x32_bf16 v[66:69], v[160:163], v[184:187], 0
	v_mfma_f32_16x16x32_bf16 v[54:57], v[18:21], v[210:213], 0
	v_mfma_f32_16x16x32_bf16 v[50:53], v[160:163], v[210:213], 0
	v_mfma_f32_16x16x32_bf16 v[38:41], v[18:21], v[218:221], 0
	v_mfma_f32_16x16x32_bf16 v[34:37], v[160:163], v[218:221], 0
	v_mfma_f32_16x16x32_bf16 v[12:15], v[18:21], v[226:229], 0
	v_mfma_f32_16x16x32_bf16 v[8:11], v[160:163], v[226:229], 0
	v_mfma_f32_16x16x32_bf16 v[70:73], v[22:25], v[188:191], v[70:73]
	v_mfma_f32_16x16x32_bf16 v[66:69], v[164:167], v[188:191], v[66:69]
	v_mfma_f32_16x16x32_bf16 v[54:57], v[22:25], v[214:217], v[54:57]
	v_mfma_f32_16x16x32_bf16 v[50:53], v[164:167], v[214:217], v[50:53]
	v_mfma_f32_16x16x32_bf16 v[38:41], v[22:25], v[222:225], v[38:41]
	v_mfma_f32_16x16x32_bf16 v[34:37], v[164:167], v[222:225], v[34:37]
	v_mfma_f32_16x16x32_bf16 v[12:15], v[22:25], v[230:233], v[12:15]
	v_mfma_f32_16x16x32_bf16 v[8:11], v[164:167], v[230:233], v[8:11]
	s_setprio 0
	s_setprio 1
	v_mfma_f32_16x16x32_bf16 v[46:49], v[168:171], v[210:213], 0
	v_mfma_f32_16x16x32_bf16 v[42:45], v[176:179], v[210:213], 0
	v_mfma_f32_16x16x32_bf16 v[30:33], v[168:171], v[218:221], 0
	v_mfma_f32_16x16x32_bf16 v[26:29], v[176:179], v[218:221], 0
	v_mfma_f32_16x16x32_bf16 v[4:7], v[168:171], v[226:229], 0
	v_mfma_f32_16x16x32_bf16 v[0:3], v[176:179], v[226:229], 0
	v_mfma_f32_16x16x32_bf16 v[18:21], v[168:171], v[184:187], 0
	v_mfma_f32_16x16x32_bf16 v[22:25], v[176:179], v[184:187], 0
	v_mfma_f32_16x16x32_bf16 v[46:49], v[172:175], v[214:217], v[46:49]
	v_mfma_f32_16x16x32_bf16 v[42:45], v[180:183], v[214:217], v[42:45]
	v_mfma_f32_16x16x32_bf16 v[30:33], v[172:175], v[222:225], v[30:33]
	v_mfma_f32_16x16x32_bf16 v[26:29], v[180:183], v[222:225], v[26:29]
	v_mfma_f32_16x16x32_bf16 v[4:7], v[172:175], v[230:233], v[4:7]
	v_mfma_f32_16x16x32_bf16 v[0:3], v[180:183], v[230:233], v[0:3]
	v_mfma_f32_16x16x32_bf16 v[18:21], v[172:175], v[188:191], v[18:21]
	v_mfma_f32_16x16x32_bf16 v[22:25], v[180:183], v[188:191], v[22:25]
	s_barrier
; #define PG8_STAGE(bufoff, gbase, voff) do { _Pragma("unroll") for (int _i = 0; _i < 2; ++_i) \
;         __builtin_amdgcn_global_load_lds((const unsigned*)((const char*)(gbase) + (voff)[_i]), (PG8_LAS unsigned*)(lds + (bufoff) + ldsw + _i * 8192), 16, 0, 0); } while (0)
; #define PG8_LDA(dst, b, h) do { _Pragma("unroll") for (int m = 0; m < 4; ++m) _Pragma("unroll") for (int k = 0; k < 2; ++k) dst[m][k] = *(const PG8_LAS bf16x8*)(lds + PG8_SA(b, h) + aoff + m * 2048 + k * 1024); } while (0)
; #define PG8_LDB(dst, b, h) do { _Pragma("unroll") for (int n = 0; n < 2; ++n) _Pragma("unroll") for (int k = 0; k < 2; ++k) dst[n][k] = *(const PG8_LAS bf16x8*)(lds + PG8_SB(b, h) + boff + n * 2048 + k * 1024); } while (0)
; #define PG8_MMA(ai, bj, At, Bt) do { __builtin_amdgcn_s_setprio(1); _Pragma("unroll") for (int m = 0; m < 4; ++m) _Pragma("unroll") for (int n = 0; n < 2; ++n) _Pragma("unroll") for (int k = 0; k < 2; ++k) \
;         acc[ai][bj][m][n] = __builtin_amdgcn_mfma_f32_16x16x32_bf16(Bt[n][k], At[m][k], acc[ai][bj][m][n], 0, 0, 0); __builtin_amdgcn_s_setprio(0); } while (0)
; #define PG8_WAIT_V(n) asm volatile("s_waitcnt vmcnt(" #n ")" ::: "memory")
; #define PG8_WAIT_L(n) asm volatile("s_waitcnt lgkmcnt(" #n ")" ::: "memory")
; #define PG8_BAR __builtin_amdgcn_s_barrier()
; #define PG8_SCHED __builtin_amdgcn_sched_barrier(0)
; template <class Epi>
; __device__ __forceinline__ void gemm_phase(PG8_LAS unsigned char* lds, PG8_LAS unsigned char* xl, const Gemm g, const Sched& S, const Epi& E, const int wid) {
;     ...
;             PG8_LDB(B0, 1, 0); PG8_LDB(B1, 1, 1); PG8_SCHED; PG8_LDA(At, 1, 0); PG8_STAGE(PG8_SA(0, 1), a2 + hstepA, voffA);
;             PG8_WAIT_V(8); PG8_WAIT_L(0); PG8_BAR; if (do0) { PG8_MMA(0, 0, At, B0); PG8_MMA(0, 1, At, B1); } PG8_BAR; PG8_SCHED;
;             PG8_LDA(At, 1, 1); PG8_STAGE(PG8_SB(1, 0), b3, voffB); PG8_STAGE(PG8_SB(1, 1), b3 + hstepB, voffB); PG8_STAGE(PG8_SA(1, 0), a3, voffA);
;             PG8_WAIT_V(8); PG8_WAIT_L(0); PG8_BAR; if (do1) { PG8_MMA(1, 0, At, B0); PG8_MMA(1, 1, At, B1); } PG8_BAR; PG8_SCHED;
;         }
	s_setprio 0
	s_add_i32 s54, 0, 0x18000
	s_add_i32 s55, 0, 0x1c000
	ds_read_b128 v[58:61], v237 offset:32768
	ds_read_b128 v[62:65], v237 offset:33792
	ds_read_b128 v[160:163], v237 offset:34816
	ds_read_b128 v[164:167], v237 offset:35840
	ds_read_b128 v[168:171], v237 offset:49152
	ds_read_b128 v[172:175], v237 offset:50176
	ds_read_b128 v[176:179], v237 offset:51200
	ds_read_b128 v[180:183], v237 offset:52224
	s_add_u32 s20, s46, 0x80000
	s_addc_u32 s21, s47, 0
	s_mov_b32 m0, s87
	ds_read_b128 v[184:187], v159 offset:32768
	ds_read_b128 v[188:191], v159 offset:33792
	ds_read_b128 v[210:213], v159 offset:34816
	ds_read_b128 v[214:217], v159 offset:35840
	ds_read_b128 v[218:221], v159 offset:36864
	ds_read_b128 v[222:225], v159 offset:37888
	ds_read_b128 v[226:229], v159 offset:38912
	ds_read_b128 v[230:233], v159 offset:39936
	global_load_lds_dwordx4 v140, s[20:21] sc0
	s_mov_b32 m0, s88
	s_nop 0
	global_load_lds_dwordx4 v144, s[20:21] sc0
	s_waitcnt vmcnt(8)
	s_waitcnt lgkmcnt(0)
	s_setprio 1
	s_barrier
	v_mfma_f32_16x16x32_bf16 v[136:139], v[58:61], v[184:187], v[136:139]
	v_mfma_f32_16x16x32_bf16 v[132:135], v[160:163], v[184:187], v[132:135]
	v_mfma_f32_16x16x32_bf16 v[120:123], v[58:61], v[210:213], v[120:123]
	v_mfma_f32_16x16x32_bf16 v[116:119], v[160:163], v[210:213], v[116:119]
	v_mfma_f32_16x16x32_bf16 v[104:107], v[58:61], v[218:221], v[104:107]
	v_mfma_f32_16x16x32_bf16 v[100:103], v[160:163], v[218:221], v[100:103]
	v_mfma_f32_16x16x32_bf16 v[86:89], v[58:61], v[226:229], v[86:89]
	v_mfma_f32_16x16x32_bf16 v[82:85], v[160:163], v[226:229], v[82:85]
	v_mfma_f32_16x16x32_bf16 v[136:139], v[62:65], v[188:191], v[136:139]
	v_mfma_f32_16x16x32_bf16 v[132:135], v[164:167], v[188:191], v[132:135]
	v_mfma_f32_16x16x32_bf16 v[120:123], v[62:65], v[214:217], v[120:123]
	v_mfma_f32_16x16x32_bf16 v[116:119], v[164:167], v[214:217], v[116:119]
	v_mfma_f32_16x16x32_bf16 v[104:107], v[62:65], v[222:225], v[104:107]
	v_mfma_f32_16x16x32_bf16 v[100:103], v[164:167], v[222:225], v[100:103]
	v_mfma_f32_16x16x32_bf16 v[86:89], v[62:65], v[230:233], v[86:89]
	v_mfma_f32_16x16x32_bf16 v[82:85], v[164:167], v[230:233], v[82:85]
	s_setprio 0
	s_setprio 1
	v_mfma_f32_16x16x32_bf16 v[128:131], v[168:171], v[184:187], v[128:131]
	v_mfma_f32_16x16x32_bf16 v[124:127], v[176:179], v[184:187], v[124:127]
	v_mfma_f32_16x16x32_bf16 v[112:115], v[168:171], v[210:213], v[112:115]
	v_mfma_f32_16x16x32_bf16 v[108:111], v[176:179], v[210:213], v[108:111]
	v_mfma_f32_16x16x32_bf16 v[96:99], v[168:171], v[218:221], v[96:99]
	v_mfma_f32_16x16x32_bf16 v[92:95], v[176:179], v[218:221], v[92:95]
	v_mfma_f32_16x16x32_bf16 v[78:81], v[168:171], v[226:229], v[78:81]
	v_mfma_f32_16x16x32_bf16 v[74:77], v[176:179], v[226:229], v[74:77]
	v_mfma_f32_16x16x32_bf16 v[128:131], v[172:175], v[188:191], v[128:131]
	v_mfma_f32_16x16x32_bf16 v[124:127], v[180:183], v[188:191], v[124:127]
	v_mfma_f32_16x16x32_bf16 v[112:115], v[172:175], v[214:217], v[112:115]
	v_mfma_f32_16x16x32_bf16 v[108:111], v[180:183], v[214:217], v[108:111]
	v_mfma_f32_16x16x32_bf16 v[96:99], v[172:175], v[222:225], v[96:99]
	v_mfma_f32_16x16x32_bf16 v[92:95], v[180:183], v[222:225], v[92:95]
	v_mfma_f32_16x16x32_bf16 v[78:81], v[172:175], v[230:233], v[78:81]
	v_mfma_f32_16x16x32_bf16 v[74:77], v[180:183], v[230:233], v[74:77]
	s_barrier
	s_setprio 0
	s_add_i32 s20, s54, s29
	s_mov_b32 m0, s20
	ds_read_b128 v[184:187], v159 offset:49152
	ds_read_b128 v[188:191], v159 offset:50176
	ds_read_b128 v[210:213], v159 offset:51200
	ds_read_b128 v[214:217], v159 offset:52224
	ds_read_b128 v[218:221], v159 offset:53248
	ds_read_b128 v[222:225], v159 offset:54272
	ds_read_b128 v[226:229], v159 offset:55296
	ds_read_b128 v[230:233], v159 offset:56320
	global_load_lds_dwordx4 v234, s[44:45] sc0
	s_add_i32 m0, s20, 0x2000
	s_add_u32 s20, s44, 0x80080
	global_load_lds_dwordx4 v236, s[44:45] sc0
	s_addc_u32 s21, s45, 0
	s_add_i32 s44, s55, s29
	s_mov_b32 m0, s44
	s_nop 0
	global_load_lds_dwordx4 v142, s[20:21] sc0
	s_add_i32 m0, s44, 0x2000
	s_nop 0
	global_load_lds_dwordx4 v146, s[20:21] sc0
	s_mov_b32 m0, s91
	s_nop 0
	global_load_lds_dwordx4 v157, s[46:47] sc0
	s_mov_b32 m0, s92
	s_nop 0
	global_load_lds_dwordx4 v235, s[46:47] sc0
	s_waitcnt vmcnt(8)
	s_waitcnt lgkmcnt(0)
	s_setprio 1
	s_barrier
	v_mfma_f32_16x16x32_bf16 v[70:73], v[58:61], v[184:187], v[70:73]
	v_mfma_f32_16x16x32_bf16 v[66:69], v[160:163], v[184:187], v[66:69]
	v_mfma_f32_16x16x32_bf16 v[54:57], v[58:61], v[210:213], v[54:57]
	v_mfma_f32_16x16x32_bf16 v[50:53], v[160:163], v[210:213], v[50:53]
	v_mfma_f32_16x16x32_bf16 v[38:41], v[58:61], v[218:221], v[38:41]
	v_mfma_f32_16x16x32_bf16 v[34:37], v[160:163], v[218:221], v[34:37]
	v_mfma_f32_16x16x32_bf16 v[12:15], v[58:61], v[226:229], v[12:15]
	v_mfma_f32_16x16x32_bf16 v[8:11], v[160:163], v[226:229], v[8:11]
	v_mfma_f32_16x16x32_bf16 v[70:73], v[62:65], v[188:191], v[70:73]
	v_mfma_f32_16x16x32_bf16 v[66:69], v[164:167], v[188:191], v[66:69]
	v_mfma_f32_16x16x32_bf16 v[54:57], v[62:65], v[214:217], v[54:57]
	v_mfma_f32_16x16x32_bf16 v[50:53], v[164:167], v[214:217], v[50:53]
	v_mfma_f32_16x16x32_bf16 v[38:41], v[62:65], v[222:225], v[38:41]
	v_mfma_f32_16x16x32_bf16 v[34:37], v[164:167], v[222:225], v[34:37]
	v_mfma_f32_16x16x32_bf16 v[12:15], v[62:65], v[230:233], v[12:15]
	v_mfma_f32_16x16x32_bf16 v[8:11], v[164:167], v[230:233], v[8:11]
	s_setprio 0
	s_setprio 1
	v_mfma_f32_16x16x32_bf16 v[18:21], v[168:171], v[184:187], v[18:21]
	v_mfma_f32_16x16x32_bf16 v[62:65], v[172:175], v[188:191], v[18:21]
	v_mfma_f32_16x16x32_bf16 v[18:21], v[176:179], v[184:187], v[22:25]
	v_mfma_f32_16x16x32_bf16 v[58:61], v[180:183], v[188:191], v[18:21]
	v_mfma_f32_16x16x32_bf16 v[18:21], v[168:171], v[210:213], v[46:49]
	v_mfma_f32_16x16x32_bf16 v[46:49], v[172:175], v[214:217], v[18:21]
	v_mfma_f32_16x16x32_bf16 v[18:21], v[176:179], v[210:213], v[42:45]
	v_mfma_f32_16x16x32_bf16 v[42:45], v[180:183], v[214:217], v[18:21]
	v_mfma_f32_16x16x32_bf16 v[18:21], v[168:171], v[218:221], v[30:33]
	v_mfma_f32_16x16x32_bf16 v[30:33], v[172:175], v[222:225], v[18:21]
	v_mfma_f32_16x16x32_bf16 v[18:21], v[176:179], v[218:221], v[26:29]
	v_mfma_f32_16x16x32_bf16 v[4:7], v[168:171], v[226:229], v[4:7]
	v_mfma_f32_16x16x32_bf16 v[0:3], v[176:179], v[226:229], v[0:3]
	v_mfma_f32_16x16x32_bf16 v[26:29], v[180:183], v[222:225], v[18:21]
	v_mfma_f32_16x16x32_bf16 v[4:7], v[172:175], v[230:233], v[4:7]
	v_mfma_f32_16x16x32_bf16 v[0:3], v[180:183], v[230:233], v[0:3]
	s_barrier
	s_setprio 0
	s_add_i32 s62, s62, 2
	s_add_u32 s13, s13, 0x100
	s_addc_u32 s57, s57, 0
	s_cmp_gt_u32 s62, 29
	s_mov_b64 s[20:21], s[30:31]
; #define PG8_STAGE(bufoff, gbase, voff) do { _Pragma("unroll") for (int _i = 0; _i < 2; ++_i) \
;         __builtin_amdgcn_global_load_lds((const unsigned*)((const char*)(gbase) + (voff)[_i]), (PG8_LAS unsigned*)(lds + (bufoff) + ldsw + _i * 8192), 16, 0, 0); } while (0)
; #define PG8_LDA(dst, b, h) do { _Pragma("unroll") for (int m = 0; m < 4; ++m) _Pragma("unroll") for (int k = 0; k < 2; ++k) dst[m][k] = *(const PG8_LAS bf16x8*)(lds + PG8_SA(b, h) + aoff + m * 2048 + k * 1024); } while (0)
; #define PG8_LDB(dst, b, h) do { _Pragma("unroll") for (int n = 0; n < 2; ++n) _Pragma("unroll") for (int k = 0; k < 2; ++k) dst[n][k] = *(const PG8_LAS bf16x8*)(lds + PG8_SB(b, h) + boff + n * 2048 + k * 1024); } while (0)
; #define PG8_MMA(ai, bj, At, Bt) do { __builtin_amdgcn_s_setprio(1); _Pragma("unroll") for (int m = 0; m < 4; ++m) _Pragma("unroll") for (int n = 0; n < 2; ++n) _Pragma("unroll") for (int k = 0; k < 2; ++k) \
;         acc[ai][bj][m][n] = __builtin_amdgcn_mfma_f32_16x16x32_bf16(Bt[n][k], At[m][k], acc[ai][bj][m][n], 0, 0, 0); __builtin_amdgcn_s_setprio(0); } while (0)
; #define PG8_WAIT_V(n) asm volatile("s_waitcnt vmcnt(" #n ")" ::: "memory")
; #define PG8_WAIT_L(n) asm volatile("s_waitcnt lgkmcnt(" #n ")" ::: "memory")
; #define PG8_BAR __builtin_amdgcn_s_barrier()
; #define PG8_SCHED __builtin_amdgcn_sched_barrier(0)
; template <class Epi>
; __device__ __forceinline__ void gemm_phase(PG8_LAS unsigned char* lds, PG8_LAS unsigned char* xl, const Gemm g, const Sched& S, const Epi& E, const int wid) {
;     ...
;             PG8_LDB(B0, 0, 0); PG8_LDB(B1, 0, 1); PG8_SCHED; PG8_LDA(At, 0, 0); PG8_STAGE(PG8_SA(1, 1), a1 + hstepA, voffA);
;             PG8_WAIT_V(8); PG8_WAIT_L(0); PG8_BAR; if (do0) { PG8_MMA(0, 0, At, B0); PG8_MMA(0, 1, At, B1); } PG8_BAR; PG8_SCHED;
;             PG8_LDA(At, 0, 1); PG8_STAGE(PG8_SB(0, 0), b2, voffB); PG8_STAGE(PG8_SB(0, 1), b2 + hstepB, voffB); PG8_STAGE(PG8_SA(0, 0), a2, voffA);
;             PG8_WAIT_V(8); PG8_WAIT_L(0); PG8_BAR; if (do1) { PG8_MMA(1, 0, At, B0); PG8_MMA(1, 1, At, B1); } PG8_BAR; PG8_SCHED;
.LBB0_238:
	s_add_u32 s30, s20, 0x100
	s_addc_u32 s31, s21, 0
	s_add_i32 s54, 0, 0x10000
	s_cmp_eq_u32 s62, 28
	s_cselect_b32 s47, s8, s31
	s_cselect_b32 s46, s9, s30
	s_cselect_b32 s45, s10, s57
	s_cselect_b32 s44, s11, s13
	s_add_i32 s55, 0, 0x14000
	ds_read_b128 v[18:21], v237 offset:0
	ds_read_b128 v[22:25], v237 offset:1024
	ds_read_b128 v[160:163], v237 offset:2048
	ds_read_b128 v[164:167], v237 offset:3072
	ds_read_b128 v[168:171], v237 offset:16384
	ds_read_b128 v[172:175], v237 offset:17408
	ds_read_b128 v[176:179], v237 offset:18432
	ds_read_b128 v[180:183], v237 offset:19456
	s_add_i32 m0, s77, 0xc000
	ds_read_b128 v[184:187], v159
	ds_read_b128 v[188:191], v159 offset:1024
	ds_read_b128 v[210:213], v159 offset:2048
	ds_read_b128 v[214:217], v159 offset:3072
	ds_read_b128 v[218:221], v159 offset:4096
	ds_read_b128 v[222:225], v159 offset:5120
	ds_read_b128 v[226:229], v159 offset:6144
	ds_read_b128 v[230:233], v159 offset:7168
	global_load_lds_dwordx4 v148, s[20:21] sc0
	s_add_i32 m0, s77, 0xe000
	s_nop 0
	global_load_lds_dwordx4 v150, s[20:21] sc0
	s_waitcnt vmcnt(8)
	s_waitcnt lgkmcnt(0)
	s_setprio 1
	s_barrier
	v_mfma_f32_16x16x32_bf16 v[136:139], v[18:21], v[184:187], v[136:139]
	v_mfma_f32_16x16x32_bf16 v[132:135], v[160:163], v[184:187], v[132:135]
	v_mfma_f32_16x16x32_bf16 v[120:123], v[18:21], v[210:213], v[120:123]
	v_mfma_f32_16x16x32_bf16 v[116:119], v[160:163], v[210:213], v[116:119]
	v_mfma_f32_16x16x32_bf16 v[104:107], v[18:21], v[218:221], v[104:107]
	v_mfma_f32_16x16x32_bf16 v[100:103], v[160:163], v[218:221], v[100:103]
	v_mfma_f32_16x16x32_bf16 v[86:89], v[18:21], v[226:229], v[86:89]
	v_mfma_f32_16x16x32_bf16 v[82:85], v[160:163], v[226:229], v[82:85]
	v_mfma_f32_16x16x32_bf16 v[136:139], v[22:25], v[188:191], v[136:139]
	v_mfma_f32_16x16x32_bf16 v[132:135], v[164:167], v[188:191], v[132:135]
	v_mfma_f32_16x16x32_bf16 v[120:123], v[22:25], v[214:217], v[120:123]
	v_mfma_f32_16x16x32_bf16 v[116:119], v[164:167], v[214:217], v[116:119]
	v_mfma_f32_16x16x32_bf16 v[104:107], v[22:25], v[222:225], v[104:107]
	v_mfma_f32_16x16x32_bf16 v[100:103], v[164:167], v[222:225], v[100:103]
	v_mfma_f32_16x16x32_bf16 v[86:89], v[22:25], v[230:233], v[86:89]
	v_mfma_f32_16x16x32_bf16 v[82:85], v[164:167], v[230:233], v[82:85]
	s_setprio 0
	s_setprio 1
	v_mfma_f32_16x16x32_bf16 v[128:131], v[168:171], v[184:187], v[128:131]
	v_mfma_f32_16x16x32_bf16 v[124:127], v[176:179], v[184:187], v[124:127]
	v_mfma_f32_16x16x32_bf16 v[112:115], v[168:171], v[210:213], v[112:115]
	v_mfma_f32_16x16x32_bf16 v[108:111], v[176:179], v[210:213], v[108:111]
	v_mfma_f32_16x16x32_bf16 v[96:99], v[168:171], v[218:221], v[96:99]
	v_mfma_f32_16x16x32_bf16 v[92:95], v[176:179], v[218:221], v[92:95]
	v_mfma_f32_16x16x32_bf16 v[78:81], v[168:171], v[226:229], v[78:81]
	v_mfma_f32_16x16x32_bf16 v[74:77], v[176:179], v[226:229], v[74:77]
	v_mfma_f32_16x16x32_bf16 v[128:131], v[172:175], v[188:191], v[128:131]
	v_mfma_f32_16x16x32_bf16 v[124:127], v[180:183], v[188:191], v[124:127]
	v_mfma_f32_16x16x32_bf16 v[112:115], v[172:175], v[214:217], v[112:115]
	v_mfma_f32_16x16x32_bf16 v[108:111], v[180:183], v[214:217], v[108:111]
	v_mfma_f32_16x16x32_bf16 v[96:99], v[172:175], v[222:225], v[96:99]
	v_mfma_f32_16x16x32_bf16 v[92:95], v[180:183], v[222:225], v[92:95]
	v_mfma_f32_16x16x32_bf16 v[78:81], v[172:175], v[230:233], v[78:81]
	v_mfma_f32_16x16x32_bf16 v[74:77], v[180:183], v[230:233], v[74:77]
	s_barrier
	s_setprio 0
	s_add_i32 s20, s54, s29
	s_mov_b32 m0, s20
	ds_read_b128 v[184:187], v159 offset:16384
	ds_read_b128 v[188:191], v159 offset:17408
	ds_read_b128 v[210:213], v159 offset:18432
	ds_read_b128 v[214:217], v159 offset:19456
	ds_read_b128 v[218:221], v159 offset:20480
	ds_read_b128 v[222:225], v159 offset:21504
	ds_read_b128 v[226:229], v159 offset:22528
	ds_read_b128 v[230:233], v159 offset:23552
	global_load_lds_dwordx4 v142, s[44:45] sc0
	s_add_i32 m0, s20, 0x2000
	s_add_u32 s20, s44, 0x80000
	s_addc_u32 s21, s45, 0
	s_add_i32 s54, s55, s29
	global_load_lds_dwordx4 v146, s[44:45] sc0
	s_mov_b32 m0, s54
	s_nop 0
	global_load_lds_dwordx4 v142, s[20:21] sc0
	s_add_i32 m0, s54, 0x2000
	s_nop 0
	global_load_lds_dwordx4 v146, s[20:21] sc0
	s_mov_b32 m0, s77
	s_nop 0
	global_load_lds_dwordx4 v140, s[46:47] sc0
	s_mov_b32 m0, s49
	s_nop 0
	global_load_lds_dwordx4 v144, s[46:47] sc0
	s_waitcnt vmcnt(8)
	s_waitcnt lgkmcnt(0)
	s_setprio 1
	s_barrier
	v_mfma_f32_16x16x32_bf16 v[70:73], v[18:21], v[184:187], v[70:73]
	v_mfma_f32_16x16x32_bf16 v[66:69], v[160:163], v[184:187], v[66:69]
	v_mfma_f32_16x16x32_bf16 v[54:57], v[18:21], v[210:213], v[54:57]
	v_mfma_f32_16x16x32_bf16 v[50:53], v[160:163], v[210:213], v[50:53]
	v_mfma_f32_16x16x32_bf16 v[38:41], v[18:21], v[218:221], v[38:41]
	v_mfma_f32_16x16x32_bf16 v[34:37], v[160:163], v[218:221], v[34:37]
	v_mfma_f32_16x16x32_bf16 v[12:15], v[18:21], v[226:229], v[12:15]
	v_mfma_f32_16x16x32_bf16 v[8:11], v[160:163], v[226:229], v[8:11]
	v_mfma_f32_16x16x32_bf16 v[70:73], v[22:25], v[188:191], v[70:73]
	v_mfma_f32_16x16x32_bf16 v[66:69], v[164:167], v[188:191], v[66:69]
	v_mfma_f32_16x16x32_bf16 v[54:57], v[22:25], v[214:217], v[54:57]
	v_mfma_f32_16x16x32_bf16 v[50:53], v[164:167], v[214:217], v[50:53]
	v_mfma_f32_16x16x32_bf16 v[38:41], v[22:25], v[222:225], v[38:41]
	v_mfma_f32_16x16x32_bf16 v[34:37], v[164:167], v[222:225], v[34:37]
	v_mfma_f32_16x16x32_bf16 v[12:15], v[22:25], v[230:233], v[12:15]
	v_mfma_f32_16x16x32_bf16 v[8:11], v[164:167], v[230:233], v[8:11]
	s_setprio 0
	s_setprio 1
	v_mfma_f32_16x16x32_bf16 v[46:49], v[168:171], v[210:213], v[46:49]
	v_mfma_f32_16x16x32_bf16 v[42:45], v[176:179], v[210:213], v[42:45]
	v_mfma_f32_16x16x32_bf16 v[30:33], v[168:171], v[218:221], v[30:33]
	v_mfma_f32_16x16x32_bf16 v[26:29], v[176:179], v[218:221], v[26:29]
	v_mfma_f32_16x16x32_bf16 v[4:7], v[168:171], v[226:229], v[4:7]
	v_mfma_f32_16x16x32_bf16 v[0:3], v[176:179], v[226:229], v[0:3]
	v_mfma_f32_16x16x32_bf16 v[18:21], v[168:171], v[184:187], v[62:65]
	v_mfma_f32_16x16x32_bf16 v[22:25], v[176:179], v[184:187], v[58:61]
	v_mfma_f32_16x16x32_bf16 v[46:49], v[172:175], v[214:217], v[46:49]
	v_mfma_f32_16x16x32_bf16 v[42:45], v[180:183], v[214:217], v[42:45]
	v_mfma_f32_16x16x32_bf16 v[30:33], v[172:175], v[222:225], v[30:33]
	v_mfma_f32_16x16x32_bf16 v[26:29], v[180:183], v[222:225], v[26:29]
	v_mfma_f32_16x16x32_bf16 v[4:7], v[172:175], v[230:233], v[4:7]
	v_mfma_f32_16x16x32_bf16 v[0:3], v[180:183], v[230:233], v[0:3]
	v_mfma_f32_16x16x32_bf16 v[18:21], v[172:175], v[188:191], v[18:21]
	v_mfma_f32_16x16x32_bf16 v[22:25], v[180:183], v[188:191], v[22:25]
	s_barrier
; #define PG8_STAGE(bufoff, gbase, voff) do { _Pragma("unroll") for (int _i = 0; _i < 2; ++_i) \
;         __builtin_amdgcn_global_load_lds((const unsigned*)((const char*)(gbase) + (voff)[_i]), (PG8_LAS unsigned*)(lds + (bufoff) + ldsw + _i * 8192), 16, 0, 0); } while (0)
; #define PG8_LDA(dst, b, h) do { _Pragma("unroll") for (int m = 0; m < 4; ++m) _Pragma("unroll") for (int k = 0; k < 2; ++k) dst[m][k] = *(const PG8_LAS bf16x8*)(lds + PG8_SA(b, h) + aoff + m * 2048 + k * 1024); } while (0)
; #define PG8_LDB(dst, b, h) do { _Pragma("unroll") for (int n = 0; n < 2; ++n) _Pragma("unroll") for (int k = 0; k < 2; ++k) dst[n][k] = *(const PG8_LAS bf16x8*)(lds + PG8_SB(b, h) + boff + n * 2048 + k * 1024); } while (0)
; #define PG8_MMA(ai, bj, At, Bt) do { __builtin_amdgcn_s_setprio(1); _Pragma("unroll") for (int m = 0; m < 4; ++m) _Pragma("unroll") for (int n = 0; n < 2; ++n) _Pragma("unroll") for (int k = 0; k < 2; ++k) \
;         acc[ai][bj][m][n] = __builtin_amdgcn_mfma_f32_16x16x32_bf16(Bt[n][k], At[m][k], acc[ai][bj][m][n], 0, 0, 0); __builtin_amdgcn_s_setprio(0); } while (0)
; #define PG8_WAIT_V(n) asm volatile("s_waitcnt vmcnt(" #n ")" ::: "memory")
; #define PG8_WAIT_L(n) asm volatile("s_waitcnt lgkmcnt(" #n ")" ::: "memory")
; #define PG8_BAR __builtin_amdgcn_s_barrier()
; #define PG8_SCHED __builtin_amdgcn_sched_barrier(0)
; template <class Epi>
; __device__ __forceinline__ void gemm_phase(PG8_LAS unsigned char* lds, PG8_LAS unsigned char* xl, const Gemm g, const Sched& S, const Epi& E, const int wid) {
;     ...
;             PG8_LDB(B0, 1, 0); PG8_LDB(B1, 1, 1); PG8_SCHED; PG8_LDA(At, 1, 0); PG8_STAGE(PG8_SA(0, 1), a2 + hstepA, voffA);
;             PG8_WAIT_V(8); PG8_WAIT_L(0); PG8_BAR; if (do0) { PG8_MMA(0, 0, At, B0); PG8_MMA(0, 1, At, B1); } PG8_BAR; PG8_SCHED;
;             PG8_LDA(At, 1, 1); PG8_STAGE(PG8_SB(1, 0), b3, voffB); PG8_STAGE(PG8_SB(1, 1), b3 + hstepB, voffB); PG8_STAGE(PG8_SA(1, 0), a3, voffA);
;             PG8_WAIT_V(8); PG8_WAIT_L(0); PG8_BAR; if (do1) { PG8_MMA(1, 0, At, B0); PG8_MMA(1, 1, At, B1); } PG8_BAR; PG8_SCHED;
;         }
;         if (wr == 0) PG8_BAR;
	s_setprio 0
	s_add_i32 s54, 0, 0x18000
	s_add_i32 s55, 0, 0x1c000
	ds_read_b128 v[58:61], v237 offset:32768
	ds_read_b128 v[62:65], v237 offset:33792
	ds_read_b128 v[160:163], v237 offset:34816
	ds_read_b128 v[164:167], v237 offset:35840
	ds_read_b128 v[168:171], v237 offset:49152
	ds_read_b128 v[172:175], v237 offset:50176
	ds_read_b128 v[176:179], v237 offset:51200
	ds_read_b128 v[180:183], v237 offset:52224
	s_add_u32 s20, s46, 0x80000
	s_addc_u32 s21, s47, 0
	s_mov_b32 m0, s87
	ds_read_b128 v[184:187], v159 offset:32768
	ds_read_b128 v[188:191], v159 offset:33792
	ds_read_b128 v[210:213], v159 offset:34816
	ds_read_b128 v[214:217], v159 offset:35840
	ds_read_b128 v[218:221], v159 offset:36864
	ds_read_b128 v[222:225], v159 offset:37888
	ds_read_b128 v[226:229], v159 offset:38912
	ds_read_b128 v[230:233], v159 offset:39936
	global_load_lds_dwordx4 v140, s[20:21] sc0
	s_mov_b32 m0, s88
	s_nop 0
	global_load_lds_dwordx4 v144, s[20:21] sc0
	s_waitcnt vmcnt(8)
	s_waitcnt lgkmcnt(0)
	s_setprio 1
	s_barrier
	v_mfma_f32_16x16x32_bf16 v[136:139], v[58:61], v[184:187], v[136:139]
	v_mfma_f32_16x16x32_bf16 v[132:135], v[160:163], v[184:187], v[132:135]
	v_mfma_f32_16x16x32_bf16 v[120:123], v[58:61], v[210:213], v[120:123]
	v_mfma_f32_16x16x32_bf16 v[116:119], v[160:163], v[210:213], v[116:119]
	v_mfma_f32_16x16x32_bf16 v[104:107], v[58:61], v[218:221], v[104:107]
	v_mfma_f32_16x16x32_bf16 v[100:103], v[160:163], v[218:221], v[100:103]
	v_mfma_f32_16x16x32_bf16 v[86:89], v[58:61], v[226:229], v[86:89]
	v_mfma_f32_16x16x32_bf16 v[82:85], v[160:163], v[226:229], v[82:85]
	v_mfma_f32_16x16x32_bf16 v[136:139], v[62:65], v[188:191], v[136:139]
	v_mfma_f32_16x16x32_bf16 v[132:135], v[164:167], v[188:191], v[132:135]
	v_mfma_f32_16x16x32_bf16 v[120:123], v[62:65], v[214:217], v[120:123]
	v_mfma_f32_16x16x32_bf16 v[116:119], v[164:167], v[214:217], v[116:119]
	v_mfma_f32_16x16x32_bf16 v[104:107], v[62:65], v[222:225], v[104:107]
	v_mfma_f32_16x16x32_bf16 v[100:103], v[164:167], v[222:225], v[100:103]
	v_mfma_f32_16x16x32_bf16 v[86:89], v[62:65], v[230:233], v[86:89]
	v_mfma_f32_16x16x32_bf16 v[82:85], v[164:167], v[230:233], v[82:85]
	s_setprio 0
	s_setprio 1
	v_mfma_f32_16x16x32_bf16 v[128:131], v[168:171], v[184:187], v[128:131]
	v_mfma_f32_16x16x32_bf16 v[124:127], v[176:179], v[184:187], v[124:127]
	v_mfma_f32_16x16x32_bf16 v[112:115], v[168:171], v[210:213], v[112:115]
	v_mfma_f32_16x16x32_bf16 v[108:111], v[176:179], v[210:213], v[108:111]
	v_mfma_f32_16x16x32_bf16 v[96:99], v[168:171], v[218:221], v[96:99]
	v_mfma_f32_16x16x32_bf16 v[92:95], v[176:179], v[218:221], v[92:95]
	v_mfma_f32_16x16x32_bf16 v[78:81], v[168:171], v[226:229], v[78:81]
	v_mfma_f32_16x16x32_bf16 v[74:77], v[176:179], v[226:229], v[74:77]
	v_mfma_f32_16x16x32_bf16 v[128:131], v[172:175], v[188:191], v[128:131]
	v_mfma_f32_16x16x32_bf16 v[124:127], v[180:183], v[188:191], v[124:127]
	v_mfma_f32_16x16x32_bf16 v[112:115], v[172:175], v[214:217], v[112:115]
	v_mfma_f32_16x16x32_bf16 v[108:111], v[180:183], v[214:217], v[108:111]
	v_mfma_f32_16x16x32_bf16 v[96:99], v[172:175], v[222:225], v[96:99]
	v_mfma_f32_16x16x32_bf16 v[92:95], v[180:183], v[222:225], v[92:95]
	v_mfma_f32_16x16x32_bf16 v[78:81], v[172:175], v[230:233], v[78:81]
	v_mfma_f32_16x16x32_bf16 v[74:77], v[180:183], v[230:233], v[74:77]
	s_barrier
	s_setprio 0
	s_add_i32 s20, s54, s29
	s_mov_b32 m0, s20
	ds_read_b128 v[184:187], v159 offset:49152
	ds_read_b128 v[188:191], v159 offset:50176
	ds_read_b128 v[210:213], v159 offset:51200
	ds_read_b128 v[214:217], v159 offset:52224
	ds_read_b128 v[218:221], v159 offset:53248
	ds_read_b128 v[222:225], v159 offset:54272
	ds_read_b128 v[226:229], v159 offset:55296
	ds_read_b128 v[230:233], v159 offset:56320
	global_load_lds_dwordx4 v234, s[44:45] sc0
	s_add_i32 m0, s20, 0x2000
	s_add_u32 s20, s44, 0x80080
	global_load_lds_dwordx4 v236, s[44:45] sc0
	s_addc_u32 s21, s45, 0
	s_add_i32 s44, s55, s29
	s_mov_b32 m0, s44
	s_nop 0
	global_load_lds_dwordx4 v142, s[20:21] sc0
	s_add_i32 m0, s44, 0x2000
	s_nop 0
	global_load_lds_dwordx4 v146, s[20:21] sc0
	s_mov_b32 m0, s91
	s_nop 0
	global_load_lds_dwordx4 v157, s[46:47] sc0
	s_mov_b32 m0, s92
	s_nop 0
	global_load_lds_dwordx4 v235, s[46:47] sc0
	s_waitcnt vmcnt(8)
	s_waitcnt lgkmcnt(0)
	s_setprio 1
	s_barrier
	v_mfma_f32_16x16x32_bf16 v[70:73], v[58:61], v[184:187], v[70:73]
	v_mfma_f32_16x16x32_bf16 v[66:69], v[160:163], v[184:187], v[66:69]
	v_mfma_f32_16x16x32_bf16 v[54:57], v[58:61], v[210:213], v[54:57]
	v_mfma_f32_16x16x32_bf16 v[50:53], v[160:163], v[210:213], v[50:53]
	v_mfma_f32_16x16x32_bf16 v[38:41], v[58:61], v[218:221], v[38:41]
	v_mfma_f32_16x16x32_bf16 v[34:37], v[160:163], v[218:221], v[34:37]
	v_mfma_f32_16x16x32_bf16 v[12:15], v[58:61], v[226:229], v[12:15]
	v_mfma_f32_16x16x32_bf16 v[8:11], v[160:163], v[226:229], v[8:11]
	v_mfma_f32_16x16x32_bf16 v[70:73], v[62:65], v[188:191], v[70:73]
	v_mfma_f32_16x16x32_bf16 v[66:69], v[164:167], v[188:191], v[66:69]
	v_mfma_f32_16x16x32_bf16 v[54:57], v[62:65], v[214:217], v[54:57]
	v_mfma_f32_16x16x32_bf16 v[50:53], v[164:167], v[214:217], v[50:53]
	v_mfma_f32_16x16x32_bf16 v[38:41], v[62:65], v[222:225], v[38:41]
	v_mfma_f32_16x16x32_bf16 v[34:37], v[164:167], v[222:225], v[34:37]
	v_mfma_f32_16x16x32_bf16 v[12:15], v[62:65], v[230:233], v[12:15]
	v_mfma_f32_16x16x32_bf16 v[8:11], v[164:167], v[230:233], v[8:11]
	s_setprio 0
	s_setprio 1
	v_mfma_f32_16x16x32_bf16 v[18:21], v[168:171], v[184:187], v[18:21]
	v_mfma_f32_16x16x32_bf16 v[62:65], v[172:175], v[188:191], v[18:21]
	v_mfma_f32_16x16x32_bf16 v[18:21], v[176:179], v[184:187], v[22:25]
	v_mfma_f32_16x16x32_bf16 v[58:61], v[180:183], v[188:191], v[18:21]
	v_mfma_f32_16x16x32_bf16 v[18:21], v[168:171], v[210:213], v[46:49]
	v_mfma_f32_16x16x32_bf16 v[46:49], v[172:175], v[214:217], v[18:21]
	v_mfma_f32_16x16x32_bf16 v[18:21], v[176:179], v[210:213], v[42:45]
	v_mfma_f32_16x16x32_bf16 v[42:45], v[180:183], v[214:217], v[18:21]
	v_mfma_f32_16x16x32_bf16 v[18:21], v[168:171], v[218:221], v[30:33]
	v_mfma_f32_16x16x32_bf16 v[30:33], v[172:175], v[222:225], v[18:21]
	v_mfma_f32_16x16x32_bf16 v[18:21], v[176:179], v[218:221], v[26:29]
	v_mfma_f32_16x16x32_bf16 v[4:7], v[168:171], v[226:229], v[4:7]
	v_mfma_f32_16x16x32_bf16 v[0:3], v[176:179], v[226:229], v[0:3]
	v_mfma_f32_16x16x32_bf16 v[26:29], v[180:183], v[222:225], v[18:21]
	v_mfma_f32_16x16x32_bf16 v[4:7], v[172:175], v[230:233], v[4:7]
	v_mfma_f32_16x16x32_bf16 v[0:3], v[180:183], v[230:233], v[0:3]
	s_barrier
	s_setprio 0
	s_add_i32 s62, s62, 2
	s_add_u32 s13, s13, 0x100
	s_addc_u32 s57, s57, 0
	s_cmp_gt_u32 s62, 29
	s_mov_b64 s[20:21], s[30:31]
	s_cbranch_scc0 .LBB0_238
	s_and_b64 vcc, exec, s[14:15]
	s_cbranch_vccz .LBB0_241
	s_barrier

; #define PG8_STAGE(bufoff, gbase, voff) do { _Pragma("unroll") for (int _i = 0; _i < 2; ++_i) \
;         __builtin_amdgcn_global_load_lds((const unsigned*)((const char*)(gbase) + (voff)[_i]), (PG8_LAS unsigned*)(lds + (bufoff) + ldsw + _i * 8192), 16, 0, 0); } while (0)
; #define PG8_LDA(dst, b, h) do { _Pragma("unroll") for (int m = 0; m < 4; ++m) _Pragma("unroll") for (int k = 0; k < 2; ++k) dst[m][k] = *(const PG8_LAS bf16x8*)(lds + PG8_SA(b, h) + aoff + m * 2048 + k * 1024); } while (0)
; #define PG8_LDB(dst, b, h) do { _Pragma("unroll") for (int n = 0; n < 2; ++n) _Pragma("unroll") for (int k = 0; k < 2; ++k) dst[n][k] = *(const PG8_LAS bf16x8*)(lds + PG8_SB(b, h) + boff + n * 2048 + k * 1024); } while (0)
; #define PG8_MMA(ai, bj, At, Bt) do { __builtin_amdgcn_s_setprio(1); _Pragma("unroll") for (int m = 0; m < 4; ++m) _Pragma("unroll") for (int n = 0; n < 2; ++n) _Pragma("unroll") for (int k = 0; k < 2; ++k) \
;         acc[ai][bj][m][n] = __builtin_amdgcn_mfma_f32_16x16x32_bf16(Bt[n][k], At[m][k], acc[ai][bj][m][n], 0, 0, 0); __builtin_amdgcn_s_setprio(0); } while (0)
; #define PG8_WAIT_V(n) asm volatile("s_waitcnt vmcnt(" #n ")" ::: "memory")
; #define PG8_WAIT_L(n) asm volatile("s_waitcnt lgkmcnt(" #n ")" ::: "memory")
; #define PG8_BAR __builtin_amdgcn_s_barrier()
; #define PG8_SCHED __builtin_amdgcn_sched_barrier(0)
; template <class Epi>
; __device__ __forceinline__ void gemm_phase(PG8_LAS unsigned char* lds, PG8_LAS unsigned char* xl, const Gemm g, const Sched& S, const Epi& E, const int wid) {
;     ...
;             const char* a1 = cA + (size_t)(t + 1) * kstep + j1;
;             const char* a2 = last ? nA : cA + (size_t)(t + 2) * kstep + ja2; const char* b2 = last ? nB : cB + (size_t)(t + 2) * kstep + jb2;
;             const char* a3 = a2 + kstep; const char* b3 = b2 + kstep;
;             PG8_LDB(B0, 0, 0); PG8_LDB(B1, 0, 1); PG8_SCHED; PG8_LDA(At, 0, 0); PG8_STAGE(PG8_SA(1, 1), a1 + hstepA, voffA);
;             PG8_WAIT_V(8); PG8_WAIT_L(0); PG8_BAR; if (do0) { PG8_MMA(0, 0, At, B0); PG8_MMA(0, 1, At, B1); } PG8_BAR; PG8_SCHED;
;             PG8_LDA(At, 0, 1); PG8_STAGE(PG8_SB(0, 0), b2, voffB); PG8_STAGE(PG8_SB(0, 1), b2 + hstepB, voffB); PG8_STAGE(PG8_SA(0, 0), a2, voffA);
;             PG8_WAIT_V(8); PG8_WAIT_L(0); PG8_BAR; if (do1) { PG8_MMA(1, 0, At, B0); PG8_MMA(1, 1, At, B1); } PG8_BAR; PG8_SCHED;
.Ldefbar_skip_2:
	v_add_u32_e32 v190, s22, v128
	v_add_u32_e32 v191, s22, v130
	v_add_u32_e32 v226, s22, v132
	v_add_u32_e32 v227, s22, v134
	v_add_u32_e32 v228, 0x10000, v140
	s_add_u32 s76, s60, 0x100
	s_addc_u32 s77, s61, 0
	s_add_i32 s11, 0, 0x10000
	s_cmp_eq_u32 s10, 4
	s_cselect_b32 s41, s47, s77
	s_cselect_b32 s40, s46, s76
	s_cselect_b32 vcc_hi, s59, s9
	s_cselect_b32 vcc_lo, s58, s8
	s_add_i32 s21, 0, 0x14000
	ds_read_b128 v[142:145], v228 offset:0
	ds_read_b128 v[146:149], v228 offset:1024
	ds_read_b128 v[150:153], v228 offset:2048
	ds_read_b128 v[154:157], v228 offset:3072
	ds_read_b128 v[158:161], v228 offset:16384
	ds_read_b128 v[162:165], v228 offset:17408
	ds_read_b128 v[166:169], v228 offset:18432
	ds_read_b128 v[170:173], v228 offset:19456
	s_add_i32 m0, s13, 0xc000
	ds_read_b128 v[174:177], v141
	ds_read_b128 v[178:181], v141 offset:1024
	ds_read_b128 v[182:185], v141 offset:2048
	ds_read_b128 v[186:189], v141 offset:3072
	ds_read_b128 v[210:213], v141 offset:4096
	ds_read_b128 v[214:217], v141 offset:5120
	ds_read_b128 v[218:221], v141 offset:6144
	ds_read_b128 v[222:225], v141 offset:7168
	global_load_lds_dwordx4 v136, s[60:61] sc0
	s_add_i32 m0, s13, 0xe000
	s_nop 0
	global_load_lds_dwordx4 v138, s[60:61] sc0
	s_waitcnt vmcnt(8)
	s_waitcnt lgkmcnt(0)
	s_setprio 1
	s_barrier
	v_mfma_f32_16x16x32_bf16 v[124:127], v[142:145], v[174:177], 0
	v_mfma_f32_16x16x32_bf16 v[120:123], v[150:153], v[174:177], 0
	v_mfma_f32_16x16x32_bf16 v[116:119], v[142:145], v[182:185], 0
	v_mfma_f32_16x16x32_bf16 v[108:111], v[150:153], v[182:185], 0
	v_mfma_f32_16x16x32_bf16 v[100:103], v[142:145], v[210:213], 0
	v_mfma_f32_16x16x32_bf16 v[92:95], v[150:153], v[210:213], 0
	v_mfma_f32_16x16x32_bf16 v[84:87], v[142:145], v[218:221], 0
	v_mfma_f32_16x16x32_bf16 v[76:79], v[150:153], v[218:221], 0
	v_mfma_f32_16x16x32_bf16 v[124:127], v[146:149], v[178:181], v[124:127]
	v_mfma_f32_16x16x32_bf16 v[120:123], v[154:157], v[178:181], v[120:123]
	v_mfma_f32_16x16x32_bf16 v[116:119], v[146:149], v[186:189], v[116:119]
	v_mfma_f32_16x16x32_bf16 v[108:111], v[154:157], v[186:189], v[108:111]
	v_mfma_f32_16x16x32_bf16 v[100:103], v[146:149], v[214:217], v[100:103]
	v_mfma_f32_16x16x32_bf16 v[92:95], v[154:157], v[214:217], v[92:95]
	v_mfma_f32_16x16x32_bf16 v[84:87], v[146:149], v[222:225], v[84:87]
	v_mfma_f32_16x16x32_bf16 v[76:79], v[154:157], v[222:225], v[76:79]
	s_setprio 0
	s_setprio 1
	v_mfma_f32_16x16x32_bf16 v[112:115], v[158:161], v[174:177], 0
	v_mfma_f32_16x16x32_bf16 v[104:107], v[166:169], v[174:177], 0
	v_mfma_f32_16x16x32_bf16 v[96:99], v[158:161], v[182:185], 0
	v_mfma_f32_16x16x32_bf16 v[88:91], v[166:169], v[182:185], 0
	v_mfma_f32_16x16x32_bf16 v[80:83], v[158:161], v[210:213], 0
	v_mfma_f32_16x16x32_bf16 v[72:75], v[166:169], v[210:213], 0
	v_mfma_f32_16x16x32_bf16 v[68:71], v[158:161], v[218:221], 0
	v_mfma_f32_16x16x32_bf16 v[64:67], v[166:169], v[218:221], 0
	v_mfma_f32_16x16x32_bf16 v[112:115], v[162:165], v[178:181], v[112:115]
	v_mfma_f32_16x16x32_bf16 v[104:107], v[170:173], v[178:181], v[104:107]
	v_mfma_f32_16x16x32_bf16 v[96:99], v[162:165], v[186:189], v[96:99]
	v_mfma_f32_16x16x32_bf16 v[88:91], v[170:173], v[186:189], v[88:91]
	v_mfma_f32_16x16x32_bf16 v[80:83], v[162:165], v[214:217], v[80:83]
	v_mfma_f32_16x16x32_bf16 v[72:75], v[170:173], v[214:217], v[72:75]
	v_mfma_f32_16x16x32_bf16 v[68:71], v[162:165], v[222:225], v[68:71]
	v_mfma_f32_16x16x32_bf16 v[64:67], v[170:173], v[222:225], v[64:67]
	s_barrier
	s_setprio 0
	s_add_i32 s11, s11, s29
	s_mov_b32 m0, s11
	ds_read_b128 v[174:177], v141 offset:16384
	ds_read_b128 v[178:181], v141 offset:17408
	ds_read_b128 v[182:185], v141 offset:18432
	ds_read_b128 v[186:189], v141 offset:19456
	ds_read_b128 v[210:213], v141 offset:20480
	ds_read_b128 v[214:217], v141 offset:21504
	ds_read_b128 v[218:221], v141 offset:22528
	ds_read_b128 v[222:225], v141 offset:23552
	global_load_lds_dwordx4 v132, vcc sc0
	s_add_i32 m0, s11, 0x2000
	s_add_u32 s54, vcc_lo, 0x80000
	s_addc_u32 s55, vcc_hi, 0
	s_add_i32 s11, s21, s29
	global_load_lds_dwordx4 v128, vcc sc0
	s_mov_b32 m0, s11
	s_nop 0
	global_load_lds_dwordx4 v132, s[54:55] sc0
	s_add_i32 m0, s11, 0x2000
	s_nop 0
	global_load_lds_dwordx4 v128, s[54:55] sc0
	s_mov_b32 m0, s13
	s_nop 0
	global_load_lds_dwordx4 v134, s[40:41] sc0
	s_mov_b32 m0, s67
	s_nop 0
	global_load_lds_dwordx4 v130, s[40:41] sc0
	s_waitcnt vmcnt(8)
	s_waitcnt lgkmcnt(0)
	s_setprio 1
	s_barrier
	v_mfma_f32_16x16x32_bf16 v[60:63], v[142:145], v[174:177], 0
	v_mfma_f32_16x16x32_bf16 v[56:59], v[150:153], v[174:177], 0
	v_mfma_f32_16x16x32_bf16 v[52:55], v[142:145], v[182:185], 0
	v_mfma_f32_16x16x32_bf16 v[44:47], v[150:153], v[182:185], 0
	v_mfma_f32_16x16x32_bf16 v[36:39], v[142:145], v[210:213], 0
	v_mfma_f32_16x16x32_bf16 v[28:31], v[150:153], v[210:213], 0
	v_mfma_f32_16x16x32_bf16 v[20:23], v[142:145], v[218:221], 0
	v_mfma_f32_16x16x32_bf16 v[12:15], v[150:153], v[218:221], 0
	v_mfma_f32_16x16x32_bf16 v[60:63], v[146:149], v[178:181], v[60:63]
	v_mfma_f32_16x16x32_bf16 v[56:59], v[154:157], v[178:181], v[56:59]
	v_mfma_f32_16x16x32_bf16 v[52:55], v[146:149], v[186:189], v[52:55]
	v_mfma_f32_16x16x32_bf16 v[44:47], v[154:157], v[186:189], v[44:47]
	v_mfma_f32_16x16x32_bf16 v[36:39], v[146:149], v[214:217], v[36:39]
	v_mfma_f32_16x16x32_bf16 v[28:31], v[154:157], v[214:217], v[28:31]
	v_mfma_f32_16x16x32_bf16 v[20:23], v[146:149], v[222:225], v[20:23]
	v_mfma_f32_16x16x32_bf16 v[12:15], v[154:157], v[222:225], v[12:15]
	s_setprio 0
	s_setprio 1
	v_mfma_f32_16x16x32_bf16 v[48:51], v[158:161], v[174:177], 0
	v_mfma_f32_16x16x32_bf16 v[40:43], v[166:169], v[174:177], 0
	v_mfma_f32_16x16x32_bf16 v[32:35], v[158:161], v[182:185], 0
	v_mfma_f32_16x16x32_bf16 v[24:27], v[166:169], v[182:185], 0
	v_mfma_f32_16x16x32_bf16 v[16:19], v[158:161], v[210:213], 0
	v_mfma_f32_16x16x32_bf16 v[8:11], v[166:169], v[210:213], 0
	v_mfma_f32_16x16x32_bf16 v[4:7], v[158:161], v[218:221], 0
	v_mfma_f32_16x16x32_bf16 v[0:3], v[166:169], v[218:221], 0
	v_mfma_f32_16x16x32_bf16 v[48:51], v[162:165], v[178:181], v[48:51]
	v_mfma_f32_16x16x32_bf16 v[40:43], v[170:173], v[178:181], v[40:43]
	v_mfma_f32_16x16x32_bf16 v[32:35], v[162:165], v[186:189], v[32:35]
	v_mfma_f32_16x16x32_bf16 v[24:27], v[170:173], v[186:189], v[24:27]
	v_mfma_f32_16x16x32_bf16 v[16:19], v[162:165], v[214:217], v[16:19]
	v_mfma_f32_16x16x32_bf16 v[8:11], v[170:173], v[214:217], v[8:11]
	v_mfma_f32_16x16x32_bf16 v[4:7], v[162:165], v[222:225], v[4:7]
	v_mfma_f32_16x16x32_bf16 v[0:3], v[170:173], v[222:225], v[0:3]
	s_barrier
; #define PG8_STAGE(bufoff, gbase, voff) do { _Pragma("unroll") for (int _i = 0; _i < 2; ++_i) \
;         __builtin_amdgcn_global_load_lds((const unsigned*)((const char*)(gbase) + (voff)[_i]), (PG8_LAS unsigned*)(lds + (bufoff) + ldsw + _i * 8192), 16, 0, 0); } while (0)
; #define PG8_LDA(dst, b, h) do { _Pragma("unroll") for (int m = 0; m < 4; ++m) _Pragma("unroll") for (int k = 0; k < 2; ++k) dst[m][k] = *(const PG8_LAS bf16x8*)(lds + PG8_SA(b, h) + aoff + m * 2048 + k * 1024); } while (0)
; #define PG8_LDB(dst, b, h) do { _Pragma("unroll") for (int n = 0; n < 2; ++n) _Pragma("unroll") for (int k = 0; k < 2; ++k) dst[n][k] = *(const PG8_LAS bf16x8*)(lds + PG8_SB(b, h) + boff + n * 2048 + k * 1024); } while (0)
; #define PG8_MMA(ai, bj, At, Bt) do { __builtin_amdgcn_s_setprio(1); _Pragma("unroll") for (int m = 0; m < 4; ++m) _Pragma("unroll") for (int n = 0; n < 2; ++n) _Pragma("unroll") for (int k = 0; k < 2; ++k) \
;         acc[ai][bj][m][n] = __builtin_amdgcn_mfma_f32_16x16x32_bf16(Bt[n][k], At[m][k], acc[ai][bj][m][n], 0, 0, 0); __builtin_amdgcn_s_setprio(0); } while (0)
; #define PG8_WAIT_V(n) asm volatile("s_waitcnt vmcnt(" #n ")" ::: "memory")
; #define PG8_WAIT_L(n) asm volatile("s_waitcnt lgkmcnt(" #n ")" ::: "memory")
; #define PG8_BAR __builtin_amdgcn_s_barrier()
; #define PG8_SCHED __builtin_amdgcn_sched_barrier(0)
; template <class Epi>
; __device__ __forceinline__ void gemm_phase(PG8_LAS unsigned char* lds, PG8_LAS unsigned char* xl, const Gemm g, const Sched& S, const Epi& E, const int wid) {
;     ...
;             PG8_LDB(B0, 1, 0); PG8_LDB(B1, 1, 1); PG8_SCHED; PG8_LDA(At, 1, 0); PG8_STAGE(PG8_SA(0, 1), a2 + hstepA, voffA);
;             PG8_WAIT_V(8); PG8_WAIT_L(0); PG8_BAR; if (do0) { PG8_MMA(0, 0, At, B0); PG8_MMA(0, 1, At, B1); } PG8_BAR; PG8_SCHED;
;             PG8_LDA(At, 1, 1); PG8_STAGE(PG8_SB(1, 0), b3, voffB); PG8_STAGE(PG8_SB(1, 1), b3 + hstepB, voffB); PG8_STAGE(PG8_SA(1, 0), a3, voffA);
;             PG8_WAIT_V(8); PG8_WAIT_L(0); PG8_BAR; if (do1) { PG8_MMA(1, 0, At, B0); PG8_MMA(1, 1, At, B1); } PG8_BAR; PG8_SCHED;
;         }
	s_setprio 0
	s_add_i32 s11, 0, 0x18000
	s_add_i32 s21, 0, 0x1c000
	ds_read_b128 v[142:145], v228 offset:32768
	ds_read_b128 v[146:149], v228 offset:33792
	ds_read_b128 v[150:153], v228 offset:34816
	ds_read_b128 v[154:157], v228 offset:35840
	ds_read_b128 v[158:161], v228 offset:49152
	ds_read_b128 v[162:165], v228 offset:50176
	ds_read_b128 v[166:169], v228 offset:51200
	ds_read_b128 v[170:173], v228 offset:52224
	s_add_u32 s100, s40, 0x100000
	s_addc_u32 s101, s41, 0
	s_mov_b32 m0, s68
	ds_read_b128 v[174:177], v141 offset:32768
	ds_read_b128 v[178:181], v141 offset:33792
	ds_read_b128 v[182:185], v141 offset:34816
	ds_read_b128 v[186:189], v141 offset:35840
	ds_read_b128 v[210:213], v141 offset:36864
	ds_read_b128 v[214:217], v141 offset:37888
	ds_read_b128 v[218:221], v141 offset:38912
	ds_read_b128 v[222:225], v141 offset:39936
	global_load_lds_dwordx4 v134, s[100:101] sc0
	s_mov_b32 m0, s69
	s_nop 0
	global_load_lds_dwordx4 v130, s[100:101] sc0
	s_waitcnt vmcnt(8)
	s_waitcnt lgkmcnt(0)
	s_setprio 1
	s_barrier
	v_mfma_f32_16x16x32_bf16 v[124:127], v[142:145], v[174:177], v[124:127]
	v_mfma_f32_16x16x32_bf16 v[120:123], v[150:153], v[174:177], v[120:123]
	v_mfma_f32_16x16x32_bf16 v[116:119], v[142:145], v[182:185], v[116:119]
	v_mfma_f32_16x16x32_bf16 v[108:111], v[150:153], v[182:185], v[108:111]
	v_mfma_f32_16x16x32_bf16 v[100:103], v[142:145], v[210:213], v[100:103]
	v_mfma_f32_16x16x32_bf16 v[92:95], v[150:153], v[210:213], v[92:95]
	v_mfma_f32_16x16x32_bf16 v[84:87], v[142:145], v[218:221], v[84:87]
	v_mfma_f32_16x16x32_bf16 v[76:79], v[150:153], v[218:221], v[76:79]
	v_mfma_f32_16x16x32_bf16 v[124:127], v[146:149], v[178:181], v[124:127]
	v_mfma_f32_16x16x32_bf16 v[120:123], v[154:157], v[178:181], v[120:123]
	v_mfma_f32_16x16x32_bf16 v[116:119], v[146:149], v[186:189], v[116:119]
	v_mfma_f32_16x16x32_bf16 v[108:111], v[154:157], v[186:189], v[108:111]
	v_mfma_f32_16x16x32_bf16 v[100:103], v[146:149], v[214:217], v[100:103]
	v_mfma_f32_16x16x32_bf16 v[92:95], v[154:157], v[214:217], v[92:95]
	v_mfma_f32_16x16x32_bf16 v[84:87], v[146:149], v[222:225], v[84:87]
	v_mfma_f32_16x16x32_bf16 v[76:79], v[154:157], v[222:225], v[76:79]
	s_setprio 0
	s_setprio 1
	v_mfma_f32_16x16x32_bf16 v[112:115], v[158:161], v[174:177], v[112:115]
	v_mfma_f32_16x16x32_bf16 v[104:107], v[166:169], v[174:177], v[104:107]
	v_mfma_f32_16x16x32_bf16 v[96:99], v[158:161], v[182:185], v[96:99]
	v_mfma_f32_16x16x32_bf16 v[88:91], v[166:169], v[182:185], v[88:91]
	v_mfma_f32_16x16x32_bf16 v[80:83], v[158:161], v[210:213], v[80:83]
	v_mfma_f32_16x16x32_bf16 v[72:75], v[166:169], v[210:213], v[72:75]
	v_mfma_f32_16x16x32_bf16 v[68:71], v[158:161], v[218:221], v[68:71]
	v_mfma_f32_16x16x32_bf16 v[64:67], v[166:169], v[218:221], v[64:67]
	v_mfma_f32_16x16x32_bf16 v[112:115], v[162:165], v[178:181], v[112:115]
	v_mfma_f32_16x16x32_bf16 v[104:107], v[170:173], v[178:181], v[104:107]
	v_mfma_f32_16x16x32_bf16 v[96:99], v[162:165], v[186:189], v[96:99]
	v_mfma_f32_16x16x32_bf16 v[88:91], v[170:173], v[186:189], v[88:91]
	v_mfma_f32_16x16x32_bf16 v[80:83], v[162:165], v[214:217], v[80:83]
	v_mfma_f32_16x16x32_bf16 v[72:75], v[170:173], v[214:217], v[72:75]
	v_mfma_f32_16x16x32_bf16 v[68:71], v[162:165], v[222:225], v[68:71]
	v_mfma_f32_16x16x32_bf16 v[64:67], v[170:173], v[222:225], v[64:67]
	s_barrier
	s_setprio 0
	s_add_i32 s11, s11, s29
	s_mov_b32 m0, s11
	ds_read_b128 v[174:177], v141 offset:49152
	ds_read_b128 v[178:181], v141 offset:50176
	ds_read_b128 v[182:185], v141 offset:51200
	ds_read_b128 v[186:189], v141 offset:52224
	ds_read_b128 v[210:213], v141 offset:53248
	ds_read_b128 v[214:217], v141 offset:54272
	ds_read_b128 v[218:221], v141 offset:55296
	ds_read_b128 v[222:225], v141 offset:56320
	global_load_lds_dwordx4 v226, vcc sc0
	s_add_i32 m0, s11, 0x2000
	s_add_u32 s100, vcc_lo, 0x80080
	global_load_lds_dwordx4 v190, vcc sc0
	s_addc_u32 s101, vcc_hi, 0
	s_add_i32 s11, s21, s29
	s_mov_b32 m0, s11
	s_nop 0
	global_load_lds_dwordx4 v132, s[100:101] sc0
	s_add_i32 m0, s11, 0x2000
	s_nop 0
	global_load_lds_dwordx4 v128, s[100:101] sc0
	s_mov_b32 m0, s88
	s_nop 0
	global_load_lds_dwordx4 v227, s[40:41] sc0
	s_mov_b32 m0, s89
	s_nop 0
	global_load_lds_dwordx4 v191, s[40:41] sc0
	s_waitcnt vmcnt(8)
	s_waitcnt lgkmcnt(0)
	s_setprio 1
	s_barrier
	v_mfma_f32_16x16x32_bf16 v[60:63], v[142:145], v[174:177], v[60:63]
	v_mfma_f32_16x16x32_bf16 v[56:59], v[150:153], v[174:177], v[56:59]
	v_mfma_f32_16x16x32_bf16 v[52:55], v[142:145], v[182:185], v[52:55]
	v_mfma_f32_16x16x32_bf16 v[44:47], v[150:153], v[182:185], v[44:47]
	v_mfma_f32_16x16x32_bf16 v[36:39], v[142:145], v[210:213], v[36:39]
	v_mfma_f32_16x16x32_bf16 v[28:31], v[150:153], v[210:213], v[28:31]
	v_mfma_f32_16x16x32_bf16 v[20:23], v[142:145], v[218:221], v[20:23]
	v_mfma_f32_16x16x32_bf16 v[12:15], v[150:153], v[218:221], v[12:15]
	v_mfma_f32_16x16x32_bf16 v[60:63], v[146:149], v[178:181], v[60:63]
	v_mfma_f32_16x16x32_bf16 v[56:59], v[154:157], v[178:181], v[56:59]
	v_mfma_f32_16x16x32_bf16 v[52:55], v[146:149], v[186:189], v[52:55]
	v_mfma_f32_16x16x32_bf16 v[44:47], v[154:157], v[186:189], v[44:47]
	v_mfma_f32_16x16x32_bf16 v[36:39], v[146:149], v[214:217], v[36:39]
	v_mfma_f32_16x16x32_bf16 v[28:31], v[154:157], v[214:217], v[28:31]
	v_mfma_f32_16x16x32_bf16 v[20:23], v[146:149], v[222:225], v[20:23]
	v_mfma_f32_16x16x32_bf16 v[12:15], v[154:157], v[222:225], v[12:15]
	s_setprio 0
	s_setprio 1
	v_mfma_f32_16x16x32_bf16 v[48:51], v[158:161], v[174:177], v[48:51]
	v_mfma_f32_16x16x32_bf16 v[40:43], v[166:169], v[174:177], v[40:43]
	v_mfma_f32_16x16x32_bf16 v[32:35], v[158:161], v[182:185], v[32:35]
	v_mfma_f32_16x16x32_bf16 v[24:27], v[166:169], v[182:185], v[24:27]
	v_mfma_f32_16x16x32_bf16 v[16:19], v[158:161], v[210:213], v[16:19]
	v_mfma_f32_16x16x32_bf16 v[8:11], v[166:169], v[210:213], v[8:11]
	v_mfma_f32_16x16x32_bf16 v[4:7], v[158:161], v[218:221], v[4:7]
	v_mfma_f32_16x16x32_bf16 v[0:3], v[166:169], v[218:221], v[0:3]
	v_mfma_f32_16x16x32_bf16 v[48:51], v[162:165], v[178:181], v[48:51]
	v_mfma_f32_16x16x32_bf16 v[40:43], v[170:173], v[178:181], v[40:43]
	v_mfma_f32_16x16x32_bf16 v[32:35], v[162:165], v[186:189], v[32:35]
	v_mfma_f32_16x16x32_bf16 v[24:27], v[170:173], v[186:189], v[24:27]
	v_mfma_f32_16x16x32_bf16 v[16:19], v[162:165], v[214:217], v[16:19]
	v_mfma_f32_16x16x32_bf16 v[8:11], v[170:173], v[214:217], v[8:11]
	v_mfma_f32_16x16x32_bf16 v[4:7], v[162:165], v[222:225], v[4:7]
	v_mfma_f32_16x16x32_bf16 v[0:3], v[170:173], v[222:225], v[0:3]
	s_barrier
	s_setprio 0
	s_add_i32 s10, s10, 2
	s_add_u32 s8, s8, 0x100
	s_addc_u32 s9, s9, 0
	s_cmp_gt_u32 s10, 5
	s_mov_b64 s[60:61], s[76:77]
; #define PG8_STAGE(bufoff, gbase, voff) do { _Pragma("unroll") for (int _i = 0; _i < 2; ++_i) \
;         __builtin_amdgcn_global_load_lds((const unsigned*)((const char*)(gbase) + (voff)[_i]), (PG8_LAS unsigned*)(lds + (bufoff) + ldsw + _i * 8192), 16, 0, 0); } while (0)
; #define PG8_LDA(dst, b, h) do { _Pragma("unroll") for (int m = 0; m < 4; ++m) _Pragma("unroll") for (int k = 0; k < 2; ++k) dst[m][k] = *(const PG8_LAS bf16x8*)(lds + PG8_SA(b, h) + aoff + m * 2048 + k * 1024); } while (0)
; #define PG8_LDB(dst, b, h) do { _Pragma("unroll") for (int n = 0; n < 2; ++n) _Pragma("unroll") for (int k = 0; k < 2; ++k) dst[n][k] = *(const PG8_LAS bf16x8*)(lds + PG8_SB(b, h) + boff + n * 2048 + k * 1024); } while (0)
; #define PG8_MMA(ai, bj, At, Bt) do { __builtin_amdgcn_s_setprio(1); _Pragma("unroll") for (int m = 0; m < 4; ++m) _Pragma("unroll") for (int n = 0; n < 2; ++n) _Pragma("unroll") for (int k = 0; k < 2; ++k) \
;         acc[ai][bj][m][n] = __builtin_amdgcn_mfma_f32_16x16x32_bf16(Bt[n][k], At[m][k], acc[ai][bj][m][n], 0, 0, 0); __builtin_amdgcn_s_setprio(0); } while (0)
; #define PG8_WAIT_V(n) asm volatile("s_waitcnt vmcnt(" #n ")" ::: "memory")
; #define PG8_WAIT_L(n) asm volatile("s_waitcnt lgkmcnt(" #n ")" ::: "memory")
; #define PG8_BAR __builtin_amdgcn_s_barrier()
; #define PG8_SCHED __builtin_amdgcn_sched_barrier(0)
; template <class Epi>
; __device__ __forceinline__ void gemm_phase(PG8_LAS unsigned char* lds, PG8_LAS unsigned char* xl, const Gemm g, const Sched& S, const Epi& E, const int wid) {
;     ...
;             const char* a1 = cA + (size_t)(t + 1) * kstep + j1;
;             const char* a2 = last ? nA : cA + (size_t)(t + 2) * kstep + ja2; const char* b2 = last ? nB : cB + (size_t)(t + 2) * kstep + jb2;
;             const char* a3 = a2 + kstep; const char* b3 = b2 + kstep;
;             PG8_LDB(B0, 0, 0); PG8_LDB(B1, 0, 1); PG8_SCHED; PG8_LDA(At, 0, 0); PG8_STAGE(PG8_SA(1, 1), a1 + hstepA, voffA);
;             PG8_WAIT_V(8); PG8_WAIT_L(0); PG8_BAR; if (do0) { PG8_MMA(0, 0, At, B0); PG8_MMA(0, 1, At, B1); } PG8_BAR; PG8_SCHED;
;             PG8_LDA(At, 0, 1); PG8_STAGE(PG8_SB(0, 0), b2, voffB); PG8_STAGE(PG8_SB(0, 1), b2 + hstepB, voffB); PG8_STAGE(PG8_SA(0, 0), a2, voffA);
;             PG8_WAIT_V(8); PG8_WAIT_L(0); PG8_BAR; if (do1) { PG8_MMA(1, 0, At, B0); PG8_MMA(1, 1, At, B1); } PG8_BAR; PG8_SCHED;
.LBB0_408:
	s_add_u32 s76, s60, 0x100
	s_addc_u32 s77, s61, 0
	s_add_i32 s11, 0, 0x10000
	s_cmp_eq_u32 s10, 4
	s_cselect_b32 s41, s47, s77
	s_cselect_b32 s40, s46, s76
	s_cselect_b32 vcc_hi, s59, s9
	s_cselect_b32 vcc_lo, s58, s8
	s_add_i32 s21, 0, 0x14000
	ds_read_b128 v[142:145], v228 offset:0
	ds_read_b128 v[146:149], v228 offset:1024
	ds_read_b128 v[150:153], v228 offset:2048
	ds_read_b128 v[154:157], v228 offset:3072
	ds_read_b128 v[158:161], v228 offset:16384
	ds_read_b128 v[162:165], v228 offset:17408
	ds_read_b128 v[166:169], v228 offset:18432
	ds_read_b128 v[170:173], v228 offset:19456
	s_add_i32 m0, s13, 0xc000
	ds_read_b128 v[174:177], v141
	ds_read_b128 v[178:181], v141 offset:1024
	ds_read_b128 v[182:185], v141 offset:2048
	ds_read_b128 v[186:189], v141 offset:3072
	ds_read_b128 v[210:213], v141 offset:4096
	ds_read_b128 v[214:217], v141 offset:5120
	ds_read_b128 v[218:221], v141 offset:6144
	ds_read_b128 v[222:225], v141 offset:7168
	global_load_lds_dwordx4 v136, s[60:61] sc0
	s_add_i32 m0, s13, 0xe000
	s_nop 0
	global_load_lds_dwordx4 v138, s[60:61] sc0
	s_waitcnt vmcnt(8)
	s_waitcnt lgkmcnt(0)
	s_setprio 1
	s_barrier
	v_mfma_f32_16x16x32_bf16 v[124:127], v[142:145], v[174:177], v[124:127]
	v_mfma_f32_16x16x32_bf16 v[120:123], v[150:153], v[174:177], v[120:123]
	v_mfma_f32_16x16x32_bf16 v[116:119], v[142:145], v[182:185], v[116:119]
	v_mfma_f32_16x16x32_bf16 v[108:111], v[150:153], v[182:185], v[108:111]
	v_mfma_f32_16x16x32_bf16 v[100:103], v[142:145], v[210:213], v[100:103]
	v_mfma_f32_16x16x32_bf16 v[92:95], v[150:153], v[210:213], v[92:95]
	v_mfma_f32_16x16x32_bf16 v[84:87], v[142:145], v[218:221], v[84:87]
	v_mfma_f32_16x16x32_bf16 v[76:79], v[150:153], v[218:221], v[76:79]
	v_mfma_f32_16x16x32_bf16 v[124:127], v[146:149], v[178:181], v[124:127]
	v_mfma_f32_16x16x32_bf16 v[120:123], v[154:157], v[178:181], v[120:123]
	v_mfma_f32_16x16x32_bf16 v[116:119], v[146:149], v[186:189], v[116:119]
	v_mfma_f32_16x16x32_bf16 v[108:111], v[154:157], v[186:189], v[108:111]
	v_mfma_f32_16x16x32_bf16 v[100:103], v[146:149], v[214:217], v[100:103]
	v_mfma_f32_16x16x32_bf16 v[92:95], v[154:157], v[214:217], v[92:95]
	v_mfma_f32_16x16x32_bf16 v[84:87], v[146:149], v[222:225], v[84:87]
	v_mfma_f32_16x16x32_bf16 v[76:79], v[154:157], v[222:225], v[76:79]
	s_setprio 0
	s_setprio 1
	v_mfma_f32_16x16x32_bf16 v[112:115], v[158:161], v[174:177], v[112:115]
	v_mfma_f32_16x16x32_bf16 v[104:107], v[166:169], v[174:177], v[104:107]
	v_mfma_f32_16x16x32_bf16 v[96:99], v[158:161], v[182:185], v[96:99]
	v_mfma_f32_16x16x32_bf16 v[88:91], v[166:169], v[182:185], v[88:91]
	v_mfma_f32_16x16x32_bf16 v[80:83], v[158:161], v[210:213], v[80:83]
	v_mfma_f32_16x16x32_bf16 v[72:75], v[166:169], v[210:213], v[72:75]
	v_mfma_f32_16x16x32_bf16 v[68:71], v[158:161], v[218:221], v[68:71]
	v_mfma_f32_16x16x32_bf16 v[64:67], v[166:169], v[218:221], v[64:67]
	v_mfma_f32_16x16x32_bf16 v[112:115], v[162:165], v[178:181], v[112:115]
	v_mfma_f32_16x16x32_bf16 v[104:107], v[170:173], v[178:181], v[104:107]
	v_mfma_f32_16x16x32_bf16 v[96:99], v[162:165], v[186:189], v[96:99]
	v_mfma_f32_16x16x32_bf16 v[88:91], v[170:173], v[186:189], v[88:91]
	v_mfma_f32_16x16x32_bf16 v[80:83], v[162:165], v[214:217], v[80:83]
	v_mfma_f32_16x16x32_bf16 v[72:75], v[170:173], v[214:217], v[72:75]
	v_mfma_f32_16x16x32_bf16 v[68:71], v[162:165], v[222:225], v[68:71]
	v_mfma_f32_16x16x32_bf16 v[64:67], v[170:173], v[222:225], v[64:67]
	s_barrier
	s_setprio 0
	s_add_i32 s11, s11, s29
	s_mov_b32 m0, s11
	ds_read_b128 v[174:177], v141 offset:16384
	ds_read_b128 v[178:181], v141 offset:17408
	ds_read_b128 v[182:185], v141 offset:18432
	ds_read_b128 v[186:189], v141 offset:19456
	ds_read_b128 v[210:213], v141 offset:20480
	ds_read_b128 v[214:217], v141 offset:21504
	ds_read_b128 v[218:221], v141 offset:22528
	ds_read_b128 v[222:225], v141 offset:23552
	global_load_lds_dwordx4 v132, vcc sc0
	s_add_i32 m0, s11, 0x2000
	s_add_u32 s54, vcc_lo, 0x80000
	s_addc_u32 s55, vcc_hi, 0
	s_add_i32 s11, s21, s29
	global_load_lds_dwordx4 v128, vcc sc0
	s_mov_b32 m0, s11
	s_nop 0
	global_load_lds_dwordx4 v132, s[54:55] sc0
	s_add_i32 m0, s11, 0x2000
	s_nop 0
	global_load_lds_dwordx4 v128, s[54:55] sc0
	s_mov_b32 m0, s13
	s_nop 0
	global_load_lds_dwordx4 v134, s[40:41] sc0
	s_mov_b32 m0, s67
	s_nop 0
	global_load_lds_dwordx4 v130, s[40:41] sc0
	s_waitcnt vmcnt(8)
	s_waitcnt lgkmcnt(0)
	s_setprio 1
	s_barrier
	v_mfma_f32_16x16x32_bf16 v[60:63], v[142:145], v[174:177], v[60:63]
	v_mfma_f32_16x16x32_bf16 v[56:59], v[150:153], v[174:177], v[56:59]
	v_mfma_f32_16x16x32_bf16 v[52:55], v[142:145], v[182:185], v[52:55]
	v_mfma_f32_16x16x32_bf16 v[44:47], v[150:153], v[182:185], v[44:47]
	v_mfma_f32_16x16x32_bf16 v[36:39], v[142:145], v[210:213], v[36:39]
	v_mfma_f32_16x16x32_bf16 v[28:31], v[150:153], v[210:213], v[28:31]
	v_mfma_f32_16x16x32_bf16 v[20:23], v[142:145], v[218:221], v[20:23]
	v_mfma_f32_16x16x32_bf16 v[12:15], v[150:153], v[218:221], v[12:15]
	v_mfma_f32_16x16x32_bf16 v[60:63], v[146:149], v[178:181], v[60:63]
	v_mfma_f32_16x16x32_bf16 v[56:59], v[154:157], v[178:181], v[56:59]
	v_mfma_f32_16x16x32_bf16 v[52:55], v[146:149], v[186:189], v[52:55]
	v_mfma_f32_16x16x32_bf16 v[44:47], v[154:157], v[186:189], v[44:47]
	v_mfma_f32_16x16x32_bf16 v[36:39], v[146:149], v[214:217], v[36:39]
	v_mfma_f32_16x16x32_bf16 v[28:31], v[154:157], v[214:217], v[28:31]
	v_mfma_f32_16x16x32_bf16 v[20:23], v[146:149], v[222:225], v[20:23]
	v_mfma_f32_16x16x32_bf16 v[12:15], v[154:157], v[222:225], v[12:15]
	s_setprio 0
	s_setprio 1
	v_mfma_f32_16x16x32_bf16 v[48:51], v[158:161], v[174:177], v[48:51]
	v_mfma_f32_16x16x32_bf16 v[40:43], v[166:169], v[174:177], v[40:43]
	v_mfma_f32_16x16x32_bf16 v[32:35], v[158:161], v[182:185], v[32:35]
	v_mfma_f32_16x16x32_bf16 v[24:27], v[166:169], v[182:185], v[24:27]
	v_mfma_f32_16x16x32_bf16 v[16:19], v[158:161], v[210:213], v[16:19]
	v_mfma_f32_16x16x32_bf16 v[8:11], v[166:169], v[210:213], v[8:11]
	v_mfma_f32_16x16x32_bf16 v[4:7], v[158:161], v[218:221], v[4:7]
	v_mfma_f32_16x16x32_bf16 v[0:3], v[166:169], v[218:221], v[0:3]
	v_mfma_f32_16x16x32_bf16 v[48:51], v[162:165], v[178:181], v[48:51]
	v_mfma_f32_16x16x32_bf16 v[40:43], v[170:173], v[178:181], v[40:43]
	v_mfma_f32_16x16x32_bf16 v[32:35], v[162:165], v[186:189], v[32:35]
	v_mfma_f32_16x16x32_bf16 v[24:27], v[170:173], v[186:189], v[24:27]
	v_mfma_f32_16x16x32_bf16 v[16:19], v[162:165], v[214:217], v[16:19]
	v_mfma_f32_16x16x32_bf16 v[8:11], v[170:173], v[214:217], v[8:11]
	v_mfma_f32_16x16x32_bf16 v[4:7], v[162:165], v[222:225], v[4:7]
	v_mfma_f32_16x16x32_bf16 v[0:3], v[170:173], v[222:225], v[0:3]
	s_barrier
; #define PG8_STAGE(bufoff, gbase, voff) do { _Pragma("unroll") for (int _i = 0; _i < 2; ++_i) \
;         __builtin_amdgcn_global_load_lds((const unsigned*)((const char*)(gbase) + (voff)[_i]), (PG8_LAS unsigned*)(lds + (bufoff) + ldsw + _i * 8192), 16, 0, 0); } while (0)
; #define PG8_LDA(dst, b, h) do { _Pragma("unroll") for (int m = 0; m < 4; ++m) _Pragma("unroll") for (int k = 0; k < 2; ++k) dst[m][k] = *(const PG8_LAS bf16x8*)(lds + PG8_SA(b, h) + aoff + m * 2048 + k * 1024); } while (0)
; #define PG8_LDB(dst, b, h) do { _Pragma("unroll") for (int n = 0; n < 2; ++n) _Pragma("unroll") for (int k = 0; k < 2; ++k) dst[n][k] = *(const PG8_LAS bf16x8*)(lds + PG8_SB(b, h) + boff + n * 2048 + k * 1024); } while (0)
; #define PG8_MMA(ai, bj, At, Bt) do { __builtin_amdgcn_s_setprio(1); _Pragma("unroll") for (int m = 0; m < 4; ++m) _Pragma("unroll") for (int n = 0; n < 2; ++n) _Pragma("unroll") for (int k = 0; k < 2; ++k) \
;         acc[ai][bj][m][n] = __builtin_amdgcn_mfma_f32_16x16x32_bf16(Bt[n][k], At[m][k], acc[ai][bj][m][n], 0, 0, 0); __builtin_amdgcn_s_setprio(0); } while (0)
; #define PG8_WAIT_V(n) asm volatile("s_waitcnt vmcnt(" #n ")" ::: "memory")
; #define PG8_WAIT_L(n) asm volatile("s_waitcnt lgkmcnt(" #n ")" ::: "memory")
; #define PG8_BAR __builtin_amdgcn_s_barrier()
; #define PG8_SCHED __builtin_amdgcn_sched_barrier(0)
; template <class Epi>
; __device__ __forceinline__ void gemm_phase(PG8_LAS unsigned char* lds, PG8_LAS unsigned char* xl, const Gemm g, const Sched& S, const Epi& E, const int wid) {
;     ...
;             PG8_LDB(B0, 1, 0); PG8_LDB(B1, 1, 1); PG8_SCHED; PG8_LDA(At, 1, 0); PG8_STAGE(PG8_SA(0, 1), a2 + hstepA, voffA);
;             PG8_WAIT_V(8); PG8_WAIT_L(0); PG8_BAR; if (do0) { PG8_MMA(0, 0, At, B0); PG8_MMA(0, 1, At, B1); } PG8_BAR; PG8_SCHED;
;             PG8_LDA(At, 1, 1); PG8_STAGE(PG8_SB(1, 0), b3, voffB); PG8_STAGE(PG8_SB(1, 1), b3 + hstepB, voffB); PG8_STAGE(PG8_SA(1, 0), a3, voffA);
;             PG8_WAIT_V(8); PG8_WAIT_L(0); PG8_BAR; if (do1) { PG8_MMA(1, 0, At, B0); PG8_MMA(1, 1, At, B1); } PG8_BAR; PG8_SCHED;
;         }
;         if (wr == 0) PG8_BAR;
	s_setprio 0
	s_add_i32 s11, 0, 0x18000
	s_add_i32 s21, 0, 0x1c000
	ds_read_b128 v[142:145], v228 offset:32768
	ds_read_b128 v[146:149], v228 offset:33792
	ds_read_b128 v[150:153], v228 offset:34816
	ds_read_b128 v[154:157], v228 offset:35840
	ds_read_b128 v[158:161], v228 offset:49152
	ds_read_b128 v[162:165], v228 offset:50176
	ds_read_b128 v[166:169], v228 offset:51200
	ds_read_b128 v[170:173], v228 offset:52224
	s_add_u32 s100, s40, 0x100000
	s_addc_u32 s101, s41, 0
	s_mov_b32 m0, s68
	ds_read_b128 v[174:177], v141 offset:32768
	ds_read_b128 v[178:181], v141 offset:33792
	ds_read_b128 v[182:185], v141 offset:34816
	ds_read_b128 v[186:189], v141 offset:35840
	ds_read_b128 v[210:213], v141 offset:36864
	ds_read_b128 v[214:217], v141 offset:37888
	ds_read_b128 v[218:221], v141 offset:38912
	ds_read_b128 v[222:225], v141 offset:39936
	global_load_lds_dwordx4 v134, s[100:101] sc0
	s_mov_b32 m0, s69
	s_nop 0
	global_load_lds_dwordx4 v130, s[100:101] sc0
	s_waitcnt vmcnt(8)
	s_waitcnt lgkmcnt(0)
	s_setprio 1
	s_barrier
	v_mfma_f32_16x16x32_bf16 v[124:127], v[142:145], v[174:177], v[124:127]
	v_mfma_f32_16x16x32_bf16 v[120:123], v[150:153], v[174:177], v[120:123]
	v_mfma_f32_16x16x32_bf16 v[116:119], v[142:145], v[182:185], v[116:119]
	v_mfma_f32_16x16x32_bf16 v[108:111], v[150:153], v[182:185], v[108:111]
	v_mfma_f32_16x16x32_bf16 v[100:103], v[142:145], v[210:213], v[100:103]
	v_mfma_f32_16x16x32_bf16 v[92:95], v[150:153], v[210:213], v[92:95]
	v_mfma_f32_16x16x32_bf16 v[84:87], v[142:145], v[218:221], v[84:87]
	v_mfma_f32_16x16x32_bf16 v[76:79], v[150:153], v[218:221], v[76:79]
	v_mfma_f32_16x16x32_bf16 v[124:127], v[146:149], v[178:181], v[124:127]
	v_mfma_f32_16x16x32_bf16 v[120:123], v[154:157], v[178:181], v[120:123]
	v_mfma_f32_16x16x32_bf16 v[116:119], v[146:149], v[186:189], v[116:119]
	v_mfma_f32_16x16x32_bf16 v[108:111], v[154:157], v[186:189], v[108:111]
	v_mfma_f32_16x16x32_bf16 v[100:103], v[146:149], v[214:217], v[100:103]
	v_mfma_f32_16x16x32_bf16 v[92:95], v[154:157], v[214:217], v[92:95]
	v_mfma_f32_16x16x32_bf16 v[84:87], v[146:149], v[222:225], v[84:87]
	v_mfma_f32_16x16x32_bf16 v[76:79], v[154:157], v[222:225], v[76:79]
	s_setprio 0
	s_setprio 1
	v_mfma_f32_16x16x32_bf16 v[112:115], v[158:161], v[174:177], v[112:115]
	v_mfma_f32_16x16x32_bf16 v[104:107], v[166:169], v[174:177], v[104:107]
	v_mfma_f32_16x16x32_bf16 v[96:99], v[158:161], v[182:185], v[96:99]
	v_mfma_f32_16x16x32_bf16 v[88:91], v[166:169], v[182:185], v[88:91]
	v_mfma_f32_16x16x32_bf16 v[80:83], v[158:161], v[210:213], v[80:83]
	v_mfma_f32_16x16x32_bf16 v[72:75], v[166:169], v[210:213], v[72:75]
	v_mfma_f32_16x16x32_bf16 v[68:71], v[158:161], v[218:221], v[68:71]
	v_mfma_f32_16x16x32_bf16 v[64:67], v[166:169], v[218:221], v[64:67]
	v_mfma_f32_16x16x32_bf16 v[112:115], v[162:165], v[178:181], v[112:115]
	v_mfma_f32_16x16x32_bf16 v[104:107], v[170:173], v[178:181], v[104:107]
	v_mfma_f32_16x16x32_bf16 v[96:99], v[162:165], v[186:189], v[96:99]
	v_mfma_f32_16x16x32_bf16 v[88:91], v[170:173], v[186:189], v[88:91]
	v_mfma_f32_16x16x32_bf16 v[80:83], v[162:165], v[214:217], v[80:83]
	v_mfma_f32_16x16x32_bf16 v[72:75], v[170:173], v[214:217], v[72:75]
	v_mfma_f32_16x16x32_bf16 v[68:71], v[162:165], v[222:225], v[68:71]
	v_mfma_f32_16x16x32_bf16 v[64:67], v[170:173], v[222:225], v[64:67]
	s_barrier
	s_setprio 0
	s_add_i32 s11, s11, s29
	s_mov_b32 m0, s11
	ds_read_b128 v[174:177], v141 offset:49152
	ds_read_b128 v[178:181], v141 offset:50176
	ds_read_b128 v[182:185], v141 offset:51200
	ds_read_b128 v[186:189], v141 offset:52224
	ds_read_b128 v[210:213], v141 offset:53248
	ds_read_b128 v[214:217], v141 offset:54272
	ds_read_b128 v[218:221], v141 offset:55296
	ds_read_b128 v[222:225], v141 offset:56320
	global_load_lds_dwordx4 v226, vcc sc0
	s_add_i32 m0, s11, 0x2000
	s_add_u32 s100, vcc_lo, 0x80080
	global_load_lds_dwordx4 v190, vcc sc0
	s_addc_u32 s101, vcc_hi, 0
	s_add_i32 s11, s21, s29
	s_mov_b32 m0, s11
	s_nop 0
	global_load_lds_dwordx4 v132, s[100:101] sc0
	s_add_i32 m0, s11, 0x2000
	s_nop 0
	global_load_lds_dwordx4 v128, s[100:101] sc0
	s_mov_b32 m0, s88
	s_nop 0
	global_load_lds_dwordx4 v227, s[40:41] sc0
	s_mov_b32 m0, s89
	s_nop 0
	global_load_lds_dwordx4 v191, s[40:41] sc0
	s_waitcnt vmcnt(8)
	s_waitcnt lgkmcnt(0)
	s_setprio 1
	s_barrier
	v_mfma_f32_16x16x32_bf16 v[60:63], v[142:145], v[174:177], v[60:63]
	v_mfma_f32_16x16x32_bf16 v[56:59], v[150:153], v[174:177], v[56:59]
	v_mfma_f32_16x16x32_bf16 v[52:55], v[142:145], v[182:185], v[52:55]
	v_mfma_f32_16x16x32_bf16 v[44:47], v[150:153], v[182:185], v[44:47]
	v_mfma_f32_16x16x32_bf16 v[36:39], v[142:145], v[210:213], v[36:39]
	v_mfma_f32_16x16x32_bf16 v[28:31], v[150:153], v[210:213], v[28:31]
	v_mfma_f32_16x16x32_bf16 v[20:23], v[142:145], v[218:221], v[20:23]
	v_mfma_f32_16x16x32_bf16 v[12:15], v[150:153], v[218:221], v[12:15]
	v_mfma_f32_16x16x32_bf16 v[60:63], v[146:149], v[178:181], v[60:63]
	v_mfma_f32_16x16x32_bf16 v[56:59], v[154:157], v[178:181], v[56:59]
	v_mfma_f32_16x16x32_bf16 v[52:55], v[146:149], v[186:189], v[52:55]
	v_mfma_f32_16x16x32_bf16 v[44:47], v[154:157], v[186:189], v[44:47]
	v_mfma_f32_16x16x32_bf16 v[36:39], v[146:149], v[214:217], v[36:39]
	v_mfma_f32_16x16x32_bf16 v[28:31], v[154:157], v[214:217], v[28:31]
	v_mfma_f32_16x16x32_bf16 v[20:23], v[146:149], v[222:225], v[20:23]
	v_mfma_f32_16x16x32_bf16 v[12:15], v[154:157], v[222:225], v[12:15]
	s_setprio 0
	s_setprio 1
	v_mfma_f32_16x16x32_bf16 v[48:51], v[158:161], v[174:177], v[48:51]
	v_mfma_f32_16x16x32_bf16 v[40:43], v[166:169], v[174:177], v[40:43]
	v_mfma_f32_16x16x32_bf16 v[32:35], v[158:161], v[182:185], v[32:35]
	v_mfma_f32_16x16x32_bf16 v[24:27], v[166:169], v[182:185], v[24:27]
	v_mfma_f32_16x16x32_bf16 v[16:19], v[158:161], v[210:213], v[16:19]
	v_mfma_f32_16x16x32_bf16 v[8:11], v[166:169], v[210:213], v[8:11]
	v_mfma_f32_16x16x32_bf16 v[4:7], v[158:161], v[218:221], v[4:7]
	v_mfma_f32_16x16x32_bf16 v[0:3], v[166:169], v[218:221], v[0:3]
	v_mfma_f32_16x16x32_bf16 v[48:51], v[162:165], v[178:181], v[48:51]
	v_mfma_f32_16x16x32_bf16 v[40:43], v[170:173], v[178:181], v[40:43]
	v_mfma_f32_16x16x32_bf16 v[32:35], v[162:165], v[186:189], v[32:35]
	v_mfma_f32_16x16x32_bf16 v[24:27], v[170:173], v[186:189], v[24:27]
	v_mfma_f32_16x16x32_bf16 v[16:19], v[162:165], v[214:217], v[16:19]
	v_mfma_f32_16x16x32_bf16 v[8:11], v[170:173], v[214:217], v[8:11]
	v_mfma_f32_16x16x32_bf16 v[4:7], v[162:165], v[222:225], v[4:7]
	v_mfma_f32_16x16x32_bf16 v[0:3], v[170:173], v[222:225], v[0:3]
	s_barrier
	s_setprio 0
	s_add_i32 s10, s10, 2
	s_add_u32 s8, s8, 0x100
	s_addc_u32 s9, s9, 0
	s_cmp_gt_u32 s10, 5
	s_mov_b64 s[60:61], s[76:77]
	s_cbranch_scc0 .LBB0_408
	s_mov_b32 s100, 0
	s_and_b64 vcc, exec, s[14:15]
	s_cbranch_vccz .LBB0_411
	s_barrier

; #define PG8_STAGE(bufoff, gbase, voff) do { _Pragma("unroll") for (int _i = 0; _i < 2; ++_i) \
;         __builtin_amdgcn_global_load_lds((const unsigned*)((const char*)(gbase) + (voff)[_i]), (PG8_LAS unsigned*)(lds + (bufoff) + ldsw + _i * 8192), 16, 0, 0); } while (0)
; #define PG8_LDA(dst, b, h) do { _Pragma("unroll") for (int m = 0; m < 4; ++m) _Pragma("unroll") for (int k = 0; k < 2; ++k) dst[m][k] = *(const PG8_LAS bf16x8*)(lds + PG8_SA(b, h) + aoff + m * 2048 + k * 1024); } while (0)
; #define PG8_LDB(dst, b, h) do { _Pragma("unroll") for (int n = 0; n < 2; ++n) _Pragma("unroll") for (int k = 0; k < 2; ++k) dst[n][k] = *(const PG8_LAS bf16x8*)(lds + PG8_SB(b, h) + boff + n * 2048 + k * 1024); } while (0)
; #define PG8_MMA(ai, bj, At, Bt) do { __builtin_amdgcn_s_setprio(1); _Pragma("unroll") for (int m = 0; m < 4; ++m) _Pragma("unroll") for (int n = 0; n < 2; ++n) _Pragma("unroll") for (int k = 0; k < 2; ++k) \
;         acc[ai][bj][m][n] = __builtin_amdgcn_mfma_f32_16x16x32_bf16(Bt[n][k], At[m][k], acc[ai][bj][m][n], 0, 0, 0); __builtin_amdgcn_s_setprio(0); } while (0)
; #define PG8_WAIT_V(n) asm volatile("s_waitcnt vmcnt(" #n ")" ::: "memory")
; #define PG8_WAIT_L(n) asm volatile("s_waitcnt lgkmcnt(" #n ")" ::: "memory")
; #define PG8_BAR __builtin_amdgcn_s_barrier()
; #define PG8_SCHED __builtin_amdgcn_sched_barrier(0)
; template <class Epi>
; __device__ __forceinline__ void gemm_phase(PG8_LAS unsigned char* lds, PG8_LAS unsigned char* xl, const Gemm g, const Sched& S, const Epi& E, const int wid) {
;     ...
;             const char* a1 = cA + (size_t)(t + 1) * kstep + j1;
;             const char* a2 = last ? nA : cA + (size_t)(t + 2) * kstep + ja2; const char* b2 = last ? nB : cB + (size_t)(t + 2) * kstep + jb2;
;             const char* a3 = a2 + kstep; const char* b3 = b2 + kstep;
;             PG8_LDB(B0, 0, 0); PG8_LDB(B1, 0, 1); PG8_SCHED; PG8_LDA(At, 0, 0); PG8_STAGE(PG8_SA(1, 1), a1 + hstepA, voffA);
;             PG8_WAIT_V(8); PG8_WAIT_L(0); PG8_BAR; if (do0) { PG8_MMA(0, 0, At, B0); PG8_MMA(0, 1, At, B1); } PG8_BAR; PG8_SCHED;
;             PG8_LDA(At, 0, 1); PG8_STAGE(PG8_SB(0, 0), b2, voffB); PG8_STAGE(PG8_SB(0, 1), b2 + hstepB, voffB); PG8_STAGE(PG8_SA(0, 0), a2, voffA);
;             PG8_WAIT_V(8); PG8_WAIT_L(0); PG8_BAR; if (do1) { PG8_MMA(1, 0, At, B0); PG8_MMA(1, 1, At, B1); } PG8_BAR; PG8_SCHED;
.Ldefbar_skip_3:
	v_add_u32_e32 v190, s22, v128
	v_add_u32_e32 v191, s22, v130
	v_add_u32_e32 v226, s22, v132
	v_add_u32_e32 v227, s22, v134
	v_add_u32_e32 v228, 0x10000, v140
	s_add_u32 s60, s58, 0x100
	s_addc_u32 s61, s59, 0
	s_add_i32 s11, 0, 0x10000
	s_cmp_eq_u32 s10, 4
	s_cselect_b32 s41, s47, s61
	s_cselect_b32 s40, s46, s60
	s_cselect_b32 s77, s57, s9
	s_cselect_b32 s76, s56, s8
	s_add_i32 s21, 0, 0x14000
	ds_read_b128 v[142:145], v228 offset:0
	ds_read_b128 v[146:149], v228 offset:1024
	ds_read_b128 v[150:153], v228 offset:2048
	ds_read_b128 v[154:157], v228 offset:3072
	ds_read_b128 v[158:161], v228 offset:16384
	ds_read_b128 v[162:165], v228 offset:17408
	ds_read_b128 v[166:169], v228 offset:18432
	ds_read_b128 v[170:173], v228 offset:19456
	s_add_i32 m0, s13, 0xc000
	ds_read_b128 v[174:177], v141
	ds_read_b128 v[178:181], v141 offset:1024
	ds_read_b128 v[182:185], v141 offset:2048
	ds_read_b128 v[186:189], v141 offset:3072
	ds_read_b128 v[210:213], v141 offset:4096
	ds_read_b128 v[214:217], v141 offset:5120
	ds_read_b128 v[218:221], v141 offset:6144
	ds_read_b128 v[222:225], v141 offset:7168
	global_load_lds_dwordx4 v136, s[58:59] sc0
	s_add_i32 m0, s13, 0xe000
	s_nop 0
	global_load_lds_dwordx4 v138, s[58:59] sc0
	s_waitcnt vmcnt(8)
	s_waitcnt lgkmcnt(0)
	s_setprio 1
	s_barrier
	v_mfma_f32_16x16x32_bf16 v[124:127], v[142:145], v[174:177], 0
	v_mfma_f32_16x16x32_bf16 v[120:123], v[150:153], v[174:177], 0
	v_mfma_f32_16x16x32_bf16 v[116:119], v[142:145], v[182:185], 0
	v_mfma_f32_16x16x32_bf16 v[108:111], v[150:153], v[182:185], 0
	v_mfma_f32_16x16x32_bf16 v[100:103], v[142:145], v[210:213], 0
	v_mfma_f32_16x16x32_bf16 v[92:95], v[150:153], v[210:213], 0
	v_mfma_f32_16x16x32_bf16 v[84:87], v[142:145], v[218:221], 0
	v_mfma_f32_16x16x32_bf16 v[76:79], v[150:153], v[218:221], 0
	v_mfma_f32_16x16x32_bf16 v[124:127], v[146:149], v[178:181], v[124:127]
	v_mfma_f32_16x16x32_bf16 v[120:123], v[154:157], v[178:181], v[120:123]
	v_mfma_f32_16x16x32_bf16 v[116:119], v[146:149], v[186:189], v[116:119]
	v_mfma_f32_16x16x32_bf16 v[108:111], v[154:157], v[186:189], v[108:111]
	v_mfma_f32_16x16x32_bf16 v[100:103], v[146:149], v[214:217], v[100:103]
	v_mfma_f32_16x16x32_bf16 v[92:95], v[154:157], v[214:217], v[92:95]
	v_mfma_f32_16x16x32_bf16 v[84:87], v[146:149], v[222:225], v[84:87]
	v_mfma_f32_16x16x32_bf16 v[76:79], v[154:157], v[222:225], v[76:79]
	s_setprio 0
	s_setprio 1
	v_mfma_f32_16x16x32_bf16 v[112:115], v[158:161], v[174:177], 0
	v_mfma_f32_16x16x32_bf16 v[104:107], v[166:169], v[174:177], 0
	v_mfma_f32_16x16x32_bf16 v[96:99], v[158:161], v[182:185], 0
	v_mfma_f32_16x16x32_bf16 v[88:91], v[166:169], v[182:185], 0
	v_mfma_f32_16x16x32_bf16 v[80:83], v[158:161], v[210:213], 0
	v_mfma_f32_16x16x32_bf16 v[72:75], v[166:169], v[210:213], 0
	v_mfma_f32_16x16x32_bf16 v[68:71], v[158:161], v[218:221], 0
	v_mfma_f32_16x16x32_bf16 v[64:67], v[166:169], v[218:221], 0
	v_mfma_f32_16x16x32_bf16 v[112:115], v[162:165], v[178:181], v[112:115]
	v_mfma_f32_16x16x32_bf16 v[104:107], v[170:173], v[178:181], v[104:107]
	v_mfma_f32_16x16x32_bf16 v[96:99], v[162:165], v[186:189], v[96:99]
	v_mfma_f32_16x16x32_bf16 v[88:91], v[170:173], v[186:189], v[88:91]
	v_mfma_f32_16x16x32_bf16 v[80:83], v[162:165], v[214:217], v[80:83]
	v_mfma_f32_16x16x32_bf16 v[72:75], v[170:173], v[214:217], v[72:75]
	v_mfma_f32_16x16x32_bf16 v[68:71], v[162:165], v[222:225], v[68:71]
	v_mfma_f32_16x16x32_bf16 v[64:67], v[170:173], v[222:225], v[64:67]
	s_barrier
	s_setprio 0
	s_add_i32 s11, s11, s29
	s_mov_b32 m0, s11
	ds_read_b128 v[174:177], v141 offset:16384
	ds_read_b128 v[178:181], v141 offset:17408
	ds_read_b128 v[182:185], v141 offset:18432
	ds_read_b128 v[186:189], v141 offset:19456
	ds_read_b128 v[210:213], v141 offset:20480
	ds_read_b128 v[214:217], v141 offset:21504
	ds_read_b128 v[218:221], v141 offset:22528
	ds_read_b128 v[222:225], v141 offset:23552
	global_load_lds_dwordx4 v132, s[76:77] sc0
	s_add_i32 m0, s11, 0x2000
	s_add_u32 s54, s76, 0x100000
	s_addc_u32 s55, s77, 0
	s_add_i32 s11, s21, s29
	global_load_lds_dwordx4 v128, s[76:77] sc0
	s_mov_b32 m0, s11
	s_nop 0
	global_load_lds_dwordx4 v132, s[54:55] sc0
	s_add_i32 m0, s11, 0x2000
	s_nop 0
	global_load_lds_dwordx4 v128, s[54:55] sc0
	s_mov_b32 m0, s13
	s_nop 0
	global_load_lds_dwordx4 v134, s[40:41] sc0
	s_mov_b32 m0, s69
	s_nop 0
	global_load_lds_dwordx4 v130, s[40:41] sc0
	s_waitcnt vmcnt(8)
	s_waitcnt lgkmcnt(0)
	s_setprio 1
	s_barrier
	v_mfma_f32_16x16x32_bf16 v[60:63], v[142:145], v[174:177], 0
	v_mfma_f32_16x16x32_bf16 v[56:59], v[150:153], v[174:177], 0
	v_mfma_f32_16x16x32_bf16 v[52:55], v[142:145], v[182:185], 0
	v_mfma_f32_16x16x32_bf16 v[44:47], v[150:153], v[182:185], 0
	v_mfma_f32_16x16x32_bf16 v[36:39], v[142:145], v[210:213], 0
	v_mfma_f32_16x16x32_bf16 v[28:31], v[150:153], v[210:213], 0
	v_mfma_f32_16x16x32_bf16 v[20:23], v[142:145], v[218:221], 0
	v_mfma_f32_16x16x32_bf16 v[12:15], v[150:153], v[218:221], 0
	v_mfma_f32_16x16x32_bf16 v[60:63], v[146:149], v[178:181], v[60:63]
	v_mfma_f32_16x16x32_bf16 v[56:59], v[154:157], v[178:181], v[56:59]
	v_mfma_f32_16x16x32_bf16 v[52:55], v[146:149], v[186:189], v[52:55]
	v_mfma_f32_16x16x32_bf16 v[44:47], v[154:157], v[186:189], v[44:47]
	v_mfma_f32_16x16x32_bf16 v[36:39], v[146:149], v[214:217], v[36:39]
	v_mfma_f32_16x16x32_bf16 v[28:31], v[154:157], v[214:217], v[28:31]
	v_mfma_f32_16x16x32_bf16 v[20:23], v[146:149], v[222:225], v[20:23]
	v_mfma_f32_16x16x32_bf16 v[12:15], v[154:157], v[222:225], v[12:15]
	s_setprio 0
	s_setprio 1
	v_mfma_f32_16x16x32_bf16 v[48:51], v[158:161], v[174:177], 0
	v_mfma_f32_16x16x32_bf16 v[40:43], v[166:169], v[174:177], 0
	v_mfma_f32_16x16x32_bf16 v[32:35], v[158:161], v[182:185], 0
	v_mfma_f32_16x16x32_bf16 v[24:27], v[166:169], v[182:185], 0
	v_mfma_f32_16x16x32_bf16 v[16:19], v[158:161], v[210:213], 0
	v_mfma_f32_16x16x32_bf16 v[8:11], v[166:169], v[210:213], 0
	v_mfma_f32_16x16x32_bf16 v[4:7], v[158:161], v[218:221], 0
	v_mfma_f32_16x16x32_bf16 v[0:3], v[166:169], v[218:221], 0
	v_mfma_f32_16x16x32_bf16 v[48:51], v[162:165], v[178:181], v[48:51]
	v_mfma_f32_16x16x32_bf16 v[40:43], v[170:173], v[178:181], v[40:43]
	v_mfma_f32_16x16x32_bf16 v[32:35], v[162:165], v[186:189], v[32:35]
	v_mfma_f32_16x16x32_bf16 v[24:27], v[170:173], v[186:189], v[24:27]
	v_mfma_f32_16x16x32_bf16 v[16:19], v[162:165], v[214:217], v[16:19]
	v_mfma_f32_16x16x32_bf16 v[8:11], v[170:173], v[214:217], v[8:11]
	v_mfma_f32_16x16x32_bf16 v[4:7], v[162:165], v[222:225], v[4:7]
	v_mfma_f32_16x16x32_bf16 v[0:3], v[170:173], v[222:225], v[0:3]
	s_barrier
; #define PG8_STAGE(bufoff, gbase, voff) do { _Pragma("unroll") for (int _i = 0; _i < 2; ++_i) \
;         __builtin_amdgcn_global_load_lds((const unsigned*)((const char*)(gbase) + (voff)[_i]), (PG8_LAS unsigned*)(lds + (bufoff) + ldsw + _i * 8192), 16, 0, 0); } while (0)
; #define PG8_LDA(dst, b, h) do { _Pragma("unroll") for (int m = 0; m < 4; ++m) _Pragma("unroll") for (int k = 0; k < 2; ++k) dst[m][k] = *(const PG8_LAS bf16x8*)(lds + PG8_SA(b, h) + aoff + m * 2048 + k * 1024); } while (0)
; #define PG8_LDB(dst, b, h) do { _Pragma("unroll") for (int n = 0; n < 2; ++n) _Pragma("unroll") for (int k = 0; k < 2; ++k) dst[n][k] = *(const PG8_LAS bf16x8*)(lds + PG8_SB(b, h) + boff + n * 2048 + k * 1024); } while (0)
; #define PG8_MMA(ai, bj, At, Bt) do { __builtin_amdgcn_s_setprio(1); _Pragma("unroll") for (int m = 0; m < 4; ++m) _Pragma("unroll") for (int n = 0; n < 2; ++n) _Pragma("unroll") for (int k = 0; k < 2; ++k) \
;         acc[ai][bj][m][n] = __builtin_amdgcn_mfma_f32_16x16x32_bf16(Bt[n][k], At[m][k], acc[ai][bj][m][n], 0, 0, 0); __builtin_amdgcn_s_setprio(0); } while (0)
; #define PG8_WAIT_V(n) asm volatile("s_waitcnt vmcnt(" #n ")" ::: "memory")
; #define PG8_WAIT_L(n) asm volatile("s_waitcnt lgkmcnt(" #n ")" ::: "memory")
; #define PG8_BAR __builtin_amdgcn_s_barrier()
; #define PG8_SCHED __builtin_amdgcn_sched_barrier(0)
; template <class Epi>
; __device__ __forceinline__ void gemm_phase(PG8_LAS unsigned char* lds, PG8_LAS unsigned char* xl, const Gemm g, const Sched& S, const Epi& E, const int wid) {
;     ...
;             PG8_LDB(B0, 1, 0); PG8_LDB(B1, 1, 1); PG8_SCHED; PG8_LDA(At, 1, 0); PG8_STAGE(PG8_SA(0, 1), a2 + hstepA, voffA);
;             PG8_WAIT_V(8); PG8_WAIT_L(0); PG8_BAR; if (do0) { PG8_MMA(0, 0, At, B0); PG8_MMA(0, 1, At, B1); } PG8_BAR; PG8_SCHED;
;             PG8_LDA(At, 1, 1); PG8_STAGE(PG8_SB(1, 0), b3, voffB); PG8_STAGE(PG8_SB(1, 1), b3 + hstepB, voffB); PG8_STAGE(PG8_SA(1, 0), a3, voffA);
;             PG8_WAIT_V(8); PG8_WAIT_L(0); PG8_BAR; if (do1) { PG8_MMA(1, 0, At, B0); PG8_MMA(1, 1, At, B1); } PG8_BAR; PG8_SCHED;
;         }
	s_setprio 0
	s_add_i32 s11, 0, 0x18000
	s_add_i32 s21, 0, 0x1c000
	ds_read_b128 v[142:145], v228 offset:32768
	ds_read_b128 v[146:149], v228 offset:33792
	ds_read_b128 v[150:153], v228 offset:34816
	ds_read_b128 v[154:157], v228 offset:35840
	ds_read_b128 v[158:161], v228 offset:49152
	ds_read_b128 v[162:165], v228 offset:50176
	ds_read_b128 v[166:169], v228 offset:51200
	ds_read_b128 v[170:173], v228 offset:52224
	s_add_u32 s100, s40, 0x80000
	s_addc_u32 s101, s41, 0
	s_mov_b32 m0, s70
	ds_read_b128 v[174:177], v141 offset:32768
	ds_read_b128 v[178:181], v141 offset:33792
	ds_read_b128 v[182:185], v141 offset:34816
	ds_read_b128 v[186:189], v141 offset:35840
	ds_read_b128 v[210:213], v141 offset:36864
	ds_read_b128 v[214:217], v141 offset:37888
	ds_read_b128 v[218:221], v141 offset:38912
	ds_read_b128 v[222:225], v141 offset:39936
	global_load_lds_dwordx4 v134, s[100:101] sc0
	s_mov_b32 m0, s71
	s_nop 0
	global_load_lds_dwordx4 v130, s[100:101] sc0
	s_waitcnt vmcnt(8)
	s_waitcnt lgkmcnt(0)
	s_setprio 1
	s_barrier
	v_mfma_f32_16x16x32_bf16 v[124:127], v[142:145], v[174:177], v[124:127]
	v_mfma_f32_16x16x32_bf16 v[120:123], v[150:153], v[174:177], v[120:123]
	v_mfma_f32_16x16x32_bf16 v[116:119], v[142:145], v[182:185], v[116:119]
	v_mfma_f32_16x16x32_bf16 v[108:111], v[150:153], v[182:185], v[108:111]
	v_mfma_f32_16x16x32_bf16 v[100:103], v[142:145], v[210:213], v[100:103]
	v_mfma_f32_16x16x32_bf16 v[92:95], v[150:153], v[210:213], v[92:95]
	v_mfma_f32_16x16x32_bf16 v[84:87], v[142:145], v[218:221], v[84:87]
	v_mfma_f32_16x16x32_bf16 v[76:79], v[150:153], v[218:221], v[76:79]
	v_mfma_f32_16x16x32_bf16 v[124:127], v[146:149], v[178:181], v[124:127]
	v_mfma_f32_16x16x32_bf16 v[120:123], v[154:157], v[178:181], v[120:123]
	v_mfma_f32_16x16x32_bf16 v[116:119], v[146:149], v[186:189], v[116:119]
	v_mfma_f32_16x16x32_bf16 v[108:111], v[154:157], v[186:189], v[108:111]
	v_mfma_f32_16x16x32_bf16 v[100:103], v[146:149], v[214:217], v[100:103]
	v_mfma_f32_16x16x32_bf16 v[92:95], v[154:157], v[214:217], v[92:95]
	v_mfma_f32_16x16x32_bf16 v[84:87], v[146:149], v[222:225], v[84:87]
	v_mfma_f32_16x16x32_bf16 v[76:79], v[154:157], v[222:225], v[76:79]
	s_setprio 0
	s_setprio 1
	v_mfma_f32_16x16x32_bf16 v[112:115], v[158:161], v[174:177], v[112:115]
	v_mfma_f32_16x16x32_bf16 v[104:107], v[166:169], v[174:177], v[104:107]
	v_mfma_f32_16x16x32_bf16 v[96:99], v[158:161], v[182:185], v[96:99]
	v_mfma_f32_16x16x32_bf16 v[88:91], v[166:169], v[182:185], v[88:91]
	v_mfma_f32_16x16x32_bf16 v[80:83], v[158:161], v[210:213], v[80:83]
	v_mfma_f32_16x16x32_bf16 v[72:75], v[166:169], v[210:213], v[72:75]
	v_mfma_f32_16x16x32_bf16 v[68:71], v[158:161], v[218:221], v[68:71]
	v_mfma_f32_16x16x32_bf16 v[64:67], v[166:169], v[218:221], v[64:67]
	v_mfma_f32_16x16x32_bf16 v[112:115], v[162:165], v[178:181], v[112:115]
	v_mfma_f32_16x16x32_bf16 v[104:107], v[170:173], v[178:181], v[104:107]
	v_mfma_f32_16x16x32_bf16 v[96:99], v[162:165], v[186:189], v[96:99]
	v_mfma_f32_16x16x32_bf16 v[88:91], v[170:173], v[186:189], v[88:91]
	v_mfma_f32_16x16x32_bf16 v[80:83], v[162:165], v[214:217], v[80:83]
	v_mfma_f32_16x16x32_bf16 v[72:75], v[170:173], v[214:217], v[72:75]
	v_mfma_f32_16x16x32_bf16 v[68:71], v[162:165], v[222:225], v[68:71]
	v_mfma_f32_16x16x32_bf16 v[64:67], v[170:173], v[222:225], v[64:67]
	s_barrier
	s_setprio 0
	s_add_i32 s11, s11, s29
	s_mov_b32 m0, s11
	ds_read_b128 v[174:177], v141 offset:49152
	ds_read_b128 v[178:181], v141 offset:50176
	ds_read_b128 v[182:185], v141 offset:51200
	ds_read_b128 v[186:189], v141 offset:52224
	ds_read_b128 v[210:213], v141 offset:53248
	ds_read_b128 v[214:217], v141 offset:54272
	ds_read_b128 v[218:221], v141 offset:55296
	ds_read_b128 v[222:225], v141 offset:56320
	global_load_lds_dwordx4 v226, s[76:77] sc0
	s_add_i32 m0, s11, 0x2000
	s_add_u32 s100, s76, 0x100080
	global_load_lds_dwordx4 v190, s[76:77] sc0
	s_addc_u32 s101, s77, 0
	s_add_i32 s11, s21, s29
	s_mov_b32 m0, s11
	s_nop 0
	global_load_lds_dwordx4 v132, s[100:101] sc0
	s_add_i32 m0, s11, 0x2000
	s_nop 0
	global_load_lds_dwordx4 v128, s[100:101] sc0
	s_mov_b32 m0, s90
	s_nop 0
	global_load_lds_dwordx4 v227, s[40:41] sc0
	s_mov_b32 m0, s91
	s_nop 0
	global_load_lds_dwordx4 v191, s[40:41] sc0
	s_waitcnt vmcnt(8)
	s_waitcnt lgkmcnt(0)
	s_setprio 1
	s_barrier
	v_mfma_f32_16x16x32_bf16 v[60:63], v[142:145], v[174:177], v[60:63]
	v_mfma_f32_16x16x32_bf16 v[56:59], v[150:153], v[174:177], v[56:59]
	v_mfma_f32_16x16x32_bf16 v[52:55], v[142:145], v[182:185], v[52:55]
	v_mfma_f32_16x16x32_bf16 v[44:47], v[150:153], v[182:185], v[44:47]
	v_mfma_f32_16x16x32_bf16 v[36:39], v[142:145], v[210:213], v[36:39]
	v_mfma_f32_16x16x32_bf16 v[28:31], v[150:153], v[210:213], v[28:31]
	v_mfma_f32_16x16x32_bf16 v[20:23], v[142:145], v[218:221], v[20:23]
	v_mfma_f32_16x16x32_bf16 v[12:15], v[150:153], v[218:221], v[12:15]
	v_mfma_f32_16x16x32_bf16 v[60:63], v[146:149], v[178:181], v[60:63]
	v_mfma_f32_16x16x32_bf16 v[56:59], v[154:157], v[178:181], v[56:59]
	v_mfma_f32_16x16x32_bf16 v[52:55], v[146:149], v[186:189], v[52:55]
	v_mfma_f32_16x16x32_bf16 v[44:47], v[154:157], v[186:189], v[44:47]
	v_mfma_f32_16x16x32_bf16 v[36:39], v[146:149], v[214:217], v[36:39]
	v_mfma_f32_16x16x32_bf16 v[28:31], v[154:157], v[214:217], v[28:31]
	v_mfma_f32_16x16x32_bf16 v[20:23], v[146:149], v[222:225], v[20:23]
	v_mfma_f32_16x16x32_bf16 v[12:15], v[154:157], v[222:225], v[12:15]
	s_setprio 0
	s_setprio 1
	v_mfma_f32_16x16x32_bf16 v[48:51], v[158:161], v[174:177], v[48:51]
	v_mfma_f32_16x16x32_bf16 v[40:43], v[166:169], v[174:177], v[40:43]
	v_mfma_f32_16x16x32_bf16 v[32:35], v[158:161], v[182:185], v[32:35]
	v_mfma_f32_16x16x32_bf16 v[24:27], v[166:169], v[182:185], v[24:27]
	v_mfma_f32_16x16x32_bf16 v[16:19], v[158:161], v[210:213], v[16:19]
	v_mfma_f32_16x16x32_bf16 v[8:11], v[166:169], v[210:213], v[8:11]
	v_mfma_f32_16x16x32_bf16 v[4:7], v[158:161], v[218:221], v[4:7]
	v_mfma_f32_16x16x32_bf16 v[0:3], v[166:169], v[218:221], v[0:3]
	v_mfma_f32_16x16x32_bf16 v[48:51], v[162:165], v[178:181], v[48:51]
	v_mfma_f32_16x16x32_bf16 v[40:43], v[170:173], v[178:181], v[40:43]
	v_mfma_f32_16x16x32_bf16 v[32:35], v[162:165], v[186:189], v[32:35]
	v_mfma_f32_16x16x32_bf16 v[24:27], v[170:173], v[186:189], v[24:27]
	v_mfma_f32_16x16x32_bf16 v[16:19], v[162:165], v[214:217], v[16:19]
	v_mfma_f32_16x16x32_bf16 v[8:11], v[170:173], v[214:217], v[8:11]
	v_mfma_f32_16x16x32_bf16 v[4:7], v[162:165], v[222:225], v[4:7]
	v_mfma_f32_16x16x32_bf16 v[0:3], v[170:173], v[222:225], v[0:3]
	s_barrier
	s_setprio 0
	s_add_i32 s10, s10, 2
	s_add_u32 s8, s8, 0x100
	s_addc_u32 s9, s9, 0
	s_cmp_gt_u32 s10, 5
	s_mov_b64 s[58:59], s[60:61]
; #define PG8_STAGE(bufoff, gbase, voff) do { _Pragma("unroll") for (int _i = 0; _i < 2; ++_i) \
;         __builtin_amdgcn_global_load_lds((const unsigned*)((const char*)(gbase) + (voff)[_i]), (PG8_LAS unsigned*)(lds + (bufoff) + ldsw + _i * 8192), 16, 0, 0); } while (0)
; #define PG8_LDA(dst, b, h) do { _Pragma("unroll") for (int m = 0; m < 4; ++m) _Pragma("unroll") for (int k = 0; k < 2; ++k) dst[m][k] = *(const PG8_LAS bf16x8*)(lds + PG8_SA(b, h) + aoff + m * 2048 + k * 1024); } while (0)
; #define PG8_LDB(dst, b, h) do { _Pragma("unroll") for (int n = 0; n < 2; ++n) _Pragma("unroll") for (int k = 0; k < 2; ++k) dst[n][k] = *(const PG8_LAS bf16x8*)(lds + PG8_SB(b, h) + boff + n * 2048 + k * 1024); } while (0)
; #define PG8_MMA(ai, bj, At, Bt) do { __builtin_amdgcn_s_setprio(1); _Pragma("unroll") for (int m = 0; m < 4; ++m) _Pragma("unroll") for (int n = 0; n < 2; ++n) _Pragma("unroll") for (int k = 0; k < 2; ++k) \
;         acc[ai][bj][m][n] = __builtin_amdgcn_mfma_f32_16x16x32_bf16(Bt[n][k], At[m][k], acc[ai][bj][m][n], 0, 0, 0); __builtin_amdgcn_s_setprio(0); } while (0)
; #define PG8_WAIT_V(n) asm volatile("s_waitcnt vmcnt(" #n ")" ::: "memory")
; #define PG8_WAIT_L(n) asm volatile("s_waitcnt lgkmcnt(" #n ")" ::: "memory")
; #define PG8_BAR __builtin_amdgcn_s_barrier()
; #define PG8_SCHED __builtin_amdgcn_sched_barrier(0)
; template <class Epi>
; __device__ __forceinline__ void gemm_phase(PG8_LAS unsigned char* lds, PG8_LAS unsigned char* xl, const Gemm g, const Sched& S, const Epi& E, const int wid) {
;     ...
;             const char* a1 = cA + (size_t)(t + 1) * kstep + j1;
;             const char* a2 = last ? nA : cA + (size_t)(t + 2) * kstep + ja2; const char* b2 = last ? nB : cB + (size_t)(t + 2) * kstep + jb2;
;             const char* a3 = a2 + kstep; const char* b3 = b2 + kstep;
;             PG8_LDB(B0, 0, 0); PG8_LDB(B1, 0, 1); PG8_SCHED; PG8_LDA(At, 0, 0); PG8_STAGE(PG8_SA(1, 1), a1 + hstepA, voffA);
;             PG8_WAIT_V(8); PG8_WAIT_L(0); PG8_BAR; if (do0) { PG8_MMA(0, 0, At, B0); PG8_MMA(0, 1, At, B1); } PG8_BAR; PG8_SCHED;
;             PG8_LDA(At, 0, 1); PG8_STAGE(PG8_SB(0, 0), b2, voffB); PG8_STAGE(PG8_SB(0, 1), b2 + hstepB, voffB); PG8_STAGE(PG8_SA(0, 0), a2, voffA);
;             PG8_WAIT_V(8); PG8_WAIT_L(0); PG8_BAR; if (do1) { PG8_MMA(1, 0, At, B0); PG8_MMA(1, 1, At, B1); } PG8_BAR; PG8_SCHED;
.LBB0_428:
	s_add_u32 s60, s58, 0x100
	s_addc_u32 s61, s59, 0
	s_add_i32 s11, 0, 0x10000
	s_cmp_eq_u32 s10, 4
	s_cselect_b32 s41, s47, s61
	s_cselect_b32 s40, s46, s60
	s_cselect_b32 s77, s57, s9
	s_cselect_b32 s76, s56, s8
	s_add_i32 s21, 0, 0x14000
	ds_read_b128 v[142:145], v228 offset:0
	ds_read_b128 v[146:149], v228 offset:1024
	ds_read_b128 v[150:153], v228 offset:2048
	ds_read_b128 v[154:157], v228 offset:3072
	ds_read_b128 v[158:161], v228 offset:16384
	ds_read_b128 v[162:165], v228 offset:17408
	ds_read_b128 v[166:169], v228 offset:18432
	ds_read_b128 v[170:173], v228 offset:19456
	s_add_i32 m0, s13, 0xc000
	ds_read_b128 v[174:177], v141
	ds_read_b128 v[178:181], v141 offset:1024
	ds_read_b128 v[182:185], v141 offset:2048
	ds_read_b128 v[186:189], v141 offset:3072
	ds_read_b128 v[210:213], v141 offset:4096
	ds_read_b128 v[214:217], v141 offset:5120
	ds_read_b128 v[218:221], v141 offset:6144
	ds_read_b128 v[222:225], v141 offset:7168
	global_load_lds_dwordx4 v136, s[58:59] sc0
	s_add_i32 m0, s13, 0xe000
	s_nop 0
	global_load_lds_dwordx4 v138, s[58:59] sc0
	s_waitcnt vmcnt(8)
	s_waitcnt lgkmcnt(0)
	s_setprio 1
	s_barrier
	v_mfma_f32_16x16x32_bf16 v[124:127], v[142:145], v[174:177], v[124:127]
	v_mfma_f32_16x16x32_bf16 v[120:123], v[150:153], v[174:177], v[120:123]
	v_mfma_f32_16x16x32_bf16 v[116:119], v[142:145], v[182:185], v[116:119]
	v_mfma_f32_16x16x32_bf16 v[108:111], v[150:153], v[182:185], v[108:111]
	v_mfma_f32_16x16x32_bf16 v[100:103], v[142:145], v[210:213], v[100:103]
	v_mfma_f32_16x16x32_bf16 v[92:95], v[150:153], v[210:213], v[92:95]
	v_mfma_f32_16x16x32_bf16 v[84:87], v[142:145], v[218:221], v[84:87]
	v_mfma_f32_16x16x32_bf16 v[76:79], v[150:153], v[218:221], v[76:79]
	v_mfma_f32_16x16x32_bf16 v[124:127], v[146:149], v[178:181], v[124:127]
	v_mfma_f32_16x16x32_bf16 v[120:123], v[154:157], v[178:181], v[120:123]
	v_mfma_f32_16x16x32_bf16 v[116:119], v[146:149], v[186:189], v[116:119]
	v_mfma_f32_16x16x32_bf16 v[108:111], v[154:157], v[186:189], v[108:111]
	v_mfma_f32_16x16x32_bf16 v[100:103], v[146:149], v[214:217], v[100:103]
	v_mfma_f32_16x16x32_bf16 v[92:95], v[154:157], v[214:217], v[92:95]
	v_mfma_f32_16x16x32_bf16 v[84:87], v[146:149], v[222:225], v[84:87]
	v_mfma_f32_16x16x32_bf16 v[76:79], v[154:157], v[222:225], v[76:79]
	s_setprio 0
	s_setprio 1
	v_mfma_f32_16x16x32_bf16 v[112:115], v[158:161], v[174:177], v[112:115]
	v_mfma_f32_16x16x32_bf16 v[104:107], v[166:169], v[174:177], v[104:107]
	v_mfma_f32_16x16x32_bf16 v[96:99], v[158:161], v[182:185], v[96:99]
	v_mfma_f32_16x16x32_bf16 v[88:91], v[166:169], v[182:185], v[88:91]
	v_mfma_f32_16x16x32_bf16 v[80:83], v[158:161], v[210:213], v[80:83]
	v_mfma_f32_16x16x32_bf16 v[72:75], v[166:169], v[210:213], v[72:75]
	v_mfma_f32_16x16x32_bf16 v[68:71], v[158:161], v[218:221], v[68:71]
	v_mfma_f32_16x16x32_bf16 v[64:67], v[166:169], v[218:221], v[64:67]
	v_mfma_f32_16x16x32_bf16 v[112:115], v[162:165], v[178:181], v[112:115]
	v_mfma_f32_16x16x32_bf16 v[104:107], v[170:173], v[178:181], v[104:107]
	v_mfma_f32_16x16x32_bf16 v[96:99], v[162:165], v[186:189], v[96:99]
	v_mfma_f32_16x16x32_bf16 v[88:91], v[170:173], v[186:189], v[88:91]
	v_mfma_f32_16x16x32_bf16 v[80:83], v[162:165], v[214:217], v[80:83]
	v_mfma_f32_16x16x32_bf16 v[72:75], v[170:173], v[214:217], v[72:75]
	v_mfma_f32_16x16x32_bf16 v[68:71], v[162:165], v[222:225], v[68:71]
	v_mfma_f32_16x16x32_bf16 v[64:67], v[170:173], v[222:225], v[64:67]
	s_barrier
	s_setprio 0
	s_add_i32 s11, s11, s29
	s_mov_b32 m0, s11
	ds_read_b128 v[174:177], v141 offset:16384
	ds_read_b128 v[178:181], v141 offset:17408
	ds_read_b128 v[182:185], v141 offset:18432
	ds_read_b128 v[186:189], v141 offset:19456
	ds_read_b128 v[210:213], v141 offset:20480
	ds_read_b128 v[214:217], v141 offset:21504
	ds_read_b128 v[218:221], v141 offset:22528
	ds_read_b128 v[222:225], v141 offset:23552
	global_load_lds_dwordx4 v132, s[76:77] sc0
	s_add_i32 m0, s11, 0x2000
	s_add_u32 s54, s76, 0x100000
	s_addc_u32 s55, s77, 0
	s_add_i32 s11, s21, s29
	global_load_lds_dwordx4 v128, s[76:77] sc0
	s_mov_b32 m0, s11
	s_nop 0
	global_load_lds_dwordx4 v132, s[54:55] sc0
	s_add_i32 m0, s11, 0x2000
	s_nop 0
	global_load_lds_dwordx4 v128, s[54:55] sc0
	s_mov_b32 m0, s13
	s_nop 0
	global_load_lds_dwordx4 v134, s[40:41] sc0
	s_mov_b32 m0, s69
	s_nop 0
	global_load_lds_dwordx4 v130, s[40:41] sc0
	s_waitcnt vmcnt(8)
	s_waitcnt lgkmcnt(0)
	s_setprio 1
	s_barrier
	v_mfma_f32_16x16x32_bf16 v[60:63], v[142:145], v[174:177], v[60:63]
	v_mfma_f32_16x16x32_bf16 v[56:59], v[150:153], v[174:177], v[56:59]
	v_mfma_f32_16x16x32_bf16 v[52:55], v[142:145], v[182:185], v[52:55]
	v_mfma_f32_16x16x32_bf16 v[44:47], v[150:153], v[182:185], v[44:47]
	v_mfma_f32_16x16x32_bf16 v[36:39], v[142:145], v[210:213], v[36:39]
	v_mfma_f32_16x16x32_bf16 v[28:31], v[150:153], v[210:213], v[28:31]
	v_mfma_f32_16x16x32_bf16 v[20:23], v[142:145], v[218:221], v[20:23]
	v_mfma_f32_16x16x32_bf16 v[12:15], v[150:153], v[218:221], v[12:15]
	v_mfma_f32_16x16x32_bf16 v[60:63], v[146:149], v[178:181], v[60:63]
	v_mfma_f32_16x16x32_bf16 v[56:59], v[154:157], v[178:181], v[56:59]
	v_mfma_f32_16x16x32_bf16 v[52:55], v[146:149], v[186:189], v[52:55]
	v_mfma_f32_16x16x32_bf16 v[44:47], v[154:157], v[186:189], v[44:47]
	v_mfma_f32_16x16x32_bf16 v[36:39], v[146:149], v[214:217], v[36:39]
	v_mfma_f32_16x16x32_bf16 v[28:31], v[154:157], v[214:217], v[28:31]
	v_mfma_f32_16x16x32_bf16 v[20:23], v[146:149], v[222:225], v[20:23]
	v_mfma_f32_16x16x32_bf16 v[12:15], v[154:157], v[222:225], v[12:15]
	s_setprio 0
	s_setprio 1
	v_mfma_f32_16x16x32_bf16 v[48:51], v[158:161], v[174:177], v[48:51]
	v_mfma_f32_16x16x32_bf16 v[40:43], v[166:169], v[174:177], v[40:43]
	v_mfma_f32_16x16x32_bf16 v[32:35], v[158:161], v[182:185], v[32:35]
	v_mfma_f32_16x16x32_bf16 v[24:27], v[166:169], v[182:185], v[24:27]
	v_mfma_f32_16x16x32_bf16 v[16:19], v[158:161], v[210:213], v[16:19]
	v_mfma_f32_16x16x32_bf16 v[8:11], v[166:169], v[210:213], v[8:11]
	v_mfma_f32_16x16x32_bf16 v[4:7], v[158:161], v[218:221], v[4:7]
	v_mfma_f32_16x16x32_bf16 v[0:3], v[166:169], v[218:221], v[0:3]
	v_mfma_f32_16x16x32_bf16 v[48:51], v[162:165], v[178:181], v[48:51]
	v_mfma_f32_16x16x32_bf16 v[40:43], v[170:173], v[178:181], v[40:43]
	v_mfma_f32_16x16x32_bf16 v[32:35], v[162:165], v[186:189], v[32:35]
	v_mfma_f32_16x16x32_bf16 v[24:27], v[170:173], v[186:189], v[24:27]
	v_mfma_f32_16x16x32_bf16 v[16:19], v[162:165], v[214:217], v[16:19]
	v_mfma_f32_16x16x32_bf16 v[8:11], v[170:173], v[214:217], v[8:11]
	v_mfma_f32_16x16x32_bf16 v[4:7], v[162:165], v[222:225], v[4:7]
	v_mfma_f32_16x16x32_bf16 v[0:3], v[170:173], v[222:225], v[0:3]
	s_barrier
; #define PG8_STAGE(bufoff, gbase, voff) do { _Pragma("unroll") for (int _i = 0; _i < 2; ++_i) \
;         __builtin_amdgcn_global_load_lds((const unsigned*)((const char*)(gbase) + (voff)[_i]), (PG8_LAS unsigned*)(lds + (bufoff) + ldsw + _i * 8192), 16, 0, 0); } while (0)
; #define PG8_LDA(dst, b, h) do { _Pragma("unroll") for (int m = 0; m < 4; ++m) _Pragma("unroll") for (int k = 0; k < 2; ++k) dst[m][k] = *(const PG8_LAS bf16x8*)(lds + PG8_SA(b, h) + aoff + m * 2048 + k * 1024); } while (0)
; #define PG8_LDB(dst, b, h) do { _Pragma("unroll") for (int n = 0; n < 2; ++n) _Pragma("unroll") for (int k = 0; k < 2; ++k) dst[n][k] = *(const PG8_LAS bf16x8*)(lds + PG8_SB(b, h) + boff + n * 2048 + k * 1024); } while (0)
; #define PG8_MMA(ai, bj, At, Bt) do { __builtin_amdgcn_s_setprio(1); _Pragma("unroll") for (int m = 0; m < 4; ++m) _Pragma("unroll") for (int n = 0; n < 2; ++n) _Pragma("unroll") for (int k = 0; k < 2; ++k) \
;         acc[ai][bj][m][n] = __builtin_amdgcn_mfma_f32_16x16x32_bf16(Bt[n][k], At[m][k], acc[ai][bj][m][n], 0, 0, 0); __builtin_amdgcn_s_setprio(0); } while (0)
; #define PG8_WAIT_V(n) asm volatile("s_waitcnt vmcnt(" #n ")" ::: "memory")
; #define PG8_WAIT_L(n) asm volatile("s_waitcnt lgkmcnt(" #n ")" ::: "memory")
; #define PG8_BAR __builtin_amdgcn_s_barrier()
; #define PG8_SCHED __builtin_amdgcn_sched_barrier(0)
; template <class Epi>
; __device__ __forceinline__ void gemm_phase(PG8_LAS unsigned char* lds, PG8_LAS unsigned char* xl, const Gemm g, const Sched& S, const Epi& E, const int wid) {
;     ...
;             PG8_LDB(B0, 1, 0); PG8_LDB(B1, 1, 1); PG8_SCHED; PG8_LDA(At, 1, 0); PG8_STAGE(PG8_SA(0, 1), a2 + hstepA, voffA);
;             PG8_WAIT_V(8); PG8_WAIT_L(0); PG8_BAR; if (do0) { PG8_MMA(0, 0, At, B0); PG8_MMA(0, 1, At, B1); } PG8_BAR; PG8_SCHED;
;             PG8_LDA(At, 1, 1); PG8_STAGE(PG8_SB(1, 0), b3, voffB); PG8_STAGE(PG8_SB(1, 1), b3 + hstepB, voffB); PG8_STAGE(PG8_SA(1, 0), a3, voffA);
;             PG8_WAIT_V(8); PG8_WAIT_L(0); PG8_BAR; if (do1) { PG8_MMA(1, 0, At, B0); PG8_MMA(1, 1, At, B1); } PG8_BAR; PG8_SCHED;
;         }
;         if (wr == 0) PG8_BAR;
	s_setprio 0
	s_add_i32 s11, 0, 0x18000
	s_add_i32 s21, 0, 0x1c000
	ds_read_b128 v[142:145], v228 offset:32768
	ds_read_b128 v[146:149], v228 offset:33792
	ds_read_b128 v[150:153], v228 offset:34816
	ds_read_b128 v[154:157], v228 offset:35840
	ds_read_b128 v[158:161], v228 offset:49152
	ds_read_b128 v[162:165], v228 offset:50176
	ds_read_b128 v[166:169], v228 offset:51200
	ds_read_b128 v[170:173], v228 offset:52224
	s_add_u32 s100, s40, 0x80000
	s_addc_u32 s101, s41, 0
	s_mov_b32 m0, s70
	ds_read_b128 v[174:177], v141 offset:32768
	ds_read_b128 v[178:181], v141 offset:33792
	ds_read_b128 v[182:185], v141 offset:34816
	ds_read_b128 v[186:189], v141 offset:35840
	ds_read_b128 v[210:213], v141 offset:36864
	ds_read_b128 v[214:217], v141 offset:37888
	ds_read_b128 v[218:221], v141 offset:38912
	ds_read_b128 v[222:225], v141 offset:39936
	global_load_lds_dwordx4 v134, s[100:101] sc0
	s_mov_b32 m0, s71
	s_nop 0
	global_load_lds_dwordx4 v130, s[100:101] sc0
	s_waitcnt vmcnt(8)
	s_waitcnt lgkmcnt(0)
	s_setprio 1
	s_barrier
	v_mfma_f32_16x16x32_bf16 v[124:127], v[142:145], v[174:177], v[124:127]
	v_mfma_f32_16x16x32_bf16 v[120:123], v[150:153], v[174:177], v[120:123]
	v_mfma_f32_16x16x32_bf16 v[116:119], v[142:145], v[182:185], v[116:119]
	v_mfma_f32_16x16x32_bf16 v[108:111], v[150:153], v[182:185], v[108:111]
	v_mfma_f32_16x16x32_bf16 v[100:103], v[142:145], v[210:213], v[100:103]
	v_mfma_f32_16x16x32_bf16 v[92:95], v[150:153], v[210:213], v[92:95]
	v_mfma_f32_16x16x32_bf16 v[84:87], v[142:145], v[218:221], v[84:87]
	v_mfma_f32_16x16x32_bf16 v[76:79], v[150:153], v[218:221], v[76:79]
	v_mfma_f32_16x16x32_bf16 v[124:127], v[146:149], v[178:181], v[124:127]
	v_mfma_f32_16x16x32_bf16 v[120:123], v[154:157], v[178:181], v[120:123]
	v_mfma_f32_16x16x32_bf16 v[116:119], v[146:149], v[186:189], v[116:119]
	v_mfma_f32_16x16x32_bf16 v[108:111], v[154:157], v[186:189], v[108:111]
	v_mfma_f32_16x16x32_bf16 v[100:103], v[146:149], v[214:217], v[100:103]
	v_mfma_f32_16x16x32_bf16 v[92:95], v[154:157], v[214:217], v[92:95]
	v_mfma_f32_16x16x32_bf16 v[84:87], v[146:149], v[222:225], v[84:87]
	v_mfma_f32_16x16x32_bf16 v[76:79], v[154:157], v[222:225], v[76:79]
	s_setprio 0
	s_setprio 1
	v_mfma_f32_16x16x32_bf16 v[112:115], v[158:161], v[174:177], v[112:115]
	v_mfma_f32_16x16x32_bf16 v[104:107], v[166:169], v[174:177], v[104:107]
	v_mfma_f32_16x16x32_bf16 v[96:99], v[158:161], v[182:185], v[96:99]
	v_mfma_f32_16x16x32_bf16 v[88:91], v[166:169], v[182:185], v[88:91]
	v_mfma_f32_16x16x32_bf16 v[80:83], v[158:161], v[210:213], v[80:83]
	v_mfma_f32_16x16x32_bf16 v[72:75], v[166:169], v[210:213], v[72:75]
	v_mfma_f32_16x16x32_bf16 v[68:71], v[158:161], v[218:221], v[68:71]
	v_mfma_f32_16x16x32_bf16 v[64:67], v[166:169], v[218:221], v[64:67]
	v_mfma_f32_16x16x32_bf16 v[112:115], v[162:165], v[178:181], v[112:115]
	v_mfma_f32_16x16x32_bf16 v[104:107], v[170:173], v[178:181], v[104:107]
	v_mfma_f32_16x16x32_bf16 v[96:99], v[162:165], v[186:189], v[96:99]
	v_mfma_f32_16x16x32_bf16 v[88:91], v[170:173], v[186:189], v[88:91]
	v_mfma_f32_16x16x32_bf16 v[80:83], v[162:165], v[214:217], v[80:83]
	v_mfma_f32_16x16x32_bf16 v[72:75], v[170:173], v[214:217], v[72:75]
	v_mfma_f32_16x16x32_bf16 v[68:71], v[162:165], v[222:225], v[68:71]
	v_mfma_f32_16x16x32_bf16 v[64:67], v[170:173], v[222:225], v[64:67]
	s_barrier
	s_setprio 0
	s_add_i32 s11, s11, s29
	s_mov_b32 m0, s11
	ds_read_b128 v[174:177], v141 offset:49152
	ds_read_b128 v[178:181], v141 offset:50176
	ds_read_b128 v[182:185], v141 offset:51200
	ds_read_b128 v[186:189], v141 offset:52224
	ds_read_b128 v[210:213], v141 offset:53248
	ds_read_b128 v[214:217], v141 offset:54272
	ds_read_b128 v[218:221], v141 offset:55296
	ds_read_b128 v[222:225], v141 offset:56320
	global_load_lds_dwordx4 v226, s[76:77] sc0
	s_add_i32 m0, s11, 0x2000
	s_add_u32 s100, s76, 0x100080
	global_load_lds_dwordx4 v190, s[76:77] sc0
	s_addc_u32 s101, s77, 0
	s_add_i32 s11, s21, s29
	s_mov_b32 m0, s11
	s_nop 0
	global_load_lds_dwordx4 v132, s[100:101] sc0
	s_add_i32 m0, s11, 0x2000
	s_nop 0
	global_load_lds_dwordx4 v128, s[100:101] sc0
	s_mov_b32 m0, s90
	s_nop 0
	global_load_lds_dwordx4 v227, s[40:41] sc0
	s_mov_b32 m0, s91
	s_nop 0
	global_load_lds_dwordx4 v191, s[40:41] sc0
	s_waitcnt vmcnt(8)
	s_waitcnt lgkmcnt(0)
	s_setprio 1
	s_barrier
	v_mfma_f32_16x16x32_bf16 v[60:63], v[142:145], v[174:177], v[60:63]
	v_mfma_f32_16x16x32_bf16 v[56:59], v[150:153], v[174:177], v[56:59]
	v_mfma_f32_16x16x32_bf16 v[52:55], v[142:145], v[182:185], v[52:55]
	v_mfma_f32_16x16x32_bf16 v[44:47], v[150:153], v[182:185], v[44:47]
	v_mfma_f32_16x16x32_bf16 v[36:39], v[142:145], v[210:213], v[36:39]
	v_mfma_f32_16x16x32_bf16 v[28:31], v[150:153], v[210:213], v[28:31]
	v_mfma_f32_16x16x32_bf16 v[20:23], v[142:145], v[218:221], v[20:23]
	v_mfma_f32_16x16x32_bf16 v[12:15], v[150:153], v[218:221], v[12:15]
	v_mfma_f32_16x16x32_bf16 v[60:63], v[146:149], v[178:181], v[60:63]
	v_mfma_f32_16x16x32_bf16 v[56:59], v[154:157], v[178:181], v[56:59]
	v_mfma_f32_16x16x32_bf16 v[52:55], v[146:149], v[186:189], v[52:55]
	v_mfma_f32_16x16x32_bf16 v[44:47], v[154:157], v[186:189], v[44:47]
	v_mfma_f32_16x16x32_bf16 v[36:39], v[146:149], v[214:217], v[36:39]
	v_mfma_f32_16x16x32_bf16 v[28:31], v[154:157], v[214:217], v[28:31]
	v_mfma_f32_16x16x32_bf16 v[20:23], v[146:149], v[222:225], v[20:23]
	v_mfma_f32_16x16x32_bf16 v[12:15], v[154:157], v[222:225], v[12:15]
	s_setprio 0
	s_setprio 1
	v_mfma_f32_16x16x32_bf16 v[48:51], v[158:161], v[174:177], v[48:51]
	v_mfma_f32_16x16x32_bf16 v[40:43], v[166:169], v[174:177], v[40:43]
	v_mfma_f32_16x16x32_bf16 v[32:35], v[158:161], v[182:185], v[32:35]
	v_mfma_f32_16x16x32_bf16 v[24:27], v[166:169], v[182:185], v[24:27]
	v_mfma_f32_16x16x32_bf16 v[16:19], v[158:161], v[210:213], v[16:19]
	v_mfma_f32_16x16x32_bf16 v[8:11], v[166:169], v[210:213], v[8:11]
	v_mfma_f32_16x16x32_bf16 v[4:7], v[158:161], v[218:221], v[4:7]
	v_mfma_f32_16x16x32_bf16 v[0:3], v[166:169], v[218:221], v[0:3]
	v_mfma_f32_16x16x32_bf16 v[48:51], v[162:165], v[178:181], v[48:51]
	v_mfma_f32_16x16x32_bf16 v[40:43], v[170:173], v[178:181], v[40:43]
	v_mfma_f32_16x16x32_bf16 v[32:35], v[162:165], v[186:189], v[32:35]
	v_mfma_f32_16x16x32_bf16 v[24:27], v[170:173], v[186:189], v[24:27]
	v_mfma_f32_16x16x32_bf16 v[16:19], v[162:165], v[214:217], v[16:19]
	v_mfma_f32_16x16x32_bf16 v[8:11], v[170:173], v[214:217], v[8:11]
	v_mfma_f32_16x16x32_bf16 v[4:7], v[162:165], v[222:225], v[4:7]
	v_mfma_f32_16x16x32_bf16 v[0:3], v[170:173], v[222:225], v[0:3]
	s_barrier
	s_setprio 0
	s_add_i32 s10, s10, 2
	s_add_u32 s8, s8, 0x100
	s_addc_u32 s9, s9, 0
	s_cmp_gt_u32 s10, 5
	s_mov_b64 s[58:59], s[60:61]
	s_cbranch_scc0 .LBB0_428
	s_mov_b32 s100, 0
	s_and_b64 vcc, exec, s[14:15]
	s_cbranch_vccz .LBB0_431
	s_barrier

; #define PG8_STAGE(bufoff, gbase, voff) do { _Pragma("unroll") for (int _i = 0; _i < 2; ++_i) \
;         __builtin_amdgcn_global_load_lds((const unsigned*)((const char*)(gbase) + (voff)[_i]), (PG8_LAS unsigned*)(lds + (bufoff) + ldsw + _i * 8192), 16, 0, 0); } while (0)
; #define PG8_LDA(dst, b, h) do { _Pragma("unroll") for (int m = 0; m < 4; ++m) _Pragma("unroll") for (int k = 0; k < 2; ++k) dst[m][k] = *(const PG8_LAS bf16x8*)(lds + PG8_SA(b, h) + aoff + m * 2048 + k * 1024); } while (0)
; #define PG8_LDB(dst, b, h) do { _Pragma("unroll") for (int n = 0; n < 2; ++n) _Pragma("unroll") for (int k = 0; k < 2; ++k) dst[n][k] = *(const PG8_LAS bf16x8*)(lds + PG8_SB(b, h) + boff + n * 2048 + k * 1024); } while (0)
; #define PG8_MMA(ai, bj, At, Bt) do { __builtin_amdgcn_s_setprio(1); _Pragma("unroll") for (int m = 0; m < 4; ++m) _Pragma("unroll") for (int n = 0; n < 2; ++n) _Pragma("unroll") for (int k = 0; k < 2; ++k) \
;         acc[ai][bj][m][n] = __builtin_amdgcn_mfma_f32_16x16x32_bf16(Bt[n][k], At[m][k], acc[ai][bj][m][n], 0, 0, 0); __builtin_amdgcn_s_setprio(0); } while (0)
; #define PG8_WAIT_V(n) asm volatile("s_waitcnt vmcnt(" #n ")" ::: "memory")
; #define PG8_WAIT_L(n) asm volatile("s_waitcnt lgkmcnt(" #n ")" ::: "memory")
; #define PG8_BAR __builtin_amdgcn_s_barrier()
; #define PG8_SCHED __builtin_amdgcn_sched_barrier(0)
; template <class Epi>
; __device__ __forceinline__ void gemm_phase(PG8_LAS unsigned char* lds, PG8_LAS unsigned char* xl, const Gemm g, const Sched& S, const Epi& E, const int wid) {
;     ...
;             const char* a1 = cA + (size_t)(t + 1) * kstep + j1;
;             const char* a2 = last ? nA : cA + (size_t)(t + 2) * kstep + ja2; const char* b2 = last ? nB : cB + (size_t)(t + 2) * kstep + jb2;
;             const char* a3 = a2 + kstep; const char* b3 = b2 + kstep;
;             PG8_LDB(B0, 0, 0); PG8_LDB(B1, 0, 1); PG8_SCHED; PG8_LDA(At, 0, 0); PG8_STAGE(PG8_SA(1, 1), a1 + hstepA, voffA);
;             PG8_WAIT_V(8); PG8_WAIT_L(0); PG8_BAR; if (do0) { PG8_MMA(0, 0, At, B0); PG8_MMA(0, 1, At, B1); } PG8_BAR; PG8_SCHED;
;             PG8_LDA(At, 0, 1); PG8_STAGE(PG8_SB(0, 0), b2, voffB); PG8_STAGE(PG8_SB(0, 1), b2 + hstepB, voffB); PG8_STAGE(PG8_SA(0, 0), a2, voffA);
;             PG8_WAIT_V(8); PG8_WAIT_L(0); PG8_BAR; if (do1) { PG8_MMA(1, 0, At, B0); PG8_MMA(1, 1, At, B1); } PG8_BAR; PG8_SCHED;
.Ldefbar_skip_4:
	v_add_u32_e32 v157, s22, v140
	v_add_u32_e32 v204, s22, v142
	v_add_u32_e32 v205, s22, v144
	v_add_u32_e32 v234, s22, v146
	v_add_u32_e32 v235, 0x10000, v158
	s_add_u32 s20, s12, 0x100
	s_addc_u32 s21, s13, 0
	s_add_i32 s54, 0, 0x10000
	s_cmp_eq_u32 s66, 28
	s_cselect_b32 s53, s8, s21
	s_cselect_b32 s52, s9, s20
	s_cselect_b32 s51, s10, s62
	s_cselect_b32 s50, s11, s59
	s_add_i32 s55, 0, 0x14000
	ds_read_b128 v[22:25], v235 offset:0
	ds_read_b128 v[26:29], v235 offset:1024
	ds_read_b128 v[160:163], v235 offset:2048
	ds_read_b128 v[164:167], v235 offset:3072
	ds_read_b128 v[168:171], v235 offset:16384
	ds_read_b128 v[172:175], v235 offset:17408
	ds_read_b128 v[176:179], v235 offset:18432
	ds_read_b128 v[180:183], v235 offset:19456
	s_add_i32 m0, s45, 0xc000
	ds_read_b128 v[184:187], v159
	ds_read_b128 v[188:191], v159 offset:1024
	ds_read_b128 v[210:213], v159 offset:2048
	ds_read_b128 v[214:217], v159 offset:3072
	ds_read_b128 v[218:221], v159 offset:4096
	ds_read_b128 v[222:225], v159 offset:5120
	ds_read_b128 v[226:229], v159 offset:6144
	ds_read_b128 v[230:233], v159 offset:7168
	global_load_lds_dwordx4 v148, s[12:13] sc0
	s_add_i32 m0, s45, 0xe000
	s_nop 0
	global_load_lds_dwordx4 v150, s[12:13] sc0
	s_waitcnt vmcnt(8)
	s_waitcnt lgkmcnt(0)
	s_setprio 1
	s_barrier
	v_mfma_f32_16x16x32_bf16 v[136:139], v[22:25], v[184:187], 0
	v_mfma_f32_16x16x32_bf16 v[132:135], v[160:163], v[184:187], 0
	v_mfma_f32_16x16x32_bf16 v[120:123], v[22:25], v[210:213], 0
	v_mfma_f32_16x16x32_bf16 v[116:119], v[160:163], v[210:213], 0
	v_mfma_f32_16x16x32_bf16 v[104:107], v[22:25], v[218:221], 0
	v_mfma_f32_16x16x32_bf16 v[100:103], v[160:163], v[218:221], 0
	v_mfma_f32_16x16x32_bf16 v[86:89], v[22:25], v[226:229], 0
	v_mfma_f32_16x16x32_bf16 v[82:85], v[160:163], v[226:229], 0
	v_mfma_f32_16x16x32_bf16 v[136:139], v[26:29], v[188:191], v[136:139]
	v_mfma_f32_16x16x32_bf16 v[132:135], v[164:167], v[188:191], v[132:135]
	v_mfma_f32_16x16x32_bf16 v[120:123], v[26:29], v[214:217], v[120:123]
	v_mfma_f32_16x16x32_bf16 v[116:119], v[164:167], v[214:217], v[116:119]
	v_mfma_f32_16x16x32_bf16 v[104:107], v[26:29], v[222:225], v[104:107]
	v_mfma_f32_16x16x32_bf16 v[100:103], v[164:167], v[222:225], v[100:103]
	v_mfma_f32_16x16x32_bf16 v[86:89], v[26:29], v[230:233], v[86:89]
	v_mfma_f32_16x16x32_bf16 v[82:85], v[164:167], v[230:233], v[82:85]
	s_setprio 0
	s_setprio 1
	v_mfma_f32_16x16x32_bf16 v[128:131], v[168:171], v[184:187], 0
	v_mfma_f32_16x16x32_bf16 v[124:127], v[176:179], v[184:187], 0
	v_mfma_f32_16x16x32_bf16 v[112:115], v[168:171], v[210:213], 0
	v_mfma_f32_16x16x32_bf16 v[108:111], v[176:179], v[210:213], 0
	v_mfma_f32_16x16x32_bf16 v[96:99], v[168:171], v[218:221], 0
	v_mfma_f32_16x16x32_bf16 v[92:95], v[176:179], v[218:221], 0
	v_mfma_f32_16x16x32_bf16 v[78:81], v[168:171], v[226:229], 0
	v_mfma_f32_16x16x32_bf16 v[74:77], v[176:179], v[226:229], 0
	v_mfma_f32_16x16x32_bf16 v[128:131], v[172:175], v[188:191], v[128:131]
	v_mfma_f32_16x16x32_bf16 v[124:127], v[180:183], v[188:191], v[124:127]
	v_mfma_f32_16x16x32_bf16 v[112:115], v[172:175], v[214:217], v[112:115]
	v_mfma_f32_16x16x32_bf16 v[108:111], v[180:183], v[214:217], v[108:111]
	v_mfma_f32_16x16x32_bf16 v[96:99], v[172:175], v[222:225], v[96:99]
	v_mfma_f32_16x16x32_bf16 v[92:95], v[180:183], v[222:225], v[92:95]
	v_mfma_f32_16x16x32_bf16 v[78:81], v[172:175], v[230:233], v[78:81]
	v_mfma_f32_16x16x32_bf16 v[74:77], v[180:183], v[230:233], v[74:77]
	s_barrier
	s_setprio 0
	s_add_i32 s12, s54, s29
	s_mov_b32 m0, s12
	ds_read_b128 v[184:187], v159 offset:16384
	ds_read_b128 v[188:191], v159 offset:17408
	ds_read_b128 v[210:213], v159 offset:18432
	ds_read_b128 v[214:217], v159 offset:19456
	ds_read_b128 v[218:221], v159 offset:20480
	ds_read_b128 v[222:225], v159 offset:21504
	ds_read_b128 v[226:229], v159 offset:22528
	ds_read_b128 v[230:233], v159 offset:23552
	global_load_lds_dwordx4 v142, s[50:51] sc0
	s_add_i32 m0, s12, 0x2000
	s_add_u32 s12, s50, 0x80000
	s_addc_u32 s13, s51, 0
	s_add_i32 s54, s55, s29
	global_load_lds_dwordx4 v146, s[50:51] sc0
	s_mov_b32 m0, s54
	s_nop 0
	global_load_lds_dwordx4 v142, s[12:13] sc0
	s_add_i32 m0, s54, 0x2000
	s_nop 0
	global_load_lds_dwordx4 v146, s[12:13] sc0
	s_mov_b32 m0, s45
	s_nop 0
	global_load_lds_dwordx4 v140, s[52:53] sc0
	s_mov_b32 m0, s41
	s_nop 0
	global_load_lds_dwordx4 v144, s[52:53] sc0
	s_waitcnt vmcnt(8)
	s_waitcnt lgkmcnt(0)
	s_setprio 1
	s_barrier
	v_mfma_f32_16x16x32_bf16 v[70:73], v[22:25], v[184:187], 0
	v_mfma_f32_16x16x32_bf16 v[66:69], v[160:163], v[184:187], 0
	v_mfma_f32_16x16x32_bf16 v[54:57], v[22:25], v[210:213], 0
	v_mfma_f32_16x16x32_bf16 v[50:53], v[160:163], v[210:213], 0
	v_mfma_f32_16x16x32_bf16 v[38:41], v[22:25], v[218:221], 0
	v_mfma_f32_16x16x32_bf16 v[34:37], v[160:163], v[218:221], 0
	v_mfma_f32_16x16x32_bf16 v[12:15], v[22:25], v[226:229], 0
	v_mfma_f32_16x16x32_bf16 v[8:11], v[160:163], v[226:229], 0
	v_mfma_f32_16x16x32_bf16 v[70:73], v[26:29], v[188:191], v[70:73]
	v_mfma_f32_16x16x32_bf16 v[66:69], v[164:167], v[188:191], v[66:69]
	v_mfma_f32_16x16x32_bf16 v[54:57], v[26:29], v[214:217], v[54:57]
	v_mfma_f32_16x16x32_bf16 v[50:53], v[164:167], v[214:217], v[50:53]
	v_mfma_f32_16x16x32_bf16 v[38:41], v[26:29], v[222:225], v[38:41]
	v_mfma_f32_16x16x32_bf16 v[34:37], v[164:167], v[222:225], v[34:37]
	v_mfma_f32_16x16x32_bf16 v[12:15], v[26:29], v[230:233], v[12:15]
	v_mfma_f32_16x16x32_bf16 v[8:11], v[164:167], v[230:233], v[8:11]
	s_setprio 0
	s_setprio 1
	v_mfma_f32_16x16x32_bf16 v[46:49], v[168:171], v[210:213], 0
	v_mfma_f32_16x16x32_bf16 v[42:45], v[176:179], v[210:213], 0
	v_mfma_f32_16x16x32_bf16 v[30:33], v[168:171], v[218:221], 0
	v_mfma_f32_16x16x32_bf16 v[18:21], v[176:179], v[218:221], 0
	v_mfma_f32_16x16x32_bf16 v[4:7], v[168:171], v[226:229], 0
	v_mfma_f32_16x16x32_bf16 v[0:3], v[176:179], v[226:229], 0
	v_mfma_f32_16x16x32_bf16 v[22:25], v[168:171], v[184:187], 0
	v_mfma_f32_16x16x32_bf16 v[26:29], v[176:179], v[184:187], 0
	v_mfma_f32_16x16x32_bf16 v[46:49], v[172:175], v[214:217], v[46:49]
	v_mfma_f32_16x16x32_bf16 v[42:45], v[180:183], v[214:217], v[42:45]
	v_mfma_f32_16x16x32_bf16 v[30:33], v[172:175], v[222:225], v[30:33]
	v_mfma_f32_16x16x32_bf16 v[18:21], v[180:183], v[222:225], v[18:21]
	v_mfma_f32_16x16x32_bf16 v[4:7], v[172:175], v[230:233], v[4:7]
	v_mfma_f32_16x16x32_bf16 v[0:3], v[180:183], v[230:233], v[0:3]
	v_mfma_f32_16x16x32_bf16 v[22:25], v[172:175], v[188:191], v[22:25]
	v_mfma_f32_16x16x32_bf16 v[26:29], v[180:183], v[188:191], v[26:29]
	s_barrier
; #define PG8_STAGE(bufoff, gbase, voff) do { _Pragma("unroll") for (int _i = 0; _i < 2; ++_i) \
;         __builtin_amdgcn_global_load_lds((const unsigned*)((const char*)(gbase) + (voff)[_i]), (PG8_LAS unsigned*)(lds + (bufoff) + ldsw + _i * 8192), 16, 0, 0); } while (0)
; #define PG8_LDA(dst, b, h) do { _Pragma("unroll") for (int m = 0; m < 4; ++m) _Pragma("unroll") for (int k = 0; k < 2; ++k) dst[m][k] = *(const PG8_LAS bf16x8*)(lds + PG8_SA(b, h) + aoff + m * 2048 + k * 1024); } while (0)
; #define PG8_LDB(dst, b, h) do { _Pragma("unroll") for (int n = 0; n < 2; ++n) _Pragma("unroll") for (int k = 0; k < 2; ++k) dst[n][k] = *(const PG8_LAS bf16x8*)(lds + PG8_SB(b, h) + boff + n * 2048 + k * 1024); } while (0)
; #define PG8_MMA(ai, bj, At, Bt) do { __builtin_amdgcn_s_setprio(1); _Pragma("unroll") for (int m = 0; m < 4; ++m) _Pragma("unroll") for (int n = 0; n < 2; ++n) _Pragma("unroll") for (int k = 0; k < 2; ++k) \
;         acc[ai][bj][m][n] = __builtin_amdgcn_mfma_f32_16x16x32_bf16(Bt[n][k], At[m][k], acc[ai][bj][m][n], 0, 0, 0); __builtin_amdgcn_s_setprio(0); } while (0)
; #define PG8_WAIT_V(n) asm volatile("s_waitcnt vmcnt(" #n ")" ::: "memory")
; #define PG8_WAIT_L(n) asm volatile("s_waitcnt lgkmcnt(" #n ")" ::: "memory")
; #define PG8_BAR __builtin_amdgcn_s_barrier()
; #define PG8_SCHED __builtin_amdgcn_sched_barrier(0)
; template <class Epi>
; __device__ __forceinline__ void gemm_phase(PG8_LAS unsigned char* lds, PG8_LAS unsigned char* xl, const Gemm g, const Sched& S, const Epi& E, const int wid) {
;     ...
;             PG8_LDB(B0, 1, 0); PG8_LDB(B1, 1, 1); PG8_SCHED; PG8_LDA(At, 1, 0); PG8_STAGE(PG8_SA(0, 1), a2 + hstepA, voffA);
;             PG8_WAIT_V(8); PG8_WAIT_L(0); PG8_BAR; if (do0) { PG8_MMA(0, 0, At, B0); PG8_MMA(0, 1, At, B1); } PG8_BAR; PG8_SCHED;
;             PG8_LDA(At, 1, 1); PG8_STAGE(PG8_SB(1, 0), b3, voffB); PG8_STAGE(PG8_SB(1, 1), b3 + hstepB, voffB); PG8_STAGE(PG8_SA(1, 0), a3, voffA);
;             PG8_WAIT_V(8); PG8_WAIT_L(0); PG8_BAR; if (do1) { PG8_MMA(1, 0, At, B0); PG8_MMA(1, 1, At, B1); } PG8_BAR; PG8_SCHED;
;         }
	s_setprio 0
	s_add_i32 s54, 0, 0x18000
	s_add_i32 s55, 0, 0x1c000
	ds_read_b128 v[58:61], v235 offset:32768
	ds_read_b128 v[62:65], v235 offset:33792
	ds_read_b128 v[160:163], v235 offset:34816
	ds_read_b128 v[164:167], v235 offset:35840
	ds_read_b128 v[168:171], v235 offset:49152
	ds_read_b128 v[172:175], v235 offset:50176
	ds_read_b128 v[176:179], v235 offset:51200
	ds_read_b128 v[180:183], v235 offset:52224
	s_add_u32 s12, s52, 0x80000
	s_addc_u32 s13, s53, 0
	s_mov_b32 m0, s88
	ds_read_b128 v[184:187], v159 offset:32768
	ds_read_b128 v[188:191], v159 offset:33792
	ds_read_b128 v[210:213], v159 offset:34816
	ds_read_b128 v[214:217], v159 offset:35840
	ds_read_b128 v[218:221], v159 offset:36864
	ds_read_b128 v[222:225], v159 offset:37888
	ds_read_b128 v[226:229], v159 offset:38912
	ds_read_b128 v[230:233], v159 offset:39936
	global_load_lds_dwordx4 v140, s[12:13] sc0
	s_mov_b32 m0, s89
	s_nop 0
	global_load_lds_dwordx4 v144, s[12:13] sc0
	s_waitcnt vmcnt(8)
	s_waitcnt lgkmcnt(0)
	s_setprio 1
	s_barrier
	v_mfma_f32_16x16x32_bf16 v[136:139], v[58:61], v[184:187], v[136:139]
	v_mfma_f32_16x16x32_bf16 v[132:135], v[160:163], v[184:187], v[132:135]
	v_mfma_f32_16x16x32_bf16 v[120:123], v[58:61], v[210:213], v[120:123]
	v_mfma_f32_16x16x32_bf16 v[116:119], v[160:163], v[210:213], v[116:119]
	v_mfma_f32_16x16x32_bf16 v[104:107], v[58:61], v[218:221], v[104:107]
	v_mfma_f32_16x16x32_bf16 v[100:103], v[160:163], v[218:221], v[100:103]
	v_mfma_f32_16x16x32_bf16 v[86:89], v[58:61], v[226:229], v[86:89]
	v_mfma_f32_16x16x32_bf16 v[82:85], v[160:163], v[226:229], v[82:85]
	v_mfma_f32_16x16x32_bf16 v[136:139], v[62:65], v[188:191], v[136:139]
	v_mfma_f32_16x16x32_bf16 v[132:135], v[164:167], v[188:191], v[132:135]
	v_mfma_f32_16x16x32_bf16 v[120:123], v[62:65], v[214:217], v[120:123]
	v_mfma_f32_16x16x32_bf16 v[116:119], v[164:167], v[214:217], v[116:119]
	v_mfma_f32_16x16x32_bf16 v[104:107], v[62:65], v[222:225], v[104:107]
	v_mfma_f32_16x16x32_bf16 v[100:103], v[164:167], v[222:225], v[100:103]
	v_mfma_f32_16x16x32_bf16 v[86:89], v[62:65], v[230:233], v[86:89]
	v_mfma_f32_16x16x32_bf16 v[82:85], v[164:167], v[230:233], v[82:85]
	s_setprio 0
	s_setprio 1
	v_mfma_f32_16x16x32_bf16 v[128:131], v[168:171], v[184:187], v[128:131]
	v_mfma_f32_16x16x32_bf16 v[124:127], v[176:179], v[184:187], v[124:127]
	v_mfma_f32_16x16x32_bf16 v[112:115], v[168:171], v[210:213], v[112:115]
	v_mfma_f32_16x16x32_bf16 v[108:111], v[176:179], v[210:213], v[108:111]
	v_mfma_f32_16x16x32_bf16 v[96:99], v[168:171], v[218:221], v[96:99]
	v_mfma_f32_16x16x32_bf16 v[92:95], v[176:179], v[218:221], v[92:95]
	v_mfma_f32_16x16x32_bf16 v[78:81], v[168:171], v[226:229], v[78:81]
	v_mfma_f32_16x16x32_bf16 v[74:77], v[176:179], v[226:229], v[74:77]
	v_mfma_f32_16x16x32_bf16 v[128:131], v[172:175], v[188:191], v[128:131]
	v_mfma_f32_16x16x32_bf16 v[124:127], v[180:183], v[188:191], v[124:127]
	v_mfma_f32_16x16x32_bf16 v[112:115], v[172:175], v[214:217], v[112:115]
	v_mfma_f32_16x16x32_bf16 v[108:111], v[180:183], v[214:217], v[108:111]
	v_mfma_f32_16x16x32_bf16 v[96:99], v[172:175], v[222:225], v[96:99]
	v_mfma_f32_16x16x32_bf16 v[92:95], v[180:183], v[222:225], v[92:95]
	v_mfma_f32_16x16x32_bf16 v[78:81], v[172:175], v[230:233], v[78:81]
	v_mfma_f32_16x16x32_bf16 v[74:77], v[180:183], v[230:233], v[74:77]
	s_barrier
	s_setprio 0
	s_add_i32 s12, s54, s29
	s_mov_b32 m0, s12
	ds_read_b128 v[184:187], v159 offset:49152
	ds_read_b128 v[188:191], v159 offset:50176
	ds_read_b128 v[210:213], v159 offset:51200
	ds_read_b128 v[214:217], v159 offset:52224
	ds_read_b128 v[218:221], v159 offset:53248
	ds_read_b128 v[222:225], v159 offset:54272
	ds_read_b128 v[226:229], v159 offset:55296
	ds_read_b128 v[230:233], v159 offset:56320
	global_load_lds_dwordx4 v204, s[50:51] sc0
	s_add_i32 m0, s12, 0x2000
	s_add_u32 s12, s50, 0x80080
	global_load_lds_dwordx4 v234, s[50:51] sc0
	s_addc_u32 s13, s51, 0
	s_add_i32 s50, s55, s29
	s_mov_b32 m0, s50
	s_nop 0
	global_load_lds_dwordx4 v142, s[12:13] sc0
	s_add_i32 m0, s50, 0x2000
	s_nop 0
	global_load_lds_dwordx4 v146, s[12:13] sc0
	s_mov_b32 m0, s90
	s_nop 0
	global_load_lds_dwordx4 v157, s[52:53] sc0
	s_mov_b32 m0, s91
	s_nop 0
	global_load_lds_dwordx4 v205, s[52:53] sc0
	s_waitcnt vmcnt(8)
	s_waitcnt lgkmcnt(0)
	s_setprio 1
	s_barrier
	v_mfma_f32_16x16x32_bf16 v[70:73], v[58:61], v[184:187], v[70:73]
	v_mfma_f32_16x16x32_bf16 v[66:69], v[160:163], v[184:187], v[66:69]
	v_mfma_f32_16x16x32_bf16 v[54:57], v[58:61], v[210:213], v[54:57]
	v_mfma_f32_16x16x32_bf16 v[50:53], v[160:163], v[210:213], v[50:53]
	v_mfma_f32_16x16x32_bf16 v[38:41], v[58:61], v[218:221], v[38:41]
	v_mfma_f32_16x16x32_bf16 v[34:37], v[160:163], v[218:221], v[34:37]
	v_mfma_f32_16x16x32_bf16 v[12:15], v[58:61], v[226:229], v[12:15]
	v_mfma_f32_16x16x32_bf16 v[8:11], v[160:163], v[226:229], v[8:11]
	v_mfma_f32_16x16x32_bf16 v[70:73], v[62:65], v[188:191], v[70:73]
	v_mfma_f32_16x16x32_bf16 v[66:69], v[164:167], v[188:191], v[66:69]
	v_mfma_f32_16x16x32_bf16 v[54:57], v[62:65], v[214:217], v[54:57]
	v_mfma_f32_16x16x32_bf16 v[50:53], v[164:167], v[214:217], v[50:53]
	v_mfma_f32_16x16x32_bf16 v[38:41], v[62:65], v[222:225], v[38:41]
	v_mfma_f32_16x16x32_bf16 v[34:37], v[164:167], v[222:225], v[34:37]
	v_mfma_f32_16x16x32_bf16 v[12:15], v[62:65], v[230:233], v[12:15]
	v_mfma_f32_16x16x32_bf16 v[8:11], v[164:167], v[230:233], v[8:11]
	s_setprio 0
	s_setprio 1
	v_mfma_f32_16x16x32_bf16 v[22:25], v[168:171], v[184:187], v[22:25]
	v_mfma_f32_16x16x32_bf16 v[62:65], v[172:175], v[188:191], v[22:25]
	v_mfma_f32_16x16x32_bf16 v[22:25], v[176:179], v[184:187], v[26:29]
	v_mfma_f32_16x16x32_bf16 v[58:61], v[180:183], v[188:191], v[22:25]
	v_mfma_f32_16x16x32_bf16 v[22:25], v[168:171], v[210:213], v[46:49]
	v_mfma_f32_16x16x32_bf16 v[46:49], v[172:175], v[214:217], v[22:25]
	v_mfma_f32_16x16x32_bf16 v[22:25], v[176:179], v[210:213], v[42:45]
	v_mfma_f32_16x16x32_bf16 v[42:45], v[180:183], v[214:217], v[22:25]
	v_mfma_f32_16x16x32_bf16 v[22:25], v[168:171], v[218:221], v[30:33]
	v_mfma_f32_16x16x32_bf16 v[18:21], v[176:179], v[218:221], v[18:21]
	v_mfma_f32_16x16x32_bf16 v[4:7], v[168:171], v[226:229], v[4:7]
	v_mfma_f32_16x16x32_bf16 v[0:3], v[176:179], v[226:229], v[0:3]
	v_mfma_f32_16x16x32_bf16 v[30:33], v[172:175], v[222:225], v[22:25]
	v_mfma_f32_16x16x32_bf16 v[18:21], v[180:183], v[222:225], v[18:21]
	v_mfma_f32_16x16x32_bf16 v[4:7], v[172:175], v[230:233], v[4:7]
	v_mfma_f32_16x16x32_bf16 v[0:3], v[180:183], v[230:233], v[0:3]
	s_barrier
	s_setprio 0
	s_add_i32 s66, s66, 2
	s_add_u32 s59, s59, 0x100
	s_addc_u32 s62, s62, 0
	s_cmp_gt_u32 s66, 29
	s_mov_b64 s[12:13], s[20:21]
; #define PG8_STAGE(bufoff, gbase, voff) do { _Pragma("unroll") for (int _i = 0; _i < 2; ++_i) \
;         __builtin_amdgcn_global_load_lds((const unsigned*)((const char*)(gbase) + (voff)[_i]), (PG8_LAS unsigned*)(lds + (bufoff) + ldsw + _i * 8192), 16, 0, 0); } while (0)
; #define PG8_LDA(dst, b, h) do { _Pragma("unroll") for (int m = 0; m < 4; ++m) _Pragma("unroll") for (int k = 0; k < 2; ++k) dst[m][k] = *(const PG8_LAS bf16x8*)(lds + PG8_SA(b, h) + aoff + m * 2048 + k * 1024); } while (0)
; #define PG8_LDB(dst, b, h) do { _Pragma("unroll") for (int n = 0; n < 2; ++n) _Pragma("unroll") for (int k = 0; k < 2; ++k) dst[n][k] = *(const PG8_LAS bf16x8*)(lds + PG8_SB(b, h) + boff + n * 2048 + k * 1024); } while (0)
; #define PG8_MMA(ai, bj, At, Bt) do { __builtin_amdgcn_s_setprio(1); _Pragma("unroll") for (int m = 0; m < 4; ++m) _Pragma("unroll") for (int n = 0; n < 2; ++n) _Pragma("unroll") for (int k = 0; k < 2; ++k) \
;         acc[ai][bj][m][n] = __builtin_amdgcn_mfma_f32_16x16x32_bf16(Bt[n][k], At[m][k], acc[ai][bj][m][n], 0, 0, 0); __builtin_amdgcn_s_setprio(0); } while (0)
; #define PG8_WAIT_V(n) asm volatile("s_waitcnt vmcnt(" #n ")" ::: "memory")
; #define PG8_WAIT_L(n) asm volatile("s_waitcnt lgkmcnt(" #n ")" ::: "memory")
; #define PG8_BAR __builtin_amdgcn_s_barrier()
; #define PG8_SCHED __builtin_amdgcn_sched_barrier(0)
; template <class Epi>
; __device__ __forceinline__ void gemm_phase(PG8_LAS unsigned char* lds, PG8_LAS unsigned char* xl, const Gemm g, const Sched& S, const Epi& E, const int wid) {
;     ...
;             const char* a1 = cA + (size_t)(t + 1) * kstep + j1;
;             const char* a2 = last ? nA : cA + (size_t)(t + 2) * kstep + ja2; const char* b2 = last ? nB : cB + (size_t)(t + 2) * kstep + jb2;
;             const char* a3 = a2 + kstep; const char* b3 = b2 + kstep;
;             PG8_LDB(B0, 0, 0); PG8_LDB(B1, 0, 1); PG8_SCHED; PG8_LDA(At, 0, 0); PG8_STAGE(PG8_SA(1, 1), a1 + hstepA, voffA);
;             PG8_WAIT_V(8); PG8_WAIT_L(0); PG8_BAR; if (do0) { PG8_MMA(0, 0, At, B0); PG8_MMA(0, 1, At, B1); } PG8_BAR; PG8_SCHED;
;             PG8_LDA(At, 0, 1); PG8_STAGE(PG8_SB(0, 0), b2, voffB); PG8_STAGE(PG8_SB(0, 1), b2 + hstepB, voffB); PG8_STAGE(PG8_SA(0, 0), a2, voffA);
;             PG8_WAIT_V(8); PG8_WAIT_L(0); PG8_BAR; if (do1) { PG8_MMA(1, 0, At, B0); PG8_MMA(1, 1, At, B1); } PG8_BAR; PG8_SCHED;
.LBB0_527:
	s_add_u32 s20, s12, 0x100
	s_addc_u32 s21, s13, 0
	s_add_i32 s54, 0, 0x10000
	s_cmp_eq_u32 s66, 28
	s_cselect_b32 s53, s8, s21
	s_cselect_b32 s52, s9, s20
	s_cselect_b32 s51, s10, s62
	s_cselect_b32 s50, s11, s59
	s_add_i32 s55, 0, 0x14000
	ds_read_b128 v[22:25], v235 offset:0
	ds_read_b128 v[26:29], v235 offset:1024
	ds_read_b128 v[160:163], v235 offset:2048
	ds_read_b128 v[164:167], v235 offset:3072
	ds_read_b128 v[168:171], v235 offset:16384
	ds_read_b128 v[172:175], v235 offset:17408
	ds_read_b128 v[176:179], v235 offset:18432
	ds_read_b128 v[180:183], v235 offset:19456
	s_add_i32 m0, s45, 0xc000
	ds_read_b128 v[184:187], v159
	ds_read_b128 v[188:191], v159 offset:1024
	ds_read_b128 v[210:213], v159 offset:2048
	ds_read_b128 v[214:217], v159 offset:3072
	ds_read_b128 v[218:221], v159 offset:4096
	ds_read_b128 v[222:225], v159 offset:5120
	ds_read_b128 v[226:229], v159 offset:6144
	ds_read_b128 v[230:233], v159 offset:7168
	global_load_lds_dwordx4 v148, s[12:13] sc0
	s_add_i32 m0, s45, 0xe000
	s_nop 0
	global_load_lds_dwordx4 v150, s[12:13] sc0
	s_waitcnt vmcnt(8)
	s_waitcnt lgkmcnt(0)
	s_setprio 1
	s_barrier
	v_mfma_f32_16x16x32_bf16 v[136:139], v[22:25], v[184:187], v[136:139]
	v_mfma_f32_16x16x32_bf16 v[132:135], v[160:163], v[184:187], v[132:135]
	v_mfma_f32_16x16x32_bf16 v[120:123], v[22:25], v[210:213], v[120:123]
	v_mfma_f32_16x16x32_bf16 v[116:119], v[160:163], v[210:213], v[116:119]
	v_mfma_f32_16x16x32_bf16 v[104:107], v[22:25], v[218:221], v[104:107]
	v_mfma_f32_16x16x32_bf16 v[100:103], v[160:163], v[218:221], v[100:103]
	v_mfma_f32_16x16x32_bf16 v[86:89], v[22:25], v[226:229], v[86:89]
	v_mfma_f32_16x16x32_bf16 v[82:85], v[160:163], v[226:229], v[82:85]
	v_mfma_f32_16x16x32_bf16 v[136:139], v[26:29], v[188:191], v[136:139]
	v_mfma_f32_16x16x32_bf16 v[132:135], v[164:167], v[188:191], v[132:135]
	v_mfma_f32_16x16x32_bf16 v[120:123], v[26:29], v[214:217], v[120:123]
	v_mfma_f32_16x16x32_bf16 v[116:119], v[164:167], v[214:217], v[116:119]
	v_mfma_f32_16x16x32_bf16 v[104:107], v[26:29], v[222:225], v[104:107]
	v_mfma_f32_16x16x32_bf16 v[100:103], v[164:167], v[222:225], v[100:103]
	v_mfma_f32_16x16x32_bf16 v[86:89], v[26:29], v[230:233], v[86:89]
	v_mfma_f32_16x16x32_bf16 v[82:85], v[164:167], v[230:233], v[82:85]
	s_setprio 0
	s_setprio 1
	v_mfma_f32_16x16x32_bf16 v[128:131], v[168:171], v[184:187], v[128:131]
	v_mfma_f32_16x16x32_bf16 v[124:127], v[176:179], v[184:187], v[124:127]
	v_mfma_f32_16x16x32_bf16 v[112:115], v[168:171], v[210:213], v[112:115]
	v_mfma_f32_16x16x32_bf16 v[108:111], v[176:179], v[210:213], v[108:111]
	v_mfma_f32_16x16x32_bf16 v[96:99], v[168:171], v[218:221], v[96:99]
	v_mfma_f32_16x16x32_bf16 v[92:95], v[176:179], v[218:221], v[92:95]
	v_mfma_f32_16x16x32_bf16 v[78:81], v[168:171], v[226:229], v[78:81]
	v_mfma_f32_16x16x32_bf16 v[74:77], v[176:179], v[226:229], v[74:77]
	v_mfma_f32_16x16x32_bf16 v[128:131], v[172:175], v[188:191], v[128:131]
	v_mfma_f32_16x16x32_bf16 v[124:127], v[180:183], v[188:191], v[124:127]
	v_mfma_f32_16x16x32_bf16 v[112:115], v[172:175], v[214:217], v[112:115]
	v_mfma_f32_16x16x32_bf16 v[108:111], v[180:183], v[214:217], v[108:111]
	v_mfma_f32_16x16x32_bf16 v[96:99], v[172:175], v[222:225], v[96:99]
	v_mfma_f32_16x16x32_bf16 v[92:95], v[180:183], v[222:225], v[92:95]
	v_mfma_f32_16x16x32_bf16 v[78:81], v[172:175], v[230:233], v[78:81]
	v_mfma_f32_16x16x32_bf16 v[74:77], v[180:183], v[230:233], v[74:77]
	s_barrier
	s_setprio 0
	s_add_i32 s12, s54, s29
	s_mov_b32 m0, s12
	ds_read_b128 v[184:187], v159 offset:16384
	ds_read_b128 v[188:191], v159 offset:17408
	ds_read_b128 v[210:213], v159 offset:18432
	ds_read_b128 v[214:217], v159 offset:19456
	ds_read_b128 v[218:221], v159 offset:20480
	ds_read_b128 v[222:225], v159 offset:21504
	ds_read_b128 v[226:229], v159 offset:22528
	ds_read_b128 v[230:233], v159 offset:23552
	global_load_lds_dwordx4 v142, s[50:51] sc0
	s_add_i32 m0, s12, 0x2000
	s_add_u32 s12, s50, 0x80000
	s_addc_u32 s13, s51, 0
	s_add_i32 s54, s55, s29
	global_load_lds_dwordx4 v146, s[50:51] sc0
	s_mov_b32 m0, s54
	s_nop 0
	global_load_lds_dwordx4 v142, s[12:13] sc0
	s_add_i32 m0, s54, 0x2000
	s_nop 0
	global_load_lds_dwordx4 v146, s[12:13] sc0
	s_mov_b32 m0, s45
	s_nop 0
	global_load_lds_dwordx4 v140, s[52:53] sc0
	s_mov_b32 m0, s41
	s_nop 0
	global_load_lds_dwordx4 v144, s[52:53] sc0
	s_waitcnt vmcnt(8)
	s_waitcnt lgkmcnt(0)
	s_setprio 1
	s_barrier
	v_mfma_f32_16x16x32_bf16 v[70:73], v[22:25], v[184:187], v[70:73]
	v_mfma_f32_16x16x32_bf16 v[66:69], v[160:163], v[184:187], v[66:69]
	v_mfma_f32_16x16x32_bf16 v[54:57], v[22:25], v[210:213], v[54:57]
	v_mfma_f32_16x16x32_bf16 v[50:53], v[160:163], v[210:213], v[50:53]
	v_mfma_f32_16x16x32_bf16 v[38:41], v[22:25], v[218:221], v[38:41]
	v_mfma_f32_16x16x32_bf16 v[34:37], v[160:163], v[218:221], v[34:37]
	v_mfma_f32_16x16x32_bf16 v[12:15], v[22:25], v[226:229], v[12:15]
	v_mfma_f32_16x16x32_bf16 v[8:11], v[160:163], v[226:229], v[8:11]
	v_mfma_f32_16x16x32_bf16 v[70:73], v[26:29], v[188:191], v[70:73]
	v_mfma_f32_16x16x32_bf16 v[66:69], v[164:167], v[188:191], v[66:69]
	v_mfma_f32_16x16x32_bf16 v[54:57], v[26:29], v[214:217], v[54:57]
	v_mfma_f32_16x16x32_bf16 v[50:53], v[164:167], v[214:217], v[50:53]
	v_mfma_f32_16x16x32_bf16 v[38:41], v[26:29], v[222:225], v[38:41]
	v_mfma_f32_16x16x32_bf16 v[34:37], v[164:167], v[222:225], v[34:37]
	v_mfma_f32_16x16x32_bf16 v[12:15], v[26:29], v[230:233], v[12:15]
	v_mfma_f32_16x16x32_bf16 v[8:11], v[164:167], v[230:233], v[8:11]
	s_setprio 0
	s_setprio 1
	v_mfma_f32_16x16x32_bf16 v[46:49], v[168:171], v[210:213], v[46:49]
	v_mfma_f32_16x16x32_bf16 v[42:45], v[176:179], v[210:213], v[42:45]
	v_mfma_f32_16x16x32_bf16 v[30:33], v[168:171], v[218:221], v[30:33]
	v_mfma_f32_16x16x32_bf16 v[18:21], v[176:179], v[218:221], v[18:21]
	v_mfma_f32_16x16x32_bf16 v[4:7], v[168:171], v[226:229], v[4:7]
	v_mfma_f32_16x16x32_bf16 v[0:3], v[176:179], v[226:229], v[0:3]
	v_mfma_f32_16x16x32_bf16 v[22:25], v[168:171], v[184:187], v[62:65]
	v_mfma_f32_16x16x32_bf16 v[26:29], v[176:179], v[184:187], v[58:61]
	v_mfma_f32_16x16x32_bf16 v[46:49], v[172:175], v[214:217], v[46:49]
	v_mfma_f32_16x16x32_bf16 v[42:45], v[180:183], v[214:217], v[42:45]
	v_mfma_f32_16x16x32_bf16 v[30:33], v[172:175], v[222:225], v[30:33]
	v_mfma_f32_16x16x32_bf16 v[18:21], v[180:183], v[222:225], v[18:21]
	v_mfma_f32_16x16x32_bf16 v[4:7], v[172:175], v[230:233], v[4:7]
	v_mfma_f32_16x16x32_bf16 v[0:3], v[180:183], v[230:233], v[0:3]
	v_mfma_f32_16x16x32_bf16 v[22:25], v[172:175], v[188:191], v[22:25]
	v_mfma_f32_16x16x32_bf16 v[26:29], v[180:183], v[188:191], v[26:29]
	s_barrier
; #define PG8_STAGE(bufoff, gbase, voff) do { _Pragma("unroll") for (int _i = 0; _i < 2; ++_i) \
;         __builtin_amdgcn_global_load_lds((const unsigned*)((const char*)(gbase) + (voff)[_i]), (PG8_LAS unsigned*)(lds + (bufoff) + ldsw + _i * 8192), 16, 0, 0); } while (0)
; #define PG8_LDA(dst, b, h) do { _Pragma("unroll") for (int m = 0; m < 4; ++m) _Pragma("unroll") for (int k = 0; k < 2; ++k) dst[m][k] = *(const PG8_LAS bf16x8*)(lds + PG8_SA(b, h) + aoff + m * 2048 + k * 1024); } while (0)
; #define PG8_LDB(dst, b, h) do { _Pragma("unroll") for (int n = 0; n < 2; ++n) _Pragma("unroll") for (int k = 0; k < 2; ++k) dst[n][k] = *(const PG8_LAS bf16x8*)(lds + PG8_SB(b, h) + boff + n * 2048 + k * 1024); } while (0)
; #define PG8_MMA(ai, bj, At, Bt) do { __builtin_amdgcn_s_setprio(1); _Pragma("unroll") for (int m = 0; m < 4; ++m) _Pragma("unroll") for (int n = 0; n < 2; ++n) _Pragma("unroll") for (int k = 0; k < 2; ++k) \
;         acc[ai][bj][m][n] = __builtin_amdgcn_mfma_f32_16x16x32_bf16(Bt[n][k], At[m][k], acc[ai][bj][m][n], 0, 0, 0); __builtin_amdgcn_s_setprio(0); } while (0)
; #define PG8_WAIT_V(n) asm volatile("s_waitcnt vmcnt(" #n ")" ::: "memory")
; #define PG8_WAIT_L(n) asm volatile("s_waitcnt lgkmcnt(" #n ")" ::: "memory")
; #define PG8_BAR __builtin_amdgcn_s_barrier()
; #define PG8_SCHED __builtin_amdgcn_sched_barrier(0)
; template <class Epi>
; __device__ __forceinline__ void gemm_phase(PG8_LAS unsigned char* lds, PG8_LAS unsigned char* xl, const Gemm g, const Sched& S, const Epi& E, const int wid) {
;     ...
;             PG8_LDB(B0, 1, 0); PG8_LDB(B1, 1, 1); PG8_SCHED; PG8_LDA(At, 1, 0); PG8_STAGE(PG8_SA(0, 1), a2 + hstepA, voffA);
;             PG8_WAIT_V(8); PG8_WAIT_L(0); PG8_BAR; if (do0) { PG8_MMA(0, 0, At, B0); PG8_MMA(0, 1, At, B1); } PG8_BAR; PG8_SCHED;
;             PG8_LDA(At, 1, 1); PG8_STAGE(PG8_SB(1, 0), b3, voffB); PG8_STAGE(PG8_SB(1, 1), b3 + hstepB, voffB); PG8_STAGE(PG8_SA(1, 0), a3, voffA);
;             PG8_WAIT_V(8); PG8_WAIT_L(0); PG8_BAR; if (do1) { PG8_MMA(1, 0, At, B0); PG8_MMA(1, 1, At, B1); } PG8_BAR; PG8_SCHED;
;         }
;         if (wr == 0) PG8_BAR;
	s_setprio 0
	s_add_i32 s54, 0, 0x18000
	s_add_i32 s55, 0, 0x1c000
	ds_read_b128 v[58:61], v235 offset:32768
	ds_read_b128 v[62:65], v235 offset:33792
	ds_read_b128 v[160:163], v235 offset:34816
	ds_read_b128 v[164:167], v235 offset:35840
	ds_read_b128 v[168:171], v235 offset:49152
	ds_read_b128 v[172:175], v235 offset:50176
	ds_read_b128 v[176:179], v235 offset:51200
	ds_read_b128 v[180:183], v235 offset:52224
	s_add_u32 s12, s52, 0x80000
	s_addc_u32 s13, s53, 0
	s_mov_b32 m0, s88
	ds_read_b128 v[184:187], v159 offset:32768
	ds_read_b128 v[188:191], v159 offset:33792
	ds_read_b128 v[210:213], v159 offset:34816
	ds_read_b128 v[214:217], v159 offset:35840
	ds_read_b128 v[218:221], v159 offset:36864
	ds_read_b128 v[222:225], v159 offset:37888
	ds_read_b128 v[226:229], v159 offset:38912
	ds_read_b128 v[230:233], v159 offset:39936
	global_load_lds_dwordx4 v140, s[12:13] sc0
	s_mov_b32 m0, s89
	s_nop 0
	global_load_lds_dwordx4 v144, s[12:13] sc0
	s_waitcnt vmcnt(8)
	s_waitcnt lgkmcnt(0)
	s_setprio 1
	s_barrier
	v_mfma_f32_16x16x32_bf16 v[136:139], v[58:61], v[184:187], v[136:139]
	v_mfma_f32_16x16x32_bf16 v[132:135], v[160:163], v[184:187], v[132:135]
	v_mfma_f32_16x16x32_bf16 v[120:123], v[58:61], v[210:213], v[120:123]
	v_mfma_f32_16x16x32_bf16 v[116:119], v[160:163], v[210:213], v[116:119]
	v_mfma_f32_16x16x32_bf16 v[104:107], v[58:61], v[218:221], v[104:107]
	v_mfma_f32_16x16x32_bf16 v[100:103], v[160:163], v[218:221], v[100:103]
	v_mfma_f32_16x16x32_bf16 v[86:89], v[58:61], v[226:229], v[86:89]
	v_mfma_f32_16x16x32_bf16 v[82:85], v[160:163], v[226:229], v[82:85]
	v_mfma_f32_16x16x32_bf16 v[136:139], v[62:65], v[188:191], v[136:139]
	v_mfma_f32_16x16x32_bf16 v[132:135], v[164:167], v[188:191], v[132:135]
	v_mfma_f32_16x16x32_bf16 v[120:123], v[62:65], v[214:217], v[120:123]
	v_mfma_f32_16x16x32_bf16 v[116:119], v[164:167], v[214:217], v[116:119]
	v_mfma_f32_16x16x32_bf16 v[104:107], v[62:65], v[222:225], v[104:107]
	v_mfma_f32_16x16x32_bf16 v[100:103], v[164:167], v[222:225], v[100:103]
	v_mfma_f32_16x16x32_bf16 v[86:89], v[62:65], v[230:233], v[86:89]
	v_mfma_f32_16x16x32_bf16 v[82:85], v[164:167], v[230:233], v[82:85]
	s_setprio 0
	s_setprio 1
	v_mfma_f32_16x16x32_bf16 v[128:131], v[168:171], v[184:187], v[128:131]
	v_mfma_f32_16x16x32_bf16 v[124:127], v[176:179], v[184:187], v[124:127]
	v_mfma_f32_16x16x32_bf16 v[112:115], v[168:171], v[210:213], v[112:115]
	v_mfma_f32_16x16x32_bf16 v[108:111], v[176:179], v[210:213], v[108:111]
	v_mfma_f32_16x16x32_bf16 v[96:99], v[168:171], v[218:221], v[96:99]
	v_mfma_f32_16x16x32_bf16 v[92:95], v[176:179], v[218:221], v[92:95]
	v_mfma_f32_16x16x32_bf16 v[78:81], v[168:171], v[226:229], v[78:81]
	v_mfma_f32_16x16x32_bf16 v[74:77], v[176:179], v[226:229], v[74:77]
	v_mfma_f32_16x16x32_bf16 v[128:131], v[172:175], v[188:191], v[128:131]
	v_mfma_f32_16x16x32_bf16 v[124:127], v[180:183], v[188:191], v[124:127]
	v_mfma_f32_16x16x32_bf16 v[112:115], v[172:175], v[214:217], v[112:115]
	v_mfma_f32_16x16x32_bf16 v[108:111], v[180:183], v[214:217], v[108:111]
	v_mfma_f32_16x16x32_bf16 v[96:99], v[172:175], v[222:225], v[96:99]
	v_mfma_f32_16x16x32_bf16 v[92:95], v[180:183], v[222:225], v[92:95]
	v_mfma_f32_16x16x32_bf16 v[78:81], v[172:175], v[230:233], v[78:81]
	v_mfma_f32_16x16x32_bf16 v[74:77], v[180:183], v[230:233], v[74:77]
	s_barrier
	s_setprio 0
	s_add_i32 s12, s54, s29
	s_mov_b32 m0, s12
	ds_read_b128 v[184:187], v159 offset:49152
	ds_read_b128 v[188:191], v159 offset:50176
	ds_read_b128 v[210:213], v159 offset:51200
	ds_read_b128 v[214:217], v159 offset:52224
	ds_read_b128 v[218:221], v159 offset:53248
	ds_read_b128 v[222:225], v159 offset:54272
	ds_read_b128 v[226:229], v159 offset:55296
	ds_read_b128 v[230:233], v159 offset:56320
	global_load_lds_dwordx4 v204, s[50:51] sc0
	s_add_i32 m0, s12, 0x2000
	s_add_u32 s12, s50, 0x80080
	global_load_lds_dwordx4 v234, s[50:51] sc0
	s_addc_u32 s13, s51, 0
	s_add_i32 s50, s55, s29
	s_mov_b32 m0, s50
	s_nop 0
	global_load_lds_dwordx4 v142, s[12:13] sc0
	s_add_i32 m0, s50, 0x2000
	s_nop 0
	global_load_lds_dwordx4 v146, s[12:13] sc0
	s_mov_b32 m0, s90
	s_nop 0
	global_load_lds_dwordx4 v157, s[52:53] sc0
	s_mov_b32 m0, s91
	s_nop 0
	global_load_lds_dwordx4 v205, s[52:53] sc0
	s_waitcnt vmcnt(8)
	s_waitcnt lgkmcnt(0)
	s_setprio 1
	s_barrier
	v_mfma_f32_16x16x32_bf16 v[70:73], v[58:61], v[184:187], v[70:73]
	v_mfma_f32_16x16x32_bf16 v[66:69], v[160:163], v[184:187], v[66:69]
	v_mfma_f32_16x16x32_bf16 v[54:57], v[58:61], v[210:213], v[54:57]
	v_mfma_f32_16x16x32_bf16 v[50:53], v[160:163], v[210:213], v[50:53]
	v_mfma_f32_16x16x32_bf16 v[38:41], v[58:61], v[218:221], v[38:41]
	v_mfma_f32_16x16x32_bf16 v[34:37], v[160:163], v[218:221], v[34:37]
	v_mfma_f32_16x16x32_bf16 v[12:15], v[58:61], v[226:229], v[12:15]
	v_mfma_f32_16x16x32_bf16 v[8:11], v[160:163], v[226:229], v[8:11]
	v_mfma_f32_16x16x32_bf16 v[70:73], v[62:65], v[188:191], v[70:73]
	v_mfma_f32_16x16x32_bf16 v[66:69], v[164:167], v[188:191], v[66:69]
	v_mfma_f32_16x16x32_bf16 v[54:57], v[62:65], v[214:217], v[54:57]
	v_mfma_f32_16x16x32_bf16 v[50:53], v[164:167], v[214:217], v[50:53]
	v_mfma_f32_16x16x32_bf16 v[38:41], v[62:65], v[222:225], v[38:41]
	v_mfma_f32_16x16x32_bf16 v[34:37], v[164:167], v[222:225], v[34:37]
	v_mfma_f32_16x16x32_bf16 v[12:15], v[62:65], v[230:233], v[12:15]
	v_mfma_f32_16x16x32_bf16 v[8:11], v[164:167], v[230:233], v[8:11]
	s_setprio 0
	s_setprio 1
	v_mfma_f32_16x16x32_bf16 v[22:25], v[168:171], v[184:187], v[22:25]
	v_mfma_f32_16x16x32_bf16 v[62:65], v[172:175], v[188:191], v[22:25]
	v_mfma_f32_16x16x32_bf16 v[22:25], v[176:179], v[184:187], v[26:29]
	v_mfma_f32_16x16x32_bf16 v[58:61], v[180:183], v[188:191], v[22:25]
	v_mfma_f32_16x16x32_bf16 v[22:25], v[168:171], v[210:213], v[46:49]
	v_mfma_f32_16x16x32_bf16 v[46:49], v[172:175], v[214:217], v[22:25]
	v_mfma_f32_16x16x32_bf16 v[22:25], v[176:179], v[210:213], v[42:45]
	v_mfma_f32_16x16x32_bf16 v[42:45], v[180:183], v[214:217], v[22:25]
	v_mfma_f32_16x16x32_bf16 v[22:25], v[168:171], v[218:221], v[30:33]
	v_mfma_f32_16x16x32_bf16 v[18:21], v[176:179], v[218:221], v[18:21]
	v_mfma_f32_16x16x32_bf16 v[4:7], v[168:171], v[226:229], v[4:7]
	v_mfma_f32_16x16x32_bf16 v[0:3], v[176:179], v[226:229], v[0:3]
	v_mfma_f32_16x16x32_bf16 v[30:33], v[172:175], v[222:225], v[22:25]
	v_mfma_f32_16x16x32_bf16 v[18:21], v[180:183], v[222:225], v[18:21]
	v_mfma_f32_16x16x32_bf16 v[4:7], v[172:175], v[230:233], v[4:7]
	v_mfma_f32_16x16x32_bf16 v[0:3], v[180:183], v[230:233], v[0:3]
	s_barrier
	s_setprio 0
	s_add_i32 s66, s66, 2
	s_add_u32 s59, s59, 0x100
	s_addc_u32 s62, s62, 0
	s_cmp_gt_u32 s66, 29
	s_mov_b64 s[12:13], s[20:21]
	s_cbranch_scc0 .LBB0_527
	s_and_b64 vcc, exec, s[14:15]
	s_cbranch_vccz .LBB0_530
	s_barrier

; #define PG8_STAGE(bufoff, gbase, voff) do { _Pragma("unroll") for (int _i = 0; _i < 2; ++_i) \
;         __builtin_amdgcn_global_load_lds((const unsigned*)((const char*)(gbase) + (voff)[_i]), (PG8_LAS unsigned*)(lds + (bufoff) + ldsw + _i * 8192), 16, 0, 0); } while (0)
; #define PG8_LDA(dst, b, h) do { _Pragma("unroll") for (int m = 0; m < 4; ++m) _Pragma("unroll") for (int k = 0; k < 2; ++k) dst[m][k] = *(const PG8_LAS bf16x8*)(lds + PG8_SA(b, h) + aoff + m * 2048 + k * 1024); } while (0)
; #define PG8_LDB(dst, b, h) do { _Pragma("unroll") for (int n = 0; n < 2; ++n) _Pragma("unroll") for (int k = 0; k < 2; ++k) dst[n][k] = *(const PG8_LAS bf16x8*)(lds + PG8_SB(b, h) + boff + n * 2048 + k * 1024); } while (0)
; #define PG8_MMA(ai, bj, At, Bt) do { __builtin_amdgcn_s_setprio(1); _Pragma("unroll") for (int m = 0; m < 4; ++m) _Pragma("unroll") for (int n = 0; n < 2; ++n) _Pragma("unroll") for (int k = 0; k < 2; ++k) \
;         acc[ai][bj][m][n] = __builtin_amdgcn_mfma_f32_16x16x32_bf16(Bt[n][k], At[m][k], acc[ai][bj][m][n], 0, 0, 0); __builtin_amdgcn_s_setprio(0); } while (0)
; #define PG8_WAIT_V(n) asm volatile("s_waitcnt vmcnt(" #n ")" ::: "memory")
; #define PG8_WAIT_L(n) asm volatile("s_waitcnt lgkmcnt(" #n ")" ::: "memory")
; #define PG8_BAR __builtin_amdgcn_s_barrier()
; #define PG8_SCHED __builtin_amdgcn_sched_barrier(0)
; template <class Epi>
; __device__ __forceinline__ void gemm_phase(PG8_LAS unsigned char* lds, PG8_LAS unsigned char* xl, const Gemm g, const Sched& S, const Epi& E, const int wid) {
;     ...
;             const char* a1 = cA + (size_t)(t + 1) * kstep + j1;
;             const char* a2 = last ? nA : cA + (size_t)(t + 2) * kstep + ja2; const char* b2 = last ? nB : cB + (size_t)(t + 2) * kstep + jb2;
;             const char* a3 = a2 + kstep; const char* b3 = b2 + kstep;
;             PG8_LDB(B0, 0, 0); PG8_LDB(B1, 0, 1); PG8_SCHED; PG8_LDA(At, 0, 0); PG8_STAGE(PG8_SA(1, 1), a1 + hstepA, voffA);
;             PG8_WAIT_V(8); PG8_WAIT_L(0); PG8_BAR; if (do0) { PG8_MMA(0, 0, At, B0); PG8_MMA(0, 1, At, B1); } PG8_BAR; PG8_SCHED;
;             PG8_LDA(At, 0, 1); PG8_STAGE(PG8_SB(0, 0), b2, voffB); PG8_STAGE(PG8_SB(0, 1), b2 + hstepB, voffB); PG8_STAGE(PG8_SA(0, 0), a2, voffA);
;             PG8_WAIT_V(8); PG8_WAIT_L(0); PG8_BAR; if (do1) { PG8_MMA(1, 0, At, B0); PG8_MMA(1, 1, At, B1); } PG8_BAR; PG8_SCHED;
.Ldefbar_skip_6:
	v_add_u32_e32 v204, s22, v188
	v_add_u32_e32 v205, s22, v190
	v_add_u32_e32 v218, s22, v210
	v_add_u32_e32 v219, s22, v212
	v_add_u32_e32 v226, 0x10000, v195
	s_add_u32 s21, s42, 0xffd40080
	s_addc_u32 s31, s43, -1
	s_add_i32 s54, 0, 0x10000
	s_cmp_eq_u32 s13, 28
	s_cselect_b32 s49, s37, s31
	s_cselect_b32 s48, s36, s21
	s_cselect_b32 s45, s8, s11
	s_cselect_b32 s44, s9, s10
	s_add_i32 s21, 0, 0x14000
	ds_read_b128 v[120:123], v226 offset:0
	ds_read_b128 v[124:127], v226 offset:1024
	ds_read_b128 v[128:131], v226 offset:2048
	ds_read_b128 v[136:139], v226 offset:3072
	ds_read_b128 v[144:147], v226 offset:16384
	ds_read_b128 v[148:151], v226 offset:17408
	ds_read_b128 v[152:155], v226 offset:18432
	ds_read_b128 v[156:159], v226 offset:19456
	s_add_i32 m0, s53, 0xc000
	ds_read_b128 v[160:163], v220
	ds_read_b128 v[164:167], v220 offset:1024
	ds_read_b128 v[168:171], v220 offset:2048
	ds_read_b128 v[172:175], v220 offset:3072
	ds_read_b128 v[176:179], v220 offset:4096
	ds_read_b128 v[180:183], v220 offset:5120
	ds_read_b128 v[184:187], v220 offset:6144
	ds_read_b128 v[222:225], v220 offset:7168
	global_load_lds_dwordx4 v214, s[42:43] sc0
	s_add_i32 m0, s53, 0xe000
	s_nop 0
	global_load_lds_dwordx4 v216, s[42:43] sc0
	s_waitcnt vmcnt(8)
	s_waitcnt lgkmcnt(0)
	s_setprio 1
	s_barrier
	v_mfma_f32_16x16x32_bf16 v[140:143], v[120:123], v[160:163], 0
	v_mfma_f32_16x16x32_bf16 v[132:135], v[128:131], v[160:163], 0
	v_mfma_f32_16x16x32_bf16 v[108:111], v[120:123], v[168:171], 0
	v_mfma_f32_16x16x32_bf16 v[104:107], v[128:131], v[168:171], 0
	v_mfma_f32_16x16x32_bf16 v[92:95], v[120:123], v[176:179], 0
	v_mfma_f32_16x16x32_bf16 v[88:91], v[128:131], v[176:179], 0
	v_mfma_f32_16x16x32_bf16 v[76:79], v[120:123], v[184:187], 0
	v_mfma_f32_16x16x32_bf16 v[72:75], v[128:131], v[184:187], 0
	v_mfma_f32_16x16x32_bf16 v[140:143], v[124:127], v[164:167], v[140:143]
	v_mfma_f32_16x16x32_bf16 v[132:135], v[136:139], v[164:167], v[132:135]
	v_mfma_f32_16x16x32_bf16 v[108:111], v[124:127], v[172:175], v[108:111]
	v_mfma_f32_16x16x32_bf16 v[104:107], v[136:139], v[172:175], v[104:107]
	v_mfma_f32_16x16x32_bf16 v[92:95], v[124:127], v[180:183], v[92:95]
	v_mfma_f32_16x16x32_bf16 v[88:91], v[136:139], v[180:183], v[88:91]
	v_mfma_f32_16x16x32_bf16 v[76:79], v[124:127], v[222:225], v[76:79]
	v_mfma_f32_16x16x32_bf16 v[72:75], v[136:139], v[222:225], v[72:75]
	s_setprio 0
	s_setprio 1
	v_mfma_f32_16x16x32_bf16 v[116:119], v[144:147], v[160:163], 0
	v_mfma_f32_16x16x32_bf16 v[112:115], v[152:155], v[160:163], 0
	v_mfma_f32_16x16x32_bf16 v[100:103], v[144:147], v[168:171], 0
	v_mfma_f32_16x16x32_bf16 v[96:99], v[152:155], v[168:171], 0
	v_mfma_f32_16x16x32_bf16 v[84:87], v[144:147], v[176:179], 0
	v_mfma_f32_16x16x32_bf16 v[80:83], v[152:155], v[176:179], 0
	v_mfma_f32_16x16x32_bf16 v[68:71], v[144:147], v[184:187], 0
	v_mfma_f32_16x16x32_bf16 v[64:67], v[152:155], v[184:187], 0
	v_mfma_f32_16x16x32_bf16 v[116:119], v[148:151], v[164:167], v[116:119]
	v_mfma_f32_16x16x32_bf16 v[112:115], v[156:159], v[164:167], v[112:115]
	v_mfma_f32_16x16x32_bf16 v[100:103], v[148:151], v[172:175], v[100:103]
	v_mfma_f32_16x16x32_bf16 v[96:99], v[156:159], v[172:175], v[96:99]
	v_mfma_f32_16x16x32_bf16 v[84:87], v[148:151], v[180:183], v[84:87]
	v_mfma_f32_16x16x32_bf16 v[80:83], v[156:159], v[180:183], v[80:83]
	v_mfma_f32_16x16x32_bf16 v[68:71], v[148:151], v[222:225], v[68:71]
	v_mfma_f32_16x16x32_bf16 v[64:67], v[156:159], v[222:225], v[64:67]
	s_barrier
	s_setprio 0
	s_add_i32 s31, s54, s29
	s_mov_b32 m0, s31
	ds_read_b128 v[160:163], v220 offset:16384
	ds_read_b128 v[164:167], v220 offset:17408
	ds_read_b128 v[168:171], v220 offset:18432
	ds_read_b128 v[172:175], v220 offset:19456
	ds_read_b128 v[176:179], v220 offset:20480
	ds_read_b128 v[180:183], v220 offset:21504
	ds_read_b128 v[184:187], v220 offset:22528
	ds_read_b128 v[222:225], v220 offset:23552
	global_load_lds_dwordx4 v190, s[44:45] sc0
	s_add_i32 m0, s31, 0x2000
	s_add_u32 s54, s44, 0x80000
	s_addc_u32 s55, s45, 0
	s_add_i32 s21, s21, s29
	global_load_lds_dwordx4 v212, s[44:45] sc0
	s_mov_b32 m0, s21
	s_nop 0
	global_load_lds_dwordx4 v190, s[54:55] sc0
	s_add_i32 m0, s21, 0x2000
	s_nop 0
	global_load_lds_dwordx4 v212, s[54:55] sc0
	s_mov_b32 m0, s53
	s_nop 0
	global_load_lds_dwordx4 v188, s[48:49] sc0
	s_mov_b32 m0, s56
	s_nop 0
	global_load_lds_dwordx4 v210, s[48:49] sc0
	s_waitcnt vmcnt(8)
	s_waitcnt lgkmcnt(0)
	s_setprio 1
	s_barrier
	v_mfma_f32_16x16x32_bf16 v[60:63], v[120:123], v[160:163], 0
	v_mfma_f32_16x16x32_bf16 v[56:59], v[128:131], v[160:163], 0
	v_mfma_f32_16x16x32_bf16 v[44:47], v[120:123], v[168:171], 0
	v_mfma_f32_16x16x32_bf16 v[40:43], v[128:131], v[168:171], 0
	v_mfma_f32_16x16x32_bf16 v[28:31], v[120:123], v[176:179], 0
	v_mfma_f32_16x16x32_bf16 v[24:27], v[128:131], v[176:179], 0
	v_mfma_f32_16x16x32_bf16 v[12:15], v[120:123], v[184:187], 0
	v_mfma_f32_16x16x32_bf16 v[8:11], v[128:131], v[184:187], 0
	v_mfma_f32_16x16x32_bf16 v[60:63], v[124:127], v[164:167], v[60:63]
	v_mfma_f32_16x16x32_bf16 v[56:59], v[136:139], v[164:167], v[56:59]
	v_mfma_f32_16x16x32_bf16 v[44:47], v[124:127], v[172:175], v[44:47]
	v_mfma_f32_16x16x32_bf16 v[40:43], v[136:139], v[172:175], v[40:43]
	v_mfma_f32_16x16x32_bf16 v[28:31], v[124:127], v[180:183], v[28:31]
	v_mfma_f32_16x16x32_bf16 v[24:27], v[136:139], v[180:183], v[24:27]
	v_mfma_f32_16x16x32_bf16 v[12:15], v[124:127], v[222:225], v[12:15]
	v_mfma_f32_16x16x32_bf16 v[8:11], v[136:139], v[222:225], v[8:11]
	s_setprio 0
	s_setprio 1
	v_mfma_f32_16x16x32_bf16 v[52:55], v[144:147], v[160:163], 0
	v_mfma_f32_16x16x32_bf16 v[48:51], v[152:155], v[160:163], 0
	v_mfma_f32_16x16x32_bf16 v[36:39], v[144:147], v[168:171], 0
	v_mfma_f32_16x16x32_bf16 v[32:35], v[152:155], v[168:171], 0
	v_mfma_f32_16x16x32_bf16 v[20:23], v[144:147], v[176:179], 0
	v_mfma_f32_16x16x32_bf16 v[16:19], v[152:155], v[176:179], 0
	v_mfma_f32_16x16x32_bf16 v[4:7], v[144:147], v[184:187], 0
	v_mfma_f32_16x16x32_bf16 v[0:3], v[152:155], v[184:187], 0
	v_mfma_f32_16x16x32_bf16 v[52:55], v[148:151], v[164:167], v[52:55]
	v_mfma_f32_16x16x32_bf16 v[48:51], v[156:159], v[164:167], v[48:51]
	v_mfma_f32_16x16x32_bf16 v[36:39], v[148:151], v[172:175], v[36:39]
	v_mfma_f32_16x16x32_bf16 v[32:35], v[156:159], v[172:175], v[32:35]
	v_mfma_f32_16x16x32_bf16 v[20:23], v[148:151], v[180:183], v[20:23]
	v_mfma_f32_16x16x32_bf16 v[16:19], v[156:159], v[180:183], v[16:19]
	v_mfma_f32_16x16x32_bf16 v[4:7], v[148:151], v[222:225], v[4:7]
	v_mfma_f32_16x16x32_bf16 v[0:3], v[156:159], v[222:225], v[0:3]
	s_barrier
; #define PG8_STAGE(bufoff, gbase, voff) do { _Pragma("unroll") for (int _i = 0; _i < 2; ++_i) \
;         __builtin_amdgcn_global_load_lds((const unsigned*)((const char*)(gbase) + (voff)[_i]), (PG8_LAS unsigned*)(lds + (bufoff) + ldsw + _i * 8192), 16, 0, 0); } while (0)
; #define PG8_LDA(dst, b, h) do { _Pragma("unroll") for (int m = 0; m < 4; ++m) _Pragma("unroll") for (int k = 0; k < 2; ++k) dst[m][k] = *(const PG8_LAS bf16x8*)(lds + PG8_SA(b, h) + aoff + m * 2048 + k * 1024); } while (0)
; #define PG8_LDB(dst, b, h) do { _Pragma("unroll") for (int n = 0; n < 2; ++n) _Pragma("unroll") for (int k = 0; k < 2; ++k) dst[n][k] = *(const PG8_LAS bf16x8*)(lds + PG8_SB(b, h) + boff + n * 2048 + k * 1024); } while (0)
; #define PG8_MMA(ai, bj, At, Bt) do { __builtin_amdgcn_s_setprio(1); _Pragma("unroll") for (int m = 0; m < 4; ++m) _Pragma("unroll") for (int n = 0; n < 2; ++n) _Pragma("unroll") for (int k = 0; k < 2; ++k) \
;         acc[ai][bj][m][n] = __builtin_amdgcn_mfma_f32_16x16x32_bf16(Bt[n][k], At[m][k], acc[ai][bj][m][n], 0, 0, 0); __builtin_amdgcn_s_setprio(0); } while (0)
; #define PG8_WAIT_V(n) asm volatile("s_waitcnt vmcnt(" #n ")" ::: "memory")
; #define PG8_WAIT_L(n) asm volatile("s_waitcnt lgkmcnt(" #n ")" ::: "memory")
; #define PG8_BAR __builtin_amdgcn_s_barrier()
; #define PG8_SCHED __builtin_amdgcn_sched_barrier(0)
; template <class Epi>
; __device__ __forceinline__ void gemm_phase(PG8_LAS unsigned char* lds, PG8_LAS unsigned char* xl, const Gemm g, const Sched& S, const Epi& E, const int wid) {
;     ...
;             PG8_LDB(B0, 1, 0); PG8_LDB(B1, 1, 1); PG8_SCHED; PG8_LDA(At, 1, 0); PG8_STAGE(PG8_SA(0, 1), a2 + hstepA, voffA);
;             PG8_WAIT_V(8); PG8_WAIT_L(0); PG8_BAR; if (do0) { PG8_MMA(0, 0, At, B0); PG8_MMA(0, 1, At, B1); } PG8_BAR; PG8_SCHED;
;             PG8_LDA(At, 1, 1); PG8_STAGE(PG8_SB(1, 0), b3, voffB); PG8_STAGE(PG8_SB(1, 1), b3 + hstepB, voffB); PG8_STAGE(PG8_SA(1, 0), a3, voffA);
;             PG8_WAIT_V(8); PG8_WAIT_L(0); PG8_BAR; if (do1) { PG8_MMA(1, 0, At, B0); PG8_MMA(1, 1, At, B1); } PG8_BAR; PG8_SCHED;
;         }
	s_setprio 0
	s_add_i32 s21, 0, 0x18000
	s_add_i32 s31, 0, 0x1c000
	ds_read_b128 v[120:123], v226 offset:32768
	ds_read_b128 v[124:127], v226 offset:33792
	ds_read_b128 v[128:131], v226 offset:34816
	ds_read_b128 v[136:139], v226 offset:35840
	ds_read_b128 v[144:147], v226 offset:49152
	ds_read_b128 v[148:151], v226 offset:50176
	ds_read_b128 v[152:155], v226 offset:51200
	ds_read_b128 v[156:159], v226 offset:52224
	s_add_u32 s100, s48, 0x2c0000
	s_addc_u32 s101, s49, 0
	s_mov_b32 m0, s57
	ds_read_b128 v[160:163], v220 offset:32768
	ds_read_b128 v[164:167], v220 offset:33792
	ds_read_b128 v[168:171], v220 offset:34816
	ds_read_b128 v[172:175], v220 offset:35840
	ds_read_b128 v[176:179], v220 offset:36864
	ds_read_b128 v[180:183], v220 offset:37888
	ds_read_b128 v[184:187], v220 offset:38912
	ds_read_b128 v[222:225], v220 offset:39936
	global_load_lds_dwordx4 v188, s[100:101] sc0
	s_mov_b32 m0, s58
	s_nop 0
	global_load_lds_dwordx4 v210, s[100:101] sc0
	s_waitcnt vmcnt(8)
	s_waitcnt lgkmcnt(0)
	s_setprio 1
	s_barrier
	v_mfma_f32_16x16x32_bf16 v[140:143], v[120:123], v[160:163], v[140:143]
	v_mfma_f32_16x16x32_bf16 v[132:135], v[128:131], v[160:163], v[132:135]
	v_mfma_f32_16x16x32_bf16 v[108:111], v[120:123], v[168:171], v[108:111]
	v_mfma_f32_16x16x32_bf16 v[104:107], v[128:131], v[168:171], v[104:107]
	v_mfma_f32_16x16x32_bf16 v[92:95], v[120:123], v[176:179], v[92:95]
	v_mfma_f32_16x16x32_bf16 v[88:91], v[128:131], v[176:179], v[88:91]
	v_mfma_f32_16x16x32_bf16 v[76:79], v[120:123], v[184:187], v[76:79]
	v_mfma_f32_16x16x32_bf16 v[72:75], v[128:131], v[184:187], v[72:75]
	v_mfma_f32_16x16x32_bf16 v[140:143], v[124:127], v[164:167], v[140:143]
	v_mfma_f32_16x16x32_bf16 v[132:135], v[136:139], v[164:167], v[132:135]
	v_mfma_f32_16x16x32_bf16 v[108:111], v[124:127], v[172:175], v[108:111]
	v_mfma_f32_16x16x32_bf16 v[104:107], v[136:139], v[172:175], v[104:107]
	v_mfma_f32_16x16x32_bf16 v[92:95], v[124:127], v[180:183], v[92:95]
	v_mfma_f32_16x16x32_bf16 v[88:91], v[136:139], v[180:183], v[88:91]
	v_mfma_f32_16x16x32_bf16 v[76:79], v[124:127], v[222:225], v[76:79]
	v_mfma_f32_16x16x32_bf16 v[72:75], v[136:139], v[222:225], v[72:75]
	s_setprio 0
	s_setprio 1
	v_mfma_f32_16x16x32_bf16 v[116:119], v[144:147], v[160:163], v[116:119]
	v_mfma_f32_16x16x32_bf16 v[112:115], v[152:155], v[160:163], v[112:115]
	v_mfma_f32_16x16x32_bf16 v[100:103], v[144:147], v[168:171], v[100:103]
	v_mfma_f32_16x16x32_bf16 v[96:99], v[152:155], v[168:171], v[96:99]
	v_mfma_f32_16x16x32_bf16 v[84:87], v[144:147], v[176:179], v[84:87]
	v_mfma_f32_16x16x32_bf16 v[80:83], v[152:155], v[176:179], v[80:83]
	v_mfma_f32_16x16x32_bf16 v[68:71], v[144:147], v[184:187], v[68:71]
	v_mfma_f32_16x16x32_bf16 v[64:67], v[152:155], v[184:187], v[64:67]
	v_mfma_f32_16x16x32_bf16 v[116:119], v[148:151], v[164:167], v[116:119]
	v_mfma_f32_16x16x32_bf16 v[112:115], v[156:159], v[164:167], v[112:115]
	v_mfma_f32_16x16x32_bf16 v[100:103], v[148:151], v[172:175], v[100:103]
	v_mfma_f32_16x16x32_bf16 v[96:99], v[156:159], v[172:175], v[96:99]
	v_mfma_f32_16x16x32_bf16 v[84:87], v[148:151], v[180:183], v[84:87]
	v_mfma_f32_16x16x32_bf16 v[80:83], v[156:159], v[180:183], v[80:83]
	v_mfma_f32_16x16x32_bf16 v[68:71], v[148:151], v[222:225], v[68:71]
	v_mfma_f32_16x16x32_bf16 v[64:67], v[156:159], v[222:225], v[64:67]
	s_barrier
	s_setprio 0
	s_add_i32 s21, s21, s29
	s_mov_b32 m0, s21
	ds_read_b128 v[160:163], v220 offset:49152
	ds_read_b128 v[164:167], v220 offset:50176
	ds_read_b128 v[168:171], v220 offset:51200
	ds_read_b128 v[172:175], v220 offset:52224
	ds_read_b128 v[176:179], v220 offset:53248
	ds_read_b128 v[180:183], v220 offset:54272
	ds_read_b128 v[184:187], v220 offset:55296
	ds_read_b128 v[222:225], v220 offset:56320
	global_load_lds_dwordx4 v205, s[44:45] sc0
	s_add_i32 m0, s21, 0x2000
	s_add_u32 s100, s44, 0x80080
	global_load_lds_dwordx4 v219, s[44:45] sc0
	s_addc_u32 s101, s45, 0
	s_add_i32 s21, s31, s29
	s_mov_b32 m0, s21
	s_nop 0
	global_load_lds_dwordx4 v190, s[100:101] sc0
	s_add_i32 m0, s21, 0x2000
	s_nop 0
	global_load_lds_dwordx4 v212, s[100:101] sc0
	s_mov_b32 m0, s66
	s_nop 0
	global_load_lds_dwordx4 v204, s[48:49] sc0
	s_mov_b32 m0, s67
	s_nop 0
	global_load_lds_dwordx4 v218, s[48:49] sc0
	s_waitcnt vmcnt(8)
	s_waitcnt lgkmcnt(0)
	s_setprio 1
	s_barrier
	v_mfma_f32_16x16x32_bf16 v[60:63], v[120:123], v[160:163], v[60:63]
	v_mfma_f32_16x16x32_bf16 v[56:59], v[128:131], v[160:163], v[56:59]
	v_mfma_f32_16x16x32_bf16 v[44:47], v[120:123], v[168:171], v[44:47]
	v_mfma_f32_16x16x32_bf16 v[40:43], v[128:131], v[168:171], v[40:43]
	v_mfma_f32_16x16x32_bf16 v[28:31], v[120:123], v[176:179], v[28:31]
	v_mfma_f32_16x16x32_bf16 v[24:27], v[128:131], v[176:179], v[24:27]
	v_mfma_f32_16x16x32_bf16 v[12:15], v[120:123], v[184:187], v[12:15]
	v_mfma_f32_16x16x32_bf16 v[8:11], v[128:131], v[184:187], v[8:11]
	v_mfma_f32_16x16x32_bf16 v[60:63], v[124:127], v[164:167], v[60:63]
	v_mfma_f32_16x16x32_bf16 v[56:59], v[136:139], v[164:167], v[56:59]
	v_mfma_f32_16x16x32_bf16 v[44:47], v[124:127], v[172:175], v[44:47]
	v_mfma_f32_16x16x32_bf16 v[40:43], v[136:139], v[172:175], v[40:43]
	v_mfma_f32_16x16x32_bf16 v[28:31], v[124:127], v[180:183], v[28:31]
	v_mfma_f32_16x16x32_bf16 v[24:27], v[136:139], v[180:183], v[24:27]
	v_mfma_f32_16x16x32_bf16 v[12:15], v[124:127], v[222:225], v[12:15]
	v_mfma_f32_16x16x32_bf16 v[8:11], v[136:139], v[222:225], v[8:11]
	s_setprio 0
	s_setprio 1
	v_mfma_f32_16x16x32_bf16 v[52:55], v[144:147], v[160:163], v[52:55]
	v_mfma_f32_16x16x32_bf16 v[48:51], v[152:155], v[160:163], v[48:51]
	v_mfma_f32_16x16x32_bf16 v[36:39], v[144:147], v[168:171], v[36:39]
	v_mfma_f32_16x16x32_bf16 v[32:35], v[152:155], v[168:171], v[32:35]
	v_mfma_f32_16x16x32_bf16 v[20:23], v[144:147], v[176:179], v[20:23]
	v_mfma_f32_16x16x32_bf16 v[16:19], v[152:155], v[176:179], v[16:19]
	v_mfma_f32_16x16x32_bf16 v[4:7], v[144:147], v[184:187], v[4:7]
	v_mfma_f32_16x16x32_bf16 v[0:3], v[152:155], v[184:187], v[0:3]
	v_mfma_f32_16x16x32_bf16 v[52:55], v[148:151], v[164:167], v[52:55]
	v_mfma_f32_16x16x32_bf16 v[48:51], v[156:159], v[164:167], v[48:51]
	v_mfma_f32_16x16x32_bf16 v[36:39], v[148:151], v[172:175], v[36:39]
	v_mfma_f32_16x16x32_bf16 v[32:35], v[156:159], v[172:175], v[32:35]
	v_mfma_f32_16x16x32_bf16 v[20:23], v[148:151], v[180:183], v[20:23]
	v_mfma_f32_16x16x32_bf16 v[16:19], v[156:159], v[180:183], v[16:19]
	v_mfma_f32_16x16x32_bf16 v[4:7], v[148:151], v[222:225], v[4:7]
	v_mfma_f32_16x16x32_bf16 v[0:3], v[156:159], v[222:225], v[0:3]
	s_barrier
	s_setprio 0
	s_add_i32 s13, s13, 2
	s_add_u32 s42, s42, 0x100
	s_addc_u32 s43, s43, 0
	s_add_u32 s10, s10, 0x100
	s_addc_u32 s11, s11, 0
	s_cmp_gt_u32 s13, 29
; #define PG8_STAGE(bufoff, gbase, voff) do { _Pragma("unroll") for (int _i = 0; _i < 2; ++_i) \
;         __builtin_amdgcn_global_load_lds((const unsigned*)((const char*)(gbase) + (voff)[_i]), (PG8_LAS unsigned*)(lds + (bufoff) + ldsw + _i * 8192), 16, 0, 0); } while (0)
; #define PG8_LDA(dst, b, h) do { _Pragma("unroll") for (int m = 0; m < 4; ++m) _Pragma("unroll") for (int k = 0; k < 2; ++k) dst[m][k] = *(const PG8_LAS bf16x8*)(lds + PG8_SA(b, h) + aoff + m * 2048 + k * 1024); } while (0)
; #define PG8_LDB(dst, b, h) do { _Pragma("unroll") for (int n = 0; n < 2; ++n) _Pragma("unroll") for (int k = 0; k < 2; ++k) dst[n][k] = *(const PG8_LAS bf16x8*)(lds + PG8_SB(b, h) + boff + n * 2048 + k * 1024); } while (0)
; #define PG8_MMA(ai, bj, At, Bt) do { __builtin_amdgcn_s_setprio(1); _Pragma("unroll") for (int m = 0; m < 4; ++m) _Pragma("unroll") for (int n = 0; n < 2; ++n) _Pragma("unroll") for (int k = 0; k < 2; ++k) \
;         acc[ai][bj][m][n] = __builtin_amdgcn_mfma_f32_16x16x32_bf16(Bt[n][k], At[m][k], acc[ai][bj][m][n], 0, 0, 0); __builtin_amdgcn_s_setprio(0); } while (0)
; #define PG8_WAIT_V(n) asm volatile("s_waitcnt vmcnt(" #n ")" ::: "memory")
; #define PG8_WAIT_L(n) asm volatile("s_waitcnt lgkmcnt(" #n ")" ::: "memory")
; #define PG8_BAR __builtin_amdgcn_s_barrier()
; #define PG8_SCHED __builtin_amdgcn_sched_barrier(0)
; template <class Epi>
; __device__ __forceinline__ void gemm_phase(PG8_LAS unsigned char* lds, PG8_LAS unsigned char* xl, const Gemm g, const Sched& S, const Epi& E, const int wid) {
;     ...
;             const char* a1 = cA + (size_t)(t + 1) * kstep + j1;
;             const char* a2 = last ? nA : cA + (size_t)(t + 2) * kstep + ja2; const char* b2 = last ? nB : cB + (size_t)(t + 2) * kstep + jb2;
;             const char* a3 = a2 + kstep; const char* b3 = b2 + kstep;
;             PG8_LDB(B0, 0, 0); PG8_LDB(B1, 0, 1); PG8_SCHED; PG8_LDA(At, 0, 0); PG8_STAGE(PG8_SA(1, 1), a1 + hstepA, voffA);
;             PG8_WAIT_V(8); PG8_WAIT_L(0); PG8_BAR; if (do0) { PG8_MMA(0, 0, At, B0); PG8_MMA(0, 1, At, B1); } PG8_BAR; PG8_SCHED;
;             PG8_LDA(At, 0, 1); PG8_STAGE(PG8_SB(0, 0), b2, voffB); PG8_STAGE(PG8_SB(0, 1), b2 + hstepB, voffB); PG8_STAGE(PG8_SA(0, 0), a2, voffA);
;             PG8_WAIT_V(8); PG8_WAIT_L(0); PG8_BAR; if (do1) { PG8_MMA(1, 0, At, B0); PG8_MMA(1, 1, At, B1); } PG8_BAR; PG8_SCHED;
.LBB0_765:
	s_add_u32 s21, s42, 0xffd40080
	s_addc_u32 s31, s43, -1
	s_add_i32 s54, 0, 0x10000
	s_cmp_eq_u32 s13, 28
	s_cselect_b32 s49, s37, s31
	s_cselect_b32 s48, s36, s21
	s_cselect_b32 s45, s8, s11
	s_cselect_b32 s44, s9, s10
	s_add_i32 s21, 0, 0x14000
	ds_read_b128 v[120:123], v226 offset:0
	ds_read_b128 v[124:127], v226 offset:1024
	ds_read_b128 v[128:131], v226 offset:2048
	ds_read_b128 v[136:139], v226 offset:3072
	ds_read_b128 v[144:147], v226 offset:16384
	ds_read_b128 v[148:151], v226 offset:17408
	ds_read_b128 v[152:155], v226 offset:18432
	ds_read_b128 v[156:159], v226 offset:19456
	s_add_i32 m0, s53, 0xc000
	ds_read_b128 v[160:163], v220
	ds_read_b128 v[164:167], v220 offset:1024
	ds_read_b128 v[168:171], v220 offset:2048
	ds_read_b128 v[172:175], v220 offset:3072
	ds_read_b128 v[176:179], v220 offset:4096
	ds_read_b128 v[180:183], v220 offset:5120
	ds_read_b128 v[184:187], v220 offset:6144
	ds_read_b128 v[222:225], v220 offset:7168
	global_load_lds_dwordx4 v214, s[42:43] sc0
	s_add_i32 m0, s53, 0xe000
	s_nop 0
	global_load_lds_dwordx4 v216, s[42:43] sc0
	s_waitcnt vmcnt(8)
	s_waitcnt lgkmcnt(0)
	s_setprio 1
	s_barrier
	v_mfma_f32_16x16x32_bf16 v[140:143], v[120:123], v[160:163], v[140:143]
	v_mfma_f32_16x16x32_bf16 v[132:135], v[128:131], v[160:163], v[132:135]
	v_mfma_f32_16x16x32_bf16 v[108:111], v[120:123], v[168:171], v[108:111]
	v_mfma_f32_16x16x32_bf16 v[104:107], v[128:131], v[168:171], v[104:107]
	v_mfma_f32_16x16x32_bf16 v[92:95], v[120:123], v[176:179], v[92:95]
	v_mfma_f32_16x16x32_bf16 v[88:91], v[128:131], v[176:179], v[88:91]
	v_mfma_f32_16x16x32_bf16 v[76:79], v[120:123], v[184:187], v[76:79]
	v_mfma_f32_16x16x32_bf16 v[72:75], v[128:131], v[184:187], v[72:75]
	v_mfma_f32_16x16x32_bf16 v[140:143], v[124:127], v[164:167], v[140:143]
	v_mfma_f32_16x16x32_bf16 v[132:135], v[136:139], v[164:167], v[132:135]
	v_mfma_f32_16x16x32_bf16 v[108:111], v[124:127], v[172:175], v[108:111]
	v_mfma_f32_16x16x32_bf16 v[104:107], v[136:139], v[172:175], v[104:107]
	v_mfma_f32_16x16x32_bf16 v[92:95], v[124:127], v[180:183], v[92:95]
	v_mfma_f32_16x16x32_bf16 v[88:91], v[136:139], v[180:183], v[88:91]
	v_mfma_f32_16x16x32_bf16 v[76:79], v[124:127], v[222:225], v[76:79]
	v_mfma_f32_16x16x32_bf16 v[72:75], v[136:139], v[222:225], v[72:75]
	s_setprio 0
	s_setprio 1
	v_mfma_f32_16x16x32_bf16 v[116:119], v[144:147], v[160:163], v[116:119]
	v_mfma_f32_16x16x32_bf16 v[112:115], v[152:155], v[160:163], v[112:115]
	v_mfma_f32_16x16x32_bf16 v[100:103], v[144:147], v[168:171], v[100:103]
	v_mfma_f32_16x16x32_bf16 v[96:99], v[152:155], v[168:171], v[96:99]
	v_mfma_f32_16x16x32_bf16 v[84:87], v[144:147], v[176:179], v[84:87]
	v_mfma_f32_16x16x32_bf16 v[80:83], v[152:155], v[176:179], v[80:83]
	v_mfma_f32_16x16x32_bf16 v[68:71], v[144:147], v[184:187], v[68:71]
	v_mfma_f32_16x16x32_bf16 v[64:67], v[152:155], v[184:187], v[64:67]
	v_mfma_f32_16x16x32_bf16 v[116:119], v[148:151], v[164:167], v[116:119]
	v_mfma_f32_16x16x32_bf16 v[112:115], v[156:159], v[164:167], v[112:115]
	v_mfma_f32_16x16x32_bf16 v[100:103], v[148:151], v[172:175], v[100:103]
	v_mfma_f32_16x16x32_bf16 v[96:99], v[156:159], v[172:175], v[96:99]
	v_mfma_f32_16x16x32_bf16 v[84:87], v[148:151], v[180:183], v[84:87]
	v_mfma_f32_16x16x32_bf16 v[80:83], v[156:159], v[180:183], v[80:83]
	v_mfma_f32_16x16x32_bf16 v[68:71], v[148:151], v[222:225], v[68:71]
	v_mfma_f32_16x16x32_bf16 v[64:67], v[156:159], v[222:225], v[64:67]
	s_barrier
	s_setprio 0
	s_add_i32 s31, s54, s29
	s_mov_b32 m0, s31
	ds_read_b128 v[160:163], v220 offset:16384
	ds_read_b128 v[164:167], v220 offset:17408
	ds_read_b128 v[168:171], v220 offset:18432
	ds_read_b128 v[172:175], v220 offset:19456
	ds_read_b128 v[176:179], v220 offset:20480
	ds_read_b128 v[180:183], v220 offset:21504
	ds_read_b128 v[184:187], v220 offset:22528
	ds_read_b128 v[222:225], v220 offset:23552
	global_load_lds_dwordx4 v190, s[44:45] sc0
	s_add_i32 m0, s31, 0x2000
	s_add_u32 s54, s44, 0x80000
	s_addc_u32 s55, s45, 0
	s_add_i32 s21, s21, s29
	global_load_lds_dwordx4 v212, s[44:45] sc0
	s_mov_b32 m0, s21
	s_nop 0
	global_load_lds_dwordx4 v190, s[54:55] sc0
	s_add_i32 m0, s21, 0x2000
	s_nop 0
	global_load_lds_dwordx4 v212, s[54:55] sc0
	s_mov_b32 m0, s53
	s_nop 0
	global_load_lds_dwordx4 v188, s[48:49] sc0
	s_mov_b32 m0, s56
	s_nop 0
	global_load_lds_dwordx4 v210, s[48:49] sc0
	s_waitcnt vmcnt(8)
	s_waitcnt lgkmcnt(0)
	s_setprio 1
	s_barrier
	v_mfma_f32_16x16x32_bf16 v[60:63], v[120:123], v[160:163], v[60:63]
	v_mfma_f32_16x16x32_bf16 v[56:59], v[128:131], v[160:163], v[56:59]
	v_mfma_f32_16x16x32_bf16 v[44:47], v[120:123], v[168:171], v[44:47]
	v_mfma_f32_16x16x32_bf16 v[40:43], v[128:131], v[168:171], v[40:43]
	v_mfma_f32_16x16x32_bf16 v[28:31], v[120:123], v[176:179], v[28:31]
	v_mfma_f32_16x16x32_bf16 v[24:27], v[128:131], v[176:179], v[24:27]
	v_mfma_f32_16x16x32_bf16 v[12:15], v[120:123], v[184:187], v[12:15]
	v_mfma_f32_16x16x32_bf16 v[8:11], v[128:131], v[184:187], v[8:11]
	v_mfma_f32_16x16x32_bf16 v[60:63], v[124:127], v[164:167], v[60:63]
	v_mfma_f32_16x16x32_bf16 v[56:59], v[136:139], v[164:167], v[56:59]
	v_mfma_f32_16x16x32_bf16 v[44:47], v[124:127], v[172:175], v[44:47]
	v_mfma_f32_16x16x32_bf16 v[40:43], v[136:139], v[172:175], v[40:43]
	v_mfma_f32_16x16x32_bf16 v[28:31], v[124:127], v[180:183], v[28:31]
	v_mfma_f32_16x16x32_bf16 v[24:27], v[136:139], v[180:183], v[24:27]
	v_mfma_f32_16x16x32_bf16 v[12:15], v[124:127], v[222:225], v[12:15]
	v_mfma_f32_16x16x32_bf16 v[8:11], v[136:139], v[222:225], v[8:11]
	s_setprio 0
	s_setprio 1
	v_mfma_f32_16x16x32_bf16 v[52:55], v[144:147], v[160:163], v[52:55]
	v_mfma_f32_16x16x32_bf16 v[48:51], v[152:155], v[160:163], v[48:51]
	v_mfma_f32_16x16x32_bf16 v[36:39], v[144:147], v[168:171], v[36:39]
	v_mfma_f32_16x16x32_bf16 v[32:35], v[152:155], v[168:171], v[32:35]
	v_mfma_f32_16x16x32_bf16 v[20:23], v[144:147], v[176:179], v[20:23]
	v_mfma_f32_16x16x32_bf16 v[16:19], v[152:155], v[176:179], v[16:19]
	v_mfma_f32_16x16x32_bf16 v[4:7], v[144:147], v[184:187], v[4:7]
	v_mfma_f32_16x16x32_bf16 v[0:3], v[152:155], v[184:187], v[0:3]
	v_mfma_f32_16x16x32_bf16 v[52:55], v[148:151], v[164:167], v[52:55]
	v_mfma_f32_16x16x32_bf16 v[48:51], v[156:159], v[164:167], v[48:51]
	v_mfma_f32_16x16x32_bf16 v[36:39], v[148:151], v[172:175], v[36:39]
	v_mfma_f32_16x16x32_bf16 v[32:35], v[156:159], v[172:175], v[32:35]
	v_mfma_f32_16x16x32_bf16 v[20:23], v[148:151], v[180:183], v[20:23]
	v_mfma_f32_16x16x32_bf16 v[16:19], v[156:159], v[180:183], v[16:19]
	v_mfma_f32_16x16x32_bf16 v[4:7], v[148:151], v[222:225], v[4:7]
	v_mfma_f32_16x16x32_bf16 v[0:3], v[156:159], v[222:225], v[0:3]
	s_barrier
; #define PG8_STAGE(bufoff, gbase, voff) do { _Pragma("unroll") for (int _i = 0; _i < 2; ++_i) \
;         __builtin_amdgcn_global_load_lds((const unsigned*)((const char*)(gbase) + (voff)[_i]), (PG8_LAS unsigned*)(lds + (bufoff) + ldsw + _i * 8192), 16, 0, 0); } while (0)
; #define PG8_LDA(dst, b, h) do { _Pragma("unroll") for (int m = 0; m < 4; ++m) _Pragma("unroll") for (int k = 0; k < 2; ++k) dst[m][k] = *(const PG8_LAS bf16x8*)(lds + PG8_SA(b, h) + aoff + m * 2048 + k * 1024); } while (0)
; #define PG8_LDB(dst, b, h) do { _Pragma("unroll") for (int n = 0; n < 2; ++n) _Pragma("unroll") for (int k = 0; k < 2; ++k) dst[n][k] = *(const PG8_LAS bf16x8*)(lds + PG8_SB(b, h) + boff + n * 2048 + k * 1024); } while (0)
; #define PG8_MMA(ai, bj, At, Bt) do { __builtin_amdgcn_s_setprio(1); _Pragma("unroll") for (int m = 0; m < 4; ++m) _Pragma("unroll") for (int n = 0; n < 2; ++n) _Pragma("unroll") for (int k = 0; k < 2; ++k) \
;         acc[ai][bj][m][n] = __builtin_amdgcn_mfma_f32_16x16x32_bf16(Bt[n][k], At[m][k], acc[ai][bj][m][n], 0, 0, 0); __builtin_amdgcn_s_setprio(0); } while (0)
; #define PG8_WAIT_V(n) asm volatile("s_waitcnt vmcnt(" #n ")" ::: "memory")
; #define PG8_WAIT_L(n) asm volatile("s_waitcnt lgkmcnt(" #n ")" ::: "memory")
; #define PG8_BAR __builtin_amdgcn_s_barrier()
; #define PG8_SCHED __builtin_amdgcn_sched_barrier(0)
; template <class Epi>
; __device__ __forceinline__ void gemm_phase(PG8_LAS unsigned char* lds, PG8_LAS unsigned char* xl, const Gemm g, const Sched& S, const Epi& E, const int wid) {
;     ...
;             PG8_LDB(B0, 1, 0); PG8_LDB(B1, 1, 1); PG8_SCHED; PG8_LDA(At, 1, 0); PG8_STAGE(PG8_SA(0, 1), a2 + hstepA, voffA);
;             PG8_WAIT_V(8); PG8_WAIT_L(0); PG8_BAR; if (do0) { PG8_MMA(0, 0, At, B0); PG8_MMA(0, 1, At, B1); } PG8_BAR; PG8_SCHED;
;             PG8_LDA(At, 1, 1); PG8_STAGE(PG8_SB(1, 0), b3, voffB); PG8_STAGE(PG8_SB(1, 1), b3 + hstepB, voffB); PG8_STAGE(PG8_SA(1, 0), a3, voffA);
;             PG8_WAIT_V(8); PG8_WAIT_L(0); PG8_BAR; if (do1) { PG8_MMA(1, 0, At, B0); PG8_MMA(1, 1, At, B1); } PG8_BAR; PG8_SCHED;
;         }
;         if (wr == 0) PG8_BAR;
	s_setprio 0
	s_add_i32 s21, 0, 0x18000
	s_add_i32 s31, 0, 0x1c000
	ds_read_b128 v[120:123], v226 offset:32768
	ds_read_b128 v[124:127], v226 offset:33792
	ds_read_b128 v[128:131], v226 offset:34816
	ds_read_b128 v[136:139], v226 offset:35840
	ds_read_b128 v[144:147], v226 offset:49152
	ds_read_b128 v[148:151], v226 offset:50176
	ds_read_b128 v[152:155], v226 offset:51200
	ds_read_b128 v[156:159], v226 offset:52224
	s_add_u32 s100, s48, 0x2c0000
	s_addc_u32 s101, s49, 0
	s_mov_b32 m0, s57
	ds_read_b128 v[160:163], v220 offset:32768
	ds_read_b128 v[164:167], v220 offset:33792
	ds_read_b128 v[168:171], v220 offset:34816
	ds_read_b128 v[172:175], v220 offset:35840
	ds_read_b128 v[176:179], v220 offset:36864
	ds_read_b128 v[180:183], v220 offset:37888
	ds_read_b128 v[184:187], v220 offset:38912
	ds_read_b128 v[222:225], v220 offset:39936
	global_load_lds_dwordx4 v188, s[100:101] sc0
	s_mov_b32 m0, s58
	s_nop 0
	global_load_lds_dwordx4 v210, s[100:101] sc0
	s_waitcnt vmcnt(8)
	s_waitcnt lgkmcnt(0)
	s_setprio 1
	s_barrier
	v_mfma_f32_16x16x32_bf16 v[140:143], v[120:123], v[160:163], v[140:143]
	v_mfma_f32_16x16x32_bf16 v[132:135], v[128:131], v[160:163], v[132:135]
	v_mfma_f32_16x16x32_bf16 v[108:111], v[120:123], v[168:171], v[108:111]
	v_mfma_f32_16x16x32_bf16 v[104:107], v[128:131], v[168:171], v[104:107]
	v_mfma_f32_16x16x32_bf16 v[92:95], v[120:123], v[176:179], v[92:95]
	v_mfma_f32_16x16x32_bf16 v[88:91], v[128:131], v[176:179], v[88:91]
	v_mfma_f32_16x16x32_bf16 v[76:79], v[120:123], v[184:187], v[76:79]
	v_mfma_f32_16x16x32_bf16 v[72:75], v[128:131], v[184:187], v[72:75]
	v_mfma_f32_16x16x32_bf16 v[140:143], v[124:127], v[164:167], v[140:143]
	v_mfma_f32_16x16x32_bf16 v[132:135], v[136:139], v[164:167], v[132:135]
	v_mfma_f32_16x16x32_bf16 v[108:111], v[124:127], v[172:175], v[108:111]
	v_mfma_f32_16x16x32_bf16 v[104:107], v[136:139], v[172:175], v[104:107]
	v_mfma_f32_16x16x32_bf16 v[92:95], v[124:127], v[180:183], v[92:95]
	v_mfma_f32_16x16x32_bf16 v[88:91], v[136:139], v[180:183], v[88:91]
	v_mfma_f32_16x16x32_bf16 v[76:79], v[124:127], v[222:225], v[76:79]
	v_mfma_f32_16x16x32_bf16 v[72:75], v[136:139], v[222:225], v[72:75]
	s_setprio 0
	s_setprio 1
	v_mfma_f32_16x16x32_bf16 v[116:119], v[144:147], v[160:163], v[116:119]
	v_mfma_f32_16x16x32_bf16 v[112:115], v[152:155], v[160:163], v[112:115]
	v_mfma_f32_16x16x32_bf16 v[100:103], v[144:147], v[168:171], v[100:103]
	v_mfma_f32_16x16x32_bf16 v[96:99], v[152:155], v[168:171], v[96:99]
	v_mfma_f32_16x16x32_bf16 v[84:87], v[144:147], v[176:179], v[84:87]
	v_mfma_f32_16x16x32_bf16 v[80:83], v[152:155], v[176:179], v[80:83]
	v_mfma_f32_16x16x32_bf16 v[68:71], v[144:147], v[184:187], v[68:71]
	v_mfma_f32_16x16x32_bf16 v[64:67], v[152:155], v[184:187], v[64:67]
	v_mfma_f32_16x16x32_bf16 v[116:119], v[148:151], v[164:167], v[116:119]
	v_mfma_f32_16x16x32_bf16 v[112:115], v[156:159], v[164:167], v[112:115]
	v_mfma_f32_16x16x32_bf16 v[100:103], v[148:151], v[172:175], v[100:103]
	v_mfma_f32_16x16x32_bf16 v[96:99], v[156:159], v[172:175], v[96:99]
	v_mfma_f32_16x16x32_bf16 v[84:87], v[148:151], v[180:183], v[84:87]
	v_mfma_f32_16x16x32_bf16 v[80:83], v[156:159], v[180:183], v[80:83]
	v_mfma_f32_16x16x32_bf16 v[68:71], v[148:151], v[222:225], v[68:71]
	v_mfma_f32_16x16x32_bf16 v[64:67], v[156:159], v[222:225], v[64:67]
	s_barrier
	s_setprio 0
	s_add_i32 s21, s21, s29
	s_mov_b32 m0, s21
	ds_read_b128 v[160:163], v220 offset:49152
	ds_read_b128 v[164:167], v220 offset:50176
	ds_read_b128 v[168:171], v220 offset:51200
	ds_read_b128 v[172:175], v220 offset:52224
	ds_read_b128 v[176:179], v220 offset:53248
	ds_read_b128 v[180:183], v220 offset:54272
	ds_read_b128 v[184:187], v220 offset:55296
	ds_read_b128 v[222:225], v220 offset:56320
	global_load_lds_dwordx4 v205, s[44:45] sc0
	s_add_i32 m0, s21, 0x2000
	s_add_u32 s100, s44, 0x80080
	global_load_lds_dwordx4 v219, s[44:45] sc0
	s_addc_u32 s101, s45, 0
	s_add_i32 s21, s31, s29
	s_mov_b32 m0, s21
	s_nop 0
	global_load_lds_dwordx4 v190, s[100:101] sc0
	s_add_i32 m0, s21, 0x2000
	s_nop 0
	global_load_lds_dwordx4 v212, s[100:101] sc0
	s_mov_b32 m0, s66
	s_nop 0
	global_load_lds_dwordx4 v204, s[48:49] sc0
	s_mov_b32 m0, s67
	s_nop 0
	global_load_lds_dwordx4 v218, s[48:49] sc0
	s_waitcnt vmcnt(8)
	s_waitcnt lgkmcnt(0)
	s_setprio 1
	s_barrier
	v_mfma_f32_16x16x32_bf16 v[60:63], v[120:123], v[160:163], v[60:63]
	v_mfma_f32_16x16x32_bf16 v[56:59], v[128:131], v[160:163], v[56:59]
	v_mfma_f32_16x16x32_bf16 v[44:47], v[120:123], v[168:171], v[44:47]
	v_mfma_f32_16x16x32_bf16 v[40:43], v[128:131], v[168:171], v[40:43]
	v_mfma_f32_16x16x32_bf16 v[28:31], v[120:123], v[176:179], v[28:31]
	v_mfma_f32_16x16x32_bf16 v[24:27], v[128:131], v[176:179], v[24:27]
	v_mfma_f32_16x16x32_bf16 v[12:15], v[120:123], v[184:187], v[12:15]
	v_mfma_f32_16x16x32_bf16 v[8:11], v[128:131], v[184:187], v[8:11]
	v_mfma_f32_16x16x32_bf16 v[60:63], v[124:127], v[164:167], v[60:63]
	v_mfma_f32_16x16x32_bf16 v[56:59], v[136:139], v[164:167], v[56:59]
	v_mfma_f32_16x16x32_bf16 v[44:47], v[124:127], v[172:175], v[44:47]
	v_mfma_f32_16x16x32_bf16 v[40:43], v[136:139], v[172:175], v[40:43]
	v_mfma_f32_16x16x32_bf16 v[28:31], v[124:127], v[180:183], v[28:31]
	v_mfma_f32_16x16x32_bf16 v[24:27], v[136:139], v[180:183], v[24:27]
	v_mfma_f32_16x16x32_bf16 v[12:15], v[124:127], v[222:225], v[12:15]
	v_mfma_f32_16x16x32_bf16 v[8:11], v[136:139], v[222:225], v[8:11]
	s_setprio 0
	s_setprio 1
	v_mfma_f32_16x16x32_bf16 v[52:55], v[144:147], v[160:163], v[52:55]
	v_mfma_f32_16x16x32_bf16 v[48:51], v[152:155], v[160:163], v[48:51]
	v_mfma_f32_16x16x32_bf16 v[36:39], v[144:147], v[168:171], v[36:39]
	v_mfma_f32_16x16x32_bf16 v[32:35], v[152:155], v[168:171], v[32:35]
	v_mfma_f32_16x16x32_bf16 v[20:23], v[144:147], v[176:179], v[20:23]
	v_mfma_f32_16x16x32_bf16 v[16:19], v[152:155], v[176:179], v[16:19]
	v_mfma_f32_16x16x32_bf16 v[4:7], v[144:147], v[184:187], v[4:7]
	v_mfma_f32_16x16x32_bf16 v[0:3], v[152:155], v[184:187], v[0:3]
	v_mfma_f32_16x16x32_bf16 v[52:55], v[148:151], v[164:167], v[52:55]
	v_mfma_f32_16x16x32_bf16 v[48:51], v[156:159], v[164:167], v[48:51]
	v_mfma_f32_16x16x32_bf16 v[36:39], v[148:151], v[172:175], v[36:39]
	v_mfma_f32_16x16x32_bf16 v[32:35], v[156:159], v[172:175], v[32:35]
	v_mfma_f32_16x16x32_bf16 v[20:23], v[148:151], v[180:183], v[20:23]
	v_mfma_f32_16x16x32_bf16 v[16:19], v[156:159], v[180:183], v[16:19]
	v_mfma_f32_16x16x32_bf16 v[4:7], v[148:151], v[222:225], v[4:7]
	v_mfma_f32_16x16x32_bf16 v[0:3], v[156:159], v[222:225], v[0:3]
	s_barrier
	s_setprio 0
	s_add_i32 s13, s13, 2
	s_add_u32 s42, s42, 0x100
	s_addc_u32 s43, s43, 0
	s_add_u32 s10, s10, 0x100
	s_addc_u32 s11, s11, 0
	s_cmp_gt_u32 s13, 29
	s_cbranch_scc0 .LBB0_765
	s_mov_b32 s100, 0
	s_and_b64 vcc, exec, s[14:15]
	s_cbranch_vccz .LBB0_768
	s_barrier

; __device__ __forceinline__ int lane_id_opq() { int l; asm volatile("v_mbcnt_lo_u32_b32 %0, -1, 0\n\tv_mbcnt_hi_u32_b32 %0, -1, %0" : "=v"(l)); return l; }
; #define PG8_STAGE(bufoff, gbase, voff) do { _Pragma("unroll") for (int _i = 0; _i < 2; ++_i) \
;         __builtin_amdgcn_global_load_lds((const unsigned*)((const char*)(gbase) + (voff)[_i]), (PG8_LAS unsigned*)(lds + (bufoff) + ldsw + _i * 8192), 16, 0, 0); } while (0)
; #define PG8_LDA(dst, b, h) do { _Pragma("unroll") for (int m = 0; m < 4; ++m) _Pragma("unroll") for (int k = 0; k < 2; ++k) dst[m][k] = *(const PG8_LAS bf16x8*)(lds + PG8_SA(b, h) + aoff + m * 2048 + k * 1024); } while (0)
; #define PG8_LDB(dst, b, h) do { _Pragma("unroll") for (int n = 0; n < 2; ++n) _Pragma("unroll") for (int k = 0; k < 2; ++k) dst[n][k] = *(const PG8_LAS bf16x8*)(lds + PG8_SB(b, h) + boff + n * 2048 + k * 1024); } while (0)
; #define PG8_BAR __builtin_amdgcn_s_barrier()
; template <class Epi>
; __device__ __forceinline__ void gemm_phase(PG8_LAS unsigned char* lds, PG8_LAS unsigned char* xl, const Gemm g, const Sched& S, const Epi& E, const int wid) {
;     ...
;             const bool last = (t == nt - 2);
;             const bool do0 = !blkdiag_v<Epi> || t == 0, do1 = !blkdiag_v<Epi> || t != 0;
;             long j1 = 0, ja2 = 0, jb2 = 0;
;             if constexpr (Epi::MID) {
;                 if (t == g.tj) { const int lnM = lane_id_opq(); E.mid(acc, cur, wr, wc, lnM & 15, lnM >> 4); }
;                 if (t >= g.tj) j1 = g.jA;
;                 if (t + 2 >= g.tj) { ja2 = g.jA; jb2 = g.jB; } }
;             const char* a1 = cA + (size_t)(t + 1) * kstep + j1;
;             const char* a2 = last ? nA : cA + (size_t)(t + 2) * kstep + ja2; const char* b2 = last ? nB : cB + (size_t)(t + 2) * kstep + jb2;
;             const char* a3 = a2 + kstep; const char* b3 = b2 + kstep;
;             PG8_LDB(B0, 0, 0); PG8_LDB(B1, 0, 1); PG8_SCHED; PG8_LDA(At, 0, 0); PG8_STAGE(PG8_SA(1, 1), a1 + hstepA, voffA);
;             PG8_WAIT_V(8); PG8_WAIT_L(0); PG8_BAR; if (do0) { PG8_MMA(0, 0, At, B0); PG8_MMA(0, 1, At, B1); } PG8_BAR; PG8_SCHED;
;             PG8_LDA(At, 0, 1); PG8_STAGE(PG8_SB(0, 0), b2, voffB); PG8_STAGE(PG8_SB(0, 1), b2 + hstepB, voffB); PG8_STAGE(PG8_SA(0, 0), a2, voffA);
;             PG8_WAIT_V(8); PG8_WAIT_L(0); PG8_BAR; if (do1) { PG8_MMA(1, 0, At, B0); PG8_MMA(1, 1, At, B1); } PG8_BAR; PG8_SCHED;
.Ldefbar_skip_7:
	v_add_u32_e32 v204, s22, v184
	v_add_u32_e32 v205, s22, v186
	v_add_u32_e32 v214, s22, v188
	v_add_u32_e32 v215, s22, v190
	v_add_u32_e32 v226, 0x10000, v195
	s_add_u32 s46, s48, 0x100
	s_addc_u32 s47, s49, 0
	s_add_i32 s11, 0, 0x10000
	s_cmp_eq_u32 s10, 28
	s_cselect_b32 vcc_hi, s59, s47
	s_cselect_b32 vcc_lo, s58, s46
	s_cselect_b32 s51, s21, s9
	s_cselect_b32 s50, s20, s8
	s_add_i32 s13, 0, 0x14000
	ds_read_b128 v[120:123], v226 offset:0
	ds_read_b128 v[124:127], v226 offset:1024
	ds_read_b128 v[136:139], v226 offset:2048
	ds_read_b128 v[140:143], v226 offset:3072
	ds_read_b128 v[144:147], v226 offset:16384
	ds_read_b128 v[148:151], v226 offset:17408
	ds_read_b128 v[152:155], v226 offset:18432
	ds_read_b128 v[156:159], v226 offset:19456
	s_add_i32 m0, s89, 0xc000
	ds_read_b128 v[160:163], v216
	ds_read_b128 v[164:167], v216 offset:1024
	ds_read_b128 v[168:171], v216 offset:2048
	ds_read_b128 v[172:175], v216 offset:3072
	ds_read_b128 v[176:179], v216 offset:4096
	ds_read_b128 v[180:183], v216 offset:5120
	ds_read_b128 v[218:221], v216 offset:6144
	ds_read_b128 v[222:225], v216 offset:7168
	global_load_lds_dwordx4 v210, s[48:49] sc0
	s_add_i32 m0, s89, 0xe000
	s_nop 0
	global_load_lds_dwordx4 v212, s[48:49] sc0
	s_waitcnt vmcnt(8)
	s_waitcnt lgkmcnt(0)
	s_setprio 1
	s_barrier
	v_mfma_f32_16x16x32_bf16 v[132:135], v[120:123], v[160:163], 0
	v_mfma_f32_16x16x32_bf16 v[128:131], v[136:139], v[160:163], 0
	v_mfma_f32_16x16x32_bf16 v[108:111], v[120:123], v[168:171], 0
	v_mfma_f32_16x16x32_bf16 v[104:107], v[136:139], v[168:171], 0
	v_mfma_f32_16x16x32_bf16 v[92:95], v[120:123], v[176:179], 0
	v_mfma_f32_16x16x32_bf16 v[88:91], v[136:139], v[176:179], 0
	v_mfma_f32_16x16x32_bf16 v[76:79], v[120:123], v[218:221], 0
	v_mfma_f32_16x16x32_bf16 v[72:75], v[136:139], v[218:221], 0
	v_mfma_f32_16x16x32_bf16 v[132:135], v[124:127], v[164:167], v[132:135]
	v_mfma_f32_16x16x32_bf16 v[128:131], v[140:143], v[164:167], v[128:131]
	v_mfma_f32_16x16x32_bf16 v[108:111], v[124:127], v[172:175], v[108:111]
	v_mfma_f32_16x16x32_bf16 v[104:107], v[140:143], v[172:175], v[104:107]
	v_mfma_f32_16x16x32_bf16 v[92:95], v[124:127], v[180:183], v[92:95]
	v_mfma_f32_16x16x32_bf16 v[88:91], v[140:143], v[180:183], v[88:91]
	v_mfma_f32_16x16x32_bf16 v[76:79], v[124:127], v[222:225], v[76:79]
	v_mfma_f32_16x16x32_bf16 v[72:75], v[140:143], v[222:225], v[72:75]
	s_setprio 0
	s_setprio 1
	v_mfma_f32_16x16x32_bf16 v[116:119], v[144:147], v[160:163], 0
	v_mfma_f32_16x16x32_bf16 v[112:115], v[152:155], v[160:163], 0
	v_mfma_f32_16x16x32_bf16 v[100:103], v[144:147], v[168:171], 0
	v_mfma_f32_16x16x32_bf16 v[96:99], v[152:155], v[168:171], 0
	v_mfma_f32_16x16x32_bf16 v[84:87], v[144:147], v[176:179], 0
	v_mfma_f32_16x16x32_bf16 v[80:83], v[152:155], v[176:179], 0
	v_mfma_f32_16x16x32_bf16 v[68:71], v[144:147], v[218:221], 0
	v_mfma_f32_16x16x32_bf16 v[64:67], v[152:155], v[218:221], 0
	v_mfma_f32_16x16x32_bf16 v[116:119], v[148:151], v[164:167], v[116:119]
	v_mfma_f32_16x16x32_bf16 v[112:115], v[156:159], v[164:167], v[112:115]
	v_mfma_f32_16x16x32_bf16 v[100:103], v[148:151], v[172:175], v[100:103]
	v_mfma_f32_16x16x32_bf16 v[96:99], v[156:159], v[172:175], v[96:99]
	v_mfma_f32_16x16x32_bf16 v[84:87], v[148:151], v[180:183], v[84:87]
	v_mfma_f32_16x16x32_bf16 v[80:83], v[156:159], v[180:183], v[80:83]
	v_mfma_f32_16x16x32_bf16 v[68:71], v[148:151], v[222:225], v[68:71]
	v_mfma_f32_16x16x32_bf16 v[64:67], v[156:159], v[222:225], v[64:67]
	s_barrier
	s_setprio 0
	s_add_i32 s11, s11, s29
	s_mov_b32 m0, s11
	ds_read_b128 v[160:163], v216 offset:16384
	ds_read_b128 v[164:167], v216 offset:17408
	ds_read_b128 v[168:171], v216 offset:18432
	ds_read_b128 v[172:175], v216 offset:19456
	ds_read_b128 v[176:179], v216 offset:20480
	ds_read_b128 v[180:183], v216 offset:21504
	ds_read_b128 v[218:221], v216 offset:22528
	ds_read_b128 v[222:225], v216 offset:23552
	global_load_lds_dwordx4 v186, s[50:51] sc0
	s_add_i32 m0, s11, 0x2000
	s_add_u32 s48, s50, 0x80000
	s_addc_u32 s49, s51, 0
	s_add_i32 s11, s13, s29
	global_load_lds_dwordx4 v190, s[50:51] sc0
	s_mov_b32 m0, s11
	s_nop 0
	global_load_lds_dwordx4 v186, s[48:49] sc0
	s_add_i32 m0, s11, 0x2000
	s_nop 0
	global_load_lds_dwordx4 v190, s[48:49] sc0
	s_mov_b32 m0, s89
	s_nop 0
	global_load_lds_dwordx4 v184, vcc sc0
	s_mov_b32 m0, s90
	s_nop 0
	global_load_lds_dwordx4 v188, vcc sc0
	s_waitcnt vmcnt(8)
	s_waitcnt lgkmcnt(0)
	s_setprio 1
	s_barrier
	v_mfma_f32_16x16x32_bf16 v[60:63], v[120:123], v[160:163], 0
	v_mfma_f32_16x16x32_bf16 v[56:59], v[136:139], v[160:163], 0
	v_mfma_f32_16x16x32_bf16 v[44:47], v[120:123], v[168:171], 0
	v_mfma_f32_16x16x32_bf16 v[40:43], v[136:139], v[168:171], 0
	v_mfma_f32_16x16x32_bf16 v[28:31], v[120:123], v[176:179], 0
	v_mfma_f32_16x16x32_bf16 v[24:27], v[136:139], v[176:179], 0
	v_mfma_f32_16x16x32_bf16 v[12:15], v[120:123], v[218:221], 0
	v_mfma_f32_16x16x32_bf16 v[8:11], v[136:139], v[218:221], 0
	v_mfma_f32_16x16x32_bf16 v[60:63], v[124:127], v[164:167], v[60:63]
	v_mfma_f32_16x16x32_bf16 v[56:59], v[140:143], v[164:167], v[56:59]
	v_mfma_f32_16x16x32_bf16 v[44:47], v[124:127], v[172:175], v[44:47]
	v_mfma_f32_16x16x32_bf16 v[40:43], v[140:143], v[172:175], v[40:43]
	v_mfma_f32_16x16x32_bf16 v[28:31], v[124:127], v[180:183], v[28:31]
	v_mfma_f32_16x16x32_bf16 v[24:27], v[140:143], v[180:183], v[24:27]
	v_mfma_f32_16x16x32_bf16 v[12:15], v[124:127], v[222:225], v[12:15]
	v_mfma_f32_16x16x32_bf16 v[8:11], v[140:143], v[222:225], v[8:11]
	s_setprio 0
	s_setprio 1
	v_mfma_f32_16x16x32_bf16 v[52:55], v[144:147], v[160:163], 0
	v_mfma_f32_16x16x32_bf16 v[48:51], v[152:155], v[160:163], 0
	v_mfma_f32_16x16x32_bf16 v[36:39], v[144:147], v[168:171], 0
	v_mfma_f32_16x16x32_bf16 v[32:35], v[152:155], v[168:171], 0
	v_mfma_f32_16x16x32_bf16 v[20:23], v[144:147], v[176:179], 0
	v_mfma_f32_16x16x32_bf16 v[16:19], v[152:155], v[176:179], 0
	v_mfma_f32_16x16x32_bf16 v[4:7], v[144:147], v[218:221], 0
	v_mfma_f32_16x16x32_bf16 v[0:3], v[152:155], v[218:221], 0
	v_mfma_f32_16x16x32_bf16 v[52:55], v[148:151], v[164:167], v[52:55]
	v_mfma_f32_16x16x32_bf16 v[48:51], v[156:159], v[164:167], v[48:51]
	v_mfma_f32_16x16x32_bf16 v[36:39], v[148:151], v[172:175], v[36:39]
	v_mfma_f32_16x16x32_bf16 v[32:35], v[156:159], v[172:175], v[32:35]
	v_mfma_f32_16x16x32_bf16 v[20:23], v[148:151], v[180:183], v[20:23]
	v_mfma_f32_16x16x32_bf16 v[16:19], v[156:159], v[180:183], v[16:19]
	v_mfma_f32_16x16x32_bf16 v[4:7], v[148:151], v[222:225], v[4:7]
	v_mfma_f32_16x16x32_bf16 v[0:3], v[156:159], v[222:225], v[0:3]
	s_barrier
; #define PG8_STAGE(bufoff, gbase, voff) do { _Pragma("unroll") for (int _i = 0; _i < 2; ++_i) \
;         __builtin_amdgcn_global_load_lds((const unsigned*)((const char*)(gbase) + (voff)[_i]), (PG8_LAS unsigned*)(lds + (bufoff) + ldsw + _i * 8192), 16, 0, 0); } while (0)
; #define PG8_LDA(dst, b, h) do { _Pragma("unroll") for (int m = 0; m < 4; ++m) _Pragma("unroll") for (int k = 0; k < 2; ++k) dst[m][k] = *(const PG8_LAS bf16x8*)(lds + PG8_SA(b, h) + aoff + m * 2048 + k * 1024); } while (0)
; #define PG8_LDB(dst, b, h) do { _Pragma("unroll") for (int n = 0; n < 2; ++n) _Pragma("unroll") for (int k = 0; k < 2; ++k) dst[n][k] = *(const PG8_LAS bf16x8*)(lds + PG8_SB(b, h) + boff + n * 2048 + k * 1024); } while (0)
; #define PG8_MMA(ai, bj, At, Bt) do { __builtin_amdgcn_s_setprio(1); _Pragma("unroll") for (int m = 0; m < 4; ++m) _Pragma("unroll") for (int n = 0; n < 2; ++n) _Pragma("unroll") for (int k = 0; k < 2; ++k) \
;         acc[ai][bj][m][n] = __builtin_amdgcn_mfma_f32_16x16x32_bf16(Bt[n][k], At[m][k], acc[ai][bj][m][n], 0, 0, 0); __builtin_amdgcn_s_setprio(0); } while (0)
; #define PG8_WAIT_V(n) asm volatile("s_waitcnt vmcnt(" #n ")" ::: "memory")
; #define PG8_WAIT_L(n) asm volatile("s_waitcnt lgkmcnt(" #n ")" ::: "memory")
; #define PG8_BAR __builtin_amdgcn_s_barrier()
; #define PG8_SCHED __builtin_amdgcn_sched_barrier(0)
; template <class Epi>
; __device__ __forceinline__ void gemm_phase(PG8_LAS unsigned char* lds, PG8_LAS unsigned char* xl, const Gemm g, const Sched& S, const Epi& E, const int wid) {
;     ...
;             PG8_LDB(B0, 1, 0); PG8_LDB(B1, 1, 1); PG8_SCHED; PG8_LDA(At, 1, 0); PG8_STAGE(PG8_SA(0, 1), a2 + hstepA, voffA);
;             PG8_WAIT_V(8); PG8_WAIT_L(0); PG8_BAR; if (do0) { PG8_MMA(0, 0, At, B0); PG8_MMA(0, 1, At, B1); } PG8_BAR; PG8_SCHED;
;             PG8_LDA(At, 1, 1); PG8_STAGE(PG8_SB(1, 0), b3, voffB); PG8_STAGE(PG8_SB(1, 1), b3 + hstepB, voffB); PG8_STAGE(PG8_SA(1, 0), a3, voffA);
;             PG8_WAIT_V(8); PG8_WAIT_L(0); PG8_BAR; if (do1) { PG8_MMA(1, 0, At, B0); PG8_MMA(1, 1, At, B1); } PG8_BAR; PG8_SCHED;
;         }
	s_setprio 0
	s_add_i32 s11, 0, 0x18000
	s_add_i32 s13, 0, 0x1c000
	ds_read_b128 v[120:123], v226 offset:32768
	ds_read_b128 v[124:127], v226 offset:33792
	ds_read_b128 v[136:139], v226 offset:34816
	ds_read_b128 v[140:143], v226 offset:35840
	ds_read_b128 v[144:147], v226 offset:49152
	ds_read_b128 v[148:151], v226 offset:50176
	ds_read_b128 v[152:155], v226 offset:51200
	ds_read_b128 v[156:159], v226 offset:52224
	s_add_u32 s48, vcc_lo, 0x80000
	s_addc_u32 s49, vcc_hi, 0
	s_mov_b32 m0, s91
	ds_read_b128 v[160:163], v216 offset:32768
	ds_read_b128 v[164:167], v216 offset:33792
	ds_read_b128 v[168:171], v216 offset:34816
	ds_read_b128 v[172:175], v216 offset:35840
	ds_read_b128 v[176:179], v216 offset:36864
	ds_read_b128 v[180:183], v216 offset:37888
	ds_read_b128 v[218:221], v216 offset:38912
	ds_read_b128 v[222:225], v216 offset:39936
	global_load_lds_dwordx4 v184, s[48:49] sc0
	s_mov_b32 m0, s92
	s_nop 0
	global_load_lds_dwordx4 v188, s[48:49] sc0
	s_waitcnt vmcnt(8)
	s_waitcnt lgkmcnt(0)
	s_setprio 1
	s_barrier
	v_mfma_f32_16x16x32_bf16 v[132:135], v[120:123], v[160:163], v[132:135]
	v_mfma_f32_16x16x32_bf16 v[128:131], v[136:139], v[160:163], v[128:131]
	v_mfma_f32_16x16x32_bf16 v[108:111], v[120:123], v[168:171], v[108:111]
	v_mfma_f32_16x16x32_bf16 v[104:107], v[136:139], v[168:171], v[104:107]
	v_mfma_f32_16x16x32_bf16 v[92:95], v[120:123], v[176:179], v[92:95]
	v_mfma_f32_16x16x32_bf16 v[88:91], v[136:139], v[176:179], v[88:91]
	v_mfma_f32_16x16x32_bf16 v[76:79], v[120:123], v[218:221], v[76:79]
	v_mfma_f32_16x16x32_bf16 v[72:75], v[136:139], v[218:221], v[72:75]
	v_mfma_f32_16x16x32_bf16 v[132:135], v[124:127], v[164:167], v[132:135]
	v_mfma_f32_16x16x32_bf16 v[128:131], v[140:143], v[164:167], v[128:131]
	v_mfma_f32_16x16x32_bf16 v[108:111], v[124:127], v[172:175], v[108:111]
	v_mfma_f32_16x16x32_bf16 v[104:107], v[140:143], v[172:175], v[104:107]
	v_mfma_f32_16x16x32_bf16 v[92:95], v[124:127], v[180:183], v[92:95]
	v_mfma_f32_16x16x32_bf16 v[88:91], v[140:143], v[180:183], v[88:91]
	v_mfma_f32_16x16x32_bf16 v[76:79], v[124:127], v[222:225], v[76:79]
	v_mfma_f32_16x16x32_bf16 v[72:75], v[140:143], v[222:225], v[72:75]
	s_setprio 0
	s_setprio 1
	v_mfma_f32_16x16x32_bf16 v[116:119], v[144:147], v[160:163], v[116:119]
	v_mfma_f32_16x16x32_bf16 v[112:115], v[152:155], v[160:163], v[112:115]
	v_mfma_f32_16x16x32_bf16 v[100:103], v[144:147], v[168:171], v[100:103]
	v_mfma_f32_16x16x32_bf16 v[96:99], v[152:155], v[168:171], v[96:99]
	v_mfma_f32_16x16x32_bf16 v[84:87], v[144:147], v[176:179], v[84:87]
	v_mfma_f32_16x16x32_bf16 v[80:83], v[152:155], v[176:179], v[80:83]
	v_mfma_f32_16x16x32_bf16 v[68:71], v[144:147], v[218:221], v[68:71]
	v_mfma_f32_16x16x32_bf16 v[64:67], v[152:155], v[218:221], v[64:67]
	v_mfma_f32_16x16x32_bf16 v[116:119], v[148:151], v[164:167], v[116:119]
	v_mfma_f32_16x16x32_bf16 v[112:115], v[156:159], v[164:167], v[112:115]
	v_mfma_f32_16x16x32_bf16 v[100:103], v[148:151], v[172:175], v[100:103]
	v_mfma_f32_16x16x32_bf16 v[96:99], v[156:159], v[172:175], v[96:99]
	v_mfma_f32_16x16x32_bf16 v[84:87], v[148:151], v[180:183], v[84:87]
	v_mfma_f32_16x16x32_bf16 v[80:83], v[156:159], v[180:183], v[80:83]
	v_mfma_f32_16x16x32_bf16 v[68:71], v[148:151], v[222:225], v[68:71]
	v_mfma_f32_16x16x32_bf16 v[64:67], v[156:159], v[222:225], v[64:67]
	s_barrier
	s_setprio 0
	s_add_i32 s11, s11, s29
	s_mov_b32 m0, s11
	ds_read_b128 v[160:163], v216 offset:49152
	ds_read_b128 v[164:167], v216 offset:50176
	ds_read_b128 v[168:171], v216 offset:51200
	ds_read_b128 v[172:175], v216 offset:52224
	ds_read_b128 v[176:179], v216 offset:53248
	ds_read_b128 v[180:183], v216 offset:54272
	ds_read_b128 v[218:221], v216 offset:55296
	ds_read_b128 v[222:225], v216 offset:56320
	global_load_lds_dwordx4 v205, s[50:51] sc0
	s_add_i32 m0, s11, 0x2000
	s_add_u32 s48, s50, 0x80080
	global_load_lds_dwordx4 v215, s[50:51] sc0
	s_addc_u32 s49, s51, 0
	s_add_i32 s11, s13, s29
	s_mov_b32 m0, s11
	s_nop 0
	global_load_lds_dwordx4 v186, s[48:49] sc0
	s_add_i32 m0, s11, 0x2000
	s_nop 0
	global_load_lds_dwordx4 v190, s[48:49] sc0
	s_mov_b32 m0, s95
	s_nop 0
	global_load_lds_dwordx4 v204, vcc sc0
	s_mov_b32 m0, s96
	s_nop 0
	global_load_lds_dwordx4 v214, vcc sc0
	s_waitcnt vmcnt(8)
	s_waitcnt lgkmcnt(0)
	s_setprio 1
	s_barrier
	v_mfma_f32_16x16x32_bf16 v[60:63], v[120:123], v[160:163], v[60:63]
	v_mfma_f32_16x16x32_bf16 v[56:59], v[136:139], v[160:163], v[56:59]
	v_mfma_f32_16x16x32_bf16 v[44:47], v[120:123], v[168:171], v[44:47]
	v_mfma_f32_16x16x32_bf16 v[40:43], v[136:139], v[168:171], v[40:43]
	v_mfma_f32_16x16x32_bf16 v[28:31], v[120:123], v[176:179], v[28:31]
	v_mfma_f32_16x16x32_bf16 v[24:27], v[136:139], v[176:179], v[24:27]
	v_mfma_f32_16x16x32_bf16 v[12:15], v[120:123], v[218:221], v[12:15]
	v_mfma_f32_16x16x32_bf16 v[8:11], v[136:139], v[218:221], v[8:11]
	v_mfma_f32_16x16x32_bf16 v[60:63], v[124:127], v[164:167], v[60:63]
	v_mfma_f32_16x16x32_bf16 v[56:59], v[140:143], v[164:167], v[56:59]
	v_mfma_f32_16x16x32_bf16 v[44:47], v[124:127], v[172:175], v[44:47]
	v_mfma_f32_16x16x32_bf16 v[40:43], v[140:143], v[172:175], v[40:43]
	v_mfma_f32_16x16x32_bf16 v[28:31], v[124:127], v[180:183], v[28:31]
	v_mfma_f32_16x16x32_bf16 v[24:27], v[140:143], v[180:183], v[24:27]
	v_mfma_f32_16x16x32_bf16 v[12:15], v[124:127], v[222:225], v[12:15]
	v_mfma_f32_16x16x32_bf16 v[8:11], v[140:143], v[222:225], v[8:11]
	s_setprio 0
	s_setprio 1
	v_mfma_f32_16x16x32_bf16 v[52:55], v[144:147], v[160:163], v[52:55]
	v_mfma_f32_16x16x32_bf16 v[48:51], v[152:155], v[160:163], v[48:51]
	v_mfma_f32_16x16x32_bf16 v[36:39], v[144:147], v[168:171], v[36:39]
	v_mfma_f32_16x16x32_bf16 v[32:35], v[152:155], v[168:171], v[32:35]
	v_mfma_f32_16x16x32_bf16 v[20:23], v[144:147], v[176:179], v[20:23]
	v_mfma_f32_16x16x32_bf16 v[16:19], v[152:155], v[176:179], v[16:19]
	v_mfma_f32_16x16x32_bf16 v[4:7], v[144:147], v[218:221], v[4:7]
	v_mfma_f32_16x16x32_bf16 v[0:3], v[152:155], v[218:221], v[0:3]
	v_mfma_f32_16x16x32_bf16 v[52:55], v[148:151], v[164:167], v[52:55]
	v_mfma_f32_16x16x32_bf16 v[48:51], v[156:159], v[164:167], v[48:51]
	v_mfma_f32_16x16x32_bf16 v[36:39], v[148:151], v[172:175], v[36:39]
	v_mfma_f32_16x16x32_bf16 v[32:35], v[156:159], v[172:175], v[32:35]
	v_mfma_f32_16x16x32_bf16 v[20:23], v[148:151], v[180:183], v[20:23]
	v_mfma_f32_16x16x32_bf16 v[16:19], v[156:159], v[180:183], v[16:19]
	v_mfma_f32_16x16x32_bf16 v[4:7], v[148:151], v[222:225], v[4:7]
	v_mfma_f32_16x16x32_bf16 v[0:3], v[156:159], v[222:225], v[0:3]
	s_barrier
	s_setprio 0
	s_add_i32 s10, s10, 2
	s_add_u32 s8, s8, 0x100
	s_addc_u32 s9, s9, 0
	s_cmp_gt_u32 s10, 29
	s_mov_b64 s[48:49], s[46:47]
; __device__ __forceinline__ int lane_id_opq() { int l; asm volatile("v_mbcnt_lo_u32_b32 %0, -1, 0\n\tv_mbcnt_hi_u32_b32 %0, -1, %0" : "=v"(l)); return l; }
; #define PG8_STAGE(bufoff, gbase, voff) do { _Pragma("unroll") for (int _i = 0; _i < 2; ++_i) \
;         __builtin_amdgcn_global_load_lds((const unsigned*)((const char*)(gbase) + (voff)[_i]), (PG8_LAS unsigned*)(lds + (bufoff) + ldsw + _i * 8192), 16, 0, 0); } while (0)
; #define PG8_LDA(dst, b, h) do { _Pragma("unroll") for (int m = 0; m < 4; ++m) _Pragma("unroll") for (int k = 0; k < 2; ++k) dst[m][k] = *(const PG8_LAS bf16x8*)(lds + PG8_SA(b, h) + aoff + m * 2048 + k * 1024); } while (0)
; #define PG8_LDB(dst, b, h) do { _Pragma("unroll") for (int n = 0; n < 2; ++n) _Pragma("unroll") for (int k = 0; k < 2; ++k) dst[n][k] = *(const PG8_LAS bf16x8*)(lds + PG8_SB(b, h) + boff + n * 2048 + k * 1024); } while (0)
; #define PG8_BAR __builtin_amdgcn_s_barrier()
; template <class Epi>
; __device__ __forceinline__ void gemm_phase(PG8_LAS unsigned char* lds, PG8_LAS unsigned char* xl, const Gemm g, const Sched& S, const Epi& E, const int wid) {
;     ...
;             const bool last = (t == nt - 2);
;             const bool do0 = !blkdiag_v<Epi> || t == 0, do1 = !blkdiag_v<Epi> || t != 0;
;             long j1 = 0, ja2 = 0, jb2 = 0;
;             if constexpr (Epi::MID) {
;                 if (t == g.tj) { const int lnM = lane_id_opq(); E.mid(acc, cur, wr, wc, lnM & 15, lnM >> 4); }
;                 if (t >= g.tj) j1 = g.jA;
;                 if (t + 2 >= g.tj) { ja2 = g.jA; jb2 = g.jB; } }
;             const char* a1 = cA + (size_t)(t + 1) * kstep + j1;
;             const char* a2 = last ? nA : cA + (size_t)(t + 2) * kstep + ja2; const char* b2 = last ? nB : cB + (size_t)(t + 2) * kstep + jb2;
;             const char* a3 = a2 + kstep; const char* b3 = b2 + kstep;
;             PG8_LDB(B0, 0, 0); PG8_LDB(B1, 0, 1); PG8_SCHED; PG8_LDA(At, 0, 0); PG8_STAGE(PG8_SA(1, 1), a1 + hstepA, voffA);
;             PG8_WAIT_V(8); PG8_WAIT_L(0); PG8_BAR; if (do0) { PG8_MMA(0, 0, At, B0); PG8_MMA(0, 1, At, B1); } PG8_BAR; PG8_SCHED;
;             PG8_LDA(At, 0, 1); PG8_STAGE(PG8_SB(0, 0), b2, voffB); PG8_STAGE(PG8_SB(0, 1), b2 + hstepB, voffB); PG8_STAGE(PG8_SA(0, 0), a2, voffA);
;             PG8_WAIT_V(8); PG8_WAIT_L(0); PG8_BAR; if (do1) { PG8_MMA(1, 0, At, B0); PG8_MMA(1, 1, At, B1); } PG8_BAR; PG8_SCHED;
.LBB0_859:
	s_add_u32 s46, s48, 0x100
	s_addc_u32 s47, s49, 0
	s_add_i32 s11, 0, 0x10000
	s_cmp_eq_u32 s10, 28
	s_cselect_b32 vcc_hi, s59, s47
	s_cselect_b32 vcc_lo, s58, s46
	s_cselect_b32 s51, s21, s9
	s_cselect_b32 s50, s20, s8
	s_add_i32 s13, 0, 0x14000
	ds_read_b128 v[120:123], v226 offset:0
	ds_read_b128 v[124:127], v226 offset:1024
	ds_read_b128 v[136:139], v226 offset:2048
	ds_read_b128 v[140:143], v226 offset:3072
	ds_read_b128 v[144:147], v226 offset:16384
	ds_read_b128 v[148:151], v226 offset:17408
	ds_read_b128 v[152:155], v226 offset:18432
	ds_read_b128 v[156:159], v226 offset:19456
	s_add_i32 m0, s89, 0xc000
	ds_read_b128 v[160:163], v216
	ds_read_b128 v[164:167], v216 offset:1024
	ds_read_b128 v[168:171], v216 offset:2048
	ds_read_b128 v[172:175], v216 offset:3072
	ds_read_b128 v[176:179], v216 offset:4096
	ds_read_b128 v[180:183], v216 offset:5120
	ds_read_b128 v[218:221], v216 offset:6144
	ds_read_b128 v[222:225], v216 offset:7168
	global_load_lds_dwordx4 v210, s[48:49] sc0
	s_add_i32 m0, s89, 0xe000
	s_nop 0
	global_load_lds_dwordx4 v212, s[48:49] sc0
	s_waitcnt vmcnt(8)
	s_waitcnt lgkmcnt(0)
	s_setprio 1
	s_barrier
	v_mfma_f32_16x16x32_bf16 v[132:135], v[120:123], v[160:163], v[132:135]
	v_mfma_f32_16x16x32_bf16 v[128:131], v[136:139], v[160:163], v[128:131]
	v_mfma_f32_16x16x32_bf16 v[108:111], v[120:123], v[168:171], v[108:111]
	v_mfma_f32_16x16x32_bf16 v[104:107], v[136:139], v[168:171], v[104:107]
	v_mfma_f32_16x16x32_bf16 v[92:95], v[120:123], v[176:179], v[92:95]
	v_mfma_f32_16x16x32_bf16 v[88:91], v[136:139], v[176:179], v[88:91]
	v_mfma_f32_16x16x32_bf16 v[76:79], v[120:123], v[218:221], v[76:79]
	v_mfma_f32_16x16x32_bf16 v[72:75], v[136:139], v[218:221], v[72:75]
	v_mfma_f32_16x16x32_bf16 v[132:135], v[124:127], v[164:167], v[132:135]
	v_mfma_f32_16x16x32_bf16 v[128:131], v[140:143], v[164:167], v[128:131]
	v_mfma_f32_16x16x32_bf16 v[108:111], v[124:127], v[172:175], v[108:111]
	v_mfma_f32_16x16x32_bf16 v[104:107], v[140:143], v[172:175], v[104:107]
	v_mfma_f32_16x16x32_bf16 v[92:95], v[124:127], v[180:183], v[92:95]
	v_mfma_f32_16x16x32_bf16 v[88:91], v[140:143], v[180:183], v[88:91]
	v_mfma_f32_16x16x32_bf16 v[76:79], v[124:127], v[222:225], v[76:79]
	v_mfma_f32_16x16x32_bf16 v[72:75], v[140:143], v[222:225], v[72:75]
	s_setprio 0
	s_setprio 1
	v_mfma_f32_16x16x32_bf16 v[116:119], v[144:147], v[160:163], v[116:119]
	v_mfma_f32_16x16x32_bf16 v[112:115], v[152:155], v[160:163], v[112:115]
	v_mfma_f32_16x16x32_bf16 v[100:103], v[144:147], v[168:171], v[100:103]
	v_mfma_f32_16x16x32_bf16 v[96:99], v[152:155], v[168:171], v[96:99]
	v_mfma_f32_16x16x32_bf16 v[84:87], v[144:147], v[176:179], v[84:87]
	v_mfma_f32_16x16x32_bf16 v[80:83], v[152:155], v[176:179], v[80:83]
	v_mfma_f32_16x16x32_bf16 v[68:71], v[144:147], v[218:221], v[68:71]
	v_mfma_f32_16x16x32_bf16 v[64:67], v[152:155], v[218:221], v[64:67]
	v_mfma_f32_16x16x32_bf16 v[116:119], v[148:151], v[164:167], v[116:119]
	v_mfma_f32_16x16x32_bf16 v[112:115], v[156:159], v[164:167], v[112:115]
	v_mfma_f32_16x16x32_bf16 v[100:103], v[148:151], v[172:175], v[100:103]
	v_mfma_f32_16x16x32_bf16 v[96:99], v[156:159], v[172:175], v[96:99]
	v_mfma_f32_16x16x32_bf16 v[84:87], v[148:151], v[180:183], v[84:87]
	v_mfma_f32_16x16x32_bf16 v[80:83], v[156:159], v[180:183], v[80:83]
	v_mfma_f32_16x16x32_bf16 v[68:71], v[148:151], v[222:225], v[68:71]
	v_mfma_f32_16x16x32_bf16 v[64:67], v[156:159], v[222:225], v[64:67]
	s_barrier
	s_setprio 0
	s_add_i32 s11, s11, s29
	s_mov_b32 m0, s11
	ds_read_b128 v[160:163], v216 offset:16384
	ds_read_b128 v[164:167], v216 offset:17408
	ds_read_b128 v[168:171], v216 offset:18432
	ds_read_b128 v[172:175], v216 offset:19456
	ds_read_b128 v[176:179], v216 offset:20480
	ds_read_b128 v[180:183], v216 offset:21504
	ds_read_b128 v[218:221], v216 offset:22528
	ds_read_b128 v[222:225], v216 offset:23552
	global_load_lds_dwordx4 v186, s[50:51] sc0
	s_add_i32 m0, s11, 0x2000
	s_add_u32 s48, s50, 0x80000
	s_addc_u32 s49, s51, 0
	s_add_i32 s11, s13, s29
	global_load_lds_dwordx4 v190, s[50:51] sc0
	s_mov_b32 m0, s11
	s_nop 0
	global_load_lds_dwordx4 v186, s[48:49] sc0
	s_add_i32 m0, s11, 0x2000
	s_nop 0
	global_load_lds_dwordx4 v190, s[48:49] sc0
	s_mov_b32 m0, s89
	s_nop 0
	global_load_lds_dwordx4 v184, vcc sc0
	s_mov_b32 m0, s90
	s_nop 0
	global_load_lds_dwordx4 v188, vcc sc0
	s_waitcnt vmcnt(8)
	s_waitcnt lgkmcnt(0)
	s_setprio 1
	s_barrier
	v_mfma_f32_16x16x32_bf16 v[60:63], v[120:123], v[160:163], v[60:63]
	v_mfma_f32_16x16x32_bf16 v[56:59], v[136:139], v[160:163], v[56:59]
	v_mfma_f32_16x16x32_bf16 v[44:47], v[120:123], v[168:171], v[44:47]
	v_mfma_f32_16x16x32_bf16 v[40:43], v[136:139], v[168:171], v[40:43]
	v_mfma_f32_16x16x32_bf16 v[28:31], v[120:123], v[176:179], v[28:31]
	v_mfma_f32_16x16x32_bf16 v[24:27], v[136:139], v[176:179], v[24:27]
	v_mfma_f32_16x16x32_bf16 v[12:15], v[120:123], v[218:221], v[12:15]
	v_mfma_f32_16x16x32_bf16 v[8:11], v[136:139], v[218:221], v[8:11]
	v_mfma_f32_16x16x32_bf16 v[60:63], v[124:127], v[164:167], v[60:63]
	v_mfma_f32_16x16x32_bf16 v[56:59], v[140:143], v[164:167], v[56:59]
	v_mfma_f32_16x16x32_bf16 v[44:47], v[124:127], v[172:175], v[44:47]
	v_mfma_f32_16x16x32_bf16 v[40:43], v[140:143], v[172:175], v[40:43]
	v_mfma_f32_16x16x32_bf16 v[28:31], v[124:127], v[180:183], v[28:31]
	v_mfma_f32_16x16x32_bf16 v[24:27], v[140:143], v[180:183], v[24:27]
	v_mfma_f32_16x16x32_bf16 v[12:15], v[124:127], v[222:225], v[12:15]
	v_mfma_f32_16x16x32_bf16 v[8:11], v[140:143], v[222:225], v[8:11]
	s_setprio 0
	s_setprio 1
	v_mfma_f32_16x16x32_bf16 v[52:55], v[144:147], v[160:163], v[52:55]
	v_mfma_f32_16x16x32_bf16 v[48:51], v[152:155], v[160:163], v[48:51]
	v_mfma_f32_16x16x32_bf16 v[36:39], v[144:147], v[168:171], v[36:39]
	v_mfma_f32_16x16x32_bf16 v[32:35], v[152:155], v[168:171], v[32:35]
	v_mfma_f32_16x16x32_bf16 v[20:23], v[144:147], v[176:179], v[20:23]
	v_mfma_f32_16x16x32_bf16 v[16:19], v[152:155], v[176:179], v[16:19]
	v_mfma_f32_16x16x32_bf16 v[4:7], v[144:147], v[218:221], v[4:7]
	v_mfma_f32_16x16x32_bf16 v[0:3], v[152:155], v[218:221], v[0:3]
	v_mfma_f32_16x16x32_bf16 v[52:55], v[148:151], v[164:167], v[52:55]
	v_mfma_f32_16x16x32_bf16 v[48:51], v[156:159], v[164:167], v[48:51]
	v_mfma_f32_16x16x32_bf16 v[36:39], v[148:151], v[172:175], v[36:39]
	v_mfma_f32_16x16x32_bf16 v[32:35], v[156:159], v[172:175], v[32:35]
	v_mfma_f32_16x16x32_bf16 v[20:23], v[148:151], v[180:183], v[20:23]
	v_mfma_f32_16x16x32_bf16 v[16:19], v[156:159], v[180:183], v[16:19]
	v_mfma_f32_16x16x32_bf16 v[4:7], v[148:151], v[222:225], v[4:7]
	v_mfma_f32_16x16x32_bf16 v[0:3], v[156:159], v[222:225], v[0:3]
	s_barrier
; #define PG8_STAGE(bufoff, gbase, voff) do { _Pragma("unroll") for (int _i = 0; _i < 2; ++_i) \
;         __builtin_amdgcn_global_load_lds((const unsigned*)((const char*)(gbase) + (voff)[_i]), (PG8_LAS unsigned*)(lds + (bufoff) + ldsw + _i * 8192), 16, 0, 0); } while (0)
; #define PG8_LDA(dst, b, h) do { _Pragma("unroll") for (int m = 0; m < 4; ++m) _Pragma("unroll") for (int k = 0; k < 2; ++k) dst[m][k] = *(const PG8_LAS bf16x8*)(lds + PG8_SA(b, h) + aoff + m * 2048 + k * 1024); } while (0)
; #define PG8_LDB(dst, b, h) do { _Pragma("unroll") for (int n = 0; n < 2; ++n) _Pragma("unroll") for (int k = 0; k < 2; ++k) dst[n][k] = *(const PG8_LAS bf16x8*)(lds + PG8_SB(b, h) + boff + n * 2048 + k * 1024); } while (0)
; #define PG8_MMA(ai, bj, At, Bt) do { __builtin_amdgcn_s_setprio(1); _Pragma("unroll") for (int m = 0; m < 4; ++m) _Pragma("unroll") for (int n = 0; n < 2; ++n) _Pragma("unroll") for (int k = 0; k < 2; ++k) \
;         acc[ai][bj][m][n] = __builtin_amdgcn_mfma_f32_16x16x32_bf16(Bt[n][k], At[m][k], acc[ai][bj][m][n], 0, 0, 0); __builtin_amdgcn_s_setprio(0); } while (0)
; #define PG8_WAIT_V(n) asm volatile("s_waitcnt vmcnt(" #n ")" ::: "memory")
; #define PG8_WAIT_L(n) asm volatile("s_waitcnt lgkmcnt(" #n ")" ::: "memory")
; #define PG8_BAR __builtin_amdgcn_s_barrier()
; #define PG8_SCHED __builtin_amdgcn_sched_barrier(0)
; template <class Epi>
; __device__ __forceinline__ void gemm_phase(PG8_LAS unsigned char* lds, PG8_LAS unsigned char* xl, const Gemm g, const Sched& S, const Epi& E, const int wid) {
;     ...
;             PG8_LDB(B0, 1, 0); PG8_LDB(B1, 1, 1); PG8_SCHED; PG8_LDA(At, 1, 0); PG8_STAGE(PG8_SA(0, 1), a2 + hstepA, voffA);
;             PG8_WAIT_V(8); PG8_WAIT_L(0); PG8_BAR; if (do0) { PG8_MMA(0, 0, At, B0); PG8_MMA(0, 1, At, B1); } PG8_BAR; PG8_SCHED;
;             PG8_LDA(At, 1, 1); PG8_STAGE(PG8_SB(1, 0), b3, voffB); PG8_STAGE(PG8_SB(1, 1), b3 + hstepB, voffB); PG8_STAGE(PG8_SA(1, 0), a3, voffA);
;             PG8_WAIT_V(8); PG8_WAIT_L(0); PG8_BAR; if (do1) { PG8_MMA(1, 0, At, B0); PG8_MMA(1, 1, At, B1); } PG8_BAR; PG8_SCHED;
;         }
;         if (wr == 0) PG8_BAR;
	s_setprio 0
	s_add_i32 s11, 0, 0x18000
	s_add_i32 s13, 0, 0x1c000
	ds_read_b128 v[120:123], v226 offset:32768
	ds_read_b128 v[124:127], v226 offset:33792
	ds_read_b128 v[136:139], v226 offset:34816
	ds_read_b128 v[140:143], v226 offset:35840
	ds_read_b128 v[144:147], v226 offset:49152
	ds_read_b128 v[148:151], v226 offset:50176
	ds_read_b128 v[152:155], v226 offset:51200
	ds_read_b128 v[156:159], v226 offset:52224
	s_add_u32 s48, vcc_lo, 0x80000
	s_addc_u32 s49, vcc_hi, 0
	s_mov_b32 m0, s91
	ds_read_b128 v[160:163], v216 offset:32768
	ds_read_b128 v[164:167], v216 offset:33792
	ds_read_b128 v[168:171], v216 offset:34816
	ds_read_b128 v[172:175], v216 offset:35840
	ds_read_b128 v[176:179], v216 offset:36864
	ds_read_b128 v[180:183], v216 offset:37888
	ds_read_b128 v[218:221], v216 offset:38912
	ds_read_b128 v[222:225], v216 offset:39936
	global_load_lds_dwordx4 v184, s[48:49] sc0
	s_mov_b32 m0, s92
	s_nop 0
	global_load_lds_dwordx4 v188, s[48:49] sc0
	s_waitcnt vmcnt(8)
	s_waitcnt lgkmcnt(0)
	s_setprio 1
	s_barrier
	v_mfma_f32_16x16x32_bf16 v[132:135], v[120:123], v[160:163], v[132:135]
	v_mfma_f32_16x16x32_bf16 v[128:131], v[136:139], v[160:163], v[128:131]
	v_mfma_f32_16x16x32_bf16 v[108:111], v[120:123], v[168:171], v[108:111]
	v_mfma_f32_16x16x32_bf16 v[104:107], v[136:139], v[168:171], v[104:107]
	v_mfma_f32_16x16x32_bf16 v[92:95], v[120:123], v[176:179], v[92:95]
	v_mfma_f32_16x16x32_bf16 v[88:91], v[136:139], v[176:179], v[88:91]
	v_mfma_f32_16x16x32_bf16 v[76:79], v[120:123], v[218:221], v[76:79]
	v_mfma_f32_16x16x32_bf16 v[72:75], v[136:139], v[218:221], v[72:75]
	v_mfma_f32_16x16x32_bf16 v[132:135], v[124:127], v[164:167], v[132:135]
	v_mfma_f32_16x16x32_bf16 v[128:131], v[140:143], v[164:167], v[128:131]
	v_mfma_f32_16x16x32_bf16 v[108:111], v[124:127], v[172:175], v[108:111]
	v_mfma_f32_16x16x32_bf16 v[104:107], v[140:143], v[172:175], v[104:107]
	v_mfma_f32_16x16x32_bf16 v[92:95], v[124:127], v[180:183], v[92:95]
	v_mfma_f32_16x16x32_bf16 v[88:91], v[140:143], v[180:183], v[88:91]
	v_mfma_f32_16x16x32_bf16 v[76:79], v[124:127], v[222:225], v[76:79]
	v_mfma_f32_16x16x32_bf16 v[72:75], v[140:143], v[222:225], v[72:75]
	s_setprio 0
	s_setprio 1
	v_mfma_f32_16x16x32_bf16 v[116:119], v[144:147], v[160:163], v[116:119]
	v_mfma_f32_16x16x32_bf16 v[112:115], v[152:155], v[160:163], v[112:115]
	v_mfma_f32_16x16x32_bf16 v[100:103], v[144:147], v[168:171], v[100:103]
	v_mfma_f32_16x16x32_bf16 v[96:99], v[152:155], v[168:171], v[96:99]
	v_mfma_f32_16x16x32_bf16 v[84:87], v[144:147], v[176:179], v[84:87]
	v_mfma_f32_16x16x32_bf16 v[80:83], v[152:155], v[176:179], v[80:83]
	v_mfma_f32_16x16x32_bf16 v[68:71], v[144:147], v[218:221], v[68:71]
	v_mfma_f32_16x16x32_bf16 v[64:67], v[152:155], v[218:221], v[64:67]
	v_mfma_f32_16x16x32_bf16 v[116:119], v[148:151], v[164:167], v[116:119]
	v_mfma_f32_16x16x32_bf16 v[112:115], v[156:159], v[164:167], v[112:115]
	v_mfma_f32_16x16x32_bf16 v[100:103], v[148:151], v[172:175], v[100:103]
	v_mfma_f32_16x16x32_bf16 v[96:99], v[156:159], v[172:175], v[96:99]
	v_mfma_f32_16x16x32_bf16 v[84:87], v[148:151], v[180:183], v[84:87]
	v_mfma_f32_16x16x32_bf16 v[80:83], v[156:159], v[180:183], v[80:83]
	v_mfma_f32_16x16x32_bf16 v[68:71], v[148:151], v[222:225], v[68:71]
	v_mfma_f32_16x16x32_bf16 v[64:67], v[156:159], v[222:225], v[64:67]
	s_barrier
	s_setprio 0
	s_add_i32 s11, s11, s29
	s_mov_b32 m0, s11
	ds_read_b128 v[160:163], v216 offset:49152
	ds_read_b128 v[164:167], v216 offset:50176
	ds_read_b128 v[168:171], v216 offset:51200
	ds_read_b128 v[172:175], v216 offset:52224
	ds_read_b128 v[176:179], v216 offset:53248
	ds_read_b128 v[180:183], v216 offset:54272
	ds_read_b128 v[218:221], v216 offset:55296
	ds_read_b128 v[222:225], v216 offset:56320
	global_load_lds_dwordx4 v205, s[50:51] sc0
	s_add_i32 m0, s11, 0x2000
	s_add_u32 s48, s50, 0x80080
	global_load_lds_dwordx4 v215, s[50:51] sc0
	s_addc_u32 s49, s51, 0
	s_add_i32 s11, s13, s29
	s_mov_b32 m0, s11
	s_nop 0
	global_load_lds_dwordx4 v186, s[48:49] sc0
	s_add_i32 m0, s11, 0x2000
	s_nop 0
	global_load_lds_dwordx4 v190, s[48:49] sc0
	s_mov_b32 m0, s95
	s_nop 0
	global_load_lds_dwordx4 v204, vcc sc0
	s_mov_b32 m0, s96
	s_nop 0
	global_load_lds_dwordx4 v214, vcc sc0
	s_waitcnt vmcnt(8)
	s_waitcnt lgkmcnt(0)
	s_setprio 1
	s_barrier
	v_mfma_f32_16x16x32_bf16 v[60:63], v[120:123], v[160:163], v[60:63]
	v_mfma_f32_16x16x32_bf16 v[56:59], v[136:139], v[160:163], v[56:59]
	v_mfma_f32_16x16x32_bf16 v[44:47], v[120:123], v[168:171], v[44:47]
	v_mfma_f32_16x16x32_bf16 v[40:43], v[136:139], v[168:171], v[40:43]
	v_mfma_f32_16x16x32_bf16 v[28:31], v[120:123], v[176:179], v[28:31]
	v_mfma_f32_16x16x32_bf16 v[24:27], v[136:139], v[176:179], v[24:27]
	v_mfma_f32_16x16x32_bf16 v[12:15], v[120:123], v[218:221], v[12:15]
	v_mfma_f32_16x16x32_bf16 v[8:11], v[136:139], v[218:221], v[8:11]
	v_mfma_f32_16x16x32_bf16 v[60:63], v[124:127], v[164:167], v[60:63]
	v_mfma_f32_16x16x32_bf16 v[56:59], v[140:143], v[164:167], v[56:59]
	v_mfma_f32_16x16x32_bf16 v[44:47], v[124:127], v[172:175], v[44:47]
	v_mfma_f32_16x16x32_bf16 v[40:43], v[140:143], v[172:175], v[40:43]
	v_mfma_f32_16x16x32_bf16 v[28:31], v[124:127], v[180:183], v[28:31]
	v_mfma_f32_16x16x32_bf16 v[24:27], v[140:143], v[180:183], v[24:27]
	v_mfma_f32_16x16x32_bf16 v[12:15], v[124:127], v[222:225], v[12:15]
	v_mfma_f32_16x16x32_bf16 v[8:11], v[140:143], v[222:225], v[8:11]
	s_setprio 0
	s_setprio 1
	v_mfma_f32_16x16x32_bf16 v[52:55], v[144:147], v[160:163], v[52:55]
	v_mfma_f32_16x16x32_bf16 v[48:51], v[152:155], v[160:163], v[48:51]
	v_mfma_f32_16x16x32_bf16 v[36:39], v[144:147], v[168:171], v[36:39]
	v_mfma_f32_16x16x32_bf16 v[32:35], v[152:155], v[168:171], v[32:35]
	v_mfma_f32_16x16x32_bf16 v[20:23], v[144:147], v[176:179], v[20:23]
	v_mfma_f32_16x16x32_bf16 v[16:19], v[152:155], v[176:179], v[16:19]
	v_mfma_f32_16x16x32_bf16 v[4:7], v[144:147], v[218:221], v[4:7]
	v_mfma_f32_16x16x32_bf16 v[0:3], v[152:155], v[218:221], v[0:3]
	v_mfma_f32_16x16x32_bf16 v[52:55], v[148:151], v[164:167], v[52:55]
	v_mfma_f32_16x16x32_bf16 v[48:51], v[156:159], v[164:167], v[48:51]
	v_mfma_f32_16x16x32_bf16 v[36:39], v[148:151], v[172:175], v[36:39]
	v_mfma_f32_16x16x32_bf16 v[32:35], v[156:159], v[172:175], v[32:35]
	v_mfma_f32_16x16x32_bf16 v[20:23], v[148:151], v[180:183], v[20:23]
	v_mfma_f32_16x16x32_bf16 v[16:19], v[156:159], v[180:183], v[16:19]
	v_mfma_f32_16x16x32_bf16 v[4:7], v[148:151], v[222:225], v[4:7]
	v_mfma_f32_16x16x32_bf16 v[0:3], v[156:159], v[222:225], v[0:3]
	s_barrier
	s_setprio 0
	s_add_i32 s10, s10, 2
	s_add_u32 s8, s8, 0x100
	s_addc_u32 s9, s9, 0
	s_cmp_gt_u32 s10, 29
	s_mov_b64 s[48:49], s[46:47]
	s_cbranch_scc0 .LBB0_859
	s_and_b64 vcc, exec, s[14:15]
	s_cbranch_vccz .LBB0_862
	s_barrier

; __device__ __forceinline__ int lane_id_opq() { int l; asm volatile("v_mbcnt_lo_u32_b32 %0, -1, 0\n\tv_mbcnt_hi_u32_b32 %0, -1, %0" : "=v"(l)); return l; }
; #define PG8_STAGE(bufoff, gbase, voff) do { _Pragma("unroll") for (int _i = 0; _i < 2; ++_i) \
;         __builtin_amdgcn_global_load_lds((const unsigned*)((const char*)(gbase) + (voff)[_i]), (PG8_LAS unsigned*)(lds + (bufoff) + ldsw + _i * 8192), 16, 0, 0); } while (0)
; #define PG8_LDA(dst, b, h) do { _Pragma("unroll") for (int m = 0; m < 4; ++m) _Pragma("unroll") for (int k = 0; k < 2; ++k) dst[m][k] = *(const PG8_LAS bf16x8*)(lds + PG8_SA(b, h) + aoff + m * 2048 + k * 1024); } while (0)
; #define PG8_LDB(dst, b, h) do { _Pragma("unroll") for (int n = 0; n < 2; ++n) _Pragma("unroll") for (int k = 0; k < 2; ++k) dst[n][k] = *(const PG8_LAS bf16x8*)(lds + PG8_SB(b, h) + boff + n * 2048 + k * 1024); } while (0)
; #define PG8_BAR __builtin_amdgcn_s_barrier()
; template <class Epi>
; __device__ __forceinline__ void gemm_phase(PG8_LAS unsigned char* lds, PG8_LAS unsigned char* xl, const Gemm g, const Sched& S, const Epi& E, const int wid) {
;     ...
;             const bool last = (t == nt - 2);
;             const bool do0 = !blkdiag_v<Epi> || t == 0, do1 = !blkdiag_v<Epi> || t != 0;
;             long j1 = 0, ja2 = 0, jb2 = 0;
;             if constexpr (Epi::MID) {
;                 if (t == g.tj) { const int lnM = lane_id_opq(); E.mid(acc, cur, wr, wc, lnM & 15, lnM >> 4); }
;                 if (t >= g.tj) j1 = g.jA;
;                 if (t + 2 >= g.tj) { ja2 = g.jA; jb2 = g.jB; } }
;             const char* a1 = cA + (size_t)(t + 1) * kstep + j1;
;             const char* a2 = last ? nA : cA + (size_t)(t + 2) * kstep + ja2; const char* b2 = last ? nB : cB + (size_t)(t + 2) * kstep + jb2;
;             const char* a3 = a2 + kstep; const char* b3 = b2 + kstep;
;             PG8_LDB(B0, 0, 0); PG8_LDB(B1, 0, 1); PG8_SCHED; PG8_LDA(At, 0, 0); PG8_STAGE(PG8_SA(1, 1), a1 + hstepA, voffA);
;             PG8_WAIT_V(8); PG8_WAIT_L(0); PG8_BAR; if (do0) { PG8_MMA(0, 0, At, B0); PG8_MMA(0, 1, At, B1); } PG8_BAR; PG8_SCHED;
;             PG8_LDA(At, 0, 1); PG8_STAGE(PG8_SB(0, 0), b2, voffB); PG8_STAGE(PG8_SB(0, 1), b2 + hstepB, voffB); PG8_STAGE(PG8_SA(0, 0), a2, voffA);
;             PG8_WAIT_V(8); PG8_WAIT_L(0); PG8_BAR; if (do1) { PG8_MMA(1, 0, At, B0); PG8_MMA(1, 1, At, B1); } PG8_BAR; PG8_SCHED;
.Ldefbar_skip_8:
	v_add_u32_e32 v204, s22, v188
	v_add_u32_e32 v205, s22, v190
	v_add_u32_e32 v218, s22, v210
	v_add_u32_e32 v219, s22, v212
	v_add_u32_e32 v226, 0x10000, v195
	s_add_u32 s56, s52, 0x100
	s_addc_u32 s57, s53, 0
	s_add_i32 s11, 0, 0x10000
	s_cmp_eq_u32 s10, 12
	s_cselect_b32 s61, s47, s57
	s_cselect_b32 s60, s46, s56
	s_cselect_b32 s59, s51, s9
	s_cselect_b32 s58, s50, s8
	s_add_i32 s13, 0, 0x14000
	ds_read_b128 v[124:127], v226 offset:0
	ds_read_b128 v[128:131], v226 offset:1024
	ds_read_b128 v[136:139], v226 offset:2048
	ds_read_b128 v[140:143], v226 offset:3072
	ds_read_b128 v[144:147], v226 offset:16384
	ds_read_b128 v[148:151], v226 offset:17408
	ds_read_b128 v[152:155], v226 offset:18432
	ds_read_b128 v[156:159], v226 offset:19456
	s_add_i32 m0, s66, 0xc000
	ds_read_b128 v[160:163], v220
	ds_read_b128 v[164:167], v220 offset:1024
	ds_read_b128 v[168:171], v220 offset:2048
	ds_read_b128 v[172:175], v220 offset:3072
	ds_read_b128 v[176:179], v220 offset:4096
	ds_read_b128 v[180:183], v220 offset:5120
	ds_read_b128 v[184:187], v220 offset:6144
	ds_read_b128 v[222:225], v220 offset:7168
	global_load_lds_dwordx4 v214, s[52:53] sc0
	s_add_i32 m0, s66, 0xe000
	s_nop 0
	global_load_lds_dwordx4 v216, s[52:53] sc0
	s_waitcnt vmcnt(8)
	s_waitcnt lgkmcnt(0)
	s_setprio 1
	s_barrier
	v_mfma_f32_16x16x32_bf16 v[132:135], v[124:127], v[160:163], 0
	v_mfma_f32_16x16x32_bf16 v[120:123], v[136:139], v[160:163], 0
	v_mfma_f32_16x16x32_bf16 v[108:111], v[124:127], v[168:171], 0
	v_mfma_f32_16x16x32_bf16 v[104:107], v[136:139], v[168:171], 0
	v_mfma_f32_16x16x32_bf16 v[92:95], v[124:127], v[176:179], 0
	v_mfma_f32_16x16x32_bf16 v[88:91], v[136:139], v[176:179], 0
	v_mfma_f32_16x16x32_bf16 v[76:79], v[124:127], v[184:187], 0
	v_mfma_f32_16x16x32_bf16 v[72:75], v[136:139], v[184:187], 0
	v_mfma_f32_16x16x32_bf16 v[132:135], v[128:131], v[164:167], v[132:135]
	v_mfma_f32_16x16x32_bf16 v[120:123], v[140:143], v[164:167], v[120:123]
	v_mfma_f32_16x16x32_bf16 v[108:111], v[128:131], v[172:175], v[108:111]
	v_mfma_f32_16x16x32_bf16 v[104:107], v[140:143], v[172:175], v[104:107]
	v_mfma_f32_16x16x32_bf16 v[92:95], v[128:131], v[180:183], v[92:95]
	v_mfma_f32_16x16x32_bf16 v[88:91], v[140:143], v[180:183], v[88:91]
	v_mfma_f32_16x16x32_bf16 v[76:79], v[128:131], v[222:225], v[76:79]
	v_mfma_f32_16x16x32_bf16 v[72:75], v[140:143], v[222:225], v[72:75]
	s_setprio 0
	s_setprio 1
	v_mfma_f32_16x16x32_bf16 v[116:119], v[144:147], v[160:163], 0
	v_mfma_f32_16x16x32_bf16 v[112:115], v[152:155], v[160:163], 0
	v_mfma_f32_16x16x32_bf16 v[100:103], v[144:147], v[168:171], 0
	v_mfma_f32_16x16x32_bf16 v[96:99], v[152:155], v[168:171], 0
	v_mfma_f32_16x16x32_bf16 v[84:87], v[144:147], v[176:179], 0
	v_mfma_f32_16x16x32_bf16 v[80:83], v[152:155], v[176:179], 0
	v_mfma_f32_16x16x32_bf16 v[68:71], v[144:147], v[184:187], 0
	v_mfma_f32_16x16x32_bf16 v[64:67], v[152:155], v[184:187], 0
	v_mfma_f32_16x16x32_bf16 v[116:119], v[148:151], v[164:167], v[116:119]
	v_mfma_f32_16x16x32_bf16 v[112:115], v[156:159], v[164:167], v[112:115]
	v_mfma_f32_16x16x32_bf16 v[100:103], v[148:151], v[172:175], v[100:103]
	v_mfma_f32_16x16x32_bf16 v[96:99], v[156:159], v[172:175], v[96:99]
	v_mfma_f32_16x16x32_bf16 v[84:87], v[148:151], v[180:183], v[84:87]
	v_mfma_f32_16x16x32_bf16 v[80:83], v[156:159], v[180:183], v[80:83]
	v_mfma_f32_16x16x32_bf16 v[68:71], v[148:151], v[222:225], v[68:71]
	v_mfma_f32_16x16x32_bf16 v[64:67], v[156:159], v[222:225], v[64:67]
	s_barrier
	s_setprio 0
	s_add_i32 s11, s11, s29
	s_mov_b32 m0, s11
	ds_read_b128 v[160:163], v220 offset:16384
	ds_read_b128 v[164:167], v220 offset:17408
	ds_read_b128 v[168:171], v220 offset:18432
	ds_read_b128 v[172:175], v220 offset:19456
	ds_read_b128 v[176:179], v220 offset:20480
	ds_read_b128 v[180:183], v220 offset:21504
	ds_read_b128 v[184:187], v220 offset:22528
	ds_read_b128 v[222:225], v220 offset:23552
	global_load_lds_dwordx4 v190, s[58:59] sc0
	s_add_i32 m0, s11, 0x2000
	s_add_u32 s52, s58, 0x40000
	s_addc_u32 s53, s59, 0
	s_add_i32 s11, s13, s29
	global_load_lds_dwordx4 v212, s[58:59] sc0
	s_mov_b32 m0, s11
	s_nop 0
	global_load_lds_dwordx4 v190, s[52:53] sc0
	s_add_i32 m0, s11, 0x2000
	s_nop 0
	global_load_lds_dwordx4 v212, s[52:53] sc0
	s_mov_b32 m0, s66
	s_nop 0
	global_load_lds_dwordx4 v188, s[60:61] sc0
	s_mov_b32 m0, s67
	s_nop 0
	global_load_lds_dwordx4 v210, s[60:61] sc0
	s_waitcnt vmcnt(8)
	s_waitcnt lgkmcnt(0)
	s_setprio 1
	s_barrier
	v_mfma_f32_16x16x32_bf16 v[60:63], v[124:127], v[160:163], 0
	v_mfma_f32_16x16x32_bf16 v[56:59], v[136:139], v[160:163], 0
	v_mfma_f32_16x16x32_bf16 v[44:47], v[124:127], v[168:171], 0
	v_mfma_f32_16x16x32_bf16 v[40:43], v[136:139], v[168:171], 0
	v_mfma_f32_16x16x32_bf16 v[28:31], v[124:127], v[176:179], 0
	v_mfma_f32_16x16x32_bf16 v[24:27], v[136:139], v[176:179], 0
	v_mfma_f32_16x16x32_bf16 v[12:15], v[124:127], v[184:187], 0
	v_mfma_f32_16x16x32_bf16 v[8:11], v[136:139], v[184:187], 0
	v_mfma_f32_16x16x32_bf16 v[60:63], v[128:131], v[164:167], v[60:63]
	v_mfma_f32_16x16x32_bf16 v[56:59], v[140:143], v[164:167], v[56:59]
	v_mfma_f32_16x16x32_bf16 v[44:47], v[128:131], v[172:175], v[44:47]
	v_mfma_f32_16x16x32_bf16 v[40:43], v[140:143], v[172:175], v[40:43]
	v_mfma_f32_16x16x32_bf16 v[28:31], v[128:131], v[180:183], v[28:31]
	v_mfma_f32_16x16x32_bf16 v[24:27], v[140:143], v[180:183], v[24:27]
	v_mfma_f32_16x16x32_bf16 v[12:15], v[128:131], v[222:225], v[12:15]
	v_mfma_f32_16x16x32_bf16 v[8:11], v[140:143], v[222:225], v[8:11]
	s_setprio 0
	s_setprio 1
	v_mfma_f32_16x16x32_bf16 v[52:55], v[144:147], v[160:163], 0
	v_mfma_f32_16x16x32_bf16 v[48:51], v[152:155], v[160:163], 0
	v_mfma_f32_16x16x32_bf16 v[36:39], v[144:147], v[168:171], 0
	v_mfma_f32_16x16x32_bf16 v[32:35], v[152:155], v[168:171], 0
	v_mfma_f32_16x16x32_bf16 v[20:23], v[144:147], v[176:179], 0
	v_mfma_f32_16x16x32_bf16 v[16:19], v[152:155], v[176:179], 0
	v_mfma_f32_16x16x32_bf16 v[4:7], v[144:147], v[184:187], 0
	v_mfma_f32_16x16x32_bf16 v[0:3], v[152:155], v[184:187], 0
	v_mfma_f32_16x16x32_bf16 v[52:55], v[148:151], v[164:167], v[52:55]
	v_mfma_f32_16x16x32_bf16 v[48:51], v[156:159], v[164:167], v[48:51]
	v_mfma_f32_16x16x32_bf16 v[36:39], v[148:151], v[172:175], v[36:39]
	v_mfma_f32_16x16x32_bf16 v[32:35], v[156:159], v[172:175], v[32:35]
	v_mfma_f32_16x16x32_bf16 v[20:23], v[148:151], v[180:183], v[20:23]
	v_mfma_f32_16x16x32_bf16 v[16:19], v[156:159], v[180:183], v[16:19]
	v_mfma_f32_16x16x32_bf16 v[4:7], v[148:151], v[222:225], v[4:7]
	v_mfma_f32_16x16x32_bf16 v[0:3], v[156:159], v[222:225], v[0:3]
	s_barrier
; #define PG8_STAGE(bufoff, gbase, voff) do { _Pragma("unroll") for (int _i = 0; _i < 2; ++_i) \
;         __builtin_amdgcn_global_load_lds((const unsigned*)((const char*)(gbase) + (voff)[_i]), (PG8_LAS unsigned*)(lds + (bufoff) + ldsw + _i * 8192), 16, 0, 0); } while (0)
; #define PG8_LDA(dst, b, h) do { _Pragma("unroll") for (int m = 0; m < 4; ++m) _Pragma("unroll") for (int k = 0; k < 2; ++k) dst[m][k] = *(const PG8_LAS bf16x8*)(lds + PG8_SA(b, h) + aoff + m * 2048 + k * 1024); } while (0)
; #define PG8_LDB(dst, b, h) do { _Pragma("unroll") for (int n = 0; n < 2; ++n) _Pragma("unroll") for (int k = 0; k < 2; ++k) dst[n][k] = *(const PG8_LAS bf16x8*)(lds + PG8_SB(b, h) + boff + n * 2048 + k * 1024); } while (0)
; #define PG8_MMA(ai, bj, At, Bt) do { __builtin_amdgcn_s_setprio(1); _Pragma("unroll") for (int m = 0; m < 4; ++m) _Pragma("unroll") for (int n = 0; n < 2; ++n) _Pragma("unroll") for (int k = 0; k < 2; ++k) \
;         acc[ai][bj][m][n] = __builtin_amdgcn_mfma_f32_16x16x32_bf16(Bt[n][k], At[m][k], acc[ai][bj][m][n], 0, 0, 0); __builtin_amdgcn_s_setprio(0); } while (0)
; #define PG8_WAIT_V(n) asm volatile("s_waitcnt vmcnt(" #n ")" ::: "memory")
; #define PG8_WAIT_L(n) asm volatile("s_waitcnt lgkmcnt(" #n ")" ::: "memory")
; #define PG8_BAR __builtin_amdgcn_s_barrier()
; #define PG8_SCHED __builtin_amdgcn_sched_barrier(0)
; template <class Epi>
; __device__ __forceinline__ void gemm_phase(PG8_LAS unsigned char* lds, PG8_LAS unsigned char* xl, const Gemm g, const Sched& S, const Epi& E, const int wid) {
;     ...
;             PG8_LDB(B0, 1, 0); PG8_LDB(B1, 1, 1); PG8_SCHED; PG8_LDA(At, 1, 0); PG8_STAGE(PG8_SA(0, 1), a2 + hstepA, voffA);
;             PG8_WAIT_V(8); PG8_WAIT_L(0); PG8_BAR; if (do0) { PG8_MMA(0, 0, At, B0); PG8_MMA(0, 1, At, B1); } PG8_BAR; PG8_SCHED;
;             PG8_LDA(At, 1, 1); PG8_STAGE(PG8_SB(1, 0), b3, voffB); PG8_STAGE(PG8_SB(1, 1), b3 + hstepB, voffB); PG8_STAGE(PG8_SA(1, 0), a3, voffA);
;             PG8_WAIT_V(8); PG8_WAIT_L(0); PG8_BAR; if (do1) { PG8_MMA(1, 0, At, B0); PG8_MMA(1, 1, At, B1); } PG8_BAR; PG8_SCHED;
;         }
	s_setprio 0
	s_add_i32 s11, 0, 0x18000
	s_add_i32 s13, 0, 0x1c000
	ds_read_b128 v[124:127], v226 offset:32768
	ds_read_b128 v[128:131], v226 offset:33792
	ds_read_b128 v[136:139], v226 offset:34816
	ds_read_b128 v[140:143], v226 offset:35840
	ds_read_b128 v[144:147], v226 offset:49152
	ds_read_b128 v[148:151], v226 offset:50176
	ds_read_b128 v[152:155], v226 offset:51200
	ds_read_b128 v[156:159], v226 offset:52224
	s_add_u32 s52, s60, 0x40000
	s_addc_u32 s53, s61, 0
	s_mov_b32 m0, s68
	ds_read_b128 v[160:163], v220 offset:32768
	ds_read_b128 v[164:167], v220 offset:33792
	ds_read_b128 v[168:171], v220 offset:34816
	ds_read_b128 v[172:175], v220 offset:35840
	ds_read_b128 v[176:179], v220 offset:36864
	ds_read_b128 v[180:183], v220 offset:37888
	ds_read_b128 v[184:187], v220 offset:38912
	ds_read_b128 v[222:225], v220 offset:39936
	global_load_lds_dwordx4 v188, s[52:53] sc0
	s_mov_b32 m0, s69
	s_nop 0
	global_load_lds_dwordx4 v210, s[52:53] sc0
	s_waitcnt vmcnt(8)
	s_waitcnt lgkmcnt(0)
	s_setprio 1
	s_barrier
	v_mfma_f32_16x16x32_bf16 v[132:135], v[124:127], v[160:163], v[132:135]
	v_mfma_f32_16x16x32_bf16 v[120:123], v[136:139], v[160:163], v[120:123]
	v_mfma_f32_16x16x32_bf16 v[108:111], v[124:127], v[168:171], v[108:111]
	v_mfma_f32_16x16x32_bf16 v[104:107], v[136:139], v[168:171], v[104:107]
	v_mfma_f32_16x16x32_bf16 v[92:95], v[124:127], v[176:179], v[92:95]
	v_mfma_f32_16x16x32_bf16 v[88:91], v[136:139], v[176:179], v[88:91]
	v_mfma_f32_16x16x32_bf16 v[76:79], v[124:127], v[184:187], v[76:79]
	v_mfma_f32_16x16x32_bf16 v[72:75], v[136:139], v[184:187], v[72:75]
	v_mfma_f32_16x16x32_bf16 v[132:135], v[128:131], v[164:167], v[132:135]
	v_mfma_f32_16x16x32_bf16 v[120:123], v[140:143], v[164:167], v[120:123]
	v_mfma_f32_16x16x32_bf16 v[108:111], v[128:131], v[172:175], v[108:111]
	v_mfma_f32_16x16x32_bf16 v[104:107], v[140:143], v[172:175], v[104:107]
	v_mfma_f32_16x16x32_bf16 v[92:95], v[128:131], v[180:183], v[92:95]
	v_mfma_f32_16x16x32_bf16 v[88:91], v[140:143], v[180:183], v[88:91]
	v_mfma_f32_16x16x32_bf16 v[76:79], v[128:131], v[222:225], v[76:79]
	v_mfma_f32_16x16x32_bf16 v[72:75], v[140:143], v[222:225], v[72:75]
	s_setprio 0
	s_setprio 1
	v_mfma_f32_16x16x32_bf16 v[116:119], v[144:147], v[160:163], v[116:119]
	v_mfma_f32_16x16x32_bf16 v[112:115], v[152:155], v[160:163], v[112:115]
	v_mfma_f32_16x16x32_bf16 v[100:103], v[144:147], v[168:171], v[100:103]
	v_mfma_f32_16x16x32_bf16 v[96:99], v[152:155], v[168:171], v[96:99]
	v_mfma_f32_16x16x32_bf16 v[84:87], v[144:147], v[176:179], v[84:87]
	v_mfma_f32_16x16x32_bf16 v[80:83], v[152:155], v[176:179], v[80:83]
	v_mfma_f32_16x16x32_bf16 v[68:71], v[144:147], v[184:187], v[68:71]
	v_mfma_f32_16x16x32_bf16 v[64:67], v[152:155], v[184:187], v[64:67]
	v_mfma_f32_16x16x32_bf16 v[116:119], v[148:151], v[164:167], v[116:119]
	v_mfma_f32_16x16x32_bf16 v[112:115], v[156:159], v[164:167], v[112:115]
	v_mfma_f32_16x16x32_bf16 v[100:103], v[148:151], v[172:175], v[100:103]
	v_mfma_f32_16x16x32_bf16 v[96:99], v[156:159], v[172:175], v[96:99]
	v_mfma_f32_16x16x32_bf16 v[84:87], v[148:151], v[180:183], v[84:87]
	v_mfma_f32_16x16x32_bf16 v[80:83], v[156:159], v[180:183], v[80:83]
	v_mfma_f32_16x16x32_bf16 v[68:71], v[148:151], v[222:225], v[68:71]
	v_mfma_f32_16x16x32_bf16 v[64:67], v[156:159], v[222:225], v[64:67]
	s_barrier
	s_setprio 0
	s_add_i32 s11, s11, s29
	s_mov_b32 m0, s11
	ds_read_b128 v[160:163], v220 offset:49152
	ds_read_b128 v[164:167], v220 offset:50176
	ds_read_b128 v[168:171], v220 offset:51200
	ds_read_b128 v[172:175], v220 offset:52224
	ds_read_b128 v[176:179], v220 offset:53248
	ds_read_b128 v[180:183], v220 offset:54272
	ds_read_b128 v[184:187], v220 offset:55296
	ds_read_b128 v[222:225], v220 offset:56320
	global_load_lds_dwordx4 v205, s[58:59] sc0
	s_add_i32 m0, s11, 0x2000
	s_add_u32 s52, s58, 0x40080
	global_load_lds_dwordx4 v219, s[58:59] sc0
	s_addc_u32 s53, s59, 0
	s_add_i32 s11, s13, s29
	s_mov_b32 m0, s11
	s_nop 0
	global_load_lds_dwordx4 v190, s[52:53] sc0
	s_add_i32 m0, s11, 0x2000
	s_nop 0
	global_load_lds_dwordx4 v212, s[52:53] sc0
	s_mov_b32 m0, s87
	s_nop 0
	global_load_lds_dwordx4 v204, s[60:61] sc0
	s_mov_b32 m0, s88
	s_nop 0
	global_load_lds_dwordx4 v218, s[60:61] sc0
	s_waitcnt vmcnt(8)
	s_waitcnt lgkmcnt(0)
	s_setprio 1
	s_barrier
	v_mfma_f32_16x16x32_bf16 v[60:63], v[124:127], v[160:163], v[60:63]
	v_mfma_f32_16x16x32_bf16 v[56:59], v[136:139], v[160:163], v[56:59]
	v_mfma_f32_16x16x32_bf16 v[44:47], v[124:127], v[168:171], v[44:47]
	v_mfma_f32_16x16x32_bf16 v[40:43], v[136:139], v[168:171], v[40:43]
	v_mfma_f32_16x16x32_bf16 v[28:31], v[124:127], v[176:179], v[28:31]
	v_mfma_f32_16x16x32_bf16 v[24:27], v[136:139], v[176:179], v[24:27]
	v_mfma_f32_16x16x32_bf16 v[12:15], v[124:127], v[184:187], v[12:15]
	v_mfma_f32_16x16x32_bf16 v[8:11], v[136:139], v[184:187], v[8:11]
	v_mfma_f32_16x16x32_bf16 v[60:63], v[128:131], v[164:167], v[60:63]
	v_mfma_f32_16x16x32_bf16 v[56:59], v[140:143], v[164:167], v[56:59]
	v_mfma_f32_16x16x32_bf16 v[44:47], v[128:131], v[172:175], v[44:47]
	v_mfma_f32_16x16x32_bf16 v[40:43], v[140:143], v[172:175], v[40:43]
	v_mfma_f32_16x16x32_bf16 v[28:31], v[128:131], v[180:183], v[28:31]
	v_mfma_f32_16x16x32_bf16 v[24:27], v[140:143], v[180:183], v[24:27]
	v_mfma_f32_16x16x32_bf16 v[12:15], v[128:131], v[222:225], v[12:15]
	v_mfma_f32_16x16x32_bf16 v[8:11], v[140:143], v[222:225], v[8:11]
	s_setprio 0
	s_setprio 1
	v_mfma_f32_16x16x32_bf16 v[52:55], v[144:147], v[160:163], v[52:55]
	v_mfma_f32_16x16x32_bf16 v[48:51], v[152:155], v[160:163], v[48:51]
	v_mfma_f32_16x16x32_bf16 v[36:39], v[144:147], v[168:171], v[36:39]
	v_mfma_f32_16x16x32_bf16 v[32:35], v[152:155], v[168:171], v[32:35]
	v_mfma_f32_16x16x32_bf16 v[20:23], v[144:147], v[176:179], v[20:23]
	v_mfma_f32_16x16x32_bf16 v[16:19], v[152:155], v[176:179], v[16:19]
	v_mfma_f32_16x16x32_bf16 v[4:7], v[144:147], v[184:187], v[4:7]
	v_mfma_f32_16x16x32_bf16 v[0:3], v[152:155], v[184:187], v[0:3]
	v_mfma_f32_16x16x32_bf16 v[52:55], v[148:151], v[164:167], v[52:55]
	v_mfma_f32_16x16x32_bf16 v[48:51], v[156:159], v[164:167], v[48:51]
	v_mfma_f32_16x16x32_bf16 v[36:39], v[148:151], v[172:175], v[36:39]
	v_mfma_f32_16x16x32_bf16 v[32:35], v[156:159], v[172:175], v[32:35]
	v_mfma_f32_16x16x32_bf16 v[20:23], v[148:151], v[180:183], v[20:23]
	v_mfma_f32_16x16x32_bf16 v[16:19], v[156:159], v[180:183], v[16:19]
	v_mfma_f32_16x16x32_bf16 v[4:7], v[148:151], v[222:225], v[4:7]
	v_mfma_f32_16x16x32_bf16 v[0:3], v[156:159], v[222:225], v[0:3]
	s_barrier
	s_setprio 0
	s_add_i32 s10, s10, 2
	s_add_u32 s8, s8, 0x100
	s_addc_u32 s9, s9, 0
	s_cmp_gt_u32 s10, 13
	s_mov_b64 s[52:53], s[56:57]
; __device__ __forceinline__ int lane_id_opq() { int l; asm volatile("v_mbcnt_lo_u32_b32 %0, -1, 0\n\tv_mbcnt_hi_u32_b32 %0, -1, %0" : "=v"(l)); return l; }
; #define PG8_STAGE(bufoff, gbase, voff) do { _Pragma("unroll") for (int _i = 0; _i < 2; ++_i) \
;         __builtin_amdgcn_global_load_lds((const unsigned*)((const char*)(gbase) + (voff)[_i]), (PG8_LAS unsigned*)(lds + (bufoff) + ldsw + _i * 8192), 16, 0, 0); } while (0)
; #define PG8_LDA(dst, b, h) do { _Pragma("unroll") for (int m = 0; m < 4; ++m) _Pragma("unroll") for (int k = 0; k < 2; ++k) dst[m][k] = *(const PG8_LAS bf16x8*)(lds + PG8_SA(b, h) + aoff + m * 2048 + k * 1024); } while (0)
; #define PG8_LDB(dst, b, h) do { _Pragma("unroll") for (int n = 0; n < 2; ++n) _Pragma("unroll") for (int k = 0; k < 2; ++k) dst[n][k] = *(const PG8_LAS bf16x8*)(lds + PG8_SB(b, h) + boff + n * 2048 + k * 1024); } while (0)
; #define PG8_BAR __builtin_amdgcn_s_barrier()
; template <class Epi>
; __device__ __forceinline__ void gemm_phase(PG8_LAS unsigned char* lds, PG8_LAS unsigned char* xl, const Gemm g, const Sched& S, const Epi& E, const int wid) {
;     ...
;             const bool last = (t == nt - 2);
;             const bool do0 = !blkdiag_v<Epi> || t == 0, do1 = !blkdiag_v<Epi> || t != 0;
;             long j1 = 0, ja2 = 0, jb2 = 0;
;             if constexpr (Epi::MID) {
;                 if (t == g.tj) { const int lnM = lane_id_opq(); E.mid(acc, cur, wr, wc, lnM & 15, lnM >> 4); }
;                 if (t >= g.tj) j1 = g.jA;
;                 if (t + 2 >= g.tj) { ja2 = g.jA; jb2 = g.jB; } }
;             const char* a1 = cA + (size_t)(t + 1) * kstep + j1;
;             const char* a2 = last ? nA : cA + (size_t)(t + 2) * kstep + ja2; const char* b2 = last ? nB : cB + (size_t)(t + 2) * kstep + jb2;
;             const char* a3 = a2 + kstep; const char* b3 = b2 + kstep;
;             PG8_LDB(B0, 0, 0); PG8_LDB(B1, 0, 1); PG8_SCHED; PG8_LDA(At, 0, 0); PG8_STAGE(PG8_SA(1, 1), a1 + hstepA, voffA);
;             PG8_WAIT_V(8); PG8_WAIT_L(0); PG8_BAR; if (do0) { PG8_MMA(0, 0, At, B0); PG8_MMA(0, 1, At, B1); } PG8_BAR; PG8_SCHED;
;             PG8_LDA(At, 0, 1); PG8_STAGE(PG8_SB(0, 0), b2, voffB); PG8_STAGE(PG8_SB(0, 1), b2 + hstepB, voffB); PG8_STAGE(PG8_SA(0, 0), a2, voffA);
;             PG8_WAIT_V(8); PG8_WAIT_L(0); PG8_BAR; if (do1) { PG8_MMA(1, 0, At, B0); PG8_MMA(1, 1, At, B1); } PG8_BAR; PG8_SCHED;
.LBB0_959:
	s_add_u32 s56, s52, 0x100
	s_addc_u32 s57, s53, 0
	s_add_i32 s11, 0, 0x10000
	s_cmp_eq_u32 s10, 12
	s_cselect_b32 s61, s47, s57
	s_cselect_b32 s60, s46, s56
	s_cselect_b32 s59, s51, s9
	s_cselect_b32 s58, s50, s8
	s_add_i32 s13, 0, 0x14000
	ds_read_b128 v[124:127], v226 offset:0
	ds_read_b128 v[128:131], v226 offset:1024
	ds_read_b128 v[136:139], v226 offset:2048
	ds_read_b128 v[140:143], v226 offset:3072
	ds_read_b128 v[144:147], v226 offset:16384
	ds_read_b128 v[148:151], v226 offset:17408
	ds_read_b128 v[152:155], v226 offset:18432
	ds_read_b128 v[156:159], v226 offset:19456
	s_add_i32 m0, s66, 0xc000
	ds_read_b128 v[160:163], v220
	ds_read_b128 v[164:167], v220 offset:1024
	ds_read_b128 v[168:171], v220 offset:2048
	ds_read_b128 v[172:175], v220 offset:3072
	ds_read_b128 v[176:179], v220 offset:4096
	ds_read_b128 v[180:183], v220 offset:5120
	ds_read_b128 v[184:187], v220 offset:6144
	ds_read_b128 v[222:225], v220 offset:7168
	global_load_lds_dwordx4 v214, s[52:53] sc0
	s_add_i32 m0, s66, 0xe000
	s_nop 0
	global_load_lds_dwordx4 v216, s[52:53] sc0
	s_waitcnt vmcnt(8)
	s_waitcnt lgkmcnt(0)
	s_setprio 1
	s_barrier
	v_mfma_f32_16x16x32_bf16 v[132:135], v[124:127], v[160:163], v[132:135]
	v_mfma_f32_16x16x32_bf16 v[120:123], v[136:139], v[160:163], v[120:123]
	v_mfma_f32_16x16x32_bf16 v[108:111], v[124:127], v[168:171], v[108:111]
	v_mfma_f32_16x16x32_bf16 v[104:107], v[136:139], v[168:171], v[104:107]
	v_mfma_f32_16x16x32_bf16 v[92:95], v[124:127], v[176:179], v[92:95]
	v_mfma_f32_16x16x32_bf16 v[88:91], v[136:139], v[176:179], v[88:91]
	v_mfma_f32_16x16x32_bf16 v[76:79], v[124:127], v[184:187], v[76:79]
	v_mfma_f32_16x16x32_bf16 v[72:75], v[136:139], v[184:187], v[72:75]
	v_mfma_f32_16x16x32_bf16 v[132:135], v[128:131], v[164:167], v[132:135]
	v_mfma_f32_16x16x32_bf16 v[120:123], v[140:143], v[164:167], v[120:123]
	v_mfma_f32_16x16x32_bf16 v[108:111], v[128:131], v[172:175], v[108:111]
	v_mfma_f32_16x16x32_bf16 v[104:107], v[140:143], v[172:175], v[104:107]
	v_mfma_f32_16x16x32_bf16 v[92:95], v[128:131], v[180:183], v[92:95]
	v_mfma_f32_16x16x32_bf16 v[88:91], v[140:143], v[180:183], v[88:91]
	v_mfma_f32_16x16x32_bf16 v[76:79], v[128:131], v[222:225], v[76:79]
	v_mfma_f32_16x16x32_bf16 v[72:75], v[140:143], v[222:225], v[72:75]
	s_setprio 0
	s_setprio 1
	v_mfma_f32_16x16x32_bf16 v[116:119], v[144:147], v[160:163], v[116:119]
	v_mfma_f32_16x16x32_bf16 v[112:115], v[152:155], v[160:163], v[112:115]
	v_mfma_f32_16x16x32_bf16 v[100:103], v[144:147], v[168:171], v[100:103]
	v_mfma_f32_16x16x32_bf16 v[96:99], v[152:155], v[168:171], v[96:99]
	v_mfma_f32_16x16x32_bf16 v[84:87], v[144:147], v[176:179], v[84:87]
	v_mfma_f32_16x16x32_bf16 v[80:83], v[152:155], v[176:179], v[80:83]
	v_mfma_f32_16x16x32_bf16 v[68:71], v[144:147], v[184:187], v[68:71]
	v_mfma_f32_16x16x32_bf16 v[64:67], v[152:155], v[184:187], v[64:67]
	v_mfma_f32_16x16x32_bf16 v[116:119], v[148:151], v[164:167], v[116:119]
	v_mfma_f32_16x16x32_bf16 v[112:115], v[156:159], v[164:167], v[112:115]
	v_mfma_f32_16x16x32_bf16 v[100:103], v[148:151], v[172:175], v[100:103]
	v_mfma_f32_16x16x32_bf16 v[96:99], v[156:159], v[172:175], v[96:99]
	v_mfma_f32_16x16x32_bf16 v[84:87], v[148:151], v[180:183], v[84:87]
	v_mfma_f32_16x16x32_bf16 v[80:83], v[156:159], v[180:183], v[80:83]
	v_mfma_f32_16x16x32_bf16 v[68:71], v[148:151], v[222:225], v[68:71]
	v_mfma_f32_16x16x32_bf16 v[64:67], v[156:159], v[222:225], v[64:67]
	s_barrier
	s_setprio 0
	s_add_i32 s11, s11, s29
	s_mov_b32 m0, s11
	ds_read_b128 v[160:163], v220 offset:16384
	ds_read_b128 v[164:167], v220 offset:17408
	ds_read_b128 v[168:171], v220 offset:18432
	ds_read_b128 v[172:175], v220 offset:19456
	ds_read_b128 v[176:179], v220 offset:20480
	ds_read_b128 v[180:183], v220 offset:21504
	ds_read_b128 v[184:187], v220 offset:22528
	ds_read_b128 v[222:225], v220 offset:23552
	global_load_lds_dwordx4 v190, s[58:59] sc0
	s_add_i32 m0, s11, 0x2000
	s_add_u32 s52, s58, 0x40000
	s_addc_u32 s53, s59, 0
	s_add_i32 s11, s13, s29
	global_load_lds_dwordx4 v212, s[58:59] sc0
	s_mov_b32 m0, s11
	s_nop 0
	global_load_lds_dwordx4 v190, s[52:53] sc0
	s_add_i32 m0, s11, 0x2000
	s_nop 0
	global_load_lds_dwordx4 v212, s[52:53] sc0
	s_mov_b32 m0, s66
	s_nop 0
	global_load_lds_dwordx4 v188, s[60:61] sc0
	s_mov_b32 m0, s67
	s_nop 0
	global_load_lds_dwordx4 v210, s[60:61] sc0
	s_waitcnt vmcnt(8)
	s_waitcnt lgkmcnt(0)
	s_setprio 1
	s_barrier
	v_mfma_f32_16x16x32_bf16 v[60:63], v[124:127], v[160:163], v[60:63]
	v_mfma_f32_16x16x32_bf16 v[56:59], v[136:139], v[160:163], v[56:59]
	v_mfma_f32_16x16x32_bf16 v[44:47], v[124:127], v[168:171], v[44:47]
	v_mfma_f32_16x16x32_bf16 v[40:43], v[136:139], v[168:171], v[40:43]
	v_mfma_f32_16x16x32_bf16 v[28:31], v[124:127], v[176:179], v[28:31]
	v_mfma_f32_16x16x32_bf16 v[24:27], v[136:139], v[176:179], v[24:27]
	v_mfma_f32_16x16x32_bf16 v[12:15], v[124:127], v[184:187], v[12:15]
	v_mfma_f32_16x16x32_bf16 v[8:11], v[136:139], v[184:187], v[8:11]
	v_mfma_f32_16x16x32_bf16 v[60:63], v[128:131], v[164:167], v[60:63]
	v_mfma_f32_16x16x32_bf16 v[56:59], v[140:143], v[164:167], v[56:59]
	v_mfma_f32_16x16x32_bf16 v[44:47], v[128:131], v[172:175], v[44:47]
	v_mfma_f32_16x16x32_bf16 v[40:43], v[140:143], v[172:175], v[40:43]
	v_mfma_f32_16x16x32_bf16 v[28:31], v[128:131], v[180:183], v[28:31]
	v_mfma_f32_16x16x32_bf16 v[24:27], v[140:143], v[180:183], v[24:27]
	v_mfma_f32_16x16x32_bf16 v[12:15], v[128:131], v[222:225], v[12:15]
	v_mfma_f32_16x16x32_bf16 v[8:11], v[140:143], v[222:225], v[8:11]
	s_setprio 0
	s_setprio 1
	v_mfma_f32_16x16x32_bf16 v[52:55], v[144:147], v[160:163], v[52:55]
	v_mfma_f32_16x16x32_bf16 v[48:51], v[152:155], v[160:163], v[48:51]
	v_mfma_f32_16x16x32_bf16 v[36:39], v[144:147], v[168:171], v[36:39]
	v_mfma_f32_16x16x32_bf16 v[32:35], v[152:155], v[168:171], v[32:35]
	v_mfma_f32_16x16x32_bf16 v[20:23], v[144:147], v[176:179], v[20:23]
	v_mfma_f32_16x16x32_bf16 v[16:19], v[152:155], v[176:179], v[16:19]
	v_mfma_f32_16x16x32_bf16 v[4:7], v[144:147], v[184:187], v[4:7]
	v_mfma_f32_16x16x32_bf16 v[0:3], v[152:155], v[184:187], v[0:3]
	v_mfma_f32_16x16x32_bf16 v[52:55], v[148:151], v[164:167], v[52:55]
	v_mfma_f32_16x16x32_bf16 v[48:51], v[156:159], v[164:167], v[48:51]
	v_mfma_f32_16x16x32_bf16 v[36:39], v[148:151], v[172:175], v[36:39]
	v_mfma_f32_16x16x32_bf16 v[32:35], v[156:159], v[172:175], v[32:35]
	v_mfma_f32_16x16x32_bf16 v[20:23], v[148:151], v[180:183], v[20:23]
	v_mfma_f32_16x16x32_bf16 v[16:19], v[156:159], v[180:183], v[16:19]
	v_mfma_f32_16x16x32_bf16 v[4:7], v[148:151], v[222:225], v[4:7]
	v_mfma_f32_16x16x32_bf16 v[0:3], v[156:159], v[222:225], v[0:3]
	s_barrier
; #define PG8_STAGE(bufoff, gbase, voff) do { _Pragma("unroll") for (int _i = 0; _i < 2; ++_i) \
;         __builtin_amdgcn_global_load_lds((const unsigned*)((const char*)(gbase) + (voff)[_i]), (PG8_LAS unsigned*)(lds + (bufoff) + ldsw + _i * 8192), 16, 0, 0); } while (0)
; #define PG8_LDA(dst, b, h) do { _Pragma("unroll") for (int m = 0; m < 4; ++m) _Pragma("unroll") for (int k = 0; k < 2; ++k) dst[m][k] = *(const PG8_LAS bf16x8*)(lds + PG8_SA(b, h) + aoff + m * 2048 + k * 1024); } while (0)
; #define PG8_LDB(dst, b, h) do { _Pragma("unroll") for (int n = 0; n < 2; ++n) _Pragma("unroll") for (int k = 0; k < 2; ++k) dst[n][k] = *(const PG8_LAS bf16x8*)(lds + PG8_SB(b, h) + boff + n * 2048 + k * 1024); } while (0)
; #define PG8_MMA(ai, bj, At, Bt) do { __builtin_amdgcn_s_setprio(1); _Pragma("unroll") for (int m = 0; m < 4; ++m) _Pragma("unroll") for (int n = 0; n < 2; ++n) _Pragma("unroll") for (int k = 0; k < 2; ++k) \
;         acc[ai][bj][m][n] = __builtin_amdgcn_mfma_f32_16x16x32_bf16(Bt[n][k], At[m][k], acc[ai][bj][m][n], 0, 0, 0); __builtin_amdgcn_s_setprio(0); } while (0)
; #define PG8_WAIT_V(n) asm volatile("s_waitcnt vmcnt(" #n ")" ::: "memory")
; #define PG8_WAIT_L(n) asm volatile("s_waitcnt lgkmcnt(" #n ")" ::: "memory")
; #define PG8_BAR __builtin_amdgcn_s_barrier()
; #define PG8_SCHED __builtin_amdgcn_sched_barrier(0)
; template <class Epi>
; __device__ __forceinline__ void gemm_phase(PG8_LAS unsigned char* lds, PG8_LAS unsigned char* xl, const Gemm g, const Sched& S, const Epi& E, const int wid) {
;     ...
;             PG8_LDB(B0, 1, 0); PG8_LDB(B1, 1, 1); PG8_SCHED; PG8_LDA(At, 1, 0); PG8_STAGE(PG8_SA(0, 1), a2 + hstepA, voffA);
;             PG8_WAIT_V(8); PG8_WAIT_L(0); PG8_BAR; if (do0) { PG8_MMA(0, 0, At, B0); PG8_MMA(0, 1, At, B1); } PG8_BAR; PG8_SCHED;
;             PG8_LDA(At, 1, 1); PG8_STAGE(PG8_SB(1, 0), b3, voffB); PG8_STAGE(PG8_SB(1, 1), b3 + hstepB, voffB); PG8_STAGE(PG8_SA(1, 0), a3, voffA);
;             PG8_WAIT_V(8); PG8_WAIT_L(0); PG8_BAR; if (do1) { PG8_MMA(1, 0, At, B0); PG8_MMA(1, 1, At, B1); } PG8_BAR; PG8_SCHED;
;         }
;         if (wr == 0) PG8_BAR;
	s_setprio 0
	s_add_i32 s11, 0, 0x18000
	s_add_i32 s13, 0, 0x1c000
	ds_read_b128 v[124:127], v226 offset:32768
	ds_read_b128 v[128:131], v226 offset:33792
	ds_read_b128 v[136:139], v226 offset:34816
	ds_read_b128 v[140:143], v226 offset:35840
	ds_read_b128 v[144:147], v226 offset:49152
	ds_read_b128 v[148:151], v226 offset:50176
	ds_read_b128 v[152:155], v226 offset:51200
	ds_read_b128 v[156:159], v226 offset:52224
	s_add_u32 s52, s60, 0x40000
	s_addc_u32 s53, s61, 0
	s_mov_b32 m0, s68
	ds_read_b128 v[160:163], v220 offset:32768
	ds_read_b128 v[164:167], v220 offset:33792
	ds_read_b128 v[168:171], v220 offset:34816
	ds_read_b128 v[172:175], v220 offset:35840
	ds_read_b128 v[176:179], v220 offset:36864
	ds_read_b128 v[180:183], v220 offset:37888
	ds_read_b128 v[184:187], v220 offset:38912
	ds_read_b128 v[222:225], v220 offset:39936
	global_load_lds_dwordx4 v188, s[52:53] sc0
	s_mov_b32 m0, s69
	s_nop 0
	global_load_lds_dwordx4 v210, s[52:53] sc0
	s_waitcnt vmcnt(8)
	s_waitcnt lgkmcnt(0)
	s_setprio 1
	s_barrier
	v_mfma_f32_16x16x32_bf16 v[132:135], v[124:127], v[160:163], v[132:135]
	v_mfma_f32_16x16x32_bf16 v[120:123], v[136:139], v[160:163], v[120:123]
	v_mfma_f32_16x16x32_bf16 v[108:111], v[124:127], v[168:171], v[108:111]
	v_mfma_f32_16x16x32_bf16 v[104:107], v[136:139], v[168:171], v[104:107]
	v_mfma_f32_16x16x32_bf16 v[92:95], v[124:127], v[176:179], v[92:95]
	v_mfma_f32_16x16x32_bf16 v[88:91], v[136:139], v[176:179], v[88:91]
	v_mfma_f32_16x16x32_bf16 v[76:79], v[124:127], v[184:187], v[76:79]
	v_mfma_f32_16x16x32_bf16 v[72:75], v[136:139], v[184:187], v[72:75]
	v_mfma_f32_16x16x32_bf16 v[132:135], v[128:131], v[164:167], v[132:135]
	v_mfma_f32_16x16x32_bf16 v[120:123], v[140:143], v[164:167], v[120:123]
	v_mfma_f32_16x16x32_bf16 v[108:111], v[128:131], v[172:175], v[108:111]
	v_mfma_f32_16x16x32_bf16 v[104:107], v[140:143], v[172:175], v[104:107]
	v_mfma_f32_16x16x32_bf16 v[92:95], v[128:131], v[180:183], v[92:95]
	v_mfma_f32_16x16x32_bf16 v[88:91], v[140:143], v[180:183], v[88:91]
	v_mfma_f32_16x16x32_bf16 v[76:79], v[128:131], v[222:225], v[76:79]
	v_mfma_f32_16x16x32_bf16 v[72:75], v[140:143], v[222:225], v[72:75]
	s_setprio 0
	s_setprio 1
	v_mfma_f32_16x16x32_bf16 v[116:119], v[144:147], v[160:163], v[116:119]
	v_mfma_f32_16x16x32_bf16 v[112:115], v[152:155], v[160:163], v[112:115]
	v_mfma_f32_16x16x32_bf16 v[100:103], v[144:147], v[168:171], v[100:103]
	v_mfma_f32_16x16x32_bf16 v[96:99], v[152:155], v[168:171], v[96:99]
	v_mfma_f32_16x16x32_bf16 v[84:87], v[144:147], v[176:179], v[84:87]
	v_mfma_f32_16x16x32_bf16 v[80:83], v[152:155], v[176:179], v[80:83]
	v_mfma_f32_16x16x32_bf16 v[68:71], v[144:147], v[184:187], v[68:71]
	v_mfma_f32_16x16x32_bf16 v[64:67], v[152:155], v[184:187], v[64:67]
	v_mfma_f32_16x16x32_bf16 v[116:119], v[148:151], v[164:167], v[116:119]
	v_mfma_f32_16x16x32_bf16 v[112:115], v[156:159], v[164:167], v[112:115]
	v_mfma_f32_16x16x32_bf16 v[100:103], v[148:151], v[172:175], v[100:103]
	v_mfma_f32_16x16x32_bf16 v[96:99], v[156:159], v[172:175], v[96:99]
	v_mfma_f32_16x16x32_bf16 v[84:87], v[148:151], v[180:183], v[84:87]
	v_mfma_f32_16x16x32_bf16 v[80:83], v[156:159], v[180:183], v[80:83]
	v_mfma_f32_16x16x32_bf16 v[68:71], v[148:151], v[222:225], v[68:71]
	v_mfma_f32_16x16x32_bf16 v[64:67], v[156:159], v[222:225], v[64:67]
	s_barrier
	s_setprio 0
	s_add_i32 s11, s11, s29
	s_mov_b32 m0, s11
	ds_read_b128 v[160:163], v220 offset:49152
	ds_read_b128 v[164:167], v220 offset:50176
	ds_read_b128 v[168:171], v220 offset:51200
	ds_read_b128 v[172:175], v220 offset:52224
	ds_read_b128 v[176:179], v220 offset:53248
	ds_read_b128 v[180:183], v220 offset:54272
	ds_read_b128 v[184:187], v220 offset:55296
	ds_read_b128 v[222:225], v220 offset:56320
	global_load_lds_dwordx4 v205, s[58:59] sc0
	s_add_i32 m0, s11, 0x2000
	s_add_u32 s52, s58, 0x40080
	global_load_lds_dwordx4 v219, s[58:59] sc0
	s_addc_u32 s53, s59, 0
	s_add_i32 s11, s13, s29
	s_mov_b32 m0, s11
	s_nop 0
	global_load_lds_dwordx4 v190, s[52:53] sc0
	s_add_i32 m0, s11, 0x2000
	s_nop 0
	global_load_lds_dwordx4 v212, s[52:53] sc0
	s_mov_b32 m0, s87
	s_nop 0
	global_load_lds_dwordx4 v204, s[60:61] sc0
	s_mov_b32 m0, s88
	s_nop 0
	global_load_lds_dwordx4 v218, s[60:61] sc0
	s_waitcnt vmcnt(8)
	s_waitcnt lgkmcnt(0)
	s_setprio 1
	s_barrier
	v_mfma_f32_16x16x32_bf16 v[60:63], v[124:127], v[160:163], v[60:63]
	v_mfma_f32_16x16x32_bf16 v[56:59], v[136:139], v[160:163], v[56:59]
	v_mfma_f32_16x16x32_bf16 v[44:47], v[124:127], v[168:171], v[44:47]
	v_mfma_f32_16x16x32_bf16 v[40:43], v[136:139], v[168:171], v[40:43]
	v_mfma_f32_16x16x32_bf16 v[28:31], v[124:127], v[176:179], v[28:31]
	v_mfma_f32_16x16x32_bf16 v[24:27], v[136:139], v[176:179], v[24:27]
	v_mfma_f32_16x16x32_bf16 v[12:15], v[124:127], v[184:187], v[12:15]
	v_mfma_f32_16x16x32_bf16 v[8:11], v[136:139], v[184:187], v[8:11]
	v_mfma_f32_16x16x32_bf16 v[60:63], v[128:131], v[164:167], v[60:63]
	v_mfma_f32_16x16x32_bf16 v[56:59], v[140:143], v[164:167], v[56:59]
	v_mfma_f32_16x16x32_bf16 v[44:47], v[128:131], v[172:175], v[44:47]
	v_mfma_f32_16x16x32_bf16 v[40:43], v[140:143], v[172:175], v[40:43]
	v_mfma_f32_16x16x32_bf16 v[28:31], v[128:131], v[180:183], v[28:31]
	v_mfma_f32_16x16x32_bf16 v[24:27], v[140:143], v[180:183], v[24:27]
	v_mfma_f32_16x16x32_bf16 v[12:15], v[128:131], v[222:225], v[12:15]
	v_mfma_f32_16x16x32_bf16 v[8:11], v[140:143], v[222:225], v[8:11]
	s_setprio 0
	s_setprio 1
	v_mfma_f32_16x16x32_bf16 v[52:55], v[144:147], v[160:163], v[52:55]
	v_mfma_f32_16x16x32_bf16 v[48:51], v[152:155], v[160:163], v[48:51]
	v_mfma_f32_16x16x32_bf16 v[36:39], v[144:147], v[168:171], v[36:39]
	v_mfma_f32_16x16x32_bf16 v[32:35], v[152:155], v[168:171], v[32:35]
	v_mfma_f32_16x16x32_bf16 v[20:23], v[144:147], v[176:179], v[20:23]
	v_mfma_f32_16x16x32_bf16 v[16:19], v[152:155], v[176:179], v[16:19]
	v_mfma_f32_16x16x32_bf16 v[4:7], v[144:147], v[184:187], v[4:7]
	v_mfma_f32_16x16x32_bf16 v[0:3], v[152:155], v[184:187], v[0:3]
	v_mfma_f32_16x16x32_bf16 v[52:55], v[148:151], v[164:167], v[52:55]
	v_mfma_f32_16x16x32_bf16 v[48:51], v[156:159], v[164:167], v[48:51]
	v_mfma_f32_16x16x32_bf16 v[36:39], v[148:151], v[172:175], v[36:39]
	v_mfma_f32_16x16x32_bf16 v[32:35], v[156:159], v[172:175], v[32:35]
	v_mfma_f32_16x16x32_bf16 v[20:23], v[148:151], v[180:183], v[20:23]
	v_mfma_f32_16x16x32_bf16 v[16:19], v[156:159], v[180:183], v[16:19]
	v_mfma_f32_16x16x32_bf16 v[4:7], v[148:151], v[222:225], v[4:7]
	v_mfma_f32_16x16x32_bf16 v[0:3], v[156:159], v[222:225], v[0:3]
	s_barrier
	s_setprio 0
	s_add_i32 s10, s10, 2
	s_add_u32 s8, s8, 0x100
	s_addc_u32 s9, s9, 0
	s_cmp_gt_u32 s10, 13
	s_mov_b64 s[52:53], s[56:57]
	s_cbranch_scc0 .LBB0_959
	s_and_b64 vcc, exec, s[14:15]
	s_cbranch_vccz .LBB0_962
	s_barrier

; __device__ __forceinline__ int lane_id_opq() { int l; asm volatile("v_mbcnt_lo_u32_b32 %0, -1, 0\n\tv_mbcnt_hi_u32_b32 %0, -1, %0" : "=v"(l)); return l; }
; #define PG8_STAGE(bufoff, gbase, voff) do { _Pragma("unroll") for (int _i = 0; _i < 2; ++_i) \
;         __builtin_amdgcn_global_load_lds((const unsigned*)((const char*)(gbase) + (voff)[_i]), (PG8_LAS unsigned*)(lds + (bufoff) + ldsw + _i * 8192), 16, 0, 0); } while (0)
; #define PG8_LDA(dst, b, h) do { _Pragma("unroll") for (int m = 0; m < 4; ++m) _Pragma("unroll") for (int k = 0; k < 2; ++k) dst[m][k] = *(const PG8_LAS bf16x8*)(lds + PG8_SA(b, h) + aoff + m * 2048 + k * 1024); } while (0)
; #define PG8_LDB(dst, b, h) do { _Pragma("unroll") for (int n = 0; n < 2; ++n) _Pragma("unroll") for (int k = 0; k < 2; ++k) dst[n][k] = *(const PG8_LAS bf16x8*)(lds + PG8_SB(b, h) + boff + n * 2048 + k * 1024); } while (0)
; #define PG8_BAR __builtin_amdgcn_s_barrier()
; template <class Epi>
; __device__ __forceinline__ void gemm_phase(PG8_LAS unsigned char* lds, PG8_LAS unsigned char* xl, const Gemm g, const Sched& S, const Epi& E, const int wid) {
;     ...
;             const bool last = (t == nt - 2);
;             const bool do0 = !blkdiag_v<Epi> || t == 0, do1 = !blkdiag_v<Epi> || t != 0;
;             long j1 = 0, ja2 = 0, jb2 = 0;
;             if constexpr (Epi::MID) {
;                 if (t == g.tj) { const int lnM = lane_id_opq(); E.mid(acc, cur, wr, wc, lnM & 15, lnM >> 4); }
;                 if (t >= g.tj) j1 = g.jA;
;                 if (t + 2 >= g.tj) { ja2 = g.jA; jb2 = g.jB; } }
;             const char* a1 = cA + (size_t)(t + 1) * kstep + j1;
;             const char* a2 = last ? nA : cA + (size_t)(t + 2) * kstep + ja2; const char* b2 = last ? nB : cB + (size_t)(t + 2) * kstep + jb2;
;             const char* a3 = a2 + kstep; const char* b3 = b2 + kstep;
;             PG8_LDB(B0, 0, 0); PG8_LDB(B1, 0, 1); PG8_SCHED; PG8_LDA(At, 0, 0); PG8_STAGE(PG8_SA(1, 1), a1 + hstepA, voffA);
;             PG8_WAIT_V(8); PG8_WAIT_L(0); PG8_BAR; if (do0) { PG8_MMA(0, 0, At, B0); PG8_MMA(0, 1, At, B1); } PG8_BAR; PG8_SCHED;
;             PG8_LDA(At, 0, 1); PG8_STAGE(PG8_SB(0, 0), b2, voffB); PG8_STAGE(PG8_SB(0, 1), b2 + hstepB, voffB); PG8_STAGE(PG8_SA(0, 0), a2, voffA);
;             PG8_WAIT_V(8); PG8_WAIT_L(0); PG8_BAR; if (do1) { PG8_MMA(1, 0, At, B0); PG8_MMA(1, 1, At, B1); } PG8_BAR; PG8_SCHED;
.Ldefbar_skip_9:
	v_add_u32_e32 v204, s22, v210
	v_add_u32_e32 v205, s22, v212
	v_add_u32_e32 v226, s22, v214
	v_add_u32_e32 v227, s22, v216
	v_add_u32_e32 v248, 0x10000, v195
	s_add_u32 s76, s44, 0x100
	s_addc_u32 s77, s45, 0
	s_add_i32 s55, 0, 0x10000
	s_cmp_eq_u32 s54, 28
	s_cselect_b32 s11, s8, s77
	s_cselect_b32 s10, s9, s76
	s_cselect_b32 vcc_hi, s49, s73
	s_cselect_b32 vcc_lo, s61, s72
	s_add_i32 s4, 0, 0x14000
	ds_read_b128 v[4:7], v248 offset:0
	ds_read_b128 v[8:11], v248 offset:1024
	ds_read_b128 v[84:87], v248 offset:2048
	ds_read_b128 v[88:91], v248 offset:3072
	ds_read_b128 v[92:95], v248 offset:16384
	ds_read_b128 v[96:99], v248 offset:17408
	ds_read_b128 v[100:103], v248 offset:18432
	ds_read_b128 v[104:107], v248 offset:19456
	s_add_i32 m0, s90, 0xc000
	ds_read_b128 v[108:111], v225
	ds_read_b128 v[172:175], v225 offset:1024
	ds_read_b128 v[176:179], v225 offset:2048
	ds_read_b128 v[180:183], v225 offset:3072
	ds_read_b128 v[184:187], v225 offset:4096
	ds_read_b128 v[188:191], v225 offset:5120
	ds_read_b128 v[230:233], v225 offset:6144
	ds_read_b128 v[234:237], v225 offset:7168
	global_load_lds_dwordx4 v218, s[44:45] sc0
	s_add_i32 m0, s90, 0xe000
	s_nop 0
	global_load_lds_dwordx4 v220, s[44:45] sc0
	s_waitcnt vmcnt(8)
	s_waitcnt lgkmcnt(0)
	s_setprio 1
	s_barrier
	v_mfma_f32_16x16x32_bf16 v[60:63], v[4:7], v[108:111], 0
	v_mfma_f32_16x16x32_bf16 v[64:67], v[84:87], v[108:111], 0
	v_mfma_f32_16x16x32_bf16 v[120:123], v[4:7], v[176:179], 0
	v_mfma_f32_16x16x32_bf16 v[124:127], v[84:87], v[176:179], 0
	v_mfma_f32_16x16x32_bf16 v[164:167], v[4:7], v[184:187], 0
	v_mfma_f32_16x16x32_bf16 v[160:163], v[84:87], v[184:187], 0
	v_mfma_f32_16x16x32_bf16 v[80:83], v[4:7], v[230:233], 0
	v_mfma_f32_16x16x32_bf16 v[128:131], v[84:87], v[230:233], 0
	v_mfma_f32_16x16x32_bf16 v[60:63], v[8:11], v[172:175], v[60:63]
	v_mfma_f32_16x16x32_bf16 v[64:67], v[88:91], v[172:175], v[64:67]
	v_mfma_f32_16x16x32_bf16 v[120:123], v[8:11], v[180:183], v[120:123]
	v_mfma_f32_16x16x32_bf16 v[124:127], v[88:91], v[180:183], v[124:127]
	v_mfma_f32_16x16x32_bf16 v[164:167], v[8:11], v[188:191], v[164:167]
	v_mfma_f32_16x16x32_bf16 v[160:163], v[88:91], v[188:191], v[160:163]
	v_mfma_f32_16x16x32_bf16 v[80:83], v[8:11], v[234:237], v[80:83]
	v_mfma_f32_16x16x32_bf16 v[128:131], v[88:91], v[234:237], v[128:131]
	s_setprio 0
	s_setprio 1
	v_mfma_f32_16x16x32_bf16 v[112:115], v[92:95], v[108:111], 0
	v_mfma_f32_16x16x32_bf16 v[108:111], v[100:103], v[108:111], 0
	v_mfma_f32_16x16x32_bf16 v[116:119], v[92:95], v[176:179], 0
	v_mfma_f32_16x16x32_bf16 v[156:159], v[96:99], v[180:183], v[116:119]
	v_mfma_f32_16x16x32_bf16 v[116:119], v[100:103], v[176:179], 0
	v_mfma_f32_16x16x32_bf16 v[152:155], v[104:107], v[180:183], v[116:119]
	v_mfma_f32_16x16x32_bf16 v[116:119], v[92:95], v[184:187], 0
	v_mfma_f32_16x16x32_bf16 v[148:151], v[96:99], v[188:191], v[116:119]
	v_mfma_f32_16x16x32_bf16 v[116:119], v[100:103], v[184:187], 0
	v_mfma_f32_16x16x32_bf16 v[144:147], v[104:107], v[188:191], v[116:119]
	v_mfma_f32_16x16x32_bf16 v[116:119], v[92:95], v[230:233], 0
	v_mfma_f32_16x16x32_bf16 v[140:143], v[96:99], v[234:237], v[116:119]
	v_mfma_f32_16x16x32_bf16 v[116:119], v[100:103], v[230:233], 0
	v_mfma_f32_16x16x32_bf16 v[112:115], v[96:99], v[172:175], v[112:115]
	v_mfma_f32_16x16x32_bf16 v[136:139], v[104:107], v[234:237], v[116:119]
	v_mfma_f32_16x16x32_bf16 v[108:111], v[104:107], v[172:175], v[108:111]
	s_barrier
	s_setprio 0
	s_add_i32 s5, s55, s29
	s_mov_b32 m0, s5
	ds_read_b128 v[116:119], v225 offset:16384
	ds_read_b128 v[172:175], v225 offset:17408
	ds_read_b128 v[176:179], v225 offset:18432
	ds_read_b128 v[180:183], v225 offset:19456
	ds_read_b128 v[184:187], v225 offset:20480
	ds_read_b128 v[188:191], v225 offset:21504
	ds_read_b128 v[230:233], v225 offset:22528
	ds_read_b128 v[234:237], v225 offset:23552
	global_load_lds_dwordx4 v212, vcc sc0
	s_add_i32 m0, s5, 0x2000
	s_add_u32 s44, vcc_lo, 0x80000
	s_addc_u32 s45, vcc_hi, 0
	s_add_i32 s4, s4, s29
	global_load_lds_dwordx4 v216, vcc sc0
	s_mov_b32 m0, s4
	s_nop 0
	global_load_lds_dwordx4 v212, s[44:45] sc0
	s_add_i32 m0, s4, 0x2000
	s_nop 0
	global_load_lds_dwordx4 v216, s[44:45] sc0
	s_mov_b32 m0, s90
	s_nop 0
	global_load_lds_dwordx4 v210, s[10:11] sc0
	s_mov_b32 m0, s13
	s_nop 0
	global_load_lds_dwordx4 v214, s[10:11] sc0
	s_waitcnt vmcnt(8)
	s_waitcnt lgkmcnt(0)
	s_setprio 1
	s_barrier
	v_mfma_f32_16x16x32_bf16 v[132:135], v[4:7], v[116:119], 0
	v_mfma_f32_16x16x32_bf16 v[68:71], v[84:87], v[116:119], 0
	v_mfma_f32_16x16x32_bf16 v[56:59], v[4:7], v[176:179], 0
	v_mfma_f32_16x16x32_bf16 v[52:55], v[84:87], v[176:179], 0
	v_mfma_f32_16x16x32_bf16 v[40:43], v[4:7], v[184:187], 0
	v_mfma_f32_16x16x32_bf16 v[36:39], v[84:87], v[184:187], 0
	v_mfma_f32_16x16x32_bf16 v[4:7], v[4:7], v[230:233], 0
	v_mfma_f32_16x16x32_bf16 v[132:135], v[8:11], v[172:175], v[132:135]
	v_mfma_f32_16x16x32_bf16 v[68:71], v[88:91], v[172:175], v[68:71]
	v_mfma_f32_16x16x32_bf16 v[56:59], v[8:11], v[180:183], v[56:59]
	v_mfma_f32_16x16x32_bf16 v[52:55], v[88:91], v[180:183], v[52:55]
	v_mfma_f32_16x16x32_bf16 v[40:43], v[8:11], v[188:191], v[40:43]
	v_mfma_f32_16x16x32_bf16 v[36:39], v[88:91], v[188:191], v[36:39]
	v_mfma_f32_16x16x32_bf16 v[4:7], v[8:11], v[234:237], v[4:7]
	v_mfma_f32_16x16x32_bf16 v[8:11], v[84:87], v[230:233], 0
	v_mfma_f32_16x16x32_bf16 v[8:11], v[88:91], v[234:237], v[8:11]
	s_setprio 0
	s_setprio 1
	v_mfma_f32_16x16x32_bf16 v[48:51], v[92:95], v[116:119], 0
	v_mfma_f32_16x16x32_bf16 v[44:47], v[100:103], v[116:119], 0
	v_mfma_f32_16x16x32_bf16 v[32:35], v[92:95], v[176:179], 0
	v_mfma_f32_16x16x32_bf16 v[28:31], v[100:103], v[176:179], 0
	v_mfma_f32_16x16x32_bf16 v[24:27], v[92:95], v[184:187], 0
	v_mfma_f32_16x16x32_bf16 v[20:23], v[100:103], v[184:187], 0
	v_mfma_f32_16x16x32_bf16 v[16:19], v[92:95], v[230:233], 0
	v_mfma_f32_16x16x32_bf16 v[12:15], v[100:103], v[230:233], 0
	v_mfma_f32_16x16x32_bf16 v[48:51], v[96:99], v[172:175], v[48:51]
	v_mfma_f32_16x16x32_bf16 v[44:47], v[104:107], v[172:175], v[44:47]
	v_mfma_f32_16x16x32_bf16 v[32:35], v[96:99], v[180:183], v[32:35]
	v_mfma_f32_16x16x32_bf16 v[28:31], v[104:107], v[180:183], v[28:31]
	v_mfma_f32_16x16x32_bf16 v[24:27], v[96:99], v[188:191], v[24:27]
	v_mfma_f32_16x16x32_bf16 v[20:23], v[104:107], v[188:191], v[20:23]
	v_mfma_f32_16x16x32_bf16 v[16:19], v[96:99], v[234:237], v[16:19]
	v_mfma_f32_16x16x32_bf16 v[12:15], v[104:107], v[234:237], v[12:15]
	s_barrier
; #define PG8_STAGE(bufoff, gbase, voff) do { _Pragma("unroll") for (int _i = 0; _i < 2; ++_i) \
;         __builtin_amdgcn_global_load_lds((const unsigned*)((const char*)(gbase) + (voff)[_i]), (PG8_LAS unsigned*)(lds + (bufoff) + ldsw + _i * 8192), 16, 0, 0); } while (0)
; #define PG8_LDA(dst, b, h) do { _Pragma("unroll") for (int m = 0; m < 4; ++m) _Pragma("unroll") for (int k = 0; k < 2; ++k) dst[m][k] = *(const PG8_LAS bf16x8*)(lds + PG8_SA(b, h) + aoff + m * 2048 + k * 1024); } while (0)
; #define PG8_LDB(dst, b, h) do { _Pragma("unroll") for (int n = 0; n < 2; ++n) _Pragma("unroll") for (int k = 0; k < 2; ++k) dst[n][k] = *(const PG8_LAS bf16x8*)(lds + PG8_SB(b, h) + boff + n * 2048 + k * 1024); } while (0)
; #define PG8_MMA(ai, bj, At, Bt) do { __builtin_amdgcn_s_setprio(1); _Pragma("unroll") for (int m = 0; m < 4; ++m) _Pragma("unroll") for (int n = 0; n < 2; ++n) _Pragma("unroll") for (int k = 0; k < 2; ++k) \
;         acc[ai][bj][m][n] = __builtin_amdgcn_mfma_f32_16x16x32_bf16(Bt[n][k], At[m][k], acc[ai][bj][m][n], 0, 0, 0); __builtin_amdgcn_s_setprio(0); } while (0)
; #define PG8_WAIT_V(n) asm volatile("s_waitcnt vmcnt(" #n ")" ::: "memory")
; #define PG8_WAIT_L(n) asm volatile("s_waitcnt lgkmcnt(" #n ")" ::: "memory")
; #define PG8_BAR __builtin_amdgcn_s_barrier()
; #define PG8_SCHED __builtin_amdgcn_sched_barrier(0)
; template <class Epi>
; __device__ __forceinline__ void gemm_phase(PG8_LAS unsigned char* lds, PG8_LAS unsigned char* xl, const Gemm g, const Sched& S, const Epi& E, const int wid) {
;     ...
;             PG8_LDB(B0, 1, 0); PG8_LDB(B1, 1, 1); PG8_SCHED; PG8_LDA(At, 1, 0); PG8_STAGE(PG8_SA(0, 1), a2 + hstepA, voffA);
;             PG8_WAIT_V(8); PG8_WAIT_L(0); PG8_BAR; if (do0) { PG8_MMA(0, 0, At, B0); PG8_MMA(0, 1, At, B1); } PG8_BAR; PG8_SCHED;
;             PG8_LDA(At, 1, 1); PG8_STAGE(PG8_SB(1, 0), b3, voffB); PG8_STAGE(PG8_SB(1, 1), b3 + hstepB, voffB); PG8_STAGE(PG8_SA(1, 0), a3, voffA);
;             PG8_WAIT_V(8); PG8_WAIT_L(0); PG8_BAR; if (do1) { PG8_MMA(1, 0, At, B0); PG8_MMA(1, 1, At, B1); } PG8_BAR; PG8_SCHED;
;         }
	s_setprio 0
	s_add_i32 s4, 0, 0x18000
	s_add_i32 s5, 0, 0x1c000
	ds_read_b128 v[72:75], v248 offset:32768
	ds_read_b128 v[84:87], v248 offset:33792
	ds_read_b128 v[88:91], v248 offset:34816
	ds_read_b128 v[92:95], v248 offset:35840
	ds_read_b128 v[96:99], v248 offset:49152
	ds_read_b128 v[100:103], v248 offset:50176
	ds_read_b128 v[104:107], v248 offset:51200
	ds_read_b128 v[172:175], v248 offset:52224
	s_add_u32 s100, s10, 0x80000
	s_addc_u32 s101, s11, 0
	s_mov_b32 m0, s91
	ds_read_b128 v[116:119], v225 offset:32768
	ds_read_b128 v[168:171], v225 offset:33792
	ds_read_b128 v[176:179], v225 offset:34816
	ds_read_b128 v[180:183], v225 offset:35840
	ds_read_b128 v[184:187], v225 offset:36864
	ds_read_b128 v[188:191], v225 offset:37888
	ds_read_b128 v[230:233], v225 offset:38912
	ds_read_b128 v[234:237], v225 offset:39936
	global_load_lds_dwordx4 v210, s[100:101] sc0
	s_mov_b32 m0, s92
	s_nop 0
	global_load_lds_dwordx4 v214, s[100:101] sc0
	s_waitcnt vmcnt(8)
	s_waitcnt lgkmcnt(0)
	s_setprio 1
	s_barrier
	v_mfma_f32_16x16x32_bf16 v[60:63], v[72:75], v[116:119], v[60:63]
	v_mfma_f32_16x16x32_bf16 v[64:67], v[88:91], v[116:119], v[64:67]
	v_mfma_f32_16x16x32_bf16 v[120:123], v[72:75], v[176:179], v[120:123]
	v_mfma_f32_16x16x32_bf16 v[124:127], v[88:91], v[176:179], v[124:127]
	v_mfma_f32_16x16x32_bf16 v[164:167], v[72:75], v[184:187], v[164:167]
	v_mfma_f32_16x16x32_bf16 v[160:163], v[88:91], v[184:187], v[160:163]
	v_mfma_f32_16x16x32_bf16 v[80:83], v[72:75], v[230:233], v[80:83]
	v_mfma_f32_16x16x32_bf16 v[128:131], v[88:91], v[230:233], v[128:131]
	v_mfma_f32_16x16x32_bf16 v[60:63], v[84:87], v[168:171], v[60:63]
	v_mfma_f32_16x16x32_bf16 v[64:67], v[92:95], v[168:171], v[64:67]
	v_mfma_f32_16x16x32_bf16 v[120:123], v[84:87], v[180:183], v[120:123]
	v_mfma_f32_16x16x32_bf16 v[124:127], v[92:95], v[180:183], v[124:127]
	v_mfma_f32_16x16x32_bf16 v[164:167], v[84:87], v[188:191], v[164:167]
	v_mfma_f32_16x16x32_bf16 v[160:163], v[92:95], v[188:191], v[160:163]
	v_mfma_f32_16x16x32_bf16 v[80:83], v[84:87], v[234:237], v[80:83]
	v_mfma_f32_16x16x32_bf16 v[128:131], v[92:95], v[234:237], v[128:131]
	s_setprio 0
	s_setprio 1
	v_mfma_f32_16x16x32_bf16 v[108:111], v[104:107], v[116:119], v[108:111]
	v_mfma_f32_16x16x32_bf16 v[112:115], v[96:99], v[116:119], v[112:115]
	v_mfma_f32_16x16x32_bf16 v[116:119], v[172:175], v[168:171], v[108:111]
	v_mfma_f32_16x16x32_bf16 v[108:111], v[96:99], v[176:179], v[156:159]
	v_mfma_f32_16x16x32_bf16 v[156:159], v[100:103], v[180:183], v[108:111]
	v_mfma_f32_16x16x32_bf16 v[108:111], v[104:107], v[176:179], v[152:155]
	v_mfma_f32_16x16x32_bf16 v[152:155], v[172:175], v[180:183], v[108:111]
	v_mfma_f32_16x16x32_bf16 v[108:111], v[96:99], v[184:187], v[148:151]
	v_mfma_f32_16x16x32_bf16 v[148:151], v[100:103], v[188:191], v[108:111]
	v_mfma_f32_16x16x32_bf16 v[108:111], v[104:107], v[184:187], v[144:147]
	v_mfma_f32_16x16x32_bf16 v[144:147], v[172:175], v[188:191], v[108:111]
	v_mfma_f32_16x16x32_bf16 v[108:111], v[96:99], v[230:233], v[140:143]
	v_mfma_f32_16x16x32_bf16 v[140:143], v[100:103], v[234:237], v[108:111]
	v_mfma_f32_16x16x32_bf16 v[108:111], v[104:107], v[230:233], v[136:139]
	v_mfma_f32_16x16x32_bf16 v[112:115], v[100:103], v[168:171], v[112:115]
	v_mfma_f32_16x16x32_bf16 v[136:139], v[172:175], v[234:237], v[108:111]
	s_barrier
	s_setprio 0
	s_add_i32 s4, s4, s29
	s_mov_b32 m0, s4
	s_nop 0
	ds_read_b128 v[108:111], v225 offset:49152
	ds_read_b128 v[176:179], v225 offset:50176
	ds_read_b128 v[180:183], v225 offset:51200
	ds_read_b128 v[184:187], v225 offset:52224
	ds_read_b128 v[188:191], v225 offset:53248
	ds_read_b128 v[230:233], v225 offset:54272
	ds_read_b128 v[234:237], v225 offset:55296
	ds_read_b128 v[238:241], v225 offset:56320
	global_load_lds_dwordx4 v205, vcc sc0
	s_add_i32 m0, s4, 0x2000
	s_add_u32 s100, vcc_lo, 0x80080
	global_load_lds_dwordx4 v227, vcc sc0
	s_addc_u32 s101, vcc_hi, 0
	s_add_i32 s4, s5, s29
	s_mov_b32 m0, s4
	s_nop 0
	global_load_lds_dwordx4 v212, s[100:101] sc0
	s_add_i32 m0, s4, 0x2000
	s_nop 0
	global_load_lds_dwordx4 v216, s[100:101] sc0
	s_mov_b32 m0, s40
	s_nop 0
	global_load_lds_dwordx4 v204, s[10:11] sc0
	s_mov_b32 m0, s41
	s_nop 0
	global_load_lds_dwordx4 v226, s[10:11] sc0
	s_waitcnt vmcnt(8)
	s_waitcnt lgkmcnt(0)
	s_setprio 1
	s_barrier
	v_mfma_f32_16x16x32_bf16 v[4:7], v[72:75], v[234:237], v[4:7]
	v_mfma_f32_16x16x32_bf16 v[132:135], v[72:75], v[108:111], v[132:135]
	v_mfma_f32_16x16x32_bf16 v[68:71], v[88:91], v[108:111], v[68:71]
	v_mfma_f32_16x16x32_bf16 v[56:59], v[72:75], v[180:183], v[56:59]
	v_mfma_f32_16x16x32_bf16 v[52:55], v[88:91], v[180:183], v[52:55]
	v_mfma_f32_16x16x32_bf16 v[40:43], v[72:75], v[188:191], v[40:43]
	v_mfma_f32_16x16x32_bf16 v[36:39], v[88:91], v[188:191], v[36:39]
	v_mfma_f32_16x16x32_bf16 v[168:171], v[84:87], v[238:241], v[4:7]
	v_mfma_f32_16x16x32_bf16 v[4:7], v[88:91], v[234:237], v[8:11]
	v_mfma_f32_16x16x32_bf16 v[132:135], v[84:87], v[176:179], v[132:135]
	v_mfma_f32_16x16x32_bf16 v[68:71], v[92:95], v[176:179], v[68:71]
	v_mfma_f32_16x16x32_bf16 v[56:59], v[84:87], v[184:187], v[56:59]
	v_mfma_f32_16x16x32_bf16 v[52:55], v[92:95], v[184:187], v[52:55]
	v_mfma_f32_16x16x32_bf16 v[40:43], v[84:87], v[230:233], v[40:43]
	v_mfma_f32_16x16x32_bf16 v[36:39], v[92:95], v[230:233], v[36:39]
	v_mfma_f32_16x16x32_bf16 v[72:75], v[92:95], v[238:241], v[4:7]
	s_setprio 0
	s_setprio 1
	v_mfma_f32_16x16x32_bf16 v[4:7], v[96:99], v[108:111], v[48:51]
	v_mfma_f32_16x16x32_bf16 v[48:51], v[100:103], v[176:179], v[4:7]
	v_mfma_f32_16x16x32_bf16 v[4:7], v[104:107], v[108:111], v[44:47]
	v_mfma_f32_16x16x32_bf16 v[44:47], v[172:175], v[176:179], v[4:7]
	v_mfma_f32_16x16x32_bf16 v[4:7], v[96:99], v[180:183], v[32:35]
	v_mfma_f32_16x16x32_bf16 v[32:35], v[100:103], v[184:187], v[4:7]
	v_mfma_f32_16x16x32_bf16 v[4:7], v[104:107], v[180:183], v[28:31]
	v_mfma_f32_16x16x32_bf16 v[28:31], v[172:175], v[184:187], v[4:7]
	v_mfma_f32_16x16x32_bf16 v[4:7], v[96:99], v[188:191], v[24:27]
	v_mfma_f32_16x16x32_bf16 v[24:27], v[100:103], v[230:233], v[4:7]
	v_mfma_f32_16x16x32_bf16 v[4:7], v[104:107], v[188:191], v[20:23]
	v_mfma_f32_16x16x32_bf16 v[20:23], v[172:175], v[230:233], v[4:7]
	v_mfma_f32_16x16x32_bf16 v[4:7], v[96:99], v[234:237], v[16:19]
	v_mfma_f32_16x16x32_bf16 v[16:19], v[100:103], v[238:241], v[4:7]
	v_mfma_f32_16x16x32_bf16 v[4:7], v[104:107], v[234:237], v[12:15]
	v_mfma_f32_16x16x32_bf16 v[12:15], v[172:175], v[238:241], v[4:7]
	s_barrier
	s_setprio 0
	s_add_i32 s54, s54, 2
	s_add_u32 s72, s72, 0x100
	s_addc_u32 s73, s73, 0
	s_cmp_gt_u32 s54, 29
	s_mov_b64 s[44:45], s[76:77]
; __device__ __forceinline__ int lane_id_opq() { int l; asm volatile("v_mbcnt_lo_u32_b32 %0, -1, 0\n\tv_mbcnt_hi_u32_b32 %0, -1, %0" : "=v"(l)); return l; }
; #define PG8_STAGE(bufoff, gbase, voff) do { _Pragma("unroll") for (int _i = 0; _i < 2; ++_i) \
;         __builtin_amdgcn_global_load_lds((const unsigned*)((const char*)(gbase) + (voff)[_i]), (PG8_LAS unsigned*)(lds + (bufoff) + ldsw + _i * 8192), 16, 0, 0); } while (0)
; #define PG8_LDA(dst, b, h) do { _Pragma("unroll") for (int m = 0; m < 4; ++m) _Pragma("unroll") for (int k = 0; k < 2; ++k) dst[m][k] = *(const PG8_LAS bf16x8*)(lds + PG8_SA(b, h) + aoff + m * 2048 + k * 1024); } while (0)
; #define PG8_LDB(dst, b, h) do { _Pragma("unroll") for (int n = 0; n < 2; ++n) _Pragma("unroll") for (int k = 0; k < 2; ++k) dst[n][k] = *(const PG8_LAS bf16x8*)(lds + PG8_SB(b, h) + boff + n * 2048 + k * 1024); } while (0)
; #define PG8_BAR __builtin_amdgcn_s_barrier()
; template <class Epi>
; __device__ __forceinline__ void gemm_phase(PG8_LAS unsigned char* lds, PG8_LAS unsigned char* xl, const Gemm g, const Sched& S, const Epi& E, const int wid) {
;     ...
;             const bool last = (t == nt - 2);
;             const bool do0 = !blkdiag_v<Epi> || t == 0, do1 = !blkdiag_v<Epi> || t != 0;
;             long j1 = 0, ja2 = 0, jb2 = 0;
;             if constexpr (Epi::MID) {
;                 if (t == g.tj) { const int lnM = lane_id_opq(); E.mid(acc, cur, wr, wc, lnM & 15, lnM >> 4); }
;                 if (t >= g.tj) j1 = g.jA;
;                 if (t + 2 >= g.tj) { ja2 = g.jA; jb2 = g.jB; } }
;             const char* a1 = cA + (size_t)(t + 1) * kstep + j1;
;             const char* a2 = last ? nA : cA + (size_t)(t + 2) * kstep + ja2; const char* b2 = last ? nB : cB + (size_t)(t + 2) * kstep + jb2;
;             const char* a3 = a2 + kstep; const char* b3 = b2 + kstep;
;             PG8_LDB(B0, 0, 0); PG8_LDB(B1, 0, 1); PG8_SCHED; PG8_LDA(At, 0, 0); PG8_STAGE(PG8_SA(1, 1), a1 + hstepA, voffA);
;             PG8_WAIT_V(8); PG8_WAIT_L(0); PG8_BAR; if (do0) { PG8_MMA(0, 0, At, B0); PG8_MMA(0, 1, At, B1); } PG8_BAR; PG8_SCHED;
;             PG8_LDA(At, 0, 1); PG8_STAGE(PG8_SB(0, 0), b2, voffB); PG8_STAGE(PG8_SB(0, 1), b2 + hstepB, voffB); PG8_STAGE(PG8_SA(0, 0), a2, voffA);
;             PG8_WAIT_V(8); PG8_WAIT_L(0); PG8_BAR; if (do1) { PG8_MMA(1, 0, At, B0); PG8_MMA(1, 1, At, B1); } PG8_BAR; PG8_SCHED;
.LBB0_1106:
	s_add_u32 s76, s44, 0x100
	s_addc_u32 s77, s45, 0
	s_add_i32 s55, 0, 0x10000
	s_cmp_eq_u32 s54, 28
	s_cselect_b32 s11, s8, s77
	s_cselect_b32 s10, s9, s76
	s_cselect_b32 vcc_hi, s49, s73
	s_cselect_b32 vcc_lo, s61, s72
	s_add_i32 s4, 0, 0x14000
	ds_read_b128 v[4:7], v248 offset:0
	ds_read_b128 v[8:11], v248 offset:1024
	ds_read_b128 v[84:87], v248 offset:2048
	ds_read_b128 v[88:91], v248 offset:3072
	ds_read_b128 v[92:95], v248 offset:16384
	ds_read_b128 v[96:99], v248 offset:17408
	ds_read_b128 v[100:103], v248 offset:18432
	ds_read_b128 v[104:107], v248 offset:19456
	s_add_i32 m0, s90, 0xc000
	ds_read_b128 v[108:111], v225
	ds_read_b128 v[172:175], v225 offset:1024
	ds_read_b128 v[176:179], v225 offset:2048
	ds_read_b128 v[180:183], v225 offset:3072
	ds_read_b128 v[184:187], v225 offset:4096
	ds_read_b128 v[188:191], v225 offset:5120
	ds_read_b128 v[230:233], v225 offset:6144
	ds_read_b128 v[234:237], v225 offset:7168
	global_load_lds_dwordx4 v218, s[44:45] sc0
	s_add_i32 m0, s90, 0xe000
	s_nop 0
	global_load_lds_dwordx4 v220, s[44:45] sc0
	s_waitcnt vmcnt(8)
	s_waitcnt lgkmcnt(0)
	s_setprio 1
	s_barrier
	v_mfma_f32_16x16x32_bf16 v[60:63], v[4:7], v[108:111], v[60:63]
	v_mfma_f32_16x16x32_bf16 v[64:67], v[84:87], v[108:111], v[64:67]
	v_mfma_f32_16x16x32_bf16 v[120:123], v[4:7], v[176:179], v[120:123]
	v_mfma_f32_16x16x32_bf16 v[124:127], v[84:87], v[176:179], v[124:127]
	v_mfma_f32_16x16x32_bf16 v[164:167], v[4:7], v[184:187], v[164:167]
	v_mfma_f32_16x16x32_bf16 v[160:163], v[84:87], v[184:187], v[160:163]
	v_mfma_f32_16x16x32_bf16 v[80:83], v[4:7], v[230:233], v[80:83]
	v_mfma_f32_16x16x32_bf16 v[128:131], v[84:87], v[230:233], v[128:131]
	v_mfma_f32_16x16x32_bf16 v[60:63], v[8:11], v[172:175], v[60:63]
	v_mfma_f32_16x16x32_bf16 v[64:67], v[88:91], v[172:175], v[64:67]
	v_mfma_f32_16x16x32_bf16 v[120:123], v[8:11], v[180:183], v[120:123]
	v_mfma_f32_16x16x32_bf16 v[124:127], v[88:91], v[180:183], v[124:127]
	v_mfma_f32_16x16x32_bf16 v[164:167], v[8:11], v[188:191], v[164:167]
	v_mfma_f32_16x16x32_bf16 v[160:163], v[88:91], v[188:191], v[160:163]
	v_mfma_f32_16x16x32_bf16 v[80:83], v[8:11], v[234:237], v[80:83]
	v_mfma_f32_16x16x32_bf16 v[128:131], v[88:91], v[234:237], v[128:131]
	s_setprio 0
	s_setprio 1
	v_mfma_f32_16x16x32_bf16 v[112:115], v[92:95], v[108:111], v[112:115]
	v_mfma_f32_16x16x32_bf16 v[108:111], v[100:103], v[108:111], v[116:119]
	v_mfma_f32_16x16x32_bf16 v[116:119], v[92:95], v[176:179], v[156:159]
	v_mfma_f32_16x16x32_bf16 v[156:159], v[96:99], v[180:183], v[116:119]
	v_mfma_f32_16x16x32_bf16 v[116:119], v[100:103], v[176:179], v[152:155]
	v_mfma_f32_16x16x32_bf16 v[152:155], v[104:107], v[180:183], v[116:119]
	v_mfma_f32_16x16x32_bf16 v[116:119], v[92:95], v[184:187], v[148:151]
	v_mfma_f32_16x16x32_bf16 v[148:151], v[96:99], v[188:191], v[116:119]
	v_mfma_f32_16x16x32_bf16 v[116:119], v[100:103], v[184:187], v[144:147]
	v_mfma_f32_16x16x32_bf16 v[144:147], v[104:107], v[188:191], v[116:119]
	v_mfma_f32_16x16x32_bf16 v[116:119], v[92:95], v[230:233], v[140:143]
	v_mfma_f32_16x16x32_bf16 v[140:143], v[96:99], v[234:237], v[116:119]
	v_mfma_f32_16x16x32_bf16 v[116:119], v[100:103], v[230:233], v[136:139]
	v_mfma_f32_16x16x32_bf16 v[112:115], v[96:99], v[172:175], v[112:115]
	v_mfma_f32_16x16x32_bf16 v[136:139], v[104:107], v[234:237], v[116:119]
	v_mfma_f32_16x16x32_bf16 v[108:111], v[104:107], v[172:175], v[108:111]
	s_barrier
	s_setprio 0
	s_add_i32 s5, s55, s29
	s_mov_b32 m0, s5
	ds_read_b128 v[116:119], v225 offset:16384
	ds_read_b128 v[172:175], v225 offset:17408
	ds_read_b128 v[176:179], v225 offset:18432
	ds_read_b128 v[180:183], v225 offset:19456
	ds_read_b128 v[184:187], v225 offset:20480
	ds_read_b128 v[188:191], v225 offset:21504
	ds_read_b128 v[230:233], v225 offset:22528
	ds_read_b128 v[234:237], v225 offset:23552
	global_load_lds_dwordx4 v212, vcc sc0
	s_add_i32 m0, s5, 0x2000
	s_add_u32 s44, vcc_lo, 0x80000
	s_addc_u32 s45, vcc_hi, 0
	s_add_i32 s4, s4, s29
	global_load_lds_dwordx4 v216, vcc sc0
	s_mov_b32 m0, s4
	s_nop 0
	global_load_lds_dwordx4 v212, s[44:45] sc0
	s_add_i32 m0, s4, 0x2000
	s_nop 0
	global_load_lds_dwordx4 v216, s[44:45] sc0
	s_mov_b32 m0, s90
	s_nop 0
	global_load_lds_dwordx4 v210, s[10:11] sc0
	s_mov_b32 m0, s13
	s_nop 0
	global_load_lds_dwordx4 v214, s[10:11] sc0
	s_waitcnt vmcnt(8)
	s_waitcnt lgkmcnt(0)
	s_setprio 1
	s_barrier
	v_mfma_f32_16x16x32_bf16 v[132:135], v[4:7], v[116:119], v[132:135]
	v_mfma_f32_16x16x32_bf16 v[68:71], v[84:87], v[116:119], v[68:71]
	v_mfma_f32_16x16x32_bf16 v[56:59], v[4:7], v[176:179], v[56:59]
	v_mfma_f32_16x16x32_bf16 v[52:55], v[84:87], v[176:179], v[52:55]
	v_mfma_f32_16x16x32_bf16 v[40:43], v[4:7], v[184:187], v[40:43]
	v_mfma_f32_16x16x32_bf16 v[36:39], v[84:87], v[184:187], v[36:39]
	v_mfma_f32_16x16x32_bf16 v[4:7], v[4:7], v[230:233], v[168:171]
	v_mfma_f32_16x16x32_bf16 v[132:135], v[8:11], v[172:175], v[132:135]
	v_mfma_f32_16x16x32_bf16 v[68:71], v[88:91], v[172:175], v[68:71]
	v_mfma_f32_16x16x32_bf16 v[56:59], v[8:11], v[180:183], v[56:59]
	v_mfma_f32_16x16x32_bf16 v[52:55], v[88:91], v[180:183], v[52:55]
	v_mfma_f32_16x16x32_bf16 v[40:43], v[8:11], v[188:191], v[40:43]
	v_mfma_f32_16x16x32_bf16 v[36:39], v[88:91], v[188:191], v[36:39]
	v_mfma_f32_16x16x32_bf16 v[4:7], v[8:11], v[234:237], v[4:7]
	v_mfma_f32_16x16x32_bf16 v[8:11], v[84:87], v[230:233], v[72:75]
	v_mfma_f32_16x16x32_bf16 v[8:11], v[88:91], v[234:237], v[8:11]
	s_setprio 0
	s_setprio 1
	v_mfma_f32_16x16x32_bf16 v[48:51], v[92:95], v[116:119], v[48:51]
	v_mfma_f32_16x16x32_bf16 v[44:47], v[100:103], v[116:119], v[44:47]
	v_mfma_f32_16x16x32_bf16 v[32:35], v[92:95], v[176:179], v[32:35]
	v_mfma_f32_16x16x32_bf16 v[28:31], v[100:103], v[176:179], v[28:31]
	v_mfma_f32_16x16x32_bf16 v[24:27], v[92:95], v[184:187], v[24:27]
	v_mfma_f32_16x16x32_bf16 v[20:23], v[100:103], v[184:187], v[20:23]
	v_mfma_f32_16x16x32_bf16 v[16:19], v[92:95], v[230:233], v[16:19]
	v_mfma_f32_16x16x32_bf16 v[12:15], v[100:103], v[230:233], v[12:15]
	v_mfma_f32_16x16x32_bf16 v[48:51], v[96:99], v[172:175], v[48:51]
	v_mfma_f32_16x16x32_bf16 v[44:47], v[104:107], v[172:175], v[44:47]
	v_mfma_f32_16x16x32_bf16 v[32:35], v[96:99], v[180:183], v[32:35]
	v_mfma_f32_16x16x32_bf16 v[28:31], v[104:107], v[180:183], v[28:31]
	v_mfma_f32_16x16x32_bf16 v[24:27], v[96:99], v[188:191], v[24:27]
	v_mfma_f32_16x16x32_bf16 v[20:23], v[104:107], v[188:191], v[20:23]
	v_mfma_f32_16x16x32_bf16 v[16:19], v[96:99], v[234:237], v[16:19]
	v_mfma_f32_16x16x32_bf16 v[12:15], v[104:107], v[234:237], v[12:15]
	s_barrier
; #define PG8_STAGE(bufoff, gbase, voff) do { _Pragma("unroll") for (int _i = 0; _i < 2; ++_i) \
;         __builtin_amdgcn_global_load_lds((const unsigned*)((const char*)(gbase) + (voff)[_i]), (PG8_LAS unsigned*)(lds + (bufoff) + ldsw + _i * 8192), 16, 0, 0); } while (0)
; #define PG8_LDA(dst, b, h) do { _Pragma("unroll") for (int m = 0; m < 4; ++m) _Pragma("unroll") for (int k = 0; k < 2; ++k) dst[m][k] = *(const PG8_LAS bf16x8*)(lds + PG8_SA(b, h) + aoff + m * 2048 + k * 1024); } while (0)
; #define PG8_LDB(dst, b, h) do { _Pragma("unroll") for (int n = 0; n < 2; ++n) _Pragma("unroll") for (int k = 0; k < 2; ++k) dst[n][k] = *(const PG8_LAS bf16x8*)(lds + PG8_SB(b, h) + boff + n * 2048 + k * 1024); } while (0)
; #define PG8_MMA(ai, bj, At, Bt) do { __builtin_amdgcn_s_setprio(1); _Pragma("unroll") for (int m = 0; m < 4; ++m) _Pragma("unroll") for (int n = 0; n < 2; ++n) _Pragma("unroll") for (int k = 0; k < 2; ++k) \
;         acc[ai][bj][m][n] = __builtin_amdgcn_mfma_f32_16x16x32_bf16(Bt[n][k], At[m][k], acc[ai][bj][m][n], 0, 0, 0); __builtin_amdgcn_s_setprio(0); } while (0)
; #define PG8_WAIT_V(n) asm volatile("s_waitcnt vmcnt(" #n ")" ::: "memory")
; #define PG8_WAIT_L(n) asm volatile("s_waitcnt lgkmcnt(" #n ")" ::: "memory")
; #define PG8_BAR __builtin_amdgcn_s_barrier()
; #define PG8_SCHED __builtin_amdgcn_sched_barrier(0)
; template <class Epi>
; __device__ __forceinline__ void gemm_phase(PG8_LAS unsigned char* lds, PG8_LAS unsigned char* xl, const Gemm g, const Sched& S, const Epi& E, const int wid) {
;     ...
;             PG8_LDB(B0, 1, 0); PG8_LDB(B1, 1, 1); PG8_SCHED; PG8_LDA(At, 1, 0); PG8_STAGE(PG8_SA(0, 1), a2 + hstepA, voffA);
;             PG8_WAIT_V(8); PG8_WAIT_L(0); PG8_BAR; if (do0) { PG8_MMA(0, 0, At, B0); PG8_MMA(0, 1, At, B1); } PG8_BAR; PG8_SCHED;
;             PG8_LDA(At, 1, 1); PG8_STAGE(PG8_SB(1, 0), b3, voffB); PG8_STAGE(PG8_SB(1, 1), b3 + hstepB, voffB); PG8_STAGE(PG8_SA(1, 0), a3, voffA);
;             PG8_WAIT_V(8); PG8_WAIT_L(0); PG8_BAR; if (do1) { PG8_MMA(1, 0, At, B0); PG8_MMA(1, 1, At, B1); } PG8_BAR; PG8_SCHED;
;         }
;         if (wr == 0) PG8_BAR;
	s_setprio 0
	s_add_i32 s4, 0, 0x18000
	s_add_i32 s5, 0, 0x1c000
	ds_read_b128 v[72:75], v248 offset:32768
	ds_read_b128 v[84:87], v248 offset:33792
	ds_read_b128 v[88:91], v248 offset:34816
	ds_read_b128 v[92:95], v248 offset:35840
	ds_read_b128 v[96:99], v248 offset:49152
	ds_read_b128 v[100:103], v248 offset:50176
	ds_read_b128 v[104:107], v248 offset:51200
	ds_read_b128 v[172:175], v248 offset:52224
	s_add_u32 s100, s10, 0x80000
	s_addc_u32 s101, s11, 0
	s_mov_b32 m0, s91
	ds_read_b128 v[116:119], v225 offset:32768
	ds_read_b128 v[168:171], v225 offset:33792
	ds_read_b128 v[176:179], v225 offset:34816
	ds_read_b128 v[180:183], v225 offset:35840
	ds_read_b128 v[184:187], v225 offset:36864
	ds_read_b128 v[188:191], v225 offset:37888
	ds_read_b128 v[230:233], v225 offset:38912
	ds_read_b128 v[234:237], v225 offset:39936
	global_load_lds_dwordx4 v210, s[100:101] sc0
	s_mov_b32 m0, s92
	s_nop 0
	global_load_lds_dwordx4 v214, s[100:101] sc0
	s_waitcnt vmcnt(8)
	s_waitcnt lgkmcnt(0)
	s_setprio 1
	s_barrier
	v_mfma_f32_16x16x32_bf16 v[60:63], v[72:75], v[116:119], v[60:63]
	v_mfma_f32_16x16x32_bf16 v[64:67], v[88:91], v[116:119], v[64:67]
	v_mfma_f32_16x16x32_bf16 v[120:123], v[72:75], v[176:179], v[120:123]
	v_mfma_f32_16x16x32_bf16 v[124:127], v[88:91], v[176:179], v[124:127]
	v_mfma_f32_16x16x32_bf16 v[164:167], v[72:75], v[184:187], v[164:167]
	v_mfma_f32_16x16x32_bf16 v[160:163], v[88:91], v[184:187], v[160:163]
	v_mfma_f32_16x16x32_bf16 v[80:83], v[72:75], v[230:233], v[80:83]
	v_mfma_f32_16x16x32_bf16 v[128:131], v[88:91], v[230:233], v[128:131]
	v_mfma_f32_16x16x32_bf16 v[60:63], v[84:87], v[168:171], v[60:63]
	v_mfma_f32_16x16x32_bf16 v[64:67], v[92:95], v[168:171], v[64:67]
	v_mfma_f32_16x16x32_bf16 v[120:123], v[84:87], v[180:183], v[120:123]
	v_mfma_f32_16x16x32_bf16 v[124:127], v[92:95], v[180:183], v[124:127]
	v_mfma_f32_16x16x32_bf16 v[164:167], v[84:87], v[188:191], v[164:167]
	v_mfma_f32_16x16x32_bf16 v[160:163], v[92:95], v[188:191], v[160:163]
	v_mfma_f32_16x16x32_bf16 v[80:83], v[84:87], v[234:237], v[80:83]
	v_mfma_f32_16x16x32_bf16 v[128:131], v[92:95], v[234:237], v[128:131]
	s_setprio 0
	s_setprio 1
	v_mfma_f32_16x16x32_bf16 v[108:111], v[104:107], v[116:119], v[108:111]
	v_mfma_f32_16x16x32_bf16 v[112:115], v[96:99], v[116:119], v[112:115]
	v_mfma_f32_16x16x32_bf16 v[116:119], v[172:175], v[168:171], v[108:111]
	v_mfma_f32_16x16x32_bf16 v[108:111], v[96:99], v[176:179], v[156:159]
	v_mfma_f32_16x16x32_bf16 v[156:159], v[100:103], v[180:183], v[108:111]
	v_mfma_f32_16x16x32_bf16 v[108:111], v[104:107], v[176:179], v[152:155]
	v_mfma_f32_16x16x32_bf16 v[152:155], v[172:175], v[180:183], v[108:111]
	v_mfma_f32_16x16x32_bf16 v[108:111], v[96:99], v[184:187], v[148:151]
	v_mfma_f32_16x16x32_bf16 v[148:151], v[100:103], v[188:191], v[108:111]
	v_mfma_f32_16x16x32_bf16 v[108:111], v[104:107], v[184:187], v[144:147]
	v_mfma_f32_16x16x32_bf16 v[144:147], v[172:175], v[188:191], v[108:111]
	v_mfma_f32_16x16x32_bf16 v[108:111], v[96:99], v[230:233], v[140:143]
	v_mfma_f32_16x16x32_bf16 v[140:143], v[100:103], v[234:237], v[108:111]
	v_mfma_f32_16x16x32_bf16 v[108:111], v[104:107], v[230:233], v[136:139]
	v_mfma_f32_16x16x32_bf16 v[112:115], v[100:103], v[168:171], v[112:115]
	v_mfma_f32_16x16x32_bf16 v[136:139], v[172:175], v[234:237], v[108:111]
	s_barrier
	s_setprio 0
	s_add_i32 s4, s4, s29
	s_mov_b32 m0, s4
	s_nop 0
	ds_read_b128 v[108:111], v225 offset:49152
	ds_read_b128 v[176:179], v225 offset:50176
	ds_read_b128 v[180:183], v225 offset:51200
	ds_read_b128 v[184:187], v225 offset:52224
	ds_read_b128 v[188:191], v225 offset:53248
	ds_read_b128 v[230:233], v225 offset:54272
	ds_read_b128 v[234:237], v225 offset:55296
	ds_read_b128 v[238:241], v225 offset:56320
	global_load_lds_dwordx4 v205, vcc sc0
	s_add_i32 m0, s4, 0x2000
	s_add_u32 s100, vcc_lo, 0x80080
	global_load_lds_dwordx4 v227, vcc sc0
	s_addc_u32 s101, vcc_hi, 0
	s_add_i32 s4, s5, s29
	s_mov_b32 m0, s4
	s_nop 0
	global_load_lds_dwordx4 v212, s[100:101] sc0
	s_add_i32 m0, s4, 0x2000
	s_nop 0
	global_load_lds_dwordx4 v216, s[100:101] sc0
	s_mov_b32 m0, s40
	s_nop 0
	global_load_lds_dwordx4 v204, s[10:11] sc0
	s_mov_b32 m0, s41
	s_nop 0
	global_load_lds_dwordx4 v226, s[10:11] sc0
	s_waitcnt vmcnt(8)
	s_waitcnt lgkmcnt(0)
	s_setprio 1
	s_barrier
	v_mfma_f32_16x16x32_bf16 v[4:7], v[72:75], v[234:237], v[4:7]
	v_mfma_f32_16x16x32_bf16 v[132:135], v[72:75], v[108:111], v[132:135]
	v_mfma_f32_16x16x32_bf16 v[68:71], v[88:91], v[108:111], v[68:71]
	v_mfma_f32_16x16x32_bf16 v[56:59], v[72:75], v[180:183], v[56:59]
	v_mfma_f32_16x16x32_bf16 v[52:55], v[88:91], v[180:183], v[52:55]
	v_mfma_f32_16x16x32_bf16 v[40:43], v[72:75], v[188:191], v[40:43]
	v_mfma_f32_16x16x32_bf16 v[36:39], v[88:91], v[188:191], v[36:39]
	v_mfma_f32_16x16x32_bf16 v[168:171], v[84:87], v[238:241], v[4:7]
	v_mfma_f32_16x16x32_bf16 v[4:7], v[88:91], v[234:237], v[8:11]
	v_mfma_f32_16x16x32_bf16 v[132:135], v[84:87], v[176:179], v[132:135]
	v_mfma_f32_16x16x32_bf16 v[68:71], v[92:95], v[176:179], v[68:71]
	v_mfma_f32_16x16x32_bf16 v[56:59], v[84:87], v[184:187], v[56:59]
	v_mfma_f32_16x16x32_bf16 v[52:55], v[92:95], v[184:187], v[52:55]
	v_mfma_f32_16x16x32_bf16 v[40:43], v[84:87], v[230:233], v[40:43]
	v_mfma_f32_16x16x32_bf16 v[36:39], v[92:95], v[230:233], v[36:39]
	v_mfma_f32_16x16x32_bf16 v[72:75], v[92:95], v[238:241], v[4:7]
	s_setprio 0
	s_setprio 1
	v_mfma_f32_16x16x32_bf16 v[4:7], v[96:99], v[108:111], v[48:51]
	v_mfma_f32_16x16x32_bf16 v[48:51], v[100:103], v[176:179], v[4:7]
	v_mfma_f32_16x16x32_bf16 v[4:7], v[104:107], v[108:111], v[44:47]
	v_mfma_f32_16x16x32_bf16 v[44:47], v[172:175], v[176:179], v[4:7]
	v_mfma_f32_16x16x32_bf16 v[4:7], v[96:99], v[180:183], v[32:35]
	v_mfma_f32_16x16x32_bf16 v[32:35], v[100:103], v[184:187], v[4:7]
	v_mfma_f32_16x16x32_bf16 v[4:7], v[104:107], v[180:183], v[28:31]
	v_mfma_f32_16x16x32_bf16 v[28:31], v[172:175], v[184:187], v[4:7]
	v_mfma_f32_16x16x32_bf16 v[4:7], v[96:99], v[188:191], v[24:27]
	v_mfma_f32_16x16x32_bf16 v[24:27], v[100:103], v[230:233], v[4:7]
	v_mfma_f32_16x16x32_bf16 v[4:7], v[104:107], v[188:191], v[20:23]
	v_mfma_f32_16x16x32_bf16 v[20:23], v[172:175], v[230:233], v[4:7]
	v_mfma_f32_16x16x32_bf16 v[4:7], v[96:99], v[234:237], v[16:19]
	v_mfma_f32_16x16x32_bf16 v[16:19], v[100:103], v[238:241], v[4:7]
	v_mfma_f32_16x16x32_bf16 v[4:7], v[104:107], v[234:237], v[12:15]
	v_mfma_f32_16x16x32_bf16 v[12:15], v[172:175], v[238:241], v[4:7]
	s_barrier
	s_setprio 0
	s_add_i32 s54, s54, 2
	s_add_u32 s72, s72, 0x100
	s_addc_u32 s73, s73, 0
	s_cmp_gt_u32 s54, 29
	s_mov_b64 s[44:45], s[76:77]
	s_cbranch_scc0 .LBB0_1106
	s_mov_b32 s100, 0
	s_and_b64 vcc, exec, s[14:15]
	s_cbranch_vccz .LBB0_1109
	s_barrier

; __device__ __forceinline__ int lane_id_opq() { int l; asm volatile("v_mbcnt_lo_u32_b32 %0, -1, 0\n\tv_mbcnt_hi_u32_b32 %0, -1, %0" : "=v"(l)); return l; }
; #define PG8_STAGE(bufoff, gbase, voff) do { _Pragma("unroll") for (int _i = 0; _i < 2; ++_i) \
;         __builtin_amdgcn_global_load_lds((const unsigned*)((const char*)(gbase) + (voff)[_i]), (PG8_LAS unsigned*)(lds + (bufoff) + ldsw + _i * 8192), 16, 0, 0); } while (0)
; #define PG8_LDA(dst, b, h) do { _Pragma("unroll") for (int m = 0; m < 4; ++m) _Pragma("unroll") for (int k = 0; k < 2; ++k) dst[m][k] = *(const PG8_LAS bf16x8*)(lds + PG8_SA(b, h) + aoff + m * 2048 + k * 1024); } while (0)
; #define PG8_LDB(dst, b, h) do { _Pragma("unroll") for (int n = 0; n < 2; ++n) _Pragma("unroll") for (int k = 0; k < 2; ++k) dst[n][k] = *(const PG8_LAS bf16x8*)(lds + PG8_SB(b, h) + boff + n * 2048 + k * 1024); } while (0)
; #define PG8_BAR __builtin_amdgcn_s_barrier()
; template <class Epi>
; __device__ __forceinline__ void gemm_phase(PG8_LAS unsigned char* lds, PG8_LAS unsigned char* xl, const Gemm g, const Sched& S, const Epi& E, const int wid) {
;     ...
;             const bool last = (t == nt - 2);
;             const bool do0 = !blkdiag_v<Epi> || t == 0, do1 = !blkdiag_v<Epi> || t != 0;
;             long j1 = 0, ja2 = 0, jb2 = 0;
;             if constexpr (Epi::MID) {
;                 if (t == g.tj) { const int lnM = lane_id_opq(); E.mid(acc, cur, wr, wc, lnM & 15, lnM >> 4); }
;                 if (t >= g.tj) j1 = g.jA;
;                 if (t + 2 >= g.tj) { ja2 = g.jA; jb2 = g.jB; } }
;             const char* a1 = cA + (size_t)(t + 1) * kstep + j1;
;             const char* a2 = last ? nA : cA + (size_t)(t + 2) * kstep + ja2; const char* b2 = last ? nB : cB + (size_t)(t + 2) * kstep + jb2;
;             const char* a3 = a2 + kstep; const char* b3 = b2 + kstep;
;             PG8_LDB(B0, 0, 0); PG8_LDB(B1, 0, 1); PG8_SCHED; PG8_LDA(At, 0, 0); PG8_STAGE(PG8_SA(1, 1), a1 + hstepA, voffA);
;             PG8_WAIT_V(8); PG8_WAIT_L(0); PG8_BAR; if (do0) { PG8_MMA(0, 0, At, B0); PG8_MMA(0, 1, At, B1); } PG8_BAR; PG8_SCHED;
;             PG8_LDA(At, 0, 1); PG8_STAGE(PG8_SB(0, 0), b2, voffB); PG8_STAGE(PG8_SB(0, 1), b2 + hstepB, voffB); PG8_STAGE(PG8_SA(0, 0), a2, voffA);
;             PG8_WAIT_V(8); PG8_WAIT_L(0); PG8_BAR; if (do1) { PG8_MMA(1, 0, At, B0); PG8_MMA(1, 1, At, B1); } PG8_BAR; PG8_SCHED;
.Ldefbar_skip_10:
	v_add_u32_e32 v204, s22, v188
	v_add_u32_e32 v205, s22, v190
	v_add_u32_e32 v218, s22, v210
	v_add_u32_e32 v219, s22, v212
	v_add_u32_e32 v226, 0x10000, v195
	s_add_u32 s4, s36, 0xffea0080
	s_addc_u32 s5, s37, -1
	s_add_i32 s13, 0, 0x10000
	s_cmpk_eq_i32 s9, 0x54
	s_cselect_b32 s11, s21, s5
	s_cselect_b32 s10, s20, s4
	s_cselect_b32 s41, s31, s8
	s_cselect_b32 s40, s30, s1
	s_add_i32 s4, 0, 0x14000
	ds_read_b128 v[120:123], v226 offset:0
	ds_read_b128 v[124:127], v226 offset:1024
	ds_read_b128 v[128:131], v226 offset:2048
	ds_read_b128 v[136:139], v226 offset:3072
	ds_read_b128 v[144:147], v226 offset:16384
	ds_read_b128 v[148:151], v226 offset:17408
	ds_read_b128 v[152:155], v226 offset:18432
	ds_read_b128 v[156:159], v226 offset:19456
	s_add_i32 m0, s51, 0xc000
	ds_read_b128 v[160:163], v220
	ds_read_b128 v[164:167], v220 offset:1024
	ds_read_b128 v[168:171], v220 offset:2048
	ds_read_b128 v[172:175], v220 offset:3072
	ds_read_b128 v[176:179], v220 offset:4096
	ds_read_b128 v[180:183], v220 offset:5120
	ds_read_b128 v[184:187], v220 offset:6144
	ds_read_b128 v[222:225], v220 offset:7168
	global_load_lds_dwordx4 v214, s[36:37] sc0
	s_add_i32 m0, s51, 0xe000
	s_nop 0
	global_load_lds_dwordx4 v216, s[36:37] sc0
	s_waitcnt vmcnt(8)
	s_waitcnt lgkmcnt(0)
	s_setprio 1
	s_barrier
	v_mfma_f32_16x16x32_bf16 v[140:143], v[120:123], v[160:163], 0
	v_mfma_f32_16x16x32_bf16 v[132:135], v[128:131], v[160:163], 0
	v_mfma_f32_16x16x32_bf16 v[108:111], v[120:123], v[168:171], 0
	v_mfma_f32_16x16x32_bf16 v[104:107], v[128:131], v[168:171], 0
	v_mfma_f32_16x16x32_bf16 v[92:95], v[120:123], v[176:179], 0
	v_mfma_f32_16x16x32_bf16 v[88:91], v[128:131], v[176:179], 0
	v_mfma_f32_16x16x32_bf16 v[76:79], v[120:123], v[184:187], 0
	v_mfma_f32_16x16x32_bf16 v[72:75], v[128:131], v[184:187], 0
	v_mfma_f32_16x16x32_bf16 v[140:143], v[124:127], v[164:167], v[140:143]
	v_mfma_f32_16x16x32_bf16 v[132:135], v[136:139], v[164:167], v[132:135]
	v_mfma_f32_16x16x32_bf16 v[108:111], v[124:127], v[172:175], v[108:111]
	v_mfma_f32_16x16x32_bf16 v[104:107], v[136:139], v[172:175], v[104:107]
	v_mfma_f32_16x16x32_bf16 v[92:95], v[124:127], v[180:183], v[92:95]
	v_mfma_f32_16x16x32_bf16 v[88:91], v[136:139], v[180:183], v[88:91]
	v_mfma_f32_16x16x32_bf16 v[76:79], v[124:127], v[222:225], v[76:79]
	v_mfma_f32_16x16x32_bf16 v[72:75], v[136:139], v[222:225], v[72:75]
	s_setprio 0
	s_setprio 1
	v_mfma_f32_16x16x32_bf16 v[116:119], v[144:147], v[160:163], 0
	v_mfma_f32_16x16x32_bf16 v[112:115], v[152:155], v[160:163], 0
	v_mfma_f32_16x16x32_bf16 v[100:103], v[144:147], v[168:171], 0
	v_mfma_f32_16x16x32_bf16 v[96:99], v[152:155], v[168:171], 0
	v_mfma_f32_16x16x32_bf16 v[84:87], v[144:147], v[176:179], 0
	v_mfma_f32_16x16x32_bf16 v[80:83], v[152:155], v[176:179], 0
	v_mfma_f32_16x16x32_bf16 v[68:71], v[144:147], v[184:187], 0
	v_mfma_f32_16x16x32_bf16 v[64:67], v[152:155], v[184:187], 0
	v_mfma_f32_16x16x32_bf16 v[116:119], v[148:151], v[164:167], v[116:119]
	v_mfma_f32_16x16x32_bf16 v[112:115], v[156:159], v[164:167], v[112:115]
	v_mfma_f32_16x16x32_bf16 v[100:103], v[148:151], v[172:175], v[100:103]
	v_mfma_f32_16x16x32_bf16 v[96:99], v[156:159], v[172:175], v[96:99]
	v_mfma_f32_16x16x32_bf16 v[84:87], v[148:151], v[180:183], v[84:87]
	v_mfma_f32_16x16x32_bf16 v[80:83], v[156:159], v[180:183], v[80:83]
	v_mfma_f32_16x16x32_bf16 v[68:71], v[148:151], v[222:225], v[68:71]
	v_mfma_f32_16x16x32_bf16 v[64:67], v[156:159], v[222:225], v[64:67]
	s_barrier
	s_setprio 0
	s_add_i32 s5, s13, s29
	s_mov_b32 m0, s5
	ds_read_b128 v[160:163], v220 offset:16384
	ds_read_b128 v[164:167], v220 offset:17408
	ds_read_b128 v[168:171], v220 offset:18432
	ds_read_b128 v[172:175], v220 offset:19456
	ds_read_b128 v[176:179], v220 offset:20480
	ds_read_b128 v[180:183], v220 offset:21504
	ds_read_b128 v[184:187], v220 offset:22528
	ds_read_b128 v[222:225], v220 offset:23552
	global_load_lds_dwordx4 v190, s[40:41] sc0
	s_add_i32 m0, s5, 0x2000
	s_add_u32 s44, s40, 0x160000
	s_addc_u32 s45, s41, 0
	s_add_i32 s4, s4, s29
	global_load_lds_dwordx4 v212, s[40:41] sc0
	s_mov_b32 m0, s4
	s_nop 0
	global_load_lds_dwordx4 v190, s[44:45] sc0
	s_add_i32 m0, s4, 0x2000
	s_nop 0
	global_load_lds_dwordx4 v212, s[44:45] sc0
	s_mov_b32 m0, s51
	s_nop 0
	global_load_lds_dwordx4 v188, s[10:11] sc0
	s_mov_b32 m0, s52
	s_nop 0
	global_load_lds_dwordx4 v210, s[10:11] sc0
	s_waitcnt vmcnt(8)
	s_waitcnt lgkmcnt(0)
	s_setprio 1
	s_barrier
	v_mfma_f32_16x16x32_bf16 v[60:63], v[120:123], v[160:163], 0
	v_mfma_f32_16x16x32_bf16 v[56:59], v[128:131], v[160:163], 0
	v_mfma_f32_16x16x32_bf16 v[44:47], v[120:123], v[168:171], 0
	v_mfma_f32_16x16x32_bf16 v[40:43], v[128:131], v[168:171], 0
	v_mfma_f32_16x16x32_bf16 v[28:31], v[120:123], v[176:179], 0
	v_mfma_f32_16x16x32_bf16 v[24:27], v[128:131], v[176:179], 0
	v_mfma_f32_16x16x32_bf16 v[12:15], v[120:123], v[184:187], 0
	v_mfma_f32_16x16x32_bf16 v[8:11], v[128:131], v[184:187], 0
	v_mfma_f32_16x16x32_bf16 v[60:63], v[124:127], v[164:167], v[60:63]
	v_mfma_f32_16x16x32_bf16 v[56:59], v[136:139], v[164:167], v[56:59]
	v_mfma_f32_16x16x32_bf16 v[44:47], v[124:127], v[172:175], v[44:47]
	v_mfma_f32_16x16x32_bf16 v[40:43], v[136:139], v[172:175], v[40:43]
	v_mfma_f32_16x16x32_bf16 v[28:31], v[124:127], v[180:183], v[28:31]
	v_mfma_f32_16x16x32_bf16 v[24:27], v[136:139], v[180:183], v[24:27]
	v_mfma_f32_16x16x32_bf16 v[12:15], v[124:127], v[222:225], v[12:15]
	v_mfma_f32_16x16x32_bf16 v[8:11], v[136:139], v[222:225], v[8:11]
	s_setprio 0
	s_setprio 1
	v_mfma_f32_16x16x32_bf16 v[52:55], v[144:147], v[160:163], 0
	v_mfma_f32_16x16x32_bf16 v[48:51], v[152:155], v[160:163], 0
	v_mfma_f32_16x16x32_bf16 v[36:39], v[144:147], v[168:171], 0
	v_mfma_f32_16x16x32_bf16 v[32:35], v[152:155], v[168:171], 0
	v_mfma_f32_16x16x32_bf16 v[20:23], v[144:147], v[176:179], 0
	v_mfma_f32_16x16x32_bf16 v[16:19], v[152:155], v[176:179], 0
	v_mfma_f32_16x16x32_bf16 v[4:7], v[144:147], v[184:187], 0
	v_mfma_f32_16x16x32_bf16 v[0:3], v[152:155], v[184:187], 0
	v_mfma_f32_16x16x32_bf16 v[52:55], v[148:151], v[164:167], v[52:55]
	v_mfma_f32_16x16x32_bf16 v[48:51], v[156:159], v[164:167], v[48:51]
	v_mfma_f32_16x16x32_bf16 v[36:39], v[148:151], v[172:175], v[36:39]
	v_mfma_f32_16x16x32_bf16 v[32:35], v[156:159], v[172:175], v[32:35]
	v_mfma_f32_16x16x32_bf16 v[20:23], v[148:151], v[180:183], v[20:23]
	v_mfma_f32_16x16x32_bf16 v[16:19], v[156:159], v[180:183], v[16:19]
	v_mfma_f32_16x16x32_bf16 v[4:7], v[148:151], v[222:225], v[4:7]
	v_mfma_f32_16x16x32_bf16 v[0:3], v[156:159], v[222:225], v[0:3]
	s_barrier
; #define PG8_STAGE(bufoff, gbase, voff) do { _Pragma("unroll") for (int _i = 0; _i < 2; ++_i) \
;         __builtin_amdgcn_global_load_lds((const unsigned*)((const char*)(gbase) + (voff)[_i]), (PG8_LAS unsigned*)(lds + (bufoff) + ldsw + _i * 8192), 16, 0, 0); } while (0)
; #define PG8_LDA(dst, b, h) do { _Pragma("unroll") for (int m = 0; m < 4; ++m) _Pragma("unroll") for (int k = 0; k < 2; ++k) dst[m][k] = *(const PG8_LAS bf16x8*)(lds + PG8_SA(b, h) + aoff + m * 2048 + k * 1024); } while (0)
; #define PG8_LDB(dst, b, h) do { _Pragma("unroll") for (int n = 0; n < 2; ++n) _Pragma("unroll") for (int k = 0; k < 2; ++k) dst[n][k] = *(const PG8_LAS bf16x8*)(lds + PG8_SB(b, h) + boff + n * 2048 + k * 1024); } while (0)
; #define PG8_MMA(ai, bj, At, Bt) do { __builtin_amdgcn_s_setprio(1); _Pragma("unroll") for (int m = 0; m < 4; ++m) _Pragma("unroll") for (int n = 0; n < 2; ++n) _Pragma("unroll") for (int k = 0; k < 2; ++k) \
;         acc[ai][bj][m][n] = __builtin_amdgcn_mfma_f32_16x16x32_bf16(Bt[n][k], At[m][k], acc[ai][bj][m][n], 0, 0, 0); __builtin_amdgcn_s_setprio(0); } while (0)
; #define PG8_WAIT_V(n) asm volatile("s_waitcnt vmcnt(" #n ")" ::: "memory")
; #define PG8_WAIT_L(n) asm volatile("s_waitcnt lgkmcnt(" #n ")" ::: "memory")
; #define PG8_BAR __builtin_amdgcn_s_barrier()
; #define PG8_SCHED __builtin_amdgcn_sched_barrier(0)
; template <class Epi>
; __device__ __forceinline__ void gemm_phase(PG8_LAS unsigned char* lds, PG8_LAS unsigned char* xl, const Gemm g, const Sched& S, const Epi& E, const int wid) {
;     ...
;             PG8_LDB(B0, 1, 0); PG8_LDB(B1, 1, 1); PG8_SCHED; PG8_LDA(At, 1, 0); PG8_STAGE(PG8_SA(0, 1), a2 + hstepA, voffA);
;             PG8_WAIT_V(8); PG8_WAIT_L(0); PG8_BAR; if (do0) { PG8_MMA(0, 0, At, B0); PG8_MMA(0, 1, At, B1); } PG8_BAR; PG8_SCHED;
;             PG8_LDA(At, 1, 1); PG8_STAGE(PG8_SB(1, 0), b3, voffB); PG8_STAGE(PG8_SB(1, 1), b3 + hstepB, voffB); PG8_STAGE(PG8_SA(1, 0), a3, voffA);
;             PG8_WAIT_V(8); PG8_WAIT_L(0); PG8_BAR; if (do1) { PG8_MMA(1, 0, At, B0); PG8_MMA(1, 1, At, B1); } PG8_BAR; PG8_SCHED;
;         }
	s_setprio 0
	s_add_i32 s4, 0, 0x18000
	s_add_i32 s5, 0, 0x1c000
	ds_read_b128 v[120:123], v226 offset:32768
	ds_read_b128 v[124:127], v226 offset:33792
	ds_read_b128 v[128:131], v226 offset:34816
	ds_read_b128 v[136:139], v226 offset:35840
	ds_read_b128 v[144:147], v226 offset:49152
	ds_read_b128 v[148:151], v226 offset:50176
	ds_read_b128 v[152:155], v226 offset:51200
	ds_read_b128 v[156:159], v226 offset:52224
	s_add_u32 s100, s10, 0x160000
	s_addc_u32 s101, s11, 0
	s_mov_b32 m0, s53
	ds_read_b128 v[160:163], v220 offset:32768
	ds_read_b128 v[164:167], v220 offset:33792
	ds_read_b128 v[168:171], v220 offset:34816
	ds_read_b128 v[172:175], v220 offset:35840
	ds_read_b128 v[176:179], v220 offset:36864
	ds_read_b128 v[180:183], v220 offset:37888
	ds_read_b128 v[184:187], v220 offset:38912
	ds_read_b128 v[222:225], v220 offset:39936
	global_load_lds_dwordx4 v188, s[100:101] sc0
	s_mov_b32 m0, s56
	s_nop 0
	global_load_lds_dwordx4 v210, s[100:101] sc0
	s_waitcnt vmcnt(8)
	s_waitcnt lgkmcnt(0)
	s_setprio 1
	s_barrier
	v_mfma_f32_16x16x32_bf16 v[140:143], v[120:123], v[160:163], v[140:143]
	v_mfma_f32_16x16x32_bf16 v[132:135], v[128:131], v[160:163], v[132:135]
	v_mfma_f32_16x16x32_bf16 v[108:111], v[120:123], v[168:171], v[108:111]
	v_mfma_f32_16x16x32_bf16 v[104:107], v[128:131], v[168:171], v[104:107]
	v_mfma_f32_16x16x32_bf16 v[92:95], v[120:123], v[176:179], v[92:95]
	v_mfma_f32_16x16x32_bf16 v[88:91], v[128:131], v[176:179], v[88:91]
	v_mfma_f32_16x16x32_bf16 v[76:79], v[120:123], v[184:187], v[76:79]
	v_mfma_f32_16x16x32_bf16 v[72:75], v[128:131], v[184:187], v[72:75]
	v_mfma_f32_16x16x32_bf16 v[140:143], v[124:127], v[164:167], v[140:143]
	v_mfma_f32_16x16x32_bf16 v[132:135], v[136:139], v[164:167], v[132:135]
	v_mfma_f32_16x16x32_bf16 v[108:111], v[124:127], v[172:175], v[108:111]
	v_mfma_f32_16x16x32_bf16 v[104:107], v[136:139], v[172:175], v[104:107]
	v_mfma_f32_16x16x32_bf16 v[92:95], v[124:127], v[180:183], v[92:95]
	v_mfma_f32_16x16x32_bf16 v[88:91], v[136:139], v[180:183], v[88:91]
	v_mfma_f32_16x16x32_bf16 v[76:79], v[124:127], v[222:225], v[76:79]
	v_mfma_f32_16x16x32_bf16 v[72:75], v[136:139], v[222:225], v[72:75]
	s_setprio 0
	s_setprio 1
	v_mfma_f32_16x16x32_bf16 v[116:119], v[144:147], v[160:163], v[116:119]
	v_mfma_f32_16x16x32_bf16 v[112:115], v[152:155], v[160:163], v[112:115]
	v_mfma_f32_16x16x32_bf16 v[100:103], v[144:147], v[168:171], v[100:103]
	v_mfma_f32_16x16x32_bf16 v[96:99], v[152:155], v[168:171], v[96:99]
	v_mfma_f32_16x16x32_bf16 v[84:87], v[144:147], v[176:179], v[84:87]
	v_mfma_f32_16x16x32_bf16 v[80:83], v[152:155], v[176:179], v[80:83]
	v_mfma_f32_16x16x32_bf16 v[68:71], v[144:147], v[184:187], v[68:71]
	v_mfma_f32_16x16x32_bf16 v[64:67], v[152:155], v[184:187], v[64:67]
	v_mfma_f32_16x16x32_bf16 v[116:119], v[148:151], v[164:167], v[116:119]
	v_mfma_f32_16x16x32_bf16 v[112:115], v[156:159], v[164:167], v[112:115]
	v_mfma_f32_16x16x32_bf16 v[100:103], v[148:151], v[172:175], v[100:103]
	v_mfma_f32_16x16x32_bf16 v[96:99], v[156:159], v[172:175], v[96:99]
	v_mfma_f32_16x16x32_bf16 v[84:87], v[148:151], v[180:183], v[84:87]
	v_mfma_f32_16x16x32_bf16 v[80:83], v[156:159], v[180:183], v[80:83]
	v_mfma_f32_16x16x32_bf16 v[68:71], v[148:151], v[222:225], v[68:71]
	v_mfma_f32_16x16x32_bf16 v[64:67], v[156:159], v[222:225], v[64:67]
	s_barrier
	s_setprio 0
	s_add_i32 s4, s4, s29
	s_mov_b32 m0, s4
	ds_read_b128 v[160:163], v220 offset:49152
	ds_read_b128 v[164:167], v220 offset:50176
	ds_read_b128 v[168:171], v220 offset:51200
	ds_read_b128 v[172:175], v220 offset:52224
	ds_read_b128 v[176:179], v220 offset:53248
	ds_read_b128 v[180:183], v220 offset:54272
	ds_read_b128 v[184:187], v220 offset:55296
	ds_read_b128 v[222:225], v220 offset:56320
	global_load_lds_dwordx4 v205, s[40:41] sc0
	s_add_i32 m0, s4, 0x2000
	s_add_u32 s100, s40, 0x160080
	global_load_lds_dwordx4 v219, s[40:41] sc0
	s_addc_u32 s101, s41, 0
	s_add_i32 s4, s5, s29
	s_mov_b32 m0, s4
	s_nop 0
	global_load_lds_dwordx4 v190, s[100:101] sc0
	s_add_i32 m0, s4, 0x2000
	s_nop 0
	global_load_lds_dwordx4 v212, s[100:101] sc0
	s_mov_b32 m0, s61
	s_nop 0
	global_load_lds_dwordx4 v204, s[10:11] sc0
	s_mov_b32 m0, s62
	s_nop 0
	global_load_lds_dwordx4 v218, s[10:11] sc0
	s_waitcnt vmcnt(8)
	s_waitcnt lgkmcnt(0)
	s_setprio 1
	s_barrier
	v_mfma_f32_16x16x32_bf16 v[60:63], v[120:123], v[160:163], v[60:63]
	v_mfma_f32_16x16x32_bf16 v[56:59], v[128:131], v[160:163], v[56:59]
	v_mfma_f32_16x16x32_bf16 v[44:47], v[120:123], v[168:171], v[44:47]
	v_mfma_f32_16x16x32_bf16 v[40:43], v[128:131], v[168:171], v[40:43]
	v_mfma_f32_16x16x32_bf16 v[28:31], v[120:123], v[176:179], v[28:31]
	v_mfma_f32_16x16x32_bf16 v[24:27], v[128:131], v[176:179], v[24:27]
	v_mfma_f32_16x16x32_bf16 v[12:15], v[120:123], v[184:187], v[12:15]
	v_mfma_f32_16x16x32_bf16 v[8:11], v[128:131], v[184:187], v[8:11]
	v_mfma_f32_16x16x32_bf16 v[60:63], v[124:127], v[164:167], v[60:63]
	v_mfma_f32_16x16x32_bf16 v[56:59], v[136:139], v[164:167], v[56:59]
	v_mfma_f32_16x16x32_bf16 v[44:47], v[124:127], v[172:175], v[44:47]
	v_mfma_f32_16x16x32_bf16 v[40:43], v[136:139], v[172:175], v[40:43]
	v_mfma_f32_16x16x32_bf16 v[28:31], v[124:127], v[180:183], v[28:31]
	v_mfma_f32_16x16x32_bf16 v[24:27], v[136:139], v[180:183], v[24:27]
	v_mfma_f32_16x16x32_bf16 v[12:15], v[124:127], v[222:225], v[12:15]
	v_mfma_f32_16x16x32_bf16 v[8:11], v[136:139], v[222:225], v[8:11]
	s_setprio 0
	s_setprio 1
	v_mfma_f32_16x16x32_bf16 v[52:55], v[144:147], v[160:163], v[52:55]
	v_mfma_f32_16x16x32_bf16 v[48:51], v[152:155], v[160:163], v[48:51]
	v_mfma_f32_16x16x32_bf16 v[36:39], v[144:147], v[168:171], v[36:39]
	v_mfma_f32_16x16x32_bf16 v[32:35], v[152:155], v[168:171], v[32:35]
	v_mfma_f32_16x16x32_bf16 v[20:23], v[144:147], v[176:179], v[20:23]
	v_mfma_f32_16x16x32_bf16 v[16:19], v[152:155], v[176:179], v[16:19]
	v_mfma_f32_16x16x32_bf16 v[4:7], v[144:147], v[184:187], v[4:7]
	v_mfma_f32_16x16x32_bf16 v[0:3], v[152:155], v[184:187], v[0:3]
	v_mfma_f32_16x16x32_bf16 v[52:55], v[148:151], v[164:167], v[52:55]
	v_mfma_f32_16x16x32_bf16 v[48:51], v[156:159], v[164:167], v[48:51]
	v_mfma_f32_16x16x32_bf16 v[36:39], v[148:151], v[172:175], v[36:39]
	v_mfma_f32_16x16x32_bf16 v[32:35], v[156:159], v[172:175], v[32:35]
	v_mfma_f32_16x16x32_bf16 v[20:23], v[148:151], v[180:183], v[20:23]
	v_mfma_f32_16x16x32_bf16 v[16:19], v[156:159], v[180:183], v[16:19]
	v_mfma_f32_16x16x32_bf16 v[4:7], v[148:151], v[222:225], v[4:7]
	v_mfma_f32_16x16x32_bf16 v[0:3], v[156:159], v[222:225], v[0:3]
	s_barrier
	s_setprio 0
	s_add_i32 s9, s9, 2
	s_add_u32 s36, s36, 0x100
	s_addc_u32 s37, s37, 0
	s_add_u32 s1, s1, 0x100
	s_addc_u32 s8, s8, 0
	s_cmpk_gt_u32 s9, 0x55
; __device__ __forceinline__ int lane_id_opq() { int l; asm volatile("v_mbcnt_lo_u32_b32 %0, -1, 0\n\tv_mbcnt_hi_u32_b32 %0, -1, %0" : "=v"(l)); return l; }
; #define PG8_STAGE(bufoff, gbase, voff) do { _Pragma("unroll") for (int _i = 0; _i < 2; ++_i) \
;         __builtin_amdgcn_global_load_lds((const unsigned*)((const char*)(gbase) + (voff)[_i]), (PG8_LAS unsigned*)(lds + (bufoff) + ldsw + _i * 8192), 16, 0, 0); } while (0)
; #define PG8_LDA(dst, b, h) do { _Pragma("unroll") for (int m = 0; m < 4; ++m) _Pragma("unroll") for (int k = 0; k < 2; ++k) dst[m][k] = *(const PG8_LAS bf16x8*)(lds + PG8_SA(b, h) + aoff + m * 2048 + k * 1024); } while (0)
; #define PG8_LDB(dst, b, h) do { _Pragma("unroll") for (int n = 0; n < 2; ++n) _Pragma("unroll") for (int k = 0; k < 2; ++k) dst[n][k] = *(const PG8_LAS bf16x8*)(lds + PG8_SB(b, h) + boff + n * 2048 + k * 1024); } while (0)
; #define PG8_BAR __builtin_amdgcn_s_barrier()
; template <class Epi>
; __device__ __forceinline__ void gemm_phase(PG8_LAS unsigned char* lds, PG8_LAS unsigned char* xl, const Gemm g, const Sched& S, const Epi& E, const int wid) {
;     ...
;             const bool last = (t == nt - 2);
;             const bool do0 = !blkdiag_v<Epi> || t == 0, do1 = !blkdiag_v<Epi> || t != 0;
;             long j1 = 0, ja2 = 0, jb2 = 0;
;             if constexpr (Epi::MID) {
;                 if (t == g.tj) { const int lnM = lane_id_opq(); E.mid(acc, cur, wr, wc, lnM & 15, lnM >> 4); }
;                 if (t >= g.tj) j1 = g.jA;
;                 if (t + 2 >= g.tj) { ja2 = g.jA; jb2 = g.jB; } }
;             const char* a1 = cA + (size_t)(t + 1) * kstep + j1;
;             const char* a2 = last ? nA : cA + (size_t)(t + 2) * kstep + ja2; const char* b2 = last ? nB : cB + (size_t)(t + 2) * kstep + jb2;
;             const char* a3 = a2 + kstep; const char* b3 = b2 + kstep;
;             PG8_LDB(B0, 0, 0); PG8_LDB(B1, 0, 1); PG8_SCHED; PG8_LDA(At, 0, 0); PG8_STAGE(PG8_SA(1, 1), a1 + hstepA, voffA);
;             PG8_WAIT_V(8); PG8_WAIT_L(0); PG8_BAR; if (do0) { PG8_MMA(0, 0, At, B0); PG8_MMA(0, 1, At, B1); } PG8_BAR; PG8_SCHED;
;             PG8_LDA(At, 0, 1); PG8_STAGE(PG8_SB(0, 0), b2, voffB); PG8_STAGE(PG8_SB(0, 1), b2 + hstepB, voffB); PG8_STAGE(PG8_SA(0, 0), a2, voffA);
;             PG8_WAIT_V(8); PG8_WAIT_L(0); PG8_BAR; if (do1) { PG8_MMA(1, 0, At, B0); PG8_MMA(1, 1, At, B1); } PG8_BAR; PG8_SCHED;
.LBB0_1304:
	s_add_u32 s4, s36, 0xffea0080
	s_addc_u32 s5, s37, -1
	s_add_i32 s13, 0, 0x10000
	s_cmpk_eq_i32 s9, 0x54
	s_cselect_b32 s11, s21, s5
	s_cselect_b32 s10, s20, s4
	s_cselect_b32 s41, s31, s8
	s_cselect_b32 s40, s30, s1
	s_add_i32 s4, 0, 0x14000
	ds_read_b128 v[120:123], v226 offset:0
	ds_read_b128 v[124:127], v226 offset:1024
	ds_read_b128 v[128:131], v226 offset:2048
	ds_read_b128 v[136:139], v226 offset:3072
	ds_read_b128 v[144:147], v226 offset:16384
	ds_read_b128 v[148:151], v226 offset:17408
	ds_read_b128 v[152:155], v226 offset:18432
	ds_read_b128 v[156:159], v226 offset:19456
	s_add_i32 m0, s51, 0xc000
	ds_read_b128 v[160:163], v220
	ds_read_b128 v[164:167], v220 offset:1024
	ds_read_b128 v[168:171], v220 offset:2048
	ds_read_b128 v[172:175], v220 offset:3072
	ds_read_b128 v[176:179], v220 offset:4096
	ds_read_b128 v[180:183], v220 offset:5120
	ds_read_b128 v[184:187], v220 offset:6144
	ds_read_b128 v[222:225], v220 offset:7168
	global_load_lds_dwordx4 v214, s[36:37] sc0
	s_add_i32 m0, s51, 0xe000
	s_nop 0
	global_load_lds_dwordx4 v216, s[36:37] sc0
	s_waitcnt vmcnt(8)
	s_waitcnt lgkmcnt(0)
	s_setprio 1
	s_barrier
	v_mfma_f32_16x16x32_bf16 v[140:143], v[120:123], v[160:163], v[140:143]
	v_mfma_f32_16x16x32_bf16 v[132:135], v[128:131], v[160:163], v[132:135]
	v_mfma_f32_16x16x32_bf16 v[108:111], v[120:123], v[168:171], v[108:111]
	v_mfma_f32_16x16x32_bf16 v[104:107], v[128:131], v[168:171], v[104:107]
	v_mfma_f32_16x16x32_bf16 v[92:95], v[120:123], v[176:179], v[92:95]
	v_mfma_f32_16x16x32_bf16 v[88:91], v[128:131], v[176:179], v[88:91]
	v_mfma_f32_16x16x32_bf16 v[76:79], v[120:123], v[184:187], v[76:79]
	v_mfma_f32_16x16x32_bf16 v[72:75], v[128:131], v[184:187], v[72:75]
	v_mfma_f32_16x16x32_bf16 v[140:143], v[124:127], v[164:167], v[140:143]
	v_mfma_f32_16x16x32_bf16 v[132:135], v[136:139], v[164:167], v[132:135]
	v_mfma_f32_16x16x32_bf16 v[108:111], v[124:127], v[172:175], v[108:111]
	v_mfma_f32_16x16x32_bf16 v[104:107], v[136:139], v[172:175], v[104:107]
	v_mfma_f32_16x16x32_bf16 v[92:95], v[124:127], v[180:183], v[92:95]
	v_mfma_f32_16x16x32_bf16 v[88:91], v[136:139], v[180:183], v[88:91]
	v_mfma_f32_16x16x32_bf16 v[76:79], v[124:127], v[222:225], v[76:79]
	v_mfma_f32_16x16x32_bf16 v[72:75], v[136:139], v[222:225], v[72:75]
	s_setprio 0
	s_setprio 1
	v_mfma_f32_16x16x32_bf16 v[116:119], v[144:147], v[160:163], v[116:119]
	v_mfma_f32_16x16x32_bf16 v[112:115], v[152:155], v[160:163], v[112:115]
	v_mfma_f32_16x16x32_bf16 v[100:103], v[144:147], v[168:171], v[100:103]
	v_mfma_f32_16x16x32_bf16 v[96:99], v[152:155], v[168:171], v[96:99]
	v_mfma_f32_16x16x32_bf16 v[84:87], v[144:147], v[176:179], v[84:87]
	v_mfma_f32_16x16x32_bf16 v[80:83], v[152:155], v[176:179], v[80:83]
	v_mfma_f32_16x16x32_bf16 v[68:71], v[144:147], v[184:187], v[68:71]
	v_mfma_f32_16x16x32_bf16 v[64:67], v[152:155], v[184:187], v[64:67]
	v_mfma_f32_16x16x32_bf16 v[116:119], v[148:151], v[164:167], v[116:119]
	v_mfma_f32_16x16x32_bf16 v[112:115], v[156:159], v[164:167], v[112:115]
	v_mfma_f32_16x16x32_bf16 v[100:103], v[148:151], v[172:175], v[100:103]
	v_mfma_f32_16x16x32_bf16 v[96:99], v[156:159], v[172:175], v[96:99]
	v_mfma_f32_16x16x32_bf16 v[84:87], v[148:151], v[180:183], v[84:87]
	v_mfma_f32_16x16x32_bf16 v[80:83], v[156:159], v[180:183], v[80:83]
	v_mfma_f32_16x16x32_bf16 v[68:71], v[148:151], v[222:225], v[68:71]
	v_mfma_f32_16x16x32_bf16 v[64:67], v[156:159], v[222:225], v[64:67]
	s_barrier
	s_setprio 0
	s_add_i32 s5, s13, s29
	s_mov_b32 m0, s5
	ds_read_b128 v[160:163], v220 offset:16384
	ds_read_b128 v[164:167], v220 offset:17408
	ds_read_b128 v[168:171], v220 offset:18432
	ds_read_b128 v[172:175], v220 offset:19456
	ds_read_b128 v[176:179], v220 offset:20480
	ds_read_b128 v[180:183], v220 offset:21504
	ds_read_b128 v[184:187], v220 offset:22528
	ds_read_b128 v[222:225], v220 offset:23552
	global_load_lds_dwordx4 v190, s[40:41] sc0
	s_add_i32 m0, s5, 0x2000
	s_add_u32 s44, s40, 0x160000
	s_addc_u32 s45, s41, 0
	s_add_i32 s4, s4, s29
	global_load_lds_dwordx4 v212, s[40:41] sc0
	s_mov_b32 m0, s4
	s_nop 0
	global_load_lds_dwordx4 v190, s[44:45] sc0
	s_add_i32 m0, s4, 0x2000
	s_nop 0
	global_load_lds_dwordx4 v212, s[44:45] sc0
	s_mov_b32 m0, s51
	s_nop 0
	global_load_lds_dwordx4 v188, s[10:11] sc0
	s_mov_b32 m0, s52
	s_nop 0
	global_load_lds_dwordx4 v210, s[10:11] sc0
	s_waitcnt vmcnt(8)
	s_waitcnt lgkmcnt(0)
	s_setprio 1
	s_barrier
	v_mfma_f32_16x16x32_bf16 v[60:63], v[120:123], v[160:163], v[60:63]
	v_mfma_f32_16x16x32_bf16 v[56:59], v[128:131], v[160:163], v[56:59]
	v_mfma_f32_16x16x32_bf16 v[44:47], v[120:123], v[168:171], v[44:47]
	v_mfma_f32_16x16x32_bf16 v[40:43], v[128:131], v[168:171], v[40:43]
	v_mfma_f32_16x16x32_bf16 v[28:31], v[120:123], v[176:179], v[28:31]
	v_mfma_f32_16x16x32_bf16 v[24:27], v[128:131], v[176:179], v[24:27]
	v_mfma_f32_16x16x32_bf16 v[12:15], v[120:123], v[184:187], v[12:15]
	v_mfma_f32_16x16x32_bf16 v[8:11], v[128:131], v[184:187], v[8:11]
	v_mfma_f32_16x16x32_bf16 v[60:63], v[124:127], v[164:167], v[60:63]
	v_mfma_f32_16x16x32_bf16 v[56:59], v[136:139], v[164:167], v[56:59]
	v_mfma_f32_16x16x32_bf16 v[44:47], v[124:127], v[172:175], v[44:47]
	v_mfma_f32_16x16x32_bf16 v[40:43], v[136:139], v[172:175], v[40:43]
	v_mfma_f32_16x16x32_bf16 v[28:31], v[124:127], v[180:183], v[28:31]
	v_mfma_f32_16x16x32_bf16 v[24:27], v[136:139], v[180:183], v[24:27]
	v_mfma_f32_16x16x32_bf16 v[12:15], v[124:127], v[222:225], v[12:15]
	v_mfma_f32_16x16x32_bf16 v[8:11], v[136:139], v[222:225], v[8:11]
	s_setprio 0
	s_setprio 1
	v_mfma_f32_16x16x32_bf16 v[52:55], v[144:147], v[160:163], v[52:55]
	v_mfma_f32_16x16x32_bf16 v[48:51], v[152:155], v[160:163], v[48:51]
	v_mfma_f32_16x16x32_bf16 v[36:39], v[144:147], v[168:171], v[36:39]
	v_mfma_f32_16x16x32_bf16 v[32:35], v[152:155], v[168:171], v[32:35]
	v_mfma_f32_16x16x32_bf16 v[20:23], v[144:147], v[176:179], v[20:23]
	v_mfma_f32_16x16x32_bf16 v[16:19], v[152:155], v[176:179], v[16:19]
	v_mfma_f32_16x16x32_bf16 v[4:7], v[144:147], v[184:187], v[4:7]
	v_mfma_f32_16x16x32_bf16 v[0:3], v[152:155], v[184:187], v[0:3]
	v_mfma_f32_16x16x32_bf16 v[52:55], v[148:151], v[164:167], v[52:55]
	v_mfma_f32_16x16x32_bf16 v[48:51], v[156:159], v[164:167], v[48:51]
	v_mfma_f32_16x16x32_bf16 v[36:39], v[148:151], v[172:175], v[36:39]
	v_mfma_f32_16x16x32_bf16 v[32:35], v[156:159], v[172:175], v[32:35]
	v_mfma_f32_16x16x32_bf16 v[20:23], v[148:151], v[180:183], v[20:23]
	v_mfma_f32_16x16x32_bf16 v[16:19], v[156:159], v[180:183], v[16:19]
	v_mfma_f32_16x16x32_bf16 v[4:7], v[148:151], v[222:225], v[4:7]
	v_mfma_f32_16x16x32_bf16 v[0:3], v[156:159], v[222:225], v[0:3]
	s_barrier
; #define PG8_STAGE(bufoff, gbase, voff) do { _Pragma("unroll") for (int _i = 0; _i < 2; ++_i) \
;         __builtin_amdgcn_global_load_lds((const unsigned*)((const char*)(gbase) + (voff)[_i]), (PG8_LAS unsigned*)(lds + (bufoff) + ldsw + _i * 8192), 16, 0, 0); } while (0)
; #define PG8_LDA(dst, b, h) do { _Pragma("unroll") for (int m = 0; m < 4; ++m) _Pragma("unroll") for (int k = 0; k < 2; ++k) dst[m][k] = *(const PG8_LAS bf16x8*)(lds + PG8_SA(b, h) + aoff + m * 2048 + k * 1024); } while (0)
; #define PG8_LDB(dst, b, h) do { _Pragma("unroll") for (int n = 0; n < 2; ++n) _Pragma("unroll") for (int k = 0; k < 2; ++k) dst[n][k] = *(const PG8_LAS bf16x8*)(lds + PG8_SB(b, h) + boff + n * 2048 + k * 1024); } while (0)
; #define PG8_MMA(ai, bj, At, Bt) do { __builtin_amdgcn_s_setprio(1); _Pragma("unroll") for (int m = 0; m < 4; ++m) _Pragma("unroll") for (int n = 0; n < 2; ++n) _Pragma("unroll") for (int k = 0; k < 2; ++k) \
;         acc[ai][bj][m][n] = __builtin_amdgcn_mfma_f32_16x16x32_bf16(Bt[n][k], At[m][k], acc[ai][bj][m][n], 0, 0, 0); __builtin_amdgcn_s_setprio(0); } while (0)
; #define PG8_WAIT_V(n) asm volatile("s_waitcnt vmcnt(" #n ")" ::: "memory")
; #define PG8_WAIT_L(n) asm volatile("s_waitcnt lgkmcnt(" #n ")" ::: "memory")
; #define PG8_BAR __builtin_amdgcn_s_barrier()
; #define PG8_SCHED __builtin_amdgcn_sched_barrier(0)
; template <class Epi>
; __device__ __forceinline__ void gemm_phase(PG8_LAS unsigned char* lds, PG8_LAS unsigned char* xl, const Gemm g, const Sched& S, const Epi& E, const int wid) {
;     ...
;             PG8_LDB(B0, 1, 0); PG8_LDB(B1, 1, 1); PG8_SCHED; PG8_LDA(At, 1, 0); PG8_STAGE(PG8_SA(0, 1), a2 + hstepA, voffA);
;             PG8_WAIT_V(8); PG8_WAIT_L(0); PG8_BAR; if (do0) { PG8_MMA(0, 0, At, B0); PG8_MMA(0, 1, At, B1); } PG8_BAR; PG8_SCHED;
;             PG8_LDA(At, 1, 1); PG8_STAGE(PG8_SB(1, 0), b3, voffB); PG8_STAGE(PG8_SB(1, 1), b3 + hstepB, voffB); PG8_STAGE(PG8_SA(1, 0), a3, voffA);
;             PG8_WAIT_V(8); PG8_WAIT_L(0); PG8_BAR; if (do1) { PG8_MMA(1, 0, At, B0); PG8_MMA(1, 1, At, B1); } PG8_BAR; PG8_SCHED;
;         }
;         if (wr == 0) PG8_BAR;
	s_setprio 0
	s_add_i32 s4, 0, 0x18000
	s_add_i32 s5, 0, 0x1c000
	ds_read_b128 v[120:123], v226 offset:32768
	ds_read_b128 v[124:127], v226 offset:33792
	ds_read_b128 v[128:131], v226 offset:34816
	ds_read_b128 v[136:139], v226 offset:35840
	ds_read_b128 v[144:147], v226 offset:49152
	ds_read_b128 v[148:151], v226 offset:50176
	ds_read_b128 v[152:155], v226 offset:51200
	ds_read_b128 v[156:159], v226 offset:52224
	s_add_u32 s100, s10, 0x160000
	s_addc_u32 s101, s11, 0
	s_mov_b32 m0, s53
	ds_read_b128 v[160:163], v220 offset:32768
	ds_read_b128 v[164:167], v220 offset:33792
	ds_read_b128 v[168:171], v220 offset:34816
	ds_read_b128 v[172:175], v220 offset:35840
	ds_read_b128 v[176:179], v220 offset:36864
	ds_read_b128 v[180:183], v220 offset:37888
	ds_read_b128 v[184:187], v220 offset:38912
	ds_read_b128 v[222:225], v220 offset:39936
	global_load_lds_dwordx4 v188, s[100:101] sc0
	s_mov_b32 m0, s56
	s_nop 0
	global_load_lds_dwordx4 v210, s[100:101] sc0
	s_waitcnt vmcnt(8)
	s_waitcnt lgkmcnt(0)
	s_setprio 1
	s_barrier
	v_mfma_f32_16x16x32_bf16 v[140:143], v[120:123], v[160:163], v[140:143]
	v_mfma_f32_16x16x32_bf16 v[132:135], v[128:131], v[160:163], v[132:135]
	v_mfma_f32_16x16x32_bf16 v[108:111], v[120:123], v[168:171], v[108:111]
	v_mfma_f32_16x16x32_bf16 v[104:107], v[128:131], v[168:171], v[104:107]
	v_mfma_f32_16x16x32_bf16 v[92:95], v[120:123], v[176:179], v[92:95]
	v_mfma_f32_16x16x32_bf16 v[88:91], v[128:131], v[176:179], v[88:91]
	v_mfma_f32_16x16x32_bf16 v[76:79], v[120:123], v[184:187], v[76:79]
	v_mfma_f32_16x16x32_bf16 v[72:75], v[128:131], v[184:187], v[72:75]
	v_mfma_f32_16x16x32_bf16 v[140:143], v[124:127], v[164:167], v[140:143]
	v_mfma_f32_16x16x32_bf16 v[132:135], v[136:139], v[164:167], v[132:135]
	v_mfma_f32_16x16x32_bf16 v[108:111], v[124:127], v[172:175], v[108:111]
	v_mfma_f32_16x16x32_bf16 v[104:107], v[136:139], v[172:175], v[104:107]
	v_mfma_f32_16x16x32_bf16 v[92:95], v[124:127], v[180:183], v[92:95]
	v_mfma_f32_16x16x32_bf16 v[88:91], v[136:139], v[180:183], v[88:91]
	v_mfma_f32_16x16x32_bf16 v[76:79], v[124:127], v[222:225], v[76:79]
	v_mfma_f32_16x16x32_bf16 v[72:75], v[136:139], v[222:225], v[72:75]
	s_setprio 0
	s_setprio 1
	v_mfma_f32_16x16x32_bf16 v[116:119], v[144:147], v[160:163], v[116:119]
	v_mfma_f32_16x16x32_bf16 v[112:115], v[152:155], v[160:163], v[112:115]
	v_mfma_f32_16x16x32_bf16 v[100:103], v[144:147], v[168:171], v[100:103]
	v_mfma_f32_16x16x32_bf16 v[96:99], v[152:155], v[168:171], v[96:99]
	v_mfma_f32_16x16x32_bf16 v[84:87], v[144:147], v[176:179], v[84:87]
	v_mfma_f32_16x16x32_bf16 v[80:83], v[152:155], v[176:179], v[80:83]
	v_mfma_f32_16x16x32_bf16 v[68:71], v[144:147], v[184:187], v[68:71]
	v_mfma_f32_16x16x32_bf16 v[64:67], v[152:155], v[184:187], v[64:67]
	v_mfma_f32_16x16x32_bf16 v[116:119], v[148:151], v[164:167], v[116:119]
	v_mfma_f32_16x16x32_bf16 v[112:115], v[156:159], v[164:167], v[112:115]
	v_mfma_f32_16x16x32_bf16 v[100:103], v[148:151], v[172:175], v[100:103]
	v_mfma_f32_16x16x32_bf16 v[96:99], v[156:159], v[172:175], v[96:99]
	v_mfma_f32_16x16x32_bf16 v[84:87], v[148:151], v[180:183], v[84:87]
	v_mfma_f32_16x16x32_bf16 v[80:83], v[156:159], v[180:183], v[80:83]
	v_mfma_f32_16x16x32_bf16 v[68:71], v[148:151], v[222:225], v[68:71]
	v_mfma_f32_16x16x32_bf16 v[64:67], v[156:159], v[222:225], v[64:67]
	s_barrier
	s_setprio 0
	s_add_i32 s4, s4, s29
	s_mov_b32 m0, s4
	ds_read_b128 v[160:163], v220 offset:49152
	ds_read_b128 v[164:167], v220 offset:50176
	ds_read_b128 v[168:171], v220 offset:51200
	ds_read_b128 v[172:175], v220 offset:52224
	ds_read_b128 v[176:179], v220 offset:53248
	ds_read_b128 v[180:183], v220 offset:54272
	ds_read_b128 v[184:187], v220 offset:55296
	ds_read_b128 v[222:225], v220 offset:56320
	global_load_lds_dwordx4 v205, s[40:41] sc0
	s_add_i32 m0, s4, 0x2000
	s_add_u32 s100, s40, 0x160080
	global_load_lds_dwordx4 v219, s[40:41] sc0
	s_addc_u32 s101, s41, 0
	s_add_i32 s4, s5, s29
	s_mov_b32 m0, s4
	s_nop 0
	global_load_lds_dwordx4 v190, s[100:101] sc0
	s_add_i32 m0, s4, 0x2000
	s_nop 0
	global_load_lds_dwordx4 v212, s[100:101] sc0
	s_mov_b32 m0, s61
	s_nop 0
	global_load_lds_dwordx4 v204, s[10:11] sc0
	s_mov_b32 m0, s62
	s_nop 0
	global_load_lds_dwordx4 v218, s[10:11] sc0
	s_waitcnt vmcnt(8)
	s_waitcnt lgkmcnt(0)
	s_setprio 1
	s_barrier
	v_mfma_f32_16x16x32_bf16 v[60:63], v[120:123], v[160:163], v[60:63]
	v_mfma_f32_16x16x32_bf16 v[56:59], v[128:131], v[160:163], v[56:59]
	v_mfma_f32_16x16x32_bf16 v[44:47], v[120:123], v[168:171], v[44:47]
	v_mfma_f32_16x16x32_bf16 v[40:43], v[128:131], v[168:171], v[40:43]
	v_mfma_f32_16x16x32_bf16 v[28:31], v[120:123], v[176:179], v[28:31]
	v_mfma_f32_16x16x32_bf16 v[24:27], v[128:131], v[176:179], v[24:27]
	v_mfma_f32_16x16x32_bf16 v[12:15], v[120:123], v[184:187], v[12:15]
	v_mfma_f32_16x16x32_bf16 v[8:11], v[128:131], v[184:187], v[8:11]
	v_mfma_f32_16x16x32_bf16 v[60:63], v[124:127], v[164:167], v[60:63]
	v_mfma_f32_16x16x32_bf16 v[56:59], v[136:139], v[164:167], v[56:59]
	v_mfma_f32_16x16x32_bf16 v[44:47], v[124:127], v[172:175], v[44:47]
	v_mfma_f32_16x16x32_bf16 v[40:43], v[136:139], v[172:175], v[40:43]
	v_mfma_f32_16x16x32_bf16 v[28:31], v[124:127], v[180:183], v[28:31]
	v_mfma_f32_16x16x32_bf16 v[24:27], v[136:139], v[180:183], v[24:27]
	v_mfma_f32_16x16x32_bf16 v[12:15], v[124:127], v[222:225], v[12:15]
	v_mfma_f32_16x16x32_bf16 v[8:11], v[136:139], v[222:225], v[8:11]
	s_setprio 0
	s_setprio 1
	v_mfma_f32_16x16x32_bf16 v[52:55], v[144:147], v[160:163], v[52:55]
	v_mfma_f32_16x16x32_bf16 v[48:51], v[152:155], v[160:163], v[48:51]
	v_mfma_f32_16x16x32_bf16 v[36:39], v[144:147], v[168:171], v[36:39]
	v_mfma_f32_16x16x32_bf16 v[32:35], v[152:155], v[168:171], v[32:35]
	v_mfma_f32_16x16x32_bf16 v[20:23], v[144:147], v[176:179], v[20:23]
	v_mfma_f32_16x16x32_bf16 v[16:19], v[152:155], v[176:179], v[16:19]
	v_mfma_f32_16x16x32_bf16 v[4:7], v[144:147], v[184:187], v[4:7]
	v_mfma_f32_16x16x32_bf16 v[0:3], v[152:155], v[184:187], v[0:3]
	v_mfma_f32_16x16x32_bf16 v[52:55], v[148:151], v[164:167], v[52:55]
	v_mfma_f32_16x16x32_bf16 v[48:51], v[156:159], v[164:167], v[48:51]
	v_mfma_f32_16x16x32_bf16 v[36:39], v[148:151], v[172:175], v[36:39]
	v_mfma_f32_16x16x32_bf16 v[32:35], v[156:159], v[172:175], v[32:35]
	v_mfma_f32_16x16x32_bf16 v[20:23], v[148:151], v[180:183], v[20:23]
	v_mfma_f32_16x16x32_bf16 v[16:19], v[156:159], v[180:183], v[16:19]
	v_mfma_f32_16x16x32_bf16 v[4:7], v[148:151], v[222:225], v[4:7]
	v_mfma_f32_16x16x32_bf16 v[0:3], v[156:159], v[222:225], v[0:3]
	s_barrier
	s_setprio 0
	s_add_i32 s9, s9, 2
	s_add_u32 s36, s36, 0x100
	s_addc_u32 s37, s37, 0
	s_add_u32 s1, s1, 0x100
	s_addc_u32 s8, s8, 0
	s_cmpk_gt_u32 s9, 0x55
	s_cbranch_scc0 .LBB0_1304
	s_mov_b32 s100, 0
	s_and_b64 vcc, exec, s[14:15]
	s_cbranch_vccz .LBB0_1307
	s_barrier
